# lever 7 instruction selection: 1835 packed v_pk_mul/add/fma_f32 in the GEMM epilogues, P0, P2, P11 split into scalar pairs (on top of v24)
# speedup vs baseline: 1.0064x; 1.0024x over previous
.LBB0_83:
	s_ashr_i32 s10, s53, 31
	s_lshr_b32 s10, s10, 27
	s_add_i32 s10, s53, s10
	s_ashr_i32 s11, s10, 5
	s_abs_i32 s10, s11
	v_cvt_f32_u32_e32 v2, s10
	s_sub_i32 s63, 0, s10
	s_abs_i32 s48, s51
	s_xor_b32 s49, s51, s11
	v_rcp_iflag_f32_e32 v2, v2
	s_ashr_i32 s49, s49, 31
	v_mul_f32_e32 v2, 0x4f7ffffe, v2
	v_cvt_u32_f32_e32 v2, v2
	s_nop 0
	v_readfirstlane_b32 s64, v2
	s_mul_i32 s63, s63, s64
	s_mul_hi_u32 s63, s64, s63
	s_add_i32 s64, s64, s63
	s_mul_hi_u32 s63, s48, s64
	s_mul_i32 s64, s63, s10
	s_sub_i32 s48, s48, s64
	s_add_i32 s65, s63, 1
	s_sub_i32 s64, s48, s10
	s_cmp_ge_u32 s48, s10
	s_cselect_b32 s63, s65, s63
	s_cselect_b32 s48, s64, s48
	s_add_i32 s64, s63, 1
	s_cmp_ge_u32 s48, s10
	s_cselect_b32 s10, s64, s63
	s_xor_b32 s10, s10, s49
	s_sub_i32 s48, s10, s49
	s_lshl_b32 s10, s48, 6
	s_cmp_eq_u64 s[4:5], 0
	s_cbranch_scc1 .LBB0_85
	v_or_b32_e32 v80, s10, v39
	v_ashrrev_i32_e32 v81, 31, v80
	v_lshl_add_u64 v[80:81], v[80:81], 2, s[4:5]
	global_load_dword v82, v[80:81], off offset:128
	global_load_dword v83, v[80:81], off offset:136
	global_load_dword v84, v[80:81], off offset:144
	global_load_dword v85, v[80:81], off offset:152
	global_load_dword v86, v[80:81], off offset:160
	global_load_dword v87, v[80:81], off offset:168
	global_load_dword v88, v[80:81], off offset:176
	global_load_dword v89, v[80:81], off offset:184
	global_load_dword v90, v[80:81], off offset:192
	global_load_dword v91, v[80:81], off offset:200
	global_load_dword v92, v[80:81], off offset:208
	global_load_dword v93, v[80:81], off offset:216
	global_load_dword v94, v[80:81], off offset:224
	global_load_dword v95, v[80:81], off offset:232
	global_load_dword v96, v[80:81], off offset:240
	global_load_dword v97, v[80:81], off offset:248
	global_load_dword v98, v[80:81], off offset:64
	global_load_dword v99, v[80:81], off offset:72
	global_load_dword v100, v[80:81], off offset:80
	global_load_dword v101, v[80:81], off offset:88
	global_load_dword v102, v[80:81], off offset:96
	global_load_dword v103, v[80:81], off offset:104
	global_load_dword v104, v[80:81], off offset:112
	global_load_dword v105, v[80:81], off offset:120
	global_load_dword v106, v[80:81], off offset:16
	global_load_dword v107, v[80:81], off offset:24
	global_load_dword v108, v[80:81], off offset:32
	global_load_dword v110, v[80:81], off offset:48
	global_load_dword v111, v[80:81], off offset:56
	global_load_dword v109, v[80:81], off offset:40
	global_load_dword v112, v[80:81], off
	global_load_dword v113, v[80:81], off offset:8
	s_waitcnt vmcnt(30)
	v_mul_f32_e32 v58, v58, v82
	v_mul_f32_e32 v59, v59, v83
	s_waitcnt vmcnt(28)
	v_mul_f32_e32 v60, v60, v84
	v_mul_f32_e32 v61, v61, v85
	s_waitcnt vmcnt(26)
	v_mul_f32_e32 v62, v62, v86
	v_mul_f32_e32 v63, v63, v87
	s_waitcnt vmcnt(24)
	v_mul_f32_e32 v64, v64, v88
	v_mul_f32_e32 v65, v65, v89
	s_waitcnt vmcnt(22)
	v_mul_f32_e32 v66, v66, v90
	v_mul_f32_e32 v67, v67, v91
	s_waitcnt vmcnt(20)
	v_mul_f32_e32 v68, v68, v92
	v_mul_f32_e32 v69, v69, v93
	s_waitcnt vmcnt(18)
	v_mul_f32_e32 v70, v70, v94
	v_mul_f32_e32 v71, v71, v95
	s_waitcnt vmcnt(16)
	v_mul_f32_e32 v72, v72, v96
	v_mul_f32_e32 v73, v73, v97
	s_waitcnt vmcnt(14)
	v_mul_f32_e32 v50, v50, v98
	v_mul_f32_e32 v51, v51, v99
	s_waitcnt vmcnt(12)
	v_mul_f32_e32 v52, v52, v100
	v_mul_f32_e32 v53, v53, v101
	s_waitcnt vmcnt(10)
	v_mul_f32_e32 v54, v54, v102
	v_mul_f32_e32 v55, v55, v103
	s_waitcnt vmcnt(8)
	v_mul_f32_e32 v56, v56, v104
	v_mul_f32_e32 v57, v57, v105
	s_waitcnt vmcnt(6)
	v_mul_f32_e32 v44, v44, v106
	v_mul_f32_e32 v45, v45, v107
	s_waitcnt vmcnt(3)
	v_mul_f32_e32 v48, v48, v110
	v_mul_f32_e32 v49, v49, v111
	s_waitcnt vmcnt(2)
	v_mul_f32_e32 v46, v46, v108
	v_mul_f32_e32 v47, v47, v109
	s_waitcnt vmcnt(0)
	v_mul_f32_e32 v42, v42, v112
	v_mul_f32_e32 v43, v43, v113

.LBB0_122:
	s_ashr_i32 s6, s60, 31
	s_lshr_b32 s6, s6, 27
	s_add_i32 s6, s60, s6
	s_ashr_i32 s7, s6, 5
	s_abs_i32 s6, s7
	v_cvt_f32_u32_e32 v87, s6
	s_sub_i32 s48, 0, s6
	s_abs_i32 s10, s58
	s_xor_b32 s11, s58, s7
	v_rcp_iflag_f32_e32 v87, v87
	s_ashr_i32 s11, s11, 31
	v_mul_f32_e32 v87, 0x4f7ffffe, v87
	v_cvt_u32_f32_e32 v87, v87
	s_nop 0
	v_readfirstlane_b32 s49, v87
	s_mul_i32 s48, s48, s49
	s_mul_hi_u32 s48, s49, s48
	s_add_i32 s49, s49, s48
	s_mul_hi_u32 s48, s10, s49
	s_mul_i32 s49, s48, s6
	s_sub_i32 s10, s10, s49
	s_add_i32 s62, s48, 1
	s_sub_i32 s49, s10, s6
	s_cmp_ge_u32 s10, s6
	s_cselect_b32 s48, s62, s48
	s_cselect_b32 s10, s49, s10
	s_add_i32 s49, s48, 1
	s_cmp_ge_u32 s10, s6
	s_cselect_b32 s6, s49, s48
	s_xor_b32 s6, s6, s11
	s_sub_i32 s10, s6, s11
	s_lshl_b32 s6, s10, 6
	s_cmp_eq_u64 s[8:9], 0
	s_cbranch_scc1 .LBB0_124
	v_or_b32_e32 v88, s6, v39
	v_ashrrev_i32_e32 v89, 31, v88
	v_lshl_add_u64 v[88:89], v[88:89], 2, s[8:9]
	global_load_dword v90, v[88:89], off offset:128
	global_load_dword v91, v[88:89], off offset:136
	global_load_dword v92, v[88:89], off offset:144
	global_load_dword v93, v[88:89], off offset:152
	global_load_dword v94, v[88:89], off offset:160
	global_load_dword v95, v[88:89], off offset:168
	global_load_dword v96, v[88:89], off offset:176
	global_load_dword v97, v[88:89], off offset:184
	global_load_dword v98, v[88:89], off offset:192
	global_load_dword v99, v[88:89], off offset:200
	global_load_dword v100, v[88:89], off offset:208
	global_load_dword v101, v[88:89], off offset:216
	global_load_dword v102, v[88:89], off offset:224
	global_load_dword v103, v[88:89], off offset:232
	global_load_dword v104, v[88:89], off offset:240
	global_load_dword v105, v[88:89], off offset:248
	global_load_dword v106, v[88:89], off offset:64
	global_load_dword v107, v[88:89], off offset:72
	global_load_dword v108, v[88:89], off offset:80
	global_load_dword v109, v[88:89], off offset:88
	global_load_dword v110, v[88:89], off offset:96
	global_load_dword v111, v[88:89], off offset:104
	global_load_dword v112, v[88:89], off offset:112
	global_load_dword v113, v[88:89], off offset:120
	global_load_dword v114, v[88:89], off offset:16
	global_load_dword v115, v[88:89], off offset:24
	global_load_dword v116, v[88:89], off offset:32
	global_load_dword v118, v[88:89], off offset:48
	global_load_dword v119, v[88:89], off offset:56
	global_load_dword v117, v[88:89], off offset:40
	global_load_dword v120, v[88:89], off
	global_load_dword v121, v[88:89], off offset:8
	s_waitcnt vmcnt(30)
	v_mul_f32_e32 v20, v20, v90
	v_mul_f32_e32 v21, v21, v91
	s_waitcnt vmcnt(28)
	v_mul_f32_e32 v22, v22, v92
	v_mul_f32_e32 v23, v23, v93
	s_waitcnt vmcnt(26)
	v_mul_f32_e32 v24, v24, v94
	v_mul_f32_e32 v25, v25, v95
	s_waitcnt vmcnt(24)
	v_mul_f32_e32 v26, v26, v96
	v_mul_f32_e32 v27, v27, v97
	s_waitcnt vmcnt(22)
	v_mul_f32_e32 v28, v28, v98
	v_mul_f32_e32 v29, v29, v99
	s_waitcnt vmcnt(20)
	v_mul_f32_e32 v30, v30, v100
	v_mul_f32_e32 v31, v31, v101
	s_waitcnt vmcnt(18)
	v_mul_f32_e32 v32, v32, v102
	v_mul_f32_e32 v33, v33, v103
	s_waitcnt vmcnt(16)
	v_mul_f32_e32 v34, v34, v104
	v_mul_f32_e32 v35, v35, v105
	s_waitcnt vmcnt(14)
	v_mul_f32_e32 v12, v12, v106
	v_mul_f32_e32 v13, v13, v107
	s_waitcnt vmcnt(12)
	v_mul_f32_e32 v14, v14, v108
	v_mul_f32_e32 v15, v15, v109
	s_waitcnt vmcnt(10)
	v_mul_f32_e32 v16, v16, v110
	v_mul_f32_e32 v17, v17, v111
	s_waitcnt vmcnt(8)
	v_mul_f32_e32 v18, v18, v112
	v_mul_f32_e32 v19, v19, v113
	s_waitcnt vmcnt(6)
	v_mul_f32_e32 v6, v6, v114
	v_mul_f32_e32 v7, v7, v115
	s_waitcnt vmcnt(3)
	v_mul_f32_e32 v10, v10, v118
	v_mul_f32_e32 v11, v11, v119
	s_waitcnt vmcnt(2)
	v_mul_f32_e32 v8, v8, v116
	v_mul_f32_e32 v9, v9, v117
	s_waitcnt vmcnt(0)
	v_mul_f32_e32 v4, v4, v120
	v_mul_f32_e32 v5, v5, v121

.LBB0_223:
	v_lshl_add_u32 v164, s10, 8, v170
	v_ashrrev_i32_e32 v165, 31, v164
	v_or_b32_e32 v162, 16, v164
	v_lshlrev_b64 v[148:149], 6, v[164:165]
	v_ashrrev_i32_e32 v163, 31, v162
	v_or_b32_e32 v160, 32, v164
	v_lshl_add_u64 v[148:149], v[138:139], 0, v[148:149]
	v_lshlrev_b64 v[150:151], 6, v[162:163]
	v_ashrrev_i32_e32 v161, 31, v160
	v_or_b32_e32 v158, 48, v164
	v_lshl_add_u64 v[150:151], v[138:139], 0, v[150:151]
	global_load_dwordx4 v[166:169], v[148:149], off
	global_load_dwordx4 v[182:185], v[150:151], off
	v_lshlrev_b64 v[148:149], 6, v[160:161]
	v_ashrrev_i32_e32 v159, 31, v158
	v_lshl_add_u64 v[148:149], v[138:139], 0, v[148:149]
	v_lshlrev_b64 v[150:151], 6, v[158:159]
	v_lshl_add_u64 v[150:151], v[138:139], 0, v[150:151]
	global_load_dwordx4 v[186:189], v[148:149], off
	global_load_dwordx4 v[190:193], v[150:151], off
	v_add_u32_e32 v156, 0x80, v164
	v_ashrrev_i32_e32 v157, 31, v156
	v_lshlrev_b64 v[148:149], 6, v[156:157]
	v_add_u32_e32 v154, 0x90, v164
	v_lshl_add_u64 v[148:149], v[138:139], 0, v[148:149]
	v_ashrrev_i32_e32 v155, 31, v154
	global_load_dwordx4 v[194:197], v[148:149], off
	v_lshlrev_b64 v[148:149], 6, v[154:155]
	v_lshl_add_u64 v[148:149], v[138:139], 0, v[148:149]
	global_load_dwordx4 v[198:201], v[148:149], off
	v_and_b32_e32 v148, 64, v176
	v_xor_b32_e32 v137, 16, v176
	v_add_u32_e32 v151, 64, v148
	v_xor_b32_e32 v149, 32, v176
	v_add_u32_e32 v150, 0xa0, v164
	v_cmp_lt_i32_e32 vcc, v137, v151
	v_add_u32_e32 v148, 0xb0, v164
	s_cmp_gt_i32 s8, 7
	v_cndmask_b32_e32 v137, v176, v137, vcc
	v_cmp_lt_i32_e32 vcc, v149, v151
	v_ashrrev_i32_e32 v151, 31, v150
	v_lshlrev_b64 v[152:153], 6, v[150:151]
	v_lshl_add_u64 v[152:153], v[138:139], 0, v[152:153]
	global_load_dwordx4 v[204:207], v[152:153], off
	v_cndmask_b32_e32 v179, v176, v149, vcc
	v_ashrrev_i32_e32 v149, 31, v148
	v_lshlrev_b64 v[152:153], 6, v[148:149]
	v_lshl_add_u64 v[152:153], v[138:139], 0, v[152:153]
	global_load_dwordx4 v[208:211], v[152:153], off
	v_lshlrev_b32_e32 v180, 2, v137
	v_lshlrev_b32_e32 v179, 2, v179
	s_cselect_b64 s[10:11], -1, 0
	s_and_b64 s[50:51], s[10:11], exec
	s_cselect_b32 s20, -8, 0
	s_cselect_b32 s9, 0x8000000, 0
	s_add_i32 s20, s20, s8
	s_add_u32 s50, s58, s9
	s_addc_u32 s51, s59, 0
	s_cmp_lt_i32 s8, 8
	s_waitcnt vmcnt(0)
	v_mov_b32_e32 v152, v167
	v_mov_b32_e32 v153, v168
	v_mov_b32_e32 v167, v169
	v_add_f32_e32 v152, v152, v166
	v_add_f32_e32 v153, v153, v167
	v_add_f32_e32 v137, v182, v183
	v_add_f32_e32 v152, v152, v153
	v_add_f32_e32 v167, v186, v187
	v_add_f32_e32 v168, v188, v189
	v_add_f32_e32 v153, v167, v168
	ds_bpermute_b32 v168, v180, v152
	v_add_f32_e32 v166, v184, v185
	v_add_f32_e32 v169, v190, v191
	v_add_f32_e32 v181, v192, v193
	v_add_f32_e32 v137, v137, v166
	s_waitcnt lgkmcnt(0)
	v_add_f32_e32 v152, v152, v168
	v_add_f32_e32 v166, v169, v181
	ds_bpermute_b32 v181, v180, v137
	ds_bpermute_b32 v168, v179, v152
	v_add_f32_e32 v182, v194, v195
	v_add_f32_e32 v183, v196, v197
	v_add_f32_e32 v184, v198, v199
	s_waitcnt lgkmcnt(1)
	v_add_f32_e32 v193, v137, v181
	s_waitcnt lgkmcnt(0)
	v_add_f32_e32 v137, v152, v168
	v_fmamk_f32 v137, v137, 0x3a800000, v177
	v_add_f32_e32 v185, v200, v201
	v_add_f32_e32 v167, v182, v183
	ds_bpermute_b32 v182, v180, v153
	v_add_f32_e32 v169, v184, v185
	ds_bpermute_b32 v183, v180, v166
	ds_bpermute_b32 v184, v180, v167
	s_waitcnt lgkmcnt(2)
	v_add_f32_e32 v191, v153, v182
	v_mov_b64_e32 v[198:199], s[30:31]
	s_waitcnt lgkmcnt(1)
	v_add_f32_e32 v189, v166, v183
	s_waitcnt lgkmcnt(0)
	v_add_f32_e32 v187, v167, v184
	ds_bpermute_b32 v194, v179, v193
	ds_bpermute_b32 v192, v179, v191
	ds_bpermute_b32 v190, v179, v189
	ds_bpermute_b32 v188, v179, v187
	v_rsq_f32_e32 v168, v137
	s_nop 0
	v_mul_f32_e32 v124, v124, v168
	v_mul_f32_e32 v125, v125, v168
	v_add_f32_e32 v152, v204, v205
	v_and_b32_e32 v197, 0x7fffffff, v125
	v_and_b32_e32 v196, 0x7fffffff, v124
	v_fma_f32 v196, v196, s26, 1.0
	v_fma_f32 v197, v197, s26, 1.0
	v_mul_f32_e32 v204, v124, v124
	v_mul_f32_e32 v205, v125, v125
	v_rcp_f32_e32 v196, v196
	v_rcp_f32_e32 v197, v197
	v_mul_f32_e32 v204, s40, v204
	v_mul_f32_e32 v205, s40, v205
	v_mul_f32_e32 v126, v126, v168
	v_mul_f32_e32 v127, v127, v168
	v_exp_f32_e32 v204, v204
	v_fma_f32 v200, v196, s28, v198
	v_fma_f32 v201, v197, s28, v198
	v_exp_f32_e32 v205, v205
	v_fma_f32 v200, v196, v200, s34
	v_fma_f32 v201, v197, v201, s34
	ds_bpermute_b32 v137, v180, v169
	v_add_f32_e32 v153, v206, v207
	v_fma_f32 v200, v196, v200, s36
	v_fma_f32 v201, v197, v201, s36
	v_and_b32_e32 v207, 0x7fffffff, v127
	v_and_b32_e32 v206, 0x7fffffff, v126
	v_fma_f32 v200, v196, v200, s38
	v_fma_f32 v201, v197, v201, s38
	v_fma_f32 v206, v206, s26, 1.0
	v_fma_f32 v207, v207, s26, 1.0
	v_mul_f32_e32 v196, v196, v200
	v_mul_f32_e32 v197, v197, v201
	v_rcp_f32_e32 v206, v206
	v_rcp_f32_e32 v207, v207
	v_mul_f32_e32 v196, v204, v196
	v_mul_f32_e32 v197, v205, v197
	v_cmp_gt_f32_e32 vcc, 0, v124
	v_mul_f32_e32 v204, v124, v196
	v_mul_f32_e32 v205, v125, v197
	v_fma_f32 v196, -v124, v196, v124
	v_fma_f32 v197, -v125, v197, v125
	s_waitcnt lgkmcnt(0)
	v_add_f32_e32 v185, v169, v137
	v_mul_f32_e32 v200, v126, v126
	v_mul_f32_e32 v201, v127, v127
	v_cndmask_b32_e32 v137, v196, v204, vcc
	v_cmp_gt_f32_e32 vcc, 0, v125
	v_mul_f32_e32 v122, v122, v168
	v_mul_f32_e32 v123, v123, v168
	v_mul_f32_e32 v120, v120, v168
	v_mul_f32_e32 v121, v121, v168
	v_cndmask_b32_e32 v169, v197, v205, vcc
	v_fma_f32 v124, v206, s28, v198
	v_fma_f32 v125, v207, s28, v198
	v_mul_f32_e32 v196, s40, v200
	v_mul_f32_e32 v197, s40, v201
	v_fma_f32 v124, v206, v124, s34
	v_fma_f32 v125, v207, v125, s34
	v_exp_f32_e32 v196, v196
	v_exp_f32_e32 v197, v197
	v_fma_f32 v124, v206, v124, s36
	v_fma_f32 v125, v207, v125, s36
	v_and_b32_e32 v201, 0x7fffffff, v121
	v_and_b32_e32 v200, 0x7fffffff, v120
	v_fma_f32 v124, v206, v124, s38
	v_fma_f32 v125, v207, v125, s38
	v_fma_f32 v200, v200, s26, 1.0
	v_fma_f32 v201, v201, s26, 1.0
	v_mul_f32_e32 v124, v206, v124
	v_mul_f32_e32 v125, v207, v125
	v_rcp_f32_e32 v200, v200
	v_rcp_f32_e32 v201, v201
	v_mul_f32_e32 v124, v196, v124
	v_mul_f32_e32 v125, v197, v125
	v_cmp_gt_f32_e32 vcc, 0, v126
	v_mul_f32_e32 v196, v126, v124
	v_mul_f32_e32 v197, v127, v125
	v_fma_f32 v124, -v126, v124, v126
	v_fma_f32 v125, -v127, v125, v127
	v_add_f32_e32 v166, v208, v209
	v_cndmask_b32_e32 v195, v124, v196, vcc
	v_cmp_gt_f32_e32 vcc, 0, v127
	v_mul_f32_e32 v126, v120, v120
	v_mul_f32_e32 v127, v121, v121
	v_add_f32_e32 v167, v210, v211
	v_cndmask_b32_e32 v204, v125, v197, vcc
	v_fma_f32 v124, v200, s28, v198
	v_fma_f32 v125, v201, s28, v198
	v_mul_f32_e32 v126, s40, v126
	v_mul_f32_e32 v127, s40, v127
	v_fma_f32 v124, v200, v124, s34
	v_fma_f32 v125, v201, v125, s34
	v_exp_f32_e32 v126, v126
	v_fma_f32 v124, v200, v124, s36
	v_fma_f32 v125, v201, v125, s36
	v_exp_f32_e32 v127, v127
	v_fma_f32 v124, v200, v124, s38
	v_fma_f32 v125, v201, v125, s38
	v_add_f32_e32 v152, v152, v153
	v_mul_f32_e32 v124, v200, v124
	v_mul_f32_e32 v125, v201, v125
	v_and_b32_e32 v201, 0x7fffffff, v123
	v_and_b32_e32 v200, 0x7fffffff, v122
	v_fma_f32 v200, v200, s26, 1.0
	v_fma_f32 v201, v201, s26, 1.0
	v_mul_f32_e32 v124, v126, v124
	v_mul_f32_e32 v125, v127, v125
	v_rcp_f32_e32 v200, v200
	v_rcp_f32_e32 v201, v201
	v_add_f32_e32 v166, v166, v167
	v_mul_f32_e32 v126, v120, v124
	v_mul_f32_e32 v127, v121, v125
	v_fma_f32 v124, -v120, v124, v120
	v_fma_f32 v125, -v121, v125, v121
	v_cmp_gt_f32_e32 vcc, 0, v120
	ds_bpermute_b32 v153, v180, v152
	ds_bpermute_b32 v167, v180, v166
	v_mul_f32_e32 v196, v122, v122
	v_mul_f32_e32 v197, v123, v123
	v_cndmask_b32_e32 v126, v124, v126, vcc
	v_cmp_gt_f32_e32 vcc, 0, v121
	v_fma_f32 v120, v200, s28, v198
	v_fma_f32 v121, v201, s28, v198
	s_waitcnt lgkmcnt(1)
	v_add_f32_e32 v183, v152, v153
	v_cndmask_b32_e32 v127, v125, v127, vcc
	v_mul_f32_e32 v124, s40, v196
	v_mul_f32_e32 v125, s40, v197
	v_fma_f32 v120, v200, v120, s34
	v_fma_f32 v121, v201, v121, s34
	v_exp_f32_e32 v124, v124
	v_exp_f32_e32 v125, v125
	v_fma_f32 v120, v200, v120, s36
	v_fma_f32 v121, v201, v121, s36
	s_waitcnt lgkmcnt(0)
	v_add_f32_e32 v181, v166, v167
	v_fma_f32 v120, v200, v120, s38
	v_fma_f32 v121, v201, v121, s38
	ds_bpermute_b32 v186, v179, v185
	v_mul_f32_e32 v120, v200, v120
	v_mul_f32_e32 v121, v201, v121
	ds_bpermute_b32 v184, v179, v183
	ds_bpermute_b32 v182, v179, v181
	v_mul_f32_e32 v120, v124, v120
	v_mul_f32_e32 v121, v125, v121
	v_lshl_or_b32 v152, s20, 8, v172
	v_mul_f32_e32 v124, v122, v120
	v_mul_f32_e32 v125, v123, v121
	v_fma_f32 v120, -v122, v120, v122
	v_fma_f32 v121, -v123, v121, v123
	v_cmp_gt_f32_e32 vcc, 0, v122
	v_ashrrev_i32_e32 v153, 31, v152
	v_lshl_add_u64 v[152:153], v[152:153], 1, s[50:51]
	v_cndmask_b32_e32 v124, v120, v124, vcc
	v_cmp_gt_f32_e32 vcc, 0, v123
	v_lshlrev_b64 v[166:167], 12, v[164:165]
	v_lshl_add_u64 v[166:167], v[152:153], 0, v[166:167]
	v_cndmask_b32_e32 v123, v121, v125, vcc
	v_cvt_pk_bf16_f32 v120, v137, v169
	v_cvt_pk_bf16_f32 v121, v195, v204
	v_cvt_pk_bf16_f32 v122, v126, v127
	v_cvt_pk_bf16_f32 v123, v124, v123
	v_mov_b32_e32 v124, 0
	v_mov_b32_e32 v125, 0
	global_store_dwordx4 v[166:167], v[120:123], off
	s_cbranch_scc1 .LBB0_225
	v_and_b32_e32 v125, 16, v120
	v_and_b32_e32 v124, 0xffff0000, v120
	v_lshlrev_b32_e32 v197, 16, v121
	v_lshlrev_b32_e32 v196, 16, v122
	v_and_b32_e32 v126, 0xffff0000, v121
	v_mov_b32_e32 v127, v124
	v_pk_mov_b32 v[204:205], v[196:197], v[124:125] op_sel:[1,0]
	v_lshlrev_b32_e32 v120, 16, v120
	v_and_b32_e32 v198, 0xffff0000, v123
	v_mov_b32_e32 v199, v126
	v_and_b32_e32 v122, 0xffff0000, v122
	v_lshlrev_b32_e32 v200, 16, v123
	v_mov_b32_e32 v123, v197
	v_mov_b32_e32 v121, v126
	v_mov_b32_e32 v201, v126
	v_add_f32_e32 v206, v126, v204
	v_add_f32_e32 v207, v127, v205
	v_mul_f32_e32 v126, v126, v204
	v_mul_f32_e32 v127, v127, v205
	v_add_f32_e32 v124, v120, v124
	v_add_f32_e32 v125, v120, v125
	v_mov_b32_e32 v207, v127
	v_add_f32_e32 v126, v196, v122
	v_add_f32_e32 v127, v197, v123
	v_mul_f32_e32 v204, v196, v196
	v_mul_f32_e32 v205, v197, v197
	v_mov_b32_e32 v123, v198
	v_mul_f32_e32 v125, v120, v120
	v_mov_b32_e32 v127, v205
	v_add_f32_e32 v204, v198, v200
	v_add_f32_e32 v205, v199, v201
	v_mul_f32_e32 v120, v198, v120
	v_mul_f32_e32 v121, v199, v121
	v_mov_b32_e32 v197, v200
	v_mul_f32_e32 v122, v122, v122
	v_mul_f32_e32 v123, v123, v123
	v_mov_b32_e32 v205, v121
	v_fma_f32 v122, v196, v196, v122
	v_fma_f32 v123, v197, v197, v123
	v_add_f32_e32 v124, v124, v206
	v_add_f32_e32 v125, v125, v207
	v_add_f32_e32 v120, v126, v204
	v_add_f32_e32 v121, v127, v205
	v_add_f32_e32 v123, v122, v123
	v_add_f32_e32 v122, v122, v122
	v_add_f32_e32 v120, v124, v120
	v_add_f32_e32 v121, v125, v121
	v_mov_b32_e32 v137, v123
	v_add_f32_e32 v124, v120, v136
	v_add_f32_e32 v125, v121, v137
.LBB0_225:
	v_mov_b32_e32 v169, v168
	v_mul_f32_e32 v116, v116, v168
	v_mul_f32_e32 v117, v117, v169
	v_mov_b32_e32 v120, v168
	v_and_b32_e32 v123, 0x7fffffff, v117
	v_and_b32_e32 v122, 0x7fffffff, v116
	v_fma_f32 v122, v122, s26, 1.0
	v_fma_f32 v123, v123, s26, 1.0
	v_mov_b32_e32 v121, v168
	v_rcp_f32_e32 v122, v122
	v_rcp_f32_e32 v123, v123
	v_mul_f32_e32 v118, v118, v120
	v_mul_f32_e32 v119, v119, v121
	v_mul_f32_e32 v114, v114, v120
	v_mul_f32_e32 v115, v115, v121
	v_mul_f32_e32 v112, v112, v168
	v_mul_f32_e32 v113, v113, v169
	v_mov_b64_e32 v[120:121], s[30:31]
	v_mul_f32_e32 v168, v116, v116
	v_mul_f32_e32 v169, v117, v117
	v_fma_f32 v126, v122, s28, v120
	v_fma_f32 v127, v123, s28, v120
	v_mul_f32_e32 v168, s40, v168
	v_mul_f32_e32 v169, s40, v169
	v_fma_f32 v126, v122, v126, s34
	v_fma_f32 v127, v123, v127, s34
	v_exp_f32_e32 v168, v168
	v_exp_f32_e32 v169, v169
	v_fma_f32 v126, v122, v126, s36
	v_fma_f32 v127, v123, v127, s36
	v_and_b32_e32 v197, 0x7fffffff, v119
	v_and_b32_e32 v196, 0x7fffffff, v118
	v_fma_f32 v126, v122, v126, s38
	v_fma_f32 v127, v123, v127, s38
	v_fma_f32 v196, v196, s26, 1.0
	v_fma_f32 v197, v197, s26, 1.0
	v_mul_f32_e32 v122, v122, v126
	v_mul_f32_e32 v123, v123, v127
	v_rcp_f32_e32 v196, v196
	v_rcp_f32_e32 v197, v197
	v_mul_f32_e32 v122, v168, v122
	v_mul_f32_e32 v123, v169, v123
	v_cmp_gt_f32_e32 vcc, 0, v116
	v_mul_f32_e32 v168, v116, v122
	v_mul_f32_e32 v169, v117, v123
	v_fma_f32 v122, -v116, v122, v116
	v_fma_f32 v123, -v117, v123, v117
	v_mul_f32_e32 v126, v118, v118
	v_mul_f32_e32 v127, v119, v119
	v_cndmask_b32_e32 v137, v122, v168, vcc
	v_cmp_gt_f32_e32 vcc, 0, v117
	v_fma_f32 v116, v196, s28, v120
	v_fma_f32 v117, v197, s28, v120
	s_lshl_b32 s8, s20, 3
	v_cndmask_b32_e32 v168, v123, v169, vcc
	v_mul_f32_e32 v122, s40, v126
	v_mul_f32_e32 v123, s40, v127
	v_fma_f32 v116, v196, v116, s34
	v_fma_f32 v117, v197, v117, s34
	v_exp_f32_e32 v122, v122
	v_exp_f32_e32 v123, v123
	v_fma_f32 v116, v196, v116, s36
	v_fma_f32 v117, v197, v117, s36
	v_and_b32_e32 v127, 0x7fffffff, v113
	v_and_b32_e32 v126, 0x7fffffff, v112
	v_fma_f32 v116, v196, v116, s38
	v_fma_f32 v117, v197, v117, s38
	v_fma_f32 v126, v126, s26, 1.0
	v_fma_f32 v127, v127, s26, 1.0
	v_mul_f32_e32 v116, v196, v116
	v_mul_f32_e32 v117, v197, v117
	v_rcp_f32_e32 v126, v126
	v_rcp_f32_e32 v127, v127
	v_mul_f32_e32 v116, v122, v116
	v_mul_f32_e32 v117, v123, v117
	v_cmp_gt_f32_e32 vcc, 0, v118
	v_mul_f32_e32 v122, v118, v116
	v_mul_f32_e32 v123, v119, v117
	v_fma_f32 v116, -v118, v116, v118
	v_fma_f32 v117, -v119, v117, v119
	s_or_b32 s50, s8, s62
	v_cndmask_b32_e32 v169, v116, v122, vcc
	v_cmp_gt_f32_e32 vcc, 0, v119
	v_mul_f32_e32 v118, v112, v112
	v_mul_f32_e32 v119, v113, v113
	s_ashr_i32 s51, s50, 31
	v_cndmask_b32_e32 v195, v117, v123, vcc
	v_fma_f32 v116, v126, s28, v120
	v_fma_f32 v117, v127, s28, v120
	v_mul_f32_e32 v118, s40, v118
	v_mul_f32_e32 v119, s40, v119
	v_fma_f32 v116, v126, v116, s34
	v_fma_f32 v117, v127, v117, s34
	v_exp_f32_e32 v118, v118
	v_fma_f32 v116, v126, v116, s36
	v_fma_f32 v117, v127, v117, s36
	v_exp_f32_e32 v119, v119
	v_fma_f32 v116, v126, v116, s38
	v_fma_f32 v117, v127, v117, s38
	v_cmp_gt_f32_e32 vcc, 0, v112
	v_mul_f32_e32 v116, v126, v116
	v_mul_f32_e32 v117, v127, v117
	v_and_b32_e32 v127, 0x7fffffff, v115
	v_and_b32_e32 v126, 0x7fffffff, v114
	v_fma_f32 v126, v126, s26, 1.0
	v_fma_f32 v127, v127, s26, 1.0
	v_mul_f32_e32 v116, v118, v116
	v_mul_f32_e32 v117, v119, v117
	v_rcp_f32_e32 v126, v126
	v_rcp_f32_e32 v127, v127
	v_mul_f32_e32 v118, v112, v116
	v_mul_f32_e32 v119, v113, v117
	v_fma_f32 v116, -v112, v116, v112
	v_fma_f32 v117, -v113, v117, v113
	v_mul_f32_e32 v122, v114, v114
	v_mul_f32_e32 v123, v115, v115
	v_cndmask_b32_e32 v118, v116, v118, vcc
	v_cmp_gt_f32_e32 vcc, 0, v113
	v_fma_f32 v112, v126, s28, v120
	v_fma_f32 v113, v127, s28, v120
	s_nop 0
	v_cndmask_b32_e32 v119, v117, v119, vcc
	v_mul_f32_e32 v116, s40, v122
	v_mul_f32_e32 v117, s40, v123
	v_fma_f32 v112, v126, v112, s34
	v_fma_f32 v113, v127, v113, s34
	v_exp_f32_e32 v116, v116
	v_exp_f32_e32 v117, v117
	v_fma_f32 v112, v126, v112, s36
	v_fma_f32 v113, v127, v113, s36
	v_cmp_gt_f32_e32 vcc, 0, v114
	v_fma_f32 v112, v126, v112, s38
	v_fma_f32 v113, v127, v113, s38
	s_nop 0
	v_mul_f32_e32 v112, v126, v112
	v_mul_f32_e32 v113, v127, v113
	s_nop 0
	v_mul_f32_e32 v112, v116, v112
	v_mul_f32_e32 v113, v117, v113
	s_nop 0
	v_mul_f32_e32 v116, v114, v112
	v_mul_f32_e32 v117, v115, v113
	v_fma_f32 v112, -v114, v112, v114
	v_fma_f32 v113, -v115, v113, v115
	s_nop 0
	v_cndmask_b32_e32 v116, v112, v116, vcc
	v_cmp_gt_f32_e32 vcc, 0, v115
	v_cvt_pk_bf16_f32 v112, v137, v168
	s_nop 1
	v_cndmask_b32_e32 v115, v113, v117, vcc
	v_cvt_pk_bf16_f32 v113, v169, v195
	v_cvt_pk_bf16_f32 v114, v118, v119
	v_cvt_pk_bf16_f32 v115, v116, v115
	v_cndmask_b32_e64 v116, 0, 1, s[10:11]
	v_cmp_ne_u32_e64 s[8:9], 1, v116
	s_andn2_b64 vcc, exec, s[10:11]
	global_store_dwordx4 v[166:167], v[112:115], off offset:256
	s_cbranch_vccnz .LBB0_229
	v_lshlrev_b32_e32 v116, 16, v112
	v_and_b32_e32 v112, 0xffff0000, v112
	v_lshlrev_b32_e32 v118, 16, v113
	v_and_b32_e32 v120, 0xffff0000, v113
	v_lshlrev_b32_e32 v122, 16, v114
	v_and_b32_e32 v114, 0xffff0000, v114
	v_lshlrev_b32_e32 v126, 16, v115
	v_and_b32_e32 v166, 0xffff0000, v115
	v_mul_f32_e32 v117, v116, v116
	v_mul_f32_e32 v113, v112, v112
	v_mul_f32_e32 v119, v118, v118
	v_mul_f32_e32 v121, v120, v120
	v_mul_f32_e32 v123, v122, v122
	v_mul_f32_e32 v115, v114, v114
	v_mul_f32_e32 v127, v126, v126
	v_mul_f32_e32 v167, v166, v166
	v_add_f32_e32 v112, v116, v112
	v_add_f32_e32 v113, v117, v113
	v_add_f32_e32 v116, v118, v120
	v_add_f32_e32 v117, v119, v121
	v_add_f32_e32 v114, v122, v114
	v_add_f32_e32 v115, v123, v115
	v_add_f32_e32 v112, v112, v116
	v_add_f32_e32 v113, v113, v117
	v_add_f32_e32 v116, v126, v166
	v_add_f32_e32 v117, v127, v167
	s_nop 0
	v_add_f32_e32 v114, v114, v116
	v_add_f32_e32 v115, v115, v117
	s_nop 0
	v_add_f32_e32 v112, v112, v114
	v_add_f32_e32 v113, v113, v115
	s_nop 0
	v_add_f32_e32 v112, v124, v112
	v_add_f32_e32 v113, v125, v113
	ds_bpermute_b32 v114, v180, v112
	ds_bpermute_b32 v115, v180, v113
	s_waitcnt lgkmcnt(0)
	v_add_f32_e32 v112, v112, v114
	v_add_f32_e32 v113, v113, v115
	ds_bpermute_b32 v114, v179, v112
	ds_bpermute_b32 v115, v179, v113
	s_and_saveexec_b64 s[10:11], s[4:5]
	s_cbranch_execz .LBB0_228
	v_lshlrev_b64 v[116:117], 8, v[164:165]
	v_lshl_add_u64 v[116:117], s[16:17], 0, v[116:117]
	v_lshl_add_u64 v[116:117], s[50:51], 2, v[116:117]
	s_waitcnt lgkmcnt(0)
	v_add_f32_e32 v112, v112, v114
	v_add_f32_e32 v113, v113, v115
	global_store_dwordx2 v[116:117], v[112:113], off

.LBB0_229:
	s_nop 0
	v_add_f32_e32 v112, v193, v194
	v_fmamk_f32 v112, v112, 0x3a800000, v177
	v_mov_b64_e32 v[118:119], s[30:31]
	s_waitcnt lgkmcnt(1)
	s_waitcnt lgkmcnt(0)
	v_rsq_f32_e32 v114, v112
	s_nop 0
	v_mul_f32_e32 v108, v108, v114
	v_mul_f32_e32 v109, v109, v114
	v_mul_f32_e32 v110, v110, v114
	v_mul_f32_e32 v111, v111, v114
	v_and_b32_e32 v117, 0x7fffffff, v109
	v_and_b32_e32 v116, 0x7fffffff, v108
	v_fma_f32 v116, v116, s26, 1.0
	v_fma_f32 v117, v117, s26, 1.0
	v_mul_f32_e32 v122, v108, v108
	v_mul_f32_e32 v123, v109, v109
	v_rcp_f32_e32 v116, v116
	v_rcp_f32_e32 v117, v117
	v_mul_f32_e32 v122, s40, v122
	v_mul_f32_e32 v123, s40, v123
	v_and_b32_e32 v125, 0x7fffffff, v111
	v_exp_f32_e32 v122, v122
	v_fma_f32 v120, v116, s28, v118
	v_fma_f32 v121, v117, s28, v118
	v_exp_f32_e32 v123, v123
	v_fma_f32 v120, v116, v120, s34
	v_fma_f32 v121, v117, v121, s34
	v_and_b32_e32 v124, 0x7fffffff, v110
	v_fma_f32 v120, v116, v120, s36
	v_fma_f32 v121, v117, v121, s36
	v_fma_f32 v124, v124, s26, 1.0
	v_fma_f32 v125, v125, s26, 1.0
	v_fma_f32 v120, v116, v120, s38
	v_fma_f32 v121, v117, v121, s38
	v_rcp_f32_e32 v124, v124
	v_mul_f32_e32 v116, v116, v120
	v_mul_f32_e32 v117, v117, v121
	v_rcp_f32_e32 v125, v125
	v_mul_f32_e32 v116, v122, v116
	v_mul_f32_e32 v117, v123, v117
	v_cmp_gt_f32_e32 vcc, 0, v108
	v_mul_f32_e32 v122, v108, v116
	v_mul_f32_e32 v123, v109, v117
	v_fma_f32 v116, -v108, v116, v108
	v_fma_f32 v117, -v109, v117, v109
	v_mul_f32_e32 v106, v106, v114
	v_mul_f32_e32 v107, v107, v114
	v_mul_f32_e32 v104, v104, v114
	v_mul_f32_e32 v105, v105, v114
	v_mul_f32_e32 v120, v110, v110
	v_mul_f32_e32 v121, v111, v111
	v_cndmask_b32_e32 v115, v116, v122, vcc
	v_cmp_gt_f32_e32 vcc, 0, v109
	v_fma_f32 v108, v124, s28, v118
	v_fma_f32 v109, v125, s28, v118
	v_lshlrev_b64 v[112:113], 12, v[162:163]
	v_cndmask_b32_e32 v122, v117, v123, vcc
	v_mul_f32_e32 v116, s40, v120
	v_mul_f32_e32 v117, s40, v121
	v_fma_f32 v108, v124, v108, s34
	v_fma_f32 v109, v125, v109, s34
	v_exp_f32_e32 v116, v116
	v_exp_f32_e32 v117, v117
	v_fma_f32 v108, v124, v108, s36
	v_fma_f32 v109, v125, v109, s36
	v_and_b32_e32 v121, 0x7fffffff, v105
	v_and_b32_e32 v120, 0x7fffffff, v104
	v_fma_f32 v108, v124, v108, s38
	v_fma_f32 v109, v125, v109, s38
	v_fma_f32 v120, v120, s26, 1.0
	v_fma_f32 v121, v121, s26, 1.0
	v_mul_f32_e32 v108, v124, v108
	v_mul_f32_e32 v109, v125, v109
	v_rcp_f32_e32 v120, v120
	v_rcp_f32_e32 v121, v121
	v_mul_f32_e32 v108, v116, v108
	v_mul_f32_e32 v109, v117, v109
	v_cmp_gt_f32_e32 vcc, 0, v110
	v_mul_f32_e32 v116, v110, v108
	v_mul_f32_e32 v117, v111, v109
	v_fma_f32 v108, -v110, v108, v110
	v_fma_f32 v109, -v111, v109, v111
	v_lshl_add_u64 v[112:113], v[152:153], 0, v[112:113]
	v_cndmask_b32_e32 v123, v108, v116, vcc
	v_cmp_gt_f32_e32 vcc, 0, v111
	v_mul_f32_e32 v110, v104, v104
	v_mul_f32_e32 v111, v105, v105
	s_nop 0
	v_cndmask_b32_e32 v124, v109, v117, vcc
	v_fma_f32 v108, v120, s28, v118
	v_fma_f32 v109, v121, s28, v118
	v_mul_f32_e32 v110, s40, v110
	v_mul_f32_e32 v111, s40, v111
	v_fma_f32 v108, v120, v108, s34
	v_fma_f32 v109, v121, v109, s34
	v_exp_f32_e32 v110, v110
	v_fma_f32 v108, v120, v108, s36
	v_fma_f32 v109, v121, v109, s36
	v_exp_f32_e32 v111, v111
	v_fma_f32 v108, v120, v108, s38
	v_fma_f32 v109, v121, v109, s38
	v_cmp_gt_f32_e32 vcc, 0, v104
	v_mul_f32_e32 v108, v120, v108
	v_mul_f32_e32 v109, v121, v109
	v_and_b32_e32 v121, 0x7fffffff, v107
	v_and_b32_e32 v120, 0x7fffffff, v106
	v_fma_f32 v120, v120, s26, 1.0
	v_fma_f32 v121, v121, s26, 1.0
	v_mul_f32_e32 v108, v110, v108
	v_mul_f32_e32 v109, v111, v109
	v_rcp_f32_e32 v120, v120
	v_rcp_f32_e32 v121, v121
	v_mul_f32_e32 v110, v104, v108
	v_mul_f32_e32 v111, v105, v109
	v_fma_f32 v108, -v104, v108, v104
	v_fma_f32 v109, -v105, v109, v105
	v_mul_f32_e32 v116, v106, v106
	v_mul_f32_e32 v117, v107, v107
	v_cndmask_b32_e32 v110, v108, v110, vcc
	v_cmp_gt_f32_e32 vcc, 0, v105
	v_fma_f32 v104, v120, s28, v118
	v_fma_f32 v105, v121, s28, v118
	s_nop 0
	v_cndmask_b32_e32 v111, v109, v111, vcc
	v_mul_f32_e32 v108, s40, v116
	v_mul_f32_e32 v109, s40, v117
	v_fma_f32 v104, v120, v104, s34
	v_fma_f32 v105, v121, v105, s34
	v_exp_f32_e32 v108, v108
	v_exp_f32_e32 v109, v109
	v_fma_f32 v104, v120, v104, s36
	v_fma_f32 v105, v121, v105, s36
	v_cmp_gt_f32_e32 vcc, 0, v106
	v_fma_f32 v104, v120, v104, s38
	v_fma_f32 v105, v121, v105, s38
	s_nop 0
	v_mul_f32_e32 v104, v120, v104
	v_mul_f32_e32 v105, v121, v105
	s_nop 0
	v_mul_f32_e32 v104, v108, v104
	v_mul_f32_e32 v105, v109, v105
	s_nop 0
	v_mul_f32_e32 v108, v106, v104
	v_mul_f32_e32 v109, v107, v105
	v_fma_f32 v104, -v106, v104, v106
	v_fma_f32 v105, -v107, v105, v107
	s_nop 0
	v_cndmask_b32_e32 v108, v104, v108, vcc
	v_cmp_gt_f32_e32 vcc, 0, v107
	v_cvt_pk_bf16_f32 v104, v115, v122
	s_nop 1
	v_cndmask_b32_e32 v107, v105, v109, vcc
	v_cvt_pk_bf16_f32 v105, v123, v124
	v_cvt_pk_bf16_f32 v106, v110, v111
	v_cvt_pk_bf16_f32 v107, v108, v107
	v_mov_b32_e32 v108, 0
	s_and_b64 vcc, exec, s[8:9]
	v_mov_b32_e32 v109, 0
	global_store_dwordx4 v[112:113], v[104:107], off
	s_cbranch_vccnz .LBB0_231
	v_and_b32_e32 v109, 16, v104
	v_and_b32_e32 v108, 0xffff0000, v104
	v_lshlrev_b32_e32 v117, 16, v105
	v_lshlrev_b32_e32 v116, 16, v106
	v_and_b32_e32 v110, 0xffff0000, v105
	v_mov_b32_e32 v111, v108
	v_pk_mov_b32 v[122:123], v[116:117], v[108:109] op_sel:[1,0]
	v_lshlrev_b32_e32 v104, 16, v104
	v_and_b32_e32 v118, 0xffff0000, v107
	v_mov_b32_e32 v119, v110
	v_and_b32_e32 v106, 0xffff0000, v106
	v_lshlrev_b32_e32 v120, 16, v107
	v_mov_b32_e32 v107, v117
	v_mov_b32_e32 v105, v110
	v_mov_b32_e32 v121, v110
	v_add_f32_e32 v124, v110, v122
	v_add_f32_e32 v125, v111, v123
	v_mul_f32_e32 v110, v110, v122
	v_mul_f32_e32 v111, v111, v123
	v_add_f32_e32 v108, v104, v108
	v_add_f32_e32 v109, v104, v109
	v_mov_b32_e32 v125, v111
	v_add_f32_e32 v110, v116, v106
	v_add_f32_e32 v111, v117, v107
	v_mul_f32_e32 v122, v116, v116
	v_mul_f32_e32 v123, v117, v117
	v_mov_b32_e32 v107, v118
	v_mul_f32_e32 v109, v104, v104
	v_mov_b32_e32 v111, v123
	v_add_f32_e32 v122, v118, v120
	v_add_f32_e32 v123, v119, v121
	v_mul_f32_e32 v104, v118, v104
	v_mul_f32_e32 v105, v119, v105
	v_mov_b32_e32 v117, v120
	v_mul_f32_e32 v106, v106, v106
	v_mul_f32_e32 v107, v107, v107
	v_mov_b32_e32 v123, v105
	v_fma_f32 v106, v116, v116, v106
	v_fma_f32 v107, v117, v117, v107
	v_add_f32_e32 v108, v108, v124
	v_add_f32_e32 v109, v109, v125
	v_add_f32_e32 v104, v110, v122
	v_add_f32_e32 v105, v111, v123
	v_add_f32_e32 v107, v106, v107
	v_add_f32_e32 v106, v106, v106
	v_add_f32_e32 v104, v108, v104
	v_add_f32_e32 v105, v109, v105
	v_mov_b32_e32 v137, v107
	v_add_f32_e32 v108, v104, v136
	v_add_f32_e32 v109, v105, v137
.LBB0_231:
	v_mov_b32_e32 v115, v114
	v_mul_f32_e32 v100, v100, v114
	v_mul_f32_e32 v101, v101, v115
	v_mov_b32_e32 v104, v114
	v_and_b32_e32 v107, 0x7fffffff, v101
	v_and_b32_e32 v106, 0x7fffffff, v100
	v_fma_f32 v106, v106, s26, 1.0
	v_fma_f32 v107, v107, s26, 1.0
	v_mov_b32_e32 v105, v114
	v_rcp_f32_e32 v106, v106
	v_rcp_f32_e32 v107, v107
	v_mul_f32_e32 v102, v102, v104
	v_mul_f32_e32 v103, v103, v105
	v_mul_f32_e32 v98, v98, v104
	v_mul_f32_e32 v99, v99, v105
	v_mul_f32_e32 v96, v96, v114
	v_mul_f32_e32 v97, v97, v115
	v_mov_b64_e32 v[104:105], s[30:31]
	v_mul_f32_e32 v114, v100, v100
	v_mul_f32_e32 v115, v101, v101
	v_fma_f32 v110, v106, s28, v104
	v_fma_f32 v111, v107, s28, v104
	v_mul_f32_e32 v114, s40, v114
	v_mul_f32_e32 v115, s40, v115
	v_fma_f32 v110, v106, v110, s34
	v_fma_f32 v111, v107, v111, s34
	v_exp_f32_e32 v114, v114
	v_exp_f32_e32 v115, v115
	v_fma_f32 v110, v106, v110, s36
	v_fma_f32 v111, v107, v111, s36
	v_and_b32_e32 v117, 0x7fffffff, v103
	v_and_b32_e32 v116, 0x7fffffff, v102
	v_fma_f32 v110, v106, v110, s38
	v_fma_f32 v111, v107, v111, s38
	v_fma_f32 v116, v116, s26, 1.0
	v_fma_f32 v117, v117, s26, 1.0
	v_mul_f32_e32 v106, v106, v110
	v_mul_f32_e32 v107, v107, v111
	v_rcp_f32_e32 v116, v116
	v_rcp_f32_e32 v117, v117
	v_mul_f32_e32 v106, v114, v106
	v_mul_f32_e32 v107, v115, v107
	v_cmp_gt_f32_e32 vcc, 0, v100
	v_mul_f32_e32 v114, v100, v106
	v_mul_f32_e32 v115, v101, v107
	v_fma_f32 v106, -v100, v106, v100
	v_fma_f32 v107, -v101, v107, v101
	v_mul_f32_e32 v110, v102, v102
	v_mul_f32_e32 v111, v103, v103
	v_cndmask_b32_e32 v114, v106, v114, vcc
	v_cmp_gt_f32_e32 vcc, 0, v101
	v_fma_f32 v100, v116, s28, v104
	v_fma_f32 v101, v117, s28, v104
	s_nop 0
	v_cndmask_b32_e32 v115, v107, v115, vcc
	v_mul_f32_e32 v106, s40, v110
	v_mul_f32_e32 v107, s40, v111
	v_fma_f32 v100, v116, v100, s34
	v_fma_f32 v101, v117, v101, s34
	v_exp_f32_e32 v106, v106
	v_exp_f32_e32 v107, v107
	v_fma_f32 v100, v116, v100, s36
	v_fma_f32 v101, v117, v101, s36
	v_and_b32_e32 v111, 0x7fffffff, v97
	v_and_b32_e32 v110, 0x7fffffff, v96
	v_fma_f32 v100, v116, v100, s38
	v_fma_f32 v101, v117, v101, s38
	v_fma_f32 v110, v110, s26, 1.0
	v_fma_f32 v111, v111, s26, 1.0
	v_mul_f32_e32 v100, v116, v100
	v_mul_f32_e32 v101, v117, v101
	v_rcp_f32_e32 v110, v110
	v_rcp_f32_e32 v111, v111
	v_mul_f32_e32 v100, v106, v100
	v_mul_f32_e32 v101, v107, v101
	v_cmp_gt_f32_e32 vcc, 0, v102
	v_mul_f32_e32 v106, v102, v100
	v_mul_f32_e32 v107, v103, v101
	v_fma_f32 v100, -v102, v100, v102
	v_fma_f32 v101, -v103, v101, v103
	s_nop 0
	v_cndmask_b32_e32 v116, v100, v106, vcc
	v_cmp_gt_f32_e32 vcc, 0, v103
	v_mul_f32_e32 v102, v96, v96
	v_mul_f32_e32 v103, v97, v97
	s_nop 0
	v_cndmask_b32_e32 v117, v101, v107, vcc
	v_fma_f32 v100, v110, s28, v104
	v_fma_f32 v101, v111, s28, v104
	v_mul_f32_e32 v102, s40, v102
	v_mul_f32_e32 v103, s40, v103
	v_fma_f32 v100, v110, v100, s34
	v_fma_f32 v101, v111, v101, s34
	v_exp_f32_e32 v102, v102
	v_fma_f32 v100, v110, v100, s36
	v_fma_f32 v101, v111, v101, s36
	v_exp_f32_e32 v103, v103
	v_fma_f32 v100, v110, v100, s38
	v_fma_f32 v101, v111, v101, s38
	v_cmp_gt_f32_e32 vcc, 0, v96
	v_mul_f32_e32 v100, v110, v100
	v_mul_f32_e32 v101, v111, v101
	v_and_b32_e32 v111, 0x7fffffff, v99
	v_and_b32_e32 v110, 0x7fffffff, v98
	v_fma_f32 v110, v110, s26, 1.0
	v_fma_f32 v111, v111, s26, 1.0
	v_mul_f32_e32 v100, v102, v100
	v_mul_f32_e32 v101, v103, v101
	v_rcp_f32_e32 v110, v110
	v_rcp_f32_e32 v111, v111
	v_mul_f32_e32 v102, v96, v100
	v_mul_f32_e32 v103, v97, v101
	v_fma_f32 v100, -v96, v100, v96
	v_fma_f32 v101, -v97, v101, v97
	v_mul_f32_e32 v106, v98, v98
	v_mul_f32_e32 v107, v99, v99
	v_cndmask_b32_e32 v102, v100, v102, vcc
	v_cmp_gt_f32_e32 vcc, 0, v97
	v_fma_f32 v96, v110, s28, v104
	v_fma_f32 v97, v111, s28, v104
	s_nop 0
	v_cndmask_b32_e32 v103, v101, v103, vcc
	v_mul_f32_e32 v100, s40, v106
	v_mul_f32_e32 v101, s40, v107
	v_fma_f32 v96, v110, v96, s34
	v_fma_f32 v97, v111, v97, s34
	v_exp_f32_e32 v100, v100
	v_exp_f32_e32 v101, v101
	v_fma_f32 v96, v110, v96, s36
	v_fma_f32 v97, v111, v97, s36
	v_cmp_gt_f32_e32 vcc, 0, v98
	v_fma_f32 v96, v110, v96, s38
	v_fma_f32 v97, v111, v97, s38
	s_nop 0
	v_mul_f32_e32 v96, v110, v96
	v_mul_f32_e32 v97, v111, v97
	s_nop 0
	v_mul_f32_e32 v96, v100, v96
	v_mul_f32_e32 v97, v101, v97
	s_nop 0
	v_mul_f32_e32 v100, v98, v96
	v_mul_f32_e32 v101, v99, v97
	v_fma_f32 v96, -v98, v96, v98
	v_fma_f32 v97, -v99, v97, v99
	s_nop 0
	v_cndmask_b32_e32 v100, v96, v100, vcc
	v_cmp_gt_f32_e32 vcc, 0, v99
	v_cvt_pk_bf16_f32 v96, v114, v115
	s_nop 1
	v_cndmask_b32_e32 v99, v97, v101, vcc
	s_and_b64 vcc, exec, s[8:9]
	v_cvt_pk_bf16_f32 v97, v116, v117
	v_cvt_pk_bf16_f32 v98, v102, v103
	v_cvt_pk_bf16_f32 v99, v100, v99
	global_store_dwordx4 v[112:113], v[96:99], off offset:256
	s_cbranch_vccnz .LBB0_235
	v_lshlrev_b32_e32 v100, 16, v96
	v_and_b32_e32 v96, 0xffff0000, v96
	v_lshlrev_b32_e32 v102, 16, v97
	v_and_b32_e32 v104, 0xffff0000, v97
	v_lshlrev_b32_e32 v106, 16, v98
	v_and_b32_e32 v98, 0xffff0000, v98
	v_lshlrev_b32_e32 v110, 16, v99
	v_and_b32_e32 v112, 0xffff0000, v99
	v_mul_f32_e32 v101, v100, v100
	v_mul_f32_e32 v97, v96, v96
	v_mul_f32_e32 v103, v102, v102
	v_mul_f32_e32 v105, v104, v104
	v_mul_f32_e32 v107, v106, v106
	v_mul_f32_e32 v99, v98, v98
	v_mul_f32_e32 v111, v110, v110
	v_mul_f32_e32 v113, v112, v112
	v_add_f32_e32 v96, v100, v96
	v_add_f32_e32 v97, v101, v97
	v_add_f32_e32 v100, v102, v104
	v_add_f32_e32 v101, v103, v105
	v_add_f32_e32 v98, v106, v98
	v_add_f32_e32 v99, v107, v99
	v_add_f32_e32 v96, v96, v100
	v_add_f32_e32 v97, v97, v101
	v_add_f32_e32 v100, v110, v112
	v_add_f32_e32 v101, v111, v113
	s_nop 0
	v_add_f32_e32 v98, v98, v100
	v_add_f32_e32 v99, v99, v101
	s_nop 0
	v_add_f32_e32 v96, v96, v98
	v_add_f32_e32 v97, v97, v99
	s_nop 0
	v_add_f32_e32 v96, v108, v96
	v_add_f32_e32 v97, v109, v97
	ds_bpermute_b32 v98, v180, v96
	ds_bpermute_b32 v99, v180, v97
	s_waitcnt lgkmcnt(0)
	v_add_f32_e32 v96, v96, v98
	v_add_f32_e32 v97, v97, v99
	ds_bpermute_b32 v98, v179, v96
	ds_bpermute_b32 v99, v179, v97
	s_and_saveexec_b64 s[10:11], s[4:5]
	s_cbranch_execz .LBB0_234
	v_lshlrev_b64 v[100:101], 8, v[162:163]
	v_lshl_add_u64 v[100:101], s[16:17], 0, v[100:101]
	v_lshl_add_u64 v[100:101], s[50:51], 2, v[100:101]
	s_waitcnt lgkmcnt(0)
	v_add_f32_e32 v96, v96, v98
	v_add_f32_e32 v97, v97, v99
	global_store_dwordx2 v[100:101], v[96:97], off

.LBB0_235:
	s_nop 0
	v_add_f32_e32 v96, v191, v192
	v_fmamk_f32 v96, v96, 0x3a800000, v177
	v_mov_b64_e32 v[102:103], s[30:31]
	s_waitcnt lgkmcnt(1)
	s_waitcnt lgkmcnt(0)
	v_rsq_f32_e32 v98, v96
	s_nop 0
	v_mul_f32_e32 v92, v92, v98
	v_mul_f32_e32 v93, v93, v98
	v_mul_f32_e32 v94, v94, v98
	v_mul_f32_e32 v95, v95, v98
	v_and_b32_e32 v101, 0x7fffffff, v93
	v_and_b32_e32 v100, 0x7fffffff, v92
	v_fma_f32 v100, v100, s26, 1.0
	v_fma_f32 v101, v101, s26, 1.0
	v_mul_f32_e32 v106, v92, v92
	v_mul_f32_e32 v107, v93, v93
	v_rcp_f32_e32 v100, v100
	v_rcp_f32_e32 v101, v101
	v_mul_f32_e32 v106, s40, v106
	v_mul_f32_e32 v107, s40, v107
	v_and_b32_e32 v109, 0x7fffffff, v95
	v_exp_f32_e32 v106, v106
	v_fma_f32 v104, v100, s28, v102
	v_fma_f32 v105, v101, s28, v102
	v_exp_f32_e32 v107, v107
	v_fma_f32 v104, v100, v104, s34
	v_fma_f32 v105, v101, v105, s34
	v_and_b32_e32 v108, 0x7fffffff, v94
	v_fma_f32 v104, v100, v104, s36
	v_fma_f32 v105, v101, v105, s36
	v_fma_f32 v108, v108, s26, 1.0
	v_fma_f32 v109, v109, s26, 1.0
	v_fma_f32 v104, v100, v104, s38
	v_fma_f32 v105, v101, v105, s38
	v_rcp_f32_e32 v108, v108
	v_mul_f32_e32 v100, v100, v104
	v_mul_f32_e32 v101, v101, v105
	v_rcp_f32_e32 v109, v109
	v_mul_f32_e32 v100, v106, v100
	v_mul_f32_e32 v101, v107, v101
	v_cmp_gt_f32_e32 vcc, 0, v92
	v_mul_f32_e32 v106, v92, v100
	v_mul_f32_e32 v107, v93, v101
	v_fma_f32 v100, -v92, v100, v92
	v_fma_f32 v101, -v93, v101, v93
	v_mul_f32_e32 v90, v90, v98
	v_mul_f32_e32 v91, v91, v98
	v_mul_f32_e32 v88, v88, v98
	v_mul_f32_e32 v89, v89, v98
	v_mul_f32_e32 v104, v94, v94
	v_mul_f32_e32 v105, v95, v95
	v_cndmask_b32_e32 v99, v100, v106, vcc
	v_cmp_gt_f32_e32 vcc, 0, v93
	v_fma_f32 v92, v108, s28, v102
	v_fma_f32 v93, v109, s28, v102
	v_lshlrev_b64 v[96:97], 12, v[160:161]
	v_cndmask_b32_e32 v106, v101, v107, vcc
	v_mul_f32_e32 v100, s40, v104
	v_mul_f32_e32 v101, s40, v105
	v_fma_f32 v92, v108, v92, s34
	v_fma_f32 v93, v109, v93, s34
	v_exp_f32_e32 v100, v100
	v_exp_f32_e32 v101, v101
	v_fma_f32 v92, v108, v92, s36
	v_fma_f32 v93, v109, v93, s36
	v_and_b32_e32 v105, 0x7fffffff, v89
	v_and_b32_e32 v104, 0x7fffffff, v88
	v_fma_f32 v92, v108, v92, s38
	v_fma_f32 v93, v109, v93, s38
	v_fma_f32 v104, v104, s26, 1.0
	v_fma_f32 v105, v105, s26, 1.0
	v_mul_f32_e32 v92, v108, v92
	v_mul_f32_e32 v93, v109, v93
	v_rcp_f32_e32 v104, v104
	v_rcp_f32_e32 v105, v105
	v_mul_f32_e32 v92, v100, v92
	v_mul_f32_e32 v93, v101, v93
	v_cmp_gt_f32_e32 vcc, 0, v94
	v_mul_f32_e32 v100, v94, v92
	v_mul_f32_e32 v101, v95, v93
	v_fma_f32 v92, -v94, v92, v94
	v_fma_f32 v93, -v95, v93, v95
	v_lshl_add_u64 v[96:97], v[152:153], 0, v[96:97]
	v_cndmask_b32_e32 v107, v92, v100, vcc
	v_cmp_gt_f32_e32 vcc, 0, v95
	v_mul_f32_e32 v94, v88, v88
	v_mul_f32_e32 v95, v89, v89
	s_nop 0
	v_cndmask_b32_e32 v108, v93, v101, vcc
	v_fma_f32 v92, v104, s28, v102
	v_fma_f32 v93, v105, s28, v102
	v_mul_f32_e32 v94, s40, v94
	v_mul_f32_e32 v95, s40, v95
	v_fma_f32 v92, v104, v92, s34
	v_fma_f32 v93, v105, v93, s34
	v_exp_f32_e32 v94, v94
	v_fma_f32 v92, v104, v92, s36
	v_fma_f32 v93, v105, v93, s36
	v_exp_f32_e32 v95, v95
	v_fma_f32 v92, v104, v92, s38
	v_fma_f32 v93, v105, v93, s38
	v_cmp_gt_f32_e32 vcc, 0, v88
	v_mul_f32_e32 v92, v104, v92
	v_mul_f32_e32 v93, v105, v93
	v_and_b32_e32 v105, 0x7fffffff, v91
	v_and_b32_e32 v104, 0x7fffffff, v90
	v_fma_f32 v104, v104, s26, 1.0
	v_fma_f32 v105, v105, s26, 1.0
	v_mul_f32_e32 v92, v94, v92
	v_mul_f32_e32 v93, v95, v93
	v_rcp_f32_e32 v104, v104
	v_rcp_f32_e32 v105, v105
	v_mul_f32_e32 v94, v88, v92
	v_mul_f32_e32 v95, v89, v93
	v_fma_f32 v92, -v88, v92, v88
	v_fma_f32 v93, -v89, v93, v89
	v_mul_f32_e32 v100, v90, v90
	v_mul_f32_e32 v101, v91, v91
	v_cndmask_b32_e32 v94, v92, v94, vcc
	v_cmp_gt_f32_e32 vcc, 0, v89
	v_fma_f32 v88, v104, s28, v102
	v_fma_f32 v89, v105, s28, v102
	s_nop 0
	v_cndmask_b32_e32 v95, v93, v95, vcc
	v_mul_f32_e32 v92, s40, v100
	v_mul_f32_e32 v93, s40, v101
	v_fma_f32 v88, v104, v88, s34
	v_fma_f32 v89, v105, v89, s34
	v_exp_f32_e32 v92, v92
	v_exp_f32_e32 v93, v93
	v_fma_f32 v88, v104, v88, s36
	v_fma_f32 v89, v105, v89, s36
	v_cmp_gt_f32_e32 vcc, 0, v90
	v_fma_f32 v88, v104, v88, s38
	v_fma_f32 v89, v105, v89, s38
	s_nop 0
	v_mul_f32_e32 v88, v104, v88
	v_mul_f32_e32 v89, v105, v89
	s_nop 0
	v_mul_f32_e32 v88, v92, v88
	v_mul_f32_e32 v89, v93, v89
	s_nop 0
	v_mul_f32_e32 v92, v90, v88
	v_mul_f32_e32 v93, v91, v89
	v_fma_f32 v88, -v90, v88, v90
	v_fma_f32 v89, -v91, v89, v91
	s_nop 0
	v_cndmask_b32_e32 v92, v88, v92, vcc
	v_cmp_gt_f32_e32 vcc, 0, v91
	v_cvt_pk_bf16_f32 v88, v99, v106
	s_nop 1
	v_cndmask_b32_e32 v91, v89, v93, vcc
	v_cvt_pk_bf16_f32 v89, v107, v108
	v_cvt_pk_bf16_f32 v90, v94, v95
	v_cvt_pk_bf16_f32 v91, v92, v91
	v_mov_b32_e32 v92, 0
	s_and_b64 vcc, exec, s[8:9]
	v_mov_b32_e32 v93, 0
	global_store_dwordx4 v[96:97], v[88:91], off
	s_cbranch_vccnz .LBB0_237
	v_and_b32_e32 v93, 16, v88
	v_and_b32_e32 v92, 0xffff0000, v88
	v_lshlrev_b32_e32 v101, 16, v89
	v_lshlrev_b32_e32 v100, 16, v90
	v_and_b32_e32 v94, 0xffff0000, v89
	v_mov_b32_e32 v95, v92
	v_pk_mov_b32 v[106:107], v[100:101], v[92:93] op_sel:[1,0]
	v_lshlrev_b32_e32 v88, 16, v88
	v_and_b32_e32 v102, 0xffff0000, v91
	v_mov_b32_e32 v103, v94
	v_and_b32_e32 v90, 0xffff0000, v90
	v_lshlrev_b32_e32 v104, 16, v91
	v_mov_b32_e32 v91, v101
	v_mov_b32_e32 v89, v94
	v_mov_b32_e32 v105, v94
	v_add_f32_e32 v108, v94, v106
	v_add_f32_e32 v109, v95, v107
	v_mul_f32_e32 v94, v94, v106
	v_mul_f32_e32 v95, v95, v107
	v_add_f32_e32 v92, v88, v92
	v_add_f32_e32 v93, v88, v93
	v_mov_b32_e32 v109, v95
	v_add_f32_e32 v94, v100, v90
	v_add_f32_e32 v95, v101, v91
	v_mul_f32_e32 v106, v100, v100
	v_mul_f32_e32 v107, v101, v101
	v_mov_b32_e32 v91, v102
	v_mul_f32_e32 v93, v88, v88
	v_mov_b32_e32 v95, v107
	v_add_f32_e32 v106, v102, v104
	v_add_f32_e32 v107, v103, v105
	v_mul_f32_e32 v88, v102, v88
	v_mul_f32_e32 v89, v103, v89
	v_mov_b32_e32 v101, v104
	v_mul_f32_e32 v90, v90, v90
	v_mul_f32_e32 v91, v91, v91
	v_mov_b32_e32 v107, v89
	v_fma_f32 v90, v100, v100, v90
	v_fma_f32 v91, v101, v101, v91
	v_add_f32_e32 v92, v92, v108
	v_add_f32_e32 v93, v93, v109
	v_add_f32_e32 v88, v94, v106
	v_add_f32_e32 v89, v95, v107
	v_add_f32_e32 v91, v90, v91
	v_add_f32_e32 v90, v90, v90
	v_add_f32_e32 v88, v92, v88
	v_add_f32_e32 v89, v93, v89
	v_mov_b32_e32 v137, v91
	v_add_f32_e32 v92, v88, v136
	v_add_f32_e32 v93, v89, v137
.LBB0_237:
	v_mov_b32_e32 v99, v98
	v_mul_f32_e32 v84, v84, v98
	v_mul_f32_e32 v85, v85, v99
	v_mov_b32_e32 v88, v98
	v_and_b32_e32 v91, 0x7fffffff, v85
	v_and_b32_e32 v90, 0x7fffffff, v84
	v_fma_f32 v90, v90, s26, 1.0
	v_fma_f32 v91, v91, s26, 1.0
	v_mov_b32_e32 v89, v98
	v_rcp_f32_e32 v90, v90
	v_rcp_f32_e32 v91, v91
	v_mul_f32_e32 v86, v86, v88
	v_mul_f32_e32 v87, v87, v89
	v_mul_f32_e32 v82, v82, v88
	v_mul_f32_e32 v83, v83, v89
	v_mul_f32_e32 v80, v80, v98
	v_mul_f32_e32 v81, v81, v99
	v_mov_b64_e32 v[88:89], s[30:31]
	v_mul_f32_e32 v98, v84, v84
	v_mul_f32_e32 v99, v85, v85
	v_fma_f32 v94, v90, s28, v88
	v_fma_f32 v95, v91, s28, v88
	v_mul_f32_e32 v98, s40, v98
	v_mul_f32_e32 v99, s40, v99
	v_fma_f32 v94, v90, v94, s34
	v_fma_f32 v95, v91, v95, s34
	v_exp_f32_e32 v98, v98
	v_exp_f32_e32 v99, v99
	v_fma_f32 v94, v90, v94, s36
	v_fma_f32 v95, v91, v95, s36
	v_and_b32_e32 v101, 0x7fffffff, v87
	v_and_b32_e32 v100, 0x7fffffff, v86
	v_fma_f32 v94, v90, v94, s38
	v_fma_f32 v95, v91, v95, s38
	v_fma_f32 v100, v100, s26, 1.0
	v_fma_f32 v101, v101, s26, 1.0
	v_mul_f32_e32 v90, v90, v94
	v_mul_f32_e32 v91, v91, v95
	v_rcp_f32_e32 v100, v100
	v_rcp_f32_e32 v101, v101
	v_mul_f32_e32 v90, v98, v90
	v_mul_f32_e32 v91, v99, v91
	v_cmp_gt_f32_e32 vcc, 0, v84
	v_mul_f32_e32 v98, v84, v90
	v_mul_f32_e32 v99, v85, v91
	v_fma_f32 v90, -v84, v90, v84
	v_fma_f32 v91, -v85, v91, v85
	v_mul_f32_e32 v94, v86, v86
	v_mul_f32_e32 v95, v87, v87
	v_cndmask_b32_e32 v98, v90, v98, vcc
	v_cmp_gt_f32_e32 vcc, 0, v85
	v_fma_f32 v84, v100, s28, v88
	v_fma_f32 v85, v101, s28, v88
	s_nop 0
	v_cndmask_b32_e32 v99, v91, v99, vcc
	v_mul_f32_e32 v90, s40, v94
	v_mul_f32_e32 v91, s40, v95
	v_fma_f32 v84, v100, v84, s34
	v_fma_f32 v85, v101, v85, s34
	v_exp_f32_e32 v90, v90
	v_exp_f32_e32 v91, v91
	v_fma_f32 v84, v100, v84, s36
	v_fma_f32 v85, v101, v85, s36
	v_and_b32_e32 v95, 0x7fffffff, v81
	v_and_b32_e32 v94, 0x7fffffff, v80
	v_fma_f32 v84, v100, v84, s38
	v_fma_f32 v85, v101, v85, s38
	v_fma_f32 v94, v94, s26, 1.0
	v_fma_f32 v95, v95, s26, 1.0
	v_mul_f32_e32 v84, v100, v84
	v_mul_f32_e32 v85, v101, v85
	v_rcp_f32_e32 v94, v94
	v_rcp_f32_e32 v95, v95
	v_mul_f32_e32 v84, v90, v84
	v_mul_f32_e32 v85, v91, v85
	v_cmp_gt_f32_e32 vcc, 0, v86
	v_mul_f32_e32 v90, v86, v84
	v_mul_f32_e32 v91, v87, v85
	v_fma_f32 v84, -v86, v84, v86
	v_fma_f32 v85, -v87, v85, v87
	s_nop 0
	v_cndmask_b32_e32 v100, v84, v90, vcc
	v_cmp_gt_f32_e32 vcc, 0, v87
	v_mul_f32_e32 v86, v80, v80
	v_mul_f32_e32 v87, v81, v81
	s_nop 0
	v_cndmask_b32_e32 v101, v85, v91, vcc
	v_fma_f32 v84, v94, s28, v88
	v_fma_f32 v85, v95, s28, v88
	v_mul_f32_e32 v86, s40, v86
	v_mul_f32_e32 v87, s40, v87
	v_fma_f32 v84, v94, v84, s34
	v_fma_f32 v85, v95, v85, s34
	v_exp_f32_e32 v86, v86
	v_fma_f32 v84, v94, v84, s36
	v_fma_f32 v85, v95, v85, s36
	v_exp_f32_e32 v87, v87
	v_fma_f32 v84, v94, v84, s38
	v_fma_f32 v85, v95, v85, s38
	v_cmp_gt_f32_e32 vcc, 0, v80
	v_mul_f32_e32 v84, v94, v84
	v_mul_f32_e32 v85, v95, v85
	v_and_b32_e32 v95, 0x7fffffff, v83
	v_and_b32_e32 v94, 0x7fffffff, v82
	v_fma_f32 v94, v94, s26, 1.0
	v_fma_f32 v95, v95, s26, 1.0
	v_mul_f32_e32 v84, v86, v84
	v_mul_f32_e32 v85, v87, v85
	v_rcp_f32_e32 v94, v94
	v_rcp_f32_e32 v95, v95
	v_mul_f32_e32 v86, v80, v84
	v_mul_f32_e32 v87, v81, v85
	v_fma_f32 v84, -v80, v84, v80
	v_fma_f32 v85, -v81, v85, v81
	v_mul_f32_e32 v90, v82, v82
	v_mul_f32_e32 v91, v83, v83
	v_cndmask_b32_e32 v86, v84, v86, vcc
	v_cmp_gt_f32_e32 vcc, 0, v81
	v_fma_f32 v80, v94, s28, v88
	v_fma_f32 v81, v95, s28, v88
	s_nop 0
	v_cndmask_b32_e32 v87, v85, v87, vcc
	v_mul_f32_e32 v84, s40, v90
	v_mul_f32_e32 v85, s40, v91
	v_fma_f32 v80, v94, v80, s34
	v_fma_f32 v81, v95, v81, s34
	v_exp_f32_e32 v84, v84
	v_exp_f32_e32 v85, v85
	v_fma_f32 v80, v94, v80, s36
	v_fma_f32 v81, v95, v81, s36
	v_cmp_gt_f32_e32 vcc, 0, v82
	v_fma_f32 v80, v94, v80, s38
	v_fma_f32 v81, v95, v81, s38
	s_nop 0
	v_mul_f32_e32 v80, v94, v80
	v_mul_f32_e32 v81, v95, v81
	s_nop 0
	v_mul_f32_e32 v80, v84, v80
	v_mul_f32_e32 v81, v85, v81
	s_nop 0
	v_mul_f32_e32 v84, v82, v80
	v_mul_f32_e32 v85, v83, v81
	v_fma_f32 v80, -v82, v80, v82
	v_fma_f32 v81, -v83, v81, v83
	s_nop 0
	v_cndmask_b32_e32 v84, v80, v84, vcc
	v_cmp_gt_f32_e32 vcc, 0, v83
	v_cvt_pk_bf16_f32 v80, v98, v99
	s_nop 1
	v_cndmask_b32_e32 v83, v81, v85, vcc
	s_and_b64 vcc, exec, s[8:9]
	v_cvt_pk_bf16_f32 v81, v100, v101
	v_cvt_pk_bf16_f32 v82, v86, v87
	v_cvt_pk_bf16_f32 v83, v84, v83
	global_store_dwordx4 v[96:97], v[80:83], off offset:256
	s_cbranch_vccnz .LBB0_241
	v_lshlrev_b32_e32 v84, 16, v80
	v_and_b32_e32 v80, 0xffff0000, v80
	v_lshlrev_b32_e32 v86, 16, v81
	v_and_b32_e32 v88, 0xffff0000, v81
	v_lshlrev_b32_e32 v90, 16, v82
	v_and_b32_e32 v82, 0xffff0000, v82
	v_lshlrev_b32_e32 v94, 16, v83
	v_and_b32_e32 v96, 0xffff0000, v83
	v_mul_f32_e32 v85, v84, v84
	v_mul_f32_e32 v81, v80, v80
	v_mul_f32_e32 v87, v86, v86
	v_mul_f32_e32 v89, v88, v88
	v_mul_f32_e32 v91, v90, v90
	v_mul_f32_e32 v83, v82, v82
	v_mul_f32_e32 v95, v94, v94
	v_mul_f32_e32 v97, v96, v96
	v_add_f32_e32 v80, v84, v80
	v_add_f32_e32 v81, v85, v81
	v_add_f32_e32 v84, v86, v88
	v_add_f32_e32 v85, v87, v89
	v_add_f32_e32 v82, v90, v82
	v_add_f32_e32 v83, v91, v83
	v_add_f32_e32 v80, v80, v84
	v_add_f32_e32 v81, v81, v85
	v_add_f32_e32 v84, v94, v96
	v_add_f32_e32 v85, v95, v97
	s_nop 0
	v_add_f32_e32 v82, v82, v84
	v_add_f32_e32 v83, v83, v85
	s_nop 0
	v_add_f32_e32 v80, v80, v82
	v_add_f32_e32 v81, v81, v83
	s_nop 0
	v_add_f32_e32 v80, v92, v80
	v_add_f32_e32 v81, v93, v81
	ds_bpermute_b32 v82, v180, v80
	ds_bpermute_b32 v83, v180, v81
	s_waitcnt lgkmcnt(0)
	v_add_f32_e32 v80, v80, v82
	v_add_f32_e32 v81, v81, v83
	ds_bpermute_b32 v82, v179, v80
	ds_bpermute_b32 v83, v179, v81
	s_and_saveexec_b64 s[10:11], s[4:5]
	s_cbranch_execz .LBB0_240
	v_lshlrev_b64 v[84:85], 8, v[160:161]
	v_lshl_add_u64 v[84:85], s[16:17], 0, v[84:85]
	v_lshl_add_u64 v[84:85], s[50:51], 2, v[84:85]
	s_waitcnt lgkmcnt(0)
	v_add_f32_e32 v80, v80, v82
	v_add_f32_e32 v81, v81, v83
	global_store_dwordx2 v[84:85], v[80:81], off

.LBB0_241:
	s_nop 0
	v_add_f32_e32 v80, v189, v190
	v_fmamk_f32 v80, v80, 0x3a800000, v177
	v_mov_b64_e32 v[86:87], s[30:31]
	s_waitcnt lgkmcnt(1)
	s_waitcnt lgkmcnt(0)
	v_rsq_f32_e32 v82, v80
	s_nop 0
	v_mul_f32_e32 v76, v76, v82
	v_mul_f32_e32 v77, v77, v82
	v_mul_f32_e32 v78, v78, v82
	v_mul_f32_e32 v79, v79, v82
	v_and_b32_e32 v85, 0x7fffffff, v77
	v_and_b32_e32 v84, 0x7fffffff, v76
	v_fma_f32 v84, v84, s26, 1.0
	v_fma_f32 v85, v85, s26, 1.0
	v_mul_f32_e32 v90, v76, v76
	v_mul_f32_e32 v91, v77, v77
	v_rcp_f32_e32 v84, v84
	v_rcp_f32_e32 v85, v85
	v_mul_f32_e32 v90, s40, v90
	v_mul_f32_e32 v91, s40, v91
	v_and_b32_e32 v93, 0x7fffffff, v79
	v_exp_f32_e32 v90, v90
	v_fma_f32 v88, v84, s28, v86
	v_fma_f32 v89, v85, s28, v86
	v_exp_f32_e32 v91, v91
	v_fma_f32 v88, v84, v88, s34
	v_fma_f32 v89, v85, v89, s34
	v_and_b32_e32 v92, 0x7fffffff, v78
	v_fma_f32 v88, v84, v88, s36
	v_fma_f32 v89, v85, v89, s36
	v_fma_f32 v92, v92, s26, 1.0
	v_fma_f32 v93, v93, s26, 1.0
	v_fma_f32 v88, v84, v88, s38
	v_fma_f32 v89, v85, v89, s38
	v_rcp_f32_e32 v92, v92
	v_mul_f32_e32 v84, v84, v88
	v_mul_f32_e32 v85, v85, v89
	v_rcp_f32_e32 v93, v93
	v_mul_f32_e32 v84, v90, v84
	v_mul_f32_e32 v85, v91, v85
	v_cmp_gt_f32_e32 vcc, 0, v76
	v_mul_f32_e32 v90, v76, v84
	v_mul_f32_e32 v91, v77, v85
	v_fma_f32 v84, -v76, v84, v76
	v_fma_f32 v85, -v77, v85, v77
	v_mul_f32_e32 v74, v74, v82
	v_mul_f32_e32 v75, v75, v82
	v_mul_f32_e32 v72, v72, v82
	v_mul_f32_e32 v73, v73, v82
	v_mul_f32_e32 v88, v78, v78
	v_mul_f32_e32 v89, v79, v79
	v_cndmask_b32_e32 v83, v84, v90, vcc
	v_cmp_gt_f32_e32 vcc, 0, v77
	v_fma_f32 v76, v92, s28, v86
	v_fma_f32 v77, v93, s28, v86
	v_lshlrev_b64 v[80:81], 12, v[158:159]
	v_cndmask_b32_e32 v90, v85, v91, vcc
	v_mul_f32_e32 v84, s40, v88
	v_mul_f32_e32 v85, s40, v89
	v_fma_f32 v76, v92, v76, s34
	v_fma_f32 v77, v93, v77, s34
	v_exp_f32_e32 v84, v84
	v_exp_f32_e32 v85, v85
	v_fma_f32 v76, v92, v76, s36
	v_fma_f32 v77, v93, v77, s36
	v_and_b32_e32 v89, 0x7fffffff, v73
	v_and_b32_e32 v88, 0x7fffffff, v72
	v_fma_f32 v76, v92, v76, s38
	v_fma_f32 v77, v93, v77, s38
	v_fma_f32 v88, v88, s26, 1.0
	v_fma_f32 v89, v89, s26, 1.0
	v_mul_f32_e32 v76, v92, v76
	v_mul_f32_e32 v77, v93, v77
	v_rcp_f32_e32 v88, v88
	v_rcp_f32_e32 v89, v89
	v_mul_f32_e32 v76, v84, v76
	v_mul_f32_e32 v77, v85, v77
	v_cmp_gt_f32_e32 vcc, 0, v78
	v_mul_f32_e32 v84, v78, v76
	v_mul_f32_e32 v85, v79, v77
	v_fma_f32 v76, -v78, v76, v78
	v_fma_f32 v77, -v79, v77, v79
	v_lshl_add_u64 v[80:81], v[152:153], 0, v[80:81]
	v_cndmask_b32_e32 v91, v76, v84, vcc
	v_cmp_gt_f32_e32 vcc, 0, v79
	v_mul_f32_e32 v78, v72, v72
	v_mul_f32_e32 v79, v73, v73
	s_nop 0
	v_cndmask_b32_e32 v92, v77, v85, vcc
	v_fma_f32 v76, v88, s28, v86
	v_fma_f32 v77, v89, s28, v86
	v_mul_f32_e32 v78, s40, v78
	v_mul_f32_e32 v79, s40, v79
	v_fma_f32 v76, v88, v76, s34
	v_fma_f32 v77, v89, v77, s34
	v_exp_f32_e32 v78, v78
	v_fma_f32 v76, v88, v76, s36
	v_fma_f32 v77, v89, v77, s36
	v_exp_f32_e32 v79, v79
	v_fma_f32 v76, v88, v76, s38
	v_fma_f32 v77, v89, v77, s38
	v_cmp_gt_f32_e32 vcc, 0, v72
	v_mul_f32_e32 v76, v88, v76
	v_mul_f32_e32 v77, v89, v77
	v_and_b32_e32 v89, 0x7fffffff, v75
	v_and_b32_e32 v88, 0x7fffffff, v74
	v_fma_f32 v88, v88, s26, 1.0
	v_fma_f32 v89, v89, s26, 1.0
	v_mul_f32_e32 v76, v78, v76
	v_mul_f32_e32 v77, v79, v77
	v_rcp_f32_e32 v88, v88
	v_rcp_f32_e32 v89, v89
	v_mul_f32_e32 v78, v72, v76
	v_mul_f32_e32 v79, v73, v77
	v_fma_f32 v76, -v72, v76, v72
	v_fma_f32 v77, -v73, v77, v73
	v_mul_f32_e32 v84, v74, v74
	v_mul_f32_e32 v85, v75, v75
	v_cndmask_b32_e32 v78, v76, v78, vcc
	v_cmp_gt_f32_e32 vcc, 0, v73
	v_fma_f32 v72, v88, s28, v86
	v_fma_f32 v73, v89, s28, v86
	s_nop 0
	v_cndmask_b32_e32 v79, v77, v79, vcc
	v_mul_f32_e32 v76, s40, v84
	v_mul_f32_e32 v77, s40, v85
	v_fma_f32 v72, v88, v72, s34
	v_fma_f32 v73, v89, v73, s34
	v_exp_f32_e32 v76, v76
	v_exp_f32_e32 v77, v77
	v_fma_f32 v72, v88, v72, s36
	v_fma_f32 v73, v89, v73, s36
	v_cmp_gt_f32_e32 vcc, 0, v74
	v_fma_f32 v72, v88, v72, s38
	v_fma_f32 v73, v89, v73, s38
	s_nop 0
	v_mul_f32_e32 v72, v88, v72
	v_mul_f32_e32 v73, v89, v73
	s_nop 0
	v_mul_f32_e32 v72, v76, v72
	v_mul_f32_e32 v73, v77, v73
	s_nop 0
	v_mul_f32_e32 v76, v74, v72
	v_mul_f32_e32 v77, v75, v73
	v_fma_f32 v72, -v74, v72, v74
	v_fma_f32 v73, -v75, v73, v75
	s_nop 0
	v_cndmask_b32_e32 v76, v72, v76, vcc
	v_cmp_gt_f32_e32 vcc, 0, v75
	v_cvt_pk_bf16_f32 v72, v83, v90
	s_nop 1
	v_cndmask_b32_e32 v75, v73, v77, vcc
	v_cvt_pk_bf16_f32 v73, v91, v92
	v_cvt_pk_bf16_f32 v74, v78, v79
	v_cvt_pk_bf16_f32 v75, v76, v75
	v_mov_b32_e32 v76, 0
	s_and_b64 vcc, exec, s[8:9]
	v_mov_b32_e32 v77, 0
	global_store_dwordx4 v[80:81], v[72:75], off
	s_cbranch_vccnz .LBB0_243
	v_and_b32_e32 v77, 16, v72
	v_and_b32_e32 v76, 0xffff0000, v72
	v_lshlrev_b32_e32 v85, 16, v73
	v_lshlrev_b32_e32 v84, 16, v74
	v_and_b32_e32 v78, 0xffff0000, v73
	v_mov_b32_e32 v79, v76
	v_pk_mov_b32 v[90:91], v[84:85], v[76:77] op_sel:[1,0]
	v_lshlrev_b32_e32 v72, 16, v72
	v_and_b32_e32 v86, 0xffff0000, v75
	v_mov_b32_e32 v87, v78
	v_and_b32_e32 v74, 0xffff0000, v74
	v_lshlrev_b32_e32 v88, 16, v75
	v_mov_b32_e32 v75, v85
	v_mov_b32_e32 v73, v78
	v_mov_b32_e32 v89, v78
	v_add_f32_e32 v92, v78, v90
	v_add_f32_e32 v93, v79, v91
	v_mul_f32_e32 v78, v78, v90
	v_mul_f32_e32 v79, v79, v91
	v_add_f32_e32 v76, v72, v76
	v_add_f32_e32 v77, v72, v77
	v_mov_b32_e32 v93, v79
	v_add_f32_e32 v78, v84, v74
	v_add_f32_e32 v79, v85, v75
	v_mul_f32_e32 v90, v84, v84
	v_mul_f32_e32 v91, v85, v85
	v_mov_b32_e32 v75, v86
	v_mul_f32_e32 v77, v72, v72
	v_mov_b32_e32 v79, v91
	v_add_f32_e32 v90, v86, v88
	v_add_f32_e32 v91, v87, v89
	v_mul_f32_e32 v72, v86, v72
	v_mul_f32_e32 v73, v87, v73
	v_mov_b32_e32 v85, v88
	v_mul_f32_e32 v74, v74, v74
	v_mul_f32_e32 v75, v75, v75
	v_mov_b32_e32 v91, v73
	v_fma_f32 v74, v84, v84, v74
	v_fma_f32 v75, v85, v85, v75
	v_add_f32_e32 v76, v76, v92
	v_add_f32_e32 v77, v77, v93
	v_add_f32_e32 v72, v78, v90
	v_add_f32_e32 v73, v79, v91
	v_add_f32_e32 v75, v74, v75
	v_add_f32_e32 v74, v74, v74
	v_add_f32_e32 v72, v76, v72
	v_add_f32_e32 v73, v77, v73
	v_mov_b32_e32 v137, v75
	v_add_f32_e32 v76, v72, v136
	v_add_f32_e32 v77, v73, v137
.LBB0_243:
	v_mov_b32_e32 v83, v82
	v_mul_f32_e32 v68, v68, v82
	v_mul_f32_e32 v69, v69, v83
	v_mov_b32_e32 v72, v82
	v_and_b32_e32 v75, 0x7fffffff, v69
	v_and_b32_e32 v74, 0x7fffffff, v68
	v_fma_f32 v74, v74, s26, 1.0
	v_fma_f32 v75, v75, s26, 1.0
	v_mov_b32_e32 v73, v82
	v_rcp_f32_e32 v74, v74
	v_rcp_f32_e32 v75, v75
	v_mul_f32_e32 v70, v70, v72
	v_mul_f32_e32 v71, v71, v73
	v_mul_f32_e32 v66, v66, v72
	v_mul_f32_e32 v67, v67, v73
	v_mul_f32_e32 v64, v64, v82
	v_mul_f32_e32 v65, v65, v83
	v_mov_b64_e32 v[72:73], s[30:31]
	v_mul_f32_e32 v82, v68, v68
	v_mul_f32_e32 v83, v69, v69
	v_fma_f32 v78, v74, s28, v72
	v_fma_f32 v79, v75, s28, v72
	v_mul_f32_e32 v82, s40, v82
	v_mul_f32_e32 v83, s40, v83
	v_fma_f32 v78, v74, v78, s34
	v_fma_f32 v79, v75, v79, s34
	v_exp_f32_e32 v82, v82
	v_exp_f32_e32 v83, v83
	v_fma_f32 v78, v74, v78, s36
	v_fma_f32 v79, v75, v79, s36
	v_and_b32_e32 v85, 0x7fffffff, v71
	v_and_b32_e32 v84, 0x7fffffff, v70
	v_fma_f32 v78, v74, v78, s38
	v_fma_f32 v79, v75, v79, s38
	v_fma_f32 v84, v84, s26, 1.0
	v_fma_f32 v85, v85, s26, 1.0
	v_mul_f32_e32 v74, v74, v78
	v_mul_f32_e32 v75, v75, v79
	v_rcp_f32_e32 v84, v84
	v_rcp_f32_e32 v85, v85
	v_mul_f32_e32 v74, v82, v74
	v_mul_f32_e32 v75, v83, v75
	v_cmp_gt_f32_e32 vcc, 0, v68
	v_mul_f32_e32 v82, v68, v74
	v_mul_f32_e32 v83, v69, v75
	v_fma_f32 v74, -v68, v74, v68
	v_fma_f32 v75, -v69, v75, v69
	v_mul_f32_e32 v78, v70, v70
	v_mul_f32_e32 v79, v71, v71
	v_cndmask_b32_e32 v82, v74, v82, vcc
	v_cmp_gt_f32_e32 vcc, 0, v69
	v_fma_f32 v68, v84, s28, v72
	v_fma_f32 v69, v85, s28, v72
	s_nop 0
	v_cndmask_b32_e32 v83, v75, v83, vcc
	v_mul_f32_e32 v74, s40, v78
	v_mul_f32_e32 v75, s40, v79
	v_fma_f32 v68, v84, v68, s34
	v_fma_f32 v69, v85, v69, s34
	v_exp_f32_e32 v74, v74
	v_exp_f32_e32 v75, v75
	v_fma_f32 v68, v84, v68, s36
	v_fma_f32 v69, v85, v69, s36
	v_and_b32_e32 v79, 0x7fffffff, v65
	v_and_b32_e32 v78, 0x7fffffff, v64
	v_fma_f32 v68, v84, v68, s38
	v_fma_f32 v69, v85, v69, s38
	v_fma_f32 v78, v78, s26, 1.0
	v_fma_f32 v79, v79, s26, 1.0
	v_mul_f32_e32 v68, v84, v68
	v_mul_f32_e32 v69, v85, v69
	v_rcp_f32_e32 v78, v78
	v_rcp_f32_e32 v79, v79
	v_mul_f32_e32 v68, v74, v68
	v_mul_f32_e32 v69, v75, v69
	v_cmp_gt_f32_e32 vcc, 0, v70
	v_mul_f32_e32 v74, v70, v68
	v_mul_f32_e32 v75, v71, v69
	v_fma_f32 v68, -v70, v68, v70
	v_fma_f32 v69, -v71, v69, v71
	s_nop 0
	v_cndmask_b32_e32 v84, v68, v74, vcc
	v_cmp_gt_f32_e32 vcc, 0, v71
	v_mul_f32_e32 v70, v64, v64
	v_mul_f32_e32 v71, v65, v65
	s_nop 0
	v_cndmask_b32_e32 v85, v69, v75, vcc
	v_fma_f32 v68, v78, s28, v72
	v_fma_f32 v69, v79, s28, v72
	v_mul_f32_e32 v70, s40, v70
	v_mul_f32_e32 v71, s40, v71
	v_fma_f32 v68, v78, v68, s34
	v_fma_f32 v69, v79, v69, s34
	v_exp_f32_e32 v70, v70
	v_fma_f32 v68, v78, v68, s36
	v_fma_f32 v69, v79, v69, s36
	v_exp_f32_e32 v71, v71
	v_fma_f32 v68, v78, v68, s38
	v_fma_f32 v69, v79, v69, s38
	v_cmp_gt_f32_e32 vcc, 0, v64
	v_mul_f32_e32 v68, v78, v68
	v_mul_f32_e32 v69, v79, v69
	v_and_b32_e32 v79, 0x7fffffff, v67
	v_and_b32_e32 v78, 0x7fffffff, v66
	v_fma_f32 v78, v78, s26, 1.0
	v_fma_f32 v79, v79, s26, 1.0
	v_mul_f32_e32 v68, v70, v68
	v_mul_f32_e32 v69, v71, v69
	v_rcp_f32_e32 v78, v78
	v_rcp_f32_e32 v79, v79
	v_mul_f32_e32 v70, v64, v68
	v_mul_f32_e32 v71, v65, v69
	v_fma_f32 v68, -v64, v68, v64
	v_fma_f32 v69, -v65, v69, v65
	v_mul_f32_e32 v74, v66, v66
	v_mul_f32_e32 v75, v67, v67
	v_cndmask_b32_e32 v70, v68, v70, vcc
	v_cmp_gt_f32_e32 vcc, 0, v65
	v_fma_f32 v64, v78, s28, v72
	v_fma_f32 v65, v79, s28, v72
	s_nop 0
	v_cndmask_b32_e32 v71, v69, v71, vcc
	v_mul_f32_e32 v68, s40, v74
	v_mul_f32_e32 v69, s40, v75
	v_fma_f32 v64, v78, v64, s34
	v_fma_f32 v65, v79, v65, s34
	v_exp_f32_e32 v68, v68
	v_exp_f32_e32 v69, v69
	v_fma_f32 v64, v78, v64, s36
	v_fma_f32 v65, v79, v65, s36
	v_cmp_gt_f32_e32 vcc, 0, v66
	v_fma_f32 v64, v78, v64, s38
	v_fma_f32 v65, v79, v65, s38
	s_nop 0
	v_mul_f32_e32 v64, v78, v64
	v_mul_f32_e32 v65, v79, v65
	s_nop 0
	v_mul_f32_e32 v64, v68, v64
	v_mul_f32_e32 v65, v69, v65
	s_nop 0
	v_mul_f32_e32 v68, v66, v64
	v_mul_f32_e32 v69, v67, v65
	v_fma_f32 v64, -v66, v64, v66
	v_fma_f32 v65, -v67, v65, v67
	s_nop 0
	v_cndmask_b32_e32 v68, v64, v68, vcc
	v_cmp_gt_f32_e32 vcc, 0, v67
	v_cvt_pk_bf16_f32 v64, v82, v83
	s_nop 1
	v_cndmask_b32_e32 v67, v65, v69, vcc
	s_and_b64 vcc, exec, s[8:9]
	v_cvt_pk_bf16_f32 v65, v84, v85
	v_cvt_pk_bf16_f32 v66, v70, v71
	v_cvt_pk_bf16_f32 v67, v68, v67
	global_store_dwordx4 v[80:81], v[64:67], off offset:256
	s_cbranch_vccnz .LBB0_247
	v_lshlrev_b32_e32 v68, 16, v64
	v_and_b32_e32 v64, 0xffff0000, v64
	v_lshlrev_b32_e32 v70, 16, v65
	v_and_b32_e32 v72, 0xffff0000, v65
	v_lshlrev_b32_e32 v74, 16, v66
	v_and_b32_e32 v66, 0xffff0000, v66
	v_lshlrev_b32_e32 v78, 16, v67
	v_and_b32_e32 v80, 0xffff0000, v67
	v_mul_f32_e32 v69, v68, v68
	v_mul_f32_e32 v65, v64, v64
	v_mul_f32_e32 v71, v70, v70
	v_mul_f32_e32 v73, v72, v72
	v_mul_f32_e32 v75, v74, v74
	v_mul_f32_e32 v67, v66, v66
	v_mul_f32_e32 v79, v78, v78
	v_mul_f32_e32 v81, v80, v80
	v_add_f32_e32 v64, v68, v64
	v_add_f32_e32 v65, v69, v65
	v_add_f32_e32 v68, v70, v72
	v_add_f32_e32 v69, v71, v73
	v_add_f32_e32 v66, v74, v66
	v_add_f32_e32 v67, v75, v67
	v_add_f32_e32 v64, v64, v68
	v_add_f32_e32 v65, v65, v69
	v_add_f32_e32 v68, v78, v80
	v_add_f32_e32 v69, v79, v81
	s_nop 0
	v_add_f32_e32 v66, v66, v68
	v_add_f32_e32 v67, v67, v69
	s_nop 0
	v_add_f32_e32 v64, v64, v66
	v_add_f32_e32 v65, v65, v67
	s_nop 0
	v_add_f32_e32 v64, v76, v64
	v_add_f32_e32 v65, v77, v65
	ds_bpermute_b32 v66, v180, v64
	ds_bpermute_b32 v67, v180, v65
	s_waitcnt lgkmcnt(0)
	v_add_f32_e32 v64, v64, v66
	v_add_f32_e32 v65, v65, v67
	ds_bpermute_b32 v66, v179, v64
	ds_bpermute_b32 v67, v179, v65
	s_and_saveexec_b64 s[10:11], s[4:5]
	s_cbranch_execz .LBB0_246
	v_lshlrev_b64 v[68:69], 8, v[158:159]
	v_lshl_add_u64 v[68:69], s[16:17], 0, v[68:69]
	v_lshl_add_u64 v[68:69], s[50:51], 2, v[68:69]
	s_waitcnt lgkmcnt(0)
	v_add_f32_e32 v64, v64, v66
	v_add_f32_e32 v65, v65, v67
	global_store_dwordx2 v[68:69], v[64:65], off

.LBB0_247:
	s_nop 0
	v_add_f32_e32 v64, v187, v188
	v_fmamk_f32 v64, v64, 0x3a800000, v177
	v_mov_b64_e32 v[70:71], s[30:31]
	s_waitcnt lgkmcnt(1)
	s_waitcnt lgkmcnt(0)
	v_rsq_f32_e32 v66, v64
	s_nop 0
	v_mul_f32_e32 v60, v60, v66
	v_mul_f32_e32 v61, v61, v66
	v_mul_f32_e32 v62, v62, v66
	v_mul_f32_e32 v63, v63, v66
	v_and_b32_e32 v69, 0x7fffffff, v61
	v_and_b32_e32 v68, 0x7fffffff, v60
	v_fma_f32 v68, v68, s26, 1.0
	v_fma_f32 v69, v69, s26, 1.0
	v_mul_f32_e32 v74, v60, v60
	v_mul_f32_e32 v75, v61, v61
	v_rcp_f32_e32 v68, v68
	v_rcp_f32_e32 v69, v69
	v_mul_f32_e32 v74, s40, v74
	v_mul_f32_e32 v75, s40, v75
	v_and_b32_e32 v77, 0x7fffffff, v63
	v_exp_f32_e32 v74, v74
	v_fma_f32 v72, v68, s28, v70
	v_fma_f32 v73, v69, s28, v70
	v_exp_f32_e32 v75, v75
	v_fma_f32 v72, v68, v72, s34
	v_fma_f32 v73, v69, v73, s34
	v_and_b32_e32 v76, 0x7fffffff, v62
	v_fma_f32 v72, v68, v72, s36
	v_fma_f32 v73, v69, v73, s36
	v_fma_f32 v76, v76, s26, 1.0
	v_fma_f32 v77, v77, s26, 1.0
	v_fma_f32 v72, v68, v72, s38
	v_fma_f32 v73, v69, v73, s38
	v_rcp_f32_e32 v76, v76
	v_mul_f32_e32 v68, v68, v72
	v_mul_f32_e32 v69, v69, v73
	v_rcp_f32_e32 v77, v77
	v_mul_f32_e32 v68, v74, v68
	v_mul_f32_e32 v69, v75, v69
	v_cmp_gt_f32_e32 vcc, 0, v60
	v_mul_f32_e32 v74, v60, v68
	v_mul_f32_e32 v75, v61, v69
	v_fma_f32 v68, -v60, v68, v60
	v_fma_f32 v69, -v61, v69, v61
	v_mul_f32_e32 v58, v58, v66
	v_mul_f32_e32 v59, v59, v66
	v_mul_f32_e32 v56, v56, v66
	v_mul_f32_e32 v57, v57, v66
	v_mul_f32_e32 v72, v62, v62
	v_mul_f32_e32 v73, v63, v63
	v_cndmask_b32_e32 v67, v68, v74, vcc
	v_cmp_gt_f32_e32 vcc, 0, v61
	v_fma_f32 v60, v76, s28, v70
	v_fma_f32 v61, v77, s28, v70
	v_lshlrev_b64 v[64:65], 12, v[156:157]
	v_cndmask_b32_e32 v74, v69, v75, vcc
	v_mul_f32_e32 v68, s40, v72
	v_mul_f32_e32 v69, s40, v73
	v_fma_f32 v60, v76, v60, s34
	v_fma_f32 v61, v77, v61, s34
	v_exp_f32_e32 v68, v68
	v_exp_f32_e32 v69, v69
	v_fma_f32 v60, v76, v60, s36
	v_fma_f32 v61, v77, v61, s36
	v_and_b32_e32 v73, 0x7fffffff, v57
	v_and_b32_e32 v72, 0x7fffffff, v56
	v_fma_f32 v60, v76, v60, s38
	v_fma_f32 v61, v77, v61, s38
	v_fma_f32 v72, v72, s26, 1.0
	v_fma_f32 v73, v73, s26, 1.0
	v_mul_f32_e32 v60, v76, v60
	v_mul_f32_e32 v61, v77, v61
	v_rcp_f32_e32 v72, v72
	v_rcp_f32_e32 v73, v73
	v_mul_f32_e32 v60, v68, v60
	v_mul_f32_e32 v61, v69, v61
	v_cmp_gt_f32_e32 vcc, 0, v62
	v_mul_f32_e32 v68, v62, v60
	v_mul_f32_e32 v69, v63, v61
	v_fma_f32 v60, -v62, v60, v62
	v_fma_f32 v61, -v63, v61, v63
	v_lshl_add_u64 v[64:65], v[152:153], 0, v[64:65]
	v_cndmask_b32_e32 v75, v60, v68, vcc
	v_cmp_gt_f32_e32 vcc, 0, v63
	v_mul_f32_e32 v62, v56, v56
	v_mul_f32_e32 v63, v57, v57
	s_nop 0
	v_cndmask_b32_e32 v76, v61, v69, vcc
	v_fma_f32 v60, v72, s28, v70
	v_fma_f32 v61, v73, s28, v70
	v_mul_f32_e32 v62, s40, v62
	v_mul_f32_e32 v63, s40, v63
	v_fma_f32 v60, v72, v60, s34
	v_fma_f32 v61, v73, v61, s34
	v_exp_f32_e32 v62, v62
	v_fma_f32 v60, v72, v60, s36
	v_fma_f32 v61, v73, v61, s36
	v_exp_f32_e32 v63, v63
	v_fma_f32 v60, v72, v60, s38
	v_fma_f32 v61, v73, v61, s38
	v_cmp_gt_f32_e32 vcc, 0, v56
	v_mul_f32_e32 v60, v72, v60
	v_mul_f32_e32 v61, v73, v61
	v_and_b32_e32 v73, 0x7fffffff, v59
	v_and_b32_e32 v72, 0x7fffffff, v58
	v_fma_f32 v72, v72, s26, 1.0
	v_fma_f32 v73, v73, s26, 1.0
	v_mul_f32_e32 v60, v62, v60
	v_mul_f32_e32 v61, v63, v61
	v_rcp_f32_e32 v72, v72
	v_rcp_f32_e32 v73, v73
	v_mul_f32_e32 v62, v56, v60
	v_mul_f32_e32 v63, v57, v61
	v_fma_f32 v60, -v56, v60, v56
	v_fma_f32 v61, -v57, v61, v57
	v_mul_f32_e32 v68, v58, v58
	v_mul_f32_e32 v69, v59, v59
	v_cndmask_b32_e32 v62, v60, v62, vcc
	v_cmp_gt_f32_e32 vcc, 0, v57
	v_fma_f32 v56, v72, s28, v70
	v_fma_f32 v57, v73, s28, v70
	s_nop 0
	v_cndmask_b32_e32 v63, v61, v63, vcc
	v_mul_f32_e32 v60, s40, v68
	v_mul_f32_e32 v61, s40, v69
	v_fma_f32 v56, v72, v56, s34
	v_fma_f32 v57, v73, v57, s34
	v_exp_f32_e32 v60, v60
	v_exp_f32_e32 v61, v61
	v_fma_f32 v56, v72, v56, s36
	v_fma_f32 v57, v73, v57, s36
	v_cmp_gt_f32_e32 vcc, 0, v58
	v_fma_f32 v56, v72, v56, s38
	v_fma_f32 v57, v73, v57, s38
	s_nop 0
	v_mul_f32_e32 v56, v72, v56
	v_mul_f32_e32 v57, v73, v57
	s_nop 0
	v_mul_f32_e32 v56, v60, v56
	v_mul_f32_e32 v57, v61, v57
	s_nop 0
	v_mul_f32_e32 v60, v58, v56
	v_mul_f32_e32 v61, v59, v57
	v_fma_f32 v56, -v58, v56, v58
	v_fma_f32 v57, -v59, v57, v59
	s_nop 0
	v_cndmask_b32_e32 v60, v56, v60, vcc
	v_cmp_gt_f32_e32 vcc, 0, v59
	v_cvt_pk_bf16_f32 v56, v67, v74
	s_nop 1
	v_cndmask_b32_e32 v59, v57, v61, vcc
	v_cvt_pk_bf16_f32 v57, v75, v76
	v_cvt_pk_bf16_f32 v58, v62, v63
	v_cvt_pk_bf16_f32 v59, v60, v59
	v_mov_b32_e32 v60, 0
	s_and_b64 vcc, exec, s[8:9]
	v_mov_b32_e32 v61, 0
	global_store_dwordx4 v[64:65], v[56:59], off
	s_cbranch_vccnz .LBB0_249
	v_and_b32_e32 v61, 16, v56
	v_and_b32_e32 v60, 0xffff0000, v56
	v_lshlrev_b32_e32 v69, 16, v57
	v_lshlrev_b32_e32 v68, 16, v58
	v_and_b32_e32 v62, 0xffff0000, v57
	v_mov_b32_e32 v63, v60
	v_pk_mov_b32 v[74:75], v[68:69], v[60:61] op_sel:[1,0]
	v_lshlrev_b32_e32 v56, 16, v56
	v_and_b32_e32 v70, 0xffff0000, v59
	v_mov_b32_e32 v71, v62
	v_and_b32_e32 v58, 0xffff0000, v58
	v_lshlrev_b32_e32 v72, 16, v59
	v_mov_b32_e32 v59, v69
	v_mov_b32_e32 v57, v62
	v_mov_b32_e32 v73, v62
	v_add_f32_e32 v76, v62, v74
	v_add_f32_e32 v77, v63, v75
	v_mul_f32_e32 v62, v62, v74
	v_mul_f32_e32 v63, v63, v75
	v_add_f32_e32 v60, v56, v60
	v_add_f32_e32 v61, v56, v61
	v_mov_b32_e32 v77, v63
	v_add_f32_e32 v62, v68, v58
	v_add_f32_e32 v63, v69, v59
	v_mul_f32_e32 v74, v68, v68
	v_mul_f32_e32 v75, v69, v69
	v_mov_b32_e32 v59, v70
	v_mul_f32_e32 v61, v56, v56
	v_mov_b32_e32 v63, v75
	v_add_f32_e32 v74, v70, v72
	v_add_f32_e32 v75, v71, v73
	v_mul_f32_e32 v56, v70, v56
	v_mul_f32_e32 v57, v71, v57
	v_mov_b32_e32 v69, v72
	v_mul_f32_e32 v58, v58, v58
	v_mul_f32_e32 v59, v59, v59
	v_mov_b32_e32 v75, v57
	v_fma_f32 v58, v68, v68, v58
	v_fma_f32 v59, v69, v69, v59
	v_add_f32_e32 v60, v60, v76
	v_add_f32_e32 v61, v61, v77
	v_add_f32_e32 v56, v62, v74
	v_add_f32_e32 v57, v63, v75
	v_add_f32_e32 v59, v58, v59
	v_add_f32_e32 v58, v58, v58
	v_add_f32_e32 v56, v60, v56
	v_add_f32_e32 v57, v61, v57
	v_mov_b32_e32 v137, v59
	v_add_f32_e32 v60, v56, v136
	v_add_f32_e32 v61, v57, v137
.LBB0_249:
	v_mov_b32_e32 v67, v66
	v_mul_f32_e32 v52, v52, v66
	v_mul_f32_e32 v53, v53, v67
	v_mov_b32_e32 v56, v66
	v_and_b32_e32 v59, 0x7fffffff, v53
	v_and_b32_e32 v58, 0x7fffffff, v52
	v_fma_f32 v58, v58, s26, 1.0
	v_fma_f32 v59, v59, s26, 1.0
	v_mov_b32_e32 v57, v66
	v_rcp_f32_e32 v58, v58
	v_rcp_f32_e32 v59, v59
	v_mul_f32_e32 v54, v54, v56
	v_mul_f32_e32 v55, v55, v57
	v_mul_f32_e32 v50, v50, v56
	v_mul_f32_e32 v51, v51, v57
	v_mul_f32_e32 v48, v48, v66
	v_mul_f32_e32 v49, v49, v67
	v_mov_b64_e32 v[56:57], s[30:31]
	v_mul_f32_e32 v66, v52, v52
	v_mul_f32_e32 v67, v53, v53
	v_fma_f32 v62, v58, s28, v56
	v_fma_f32 v63, v59, s28, v56
	v_mul_f32_e32 v66, s40, v66
	v_mul_f32_e32 v67, s40, v67
	v_fma_f32 v62, v58, v62, s34
	v_fma_f32 v63, v59, v63, s34
	v_exp_f32_e32 v66, v66
	v_exp_f32_e32 v67, v67
	v_fma_f32 v62, v58, v62, s36
	v_fma_f32 v63, v59, v63, s36
	v_and_b32_e32 v69, 0x7fffffff, v55
	v_and_b32_e32 v68, 0x7fffffff, v54
	v_fma_f32 v62, v58, v62, s38
	v_fma_f32 v63, v59, v63, s38
	v_fma_f32 v68, v68, s26, 1.0
	v_fma_f32 v69, v69, s26, 1.0
	v_mul_f32_e32 v58, v58, v62
	v_mul_f32_e32 v59, v59, v63
	v_rcp_f32_e32 v68, v68
	v_rcp_f32_e32 v69, v69
	v_mul_f32_e32 v58, v66, v58
	v_mul_f32_e32 v59, v67, v59
	v_cmp_gt_f32_e32 vcc, 0, v52
	v_mul_f32_e32 v66, v52, v58
	v_mul_f32_e32 v67, v53, v59
	v_fma_f32 v58, -v52, v58, v52
	v_fma_f32 v59, -v53, v59, v53
	v_mul_f32_e32 v62, v54, v54
	v_mul_f32_e32 v63, v55, v55
	v_cndmask_b32_e32 v66, v58, v66, vcc
	v_cmp_gt_f32_e32 vcc, 0, v53
	v_fma_f32 v52, v68, s28, v56
	v_fma_f32 v53, v69, s28, v56
	s_nop 0
	v_cndmask_b32_e32 v67, v59, v67, vcc
	v_mul_f32_e32 v58, s40, v62
	v_mul_f32_e32 v59, s40, v63
	v_fma_f32 v52, v68, v52, s34
	v_fma_f32 v53, v69, v53, s34
	v_exp_f32_e32 v58, v58
	v_exp_f32_e32 v59, v59
	v_fma_f32 v52, v68, v52, s36
	v_fma_f32 v53, v69, v53, s36
	v_and_b32_e32 v63, 0x7fffffff, v49
	v_and_b32_e32 v62, 0x7fffffff, v48
	v_fma_f32 v52, v68, v52, s38
	v_fma_f32 v53, v69, v53, s38
	v_fma_f32 v62, v62, s26, 1.0
	v_fma_f32 v63, v63, s26, 1.0
	v_mul_f32_e32 v52, v68, v52
	v_mul_f32_e32 v53, v69, v53
	v_rcp_f32_e32 v62, v62
	v_rcp_f32_e32 v63, v63
	v_mul_f32_e32 v52, v58, v52
	v_mul_f32_e32 v53, v59, v53
	v_cmp_gt_f32_e32 vcc, 0, v54
	v_mul_f32_e32 v58, v54, v52
	v_mul_f32_e32 v59, v55, v53
	v_fma_f32 v52, -v54, v52, v54
	v_fma_f32 v53, -v55, v53, v55
	s_nop 0
	v_cndmask_b32_e32 v68, v52, v58, vcc
	v_cmp_gt_f32_e32 vcc, 0, v55
	v_mul_f32_e32 v54, v48, v48
	v_mul_f32_e32 v55, v49, v49
	s_nop 0
	v_cndmask_b32_e32 v69, v53, v59, vcc
	v_fma_f32 v52, v62, s28, v56
	v_fma_f32 v53, v63, s28, v56
	v_mul_f32_e32 v54, s40, v54
	v_mul_f32_e32 v55, s40, v55
	v_fma_f32 v52, v62, v52, s34
	v_fma_f32 v53, v63, v53, s34
	v_exp_f32_e32 v54, v54
	v_fma_f32 v52, v62, v52, s36
	v_fma_f32 v53, v63, v53, s36
	v_exp_f32_e32 v55, v55
	v_fma_f32 v52, v62, v52, s38
	v_fma_f32 v53, v63, v53, s38
	v_cmp_gt_f32_e32 vcc, 0, v48
	v_mul_f32_e32 v52, v62, v52
	v_mul_f32_e32 v53, v63, v53
	v_and_b32_e32 v63, 0x7fffffff, v51
	v_and_b32_e32 v62, 0x7fffffff, v50
	v_fma_f32 v62, v62, s26, 1.0
	v_fma_f32 v63, v63, s26, 1.0
	v_mul_f32_e32 v52, v54, v52
	v_mul_f32_e32 v53, v55, v53
	v_rcp_f32_e32 v62, v62
	v_rcp_f32_e32 v63, v63
	v_mul_f32_e32 v54, v48, v52
	v_mul_f32_e32 v55, v49, v53
	v_fma_f32 v52, -v48, v52, v48
	v_fma_f32 v53, -v49, v53, v49
	v_mul_f32_e32 v58, v50, v50
	v_mul_f32_e32 v59, v51, v51
	v_cndmask_b32_e32 v54, v52, v54, vcc
	v_cmp_gt_f32_e32 vcc, 0, v49
	v_fma_f32 v48, v62, s28, v56
	v_fma_f32 v49, v63, s28, v56
	s_nop 0
	v_cndmask_b32_e32 v55, v53, v55, vcc
	v_mul_f32_e32 v52, s40, v58
	v_mul_f32_e32 v53, s40, v59
	v_fma_f32 v48, v62, v48, s34
	v_fma_f32 v49, v63, v49, s34
	v_exp_f32_e32 v52, v52
	v_exp_f32_e32 v53, v53
	v_fma_f32 v48, v62, v48, s36
	v_fma_f32 v49, v63, v49, s36
	v_cmp_gt_f32_e32 vcc, 0, v50
	v_fma_f32 v48, v62, v48, s38
	v_fma_f32 v49, v63, v49, s38
	s_nop 0
	v_mul_f32_e32 v48, v62, v48
	v_mul_f32_e32 v49, v63, v49
	s_nop 0
	v_mul_f32_e32 v48, v52, v48
	v_mul_f32_e32 v49, v53, v49
	s_nop 0
	v_mul_f32_e32 v52, v50, v48
	v_mul_f32_e32 v53, v51, v49
	v_fma_f32 v48, -v50, v48, v50
	v_fma_f32 v49, -v51, v49, v51
	s_nop 0
	v_cndmask_b32_e32 v52, v48, v52, vcc
	v_cmp_gt_f32_e32 vcc, 0, v51
	v_cvt_pk_bf16_f32 v48, v66, v67
	s_nop 1
	v_cndmask_b32_e32 v51, v49, v53, vcc
	s_and_b64 vcc, exec, s[8:9]
	v_cvt_pk_bf16_f32 v49, v68, v69
	v_cvt_pk_bf16_f32 v50, v54, v55
	v_cvt_pk_bf16_f32 v51, v52, v51
	global_store_dwordx4 v[64:65], v[48:51], off offset:256
	s_cbranch_vccnz .LBB0_253
	v_lshlrev_b32_e32 v52, 16, v48
	v_and_b32_e32 v48, 0xffff0000, v48
	v_lshlrev_b32_e32 v54, 16, v49
	v_and_b32_e32 v56, 0xffff0000, v49
	v_lshlrev_b32_e32 v58, 16, v50
	v_and_b32_e32 v50, 0xffff0000, v50
	v_lshlrev_b32_e32 v62, 16, v51
	v_and_b32_e32 v64, 0xffff0000, v51
	v_mul_f32_e32 v53, v52, v52
	v_mul_f32_e32 v49, v48, v48
	v_mul_f32_e32 v55, v54, v54
	v_mul_f32_e32 v57, v56, v56
	v_mul_f32_e32 v59, v58, v58
	v_mul_f32_e32 v51, v50, v50
	v_mul_f32_e32 v63, v62, v62
	v_mul_f32_e32 v65, v64, v64
	v_add_f32_e32 v48, v52, v48
	v_add_f32_e32 v49, v53, v49
	v_add_f32_e32 v52, v54, v56
	v_add_f32_e32 v53, v55, v57
	v_add_f32_e32 v50, v58, v50
	v_add_f32_e32 v51, v59, v51
	v_add_f32_e32 v48, v48, v52
	v_add_f32_e32 v49, v49, v53
	v_add_f32_e32 v52, v62, v64
	v_add_f32_e32 v53, v63, v65
	s_nop 0
	v_add_f32_e32 v50, v50, v52
	v_add_f32_e32 v51, v51, v53
	s_nop 0
	v_add_f32_e32 v48, v48, v50
	v_add_f32_e32 v49, v49, v51
	s_nop 0
	v_add_f32_e32 v48, v60, v48
	v_add_f32_e32 v49, v61, v49
	ds_bpermute_b32 v50, v180, v48
	ds_bpermute_b32 v51, v180, v49
	s_waitcnt lgkmcnt(0)
	v_add_f32_e32 v48, v48, v50
	v_add_f32_e32 v49, v49, v51
	ds_bpermute_b32 v50, v179, v48
	ds_bpermute_b32 v51, v179, v49
	s_and_saveexec_b64 s[10:11], s[4:5]
	s_cbranch_execz .LBB0_252
	v_lshlrev_b64 v[52:53], 8, v[156:157]
	v_lshl_add_u64 v[52:53], s[16:17], 0, v[52:53]
	v_lshl_add_u64 v[52:53], s[50:51], 2, v[52:53]
	s_waitcnt lgkmcnt(0)
	v_add_f32_e32 v48, v48, v50
	v_add_f32_e32 v49, v49, v51
	global_store_dwordx2 v[52:53], v[48:49], off

.LBB0_253:
	s_nop 0
	v_add_f32_e32 v48, v185, v186
	v_fmamk_f32 v48, v48, 0x3a800000, v177
	v_mov_b64_e32 v[54:55], s[30:31]
	s_waitcnt lgkmcnt(1)
	s_waitcnt lgkmcnt(0)
	v_rsq_f32_e32 v50, v48
	s_nop 0
	v_mul_f32_e32 v44, v44, v50
	v_mul_f32_e32 v45, v45, v50
	v_mul_f32_e32 v46, v46, v50
	v_mul_f32_e32 v47, v47, v50
	v_and_b32_e32 v53, 0x7fffffff, v45
	v_and_b32_e32 v52, 0x7fffffff, v44
	v_fma_f32 v52, v52, s26, 1.0
	v_fma_f32 v53, v53, s26, 1.0
	v_mul_f32_e32 v58, v44, v44
	v_mul_f32_e32 v59, v45, v45
	v_rcp_f32_e32 v52, v52
	v_rcp_f32_e32 v53, v53
	v_mul_f32_e32 v58, s40, v58
	v_mul_f32_e32 v59, s40, v59
	v_and_b32_e32 v61, 0x7fffffff, v47
	v_exp_f32_e32 v58, v58
	v_fma_f32 v56, v52, s28, v54
	v_fma_f32 v57, v53, s28, v54
	v_exp_f32_e32 v59, v59
	v_fma_f32 v56, v52, v56, s34
	v_fma_f32 v57, v53, v57, s34
	v_and_b32_e32 v60, 0x7fffffff, v46
	v_fma_f32 v56, v52, v56, s36
	v_fma_f32 v57, v53, v57, s36
	v_fma_f32 v60, v60, s26, 1.0
	v_fma_f32 v61, v61, s26, 1.0
	v_fma_f32 v56, v52, v56, s38
	v_fma_f32 v57, v53, v57, s38
	v_rcp_f32_e32 v60, v60
	v_mul_f32_e32 v52, v52, v56
	v_mul_f32_e32 v53, v53, v57
	v_rcp_f32_e32 v61, v61
	v_mul_f32_e32 v52, v58, v52
	v_mul_f32_e32 v53, v59, v53
	v_cmp_gt_f32_e32 vcc, 0, v44
	v_mul_f32_e32 v58, v44, v52
	v_mul_f32_e32 v59, v45, v53
	v_fma_f32 v52, -v44, v52, v44
	v_fma_f32 v53, -v45, v53, v45
	v_mul_f32_e32 v42, v42, v50
	v_mul_f32_e32 v43, v43, v50
	v_mul_f32_e32 v40, v40, v50
	v_mul_f32_e32 v41, v41, v50
	v_mul_f32_e32 v56, v46, v46
	v_mul_f32_e32 v57, v47, v47
	v_cndmask_b32_e32 v51, v52, v58, vcc
	v_cmp_gt_f32_e32 vcc, 0, v45
	v_fma_f32 v44, v60, s28, v54
	v_fma_f32 v45, v61, s28, v54
	v_lshlrev_b64 v[48:49], 12, v[154:155]
	v_cndmask_b32_e32 v58, v53, v59, vcc
	v_mul_f32_e32 v52, s40, v56
	v_mul_f32_e32 v53, s40, v57
	v_fma_f32 v44, v60, v44, s34
	v_fma_f32 v45, v61, v45, s34
	v_exp_f32_e32 v52, v52
	v_exp_f32_e32 v53, v53
	v_fma_f32 v44, v60, v44, s36
	v_fma_f32 v45, v61, v45, s36
	v_and_b32_e32 v57, 0x7fffffff, v41
	v_and_b32_e32 v56, 0x7fffffff, v40
	v_fma_f32 v44, v60, v44, s38
	v_fma_f32 v45, v61, v45, s38
	v_fma_f32 v56, v56, s26, 1.0
	v_fma_f32 v57, v57, s26, 1.0
	v_mul_f32_e32 v44, v60, v44
	v_mul_f32_e32 v45, v61, v45
	v_rcp_f32_e32 v56, v56
	v_rcp_f32_e32 v57, v57
	v_mul_f32_e32 v44, v52, v44
	v_mul_f32_e32 v45, v53, v45
	v_cmp_gt_f32_e32 vcc, 0, v46
	v_mul_f32_e32 v52, v46, v44
	v_mul_f32_e32 v53, v47, v45
	v_fma_f32 v44, -v46, v44, v46
	v_fma_f32 v45, -v47, v45, v47
	v_lshl_add_u64 v[48:49], v[152:153], 0, v[48:49]
	v_cndmask_b32_e32 v59, v44, v52, vcc
	v_cmp_gt_f32_e32 vcc, 0, v47
	v_mul_f32_e32 v46, v40, v40
	v_mul_f32_e32 v47, v41, v41
	s_nop 0
	v_cndmask_b32_e32 v60, v45, v53, vcc
	v_fma_f32 v44, v56, s28, v54
	v_fma_f32 v45, v57, s28, v54
	v_mul_f32_e32 v46, s40, v46
	v_mul_f32_e32 v47, s40, v47
	v_fma_f32 v44, v56, v44, s34
	v_fma_f32 v45, v57, v45, s34
	v_exp_f32_e32 v46, v46
	v_fma_f32 v44, v56, v44, s36
	v_fma_f32 v45, v57, v45, s36
	v_exp_f32_e32 v47, v47
	v_fma_f32 v44, v56, v44, s38
	v_fma_f32 v45, v57, v45, s38
	v_cmp_gt_f32_e32 vcc, 0, v40
	v_mul_f32_e32 v44, v56, v44
	v_mul_f32_e32 v45, v57, v45
	v_and_b32_e32 v57, 0x7fffffff, v43
	v_and_b32_e32 v56, 0x7fffffff, v42
	v_fma_f32 v56, v56, s26, 1.0
	v_fma_f32 v57, v57, s26, 1.0
	v_mul_f32_e32 v44, v46, v44
	v_mul_f32_e32 v45, v47, v45
	v_rcp_f32_e32 v56, v56
	v_rcp_f32_e32 v57, v57
	v_mul_f32_e32 v46, v40, v44
	v_mul_f32_e32 v47, v41, v45
	v_fma_f32 v44, -v40, v44, v40
	v_fma_f32 v45, -v41, v45, v41
	v_mul_f32_e32 v52, v42, v42
	v_mul_f32_e32 v53, v43, v43
	v_cndmask_b32_e32 v46, v44, v46, vcc
	v_cmp_gt_f32_e32 vcc, 0, v41
	v_fma_f32 v40, v56, s28, v54
	v_fma_f32 v41, v57, s28, v54
	s_nop 0
	v_cndmask_b32_e32 v47, v45, v47, vcc
	v_mul_f32_e32 v44, s40, v52
	v_mul_f32_e32 v45, s40, v53
	v_fma_f32 v40, v56, v40, s34
	v_fma_f32 v41, v57, v41, s34
	v_exp_f32_e32 v44, v44
	v_exp_f32_e32 v45, v45
	v_fma_f32 v40, v56, v40, s36
	v_fma_f32 v41, v57, v41, s36
	v_cmp_gt_f32_e32 vcc, 0, v42
	v_fma_f32 v40, v56, v40, s38
	v_fma_f32 v41, v57, v41, s38
	s_nop 0
	v_mul_f32_e32 v40, v56, v40
	v_mul_f32_e32 v41, v57, v41
	s_nop 0
	v_mul_f32_e32 v40, v44, v40
	v_mul_f32_e32 v41, v45, v41
	s_nop 0
	v_mul_f32_e32 v44, v42, v40
	v_mul_f32_e32 v45, v43, v41
	v_fma_f32 v40, -v42, v40, v42
	v_fma_f32 v41, -v43, v41, v43
	s_nop 0
	v_cndmask_b32_e32 v44, v40, v44, vcc
	v_cmp_gt_f32_e32 vcc, 0, v43
	v_cvt_pk_bf16_f32 v40, v51, v58
	s_nop 1
	v_cndmask_b32_e32 v43, v41, v45, vcc
	v_cvt_pk_bf16_f32 v41, v59, v60
	v_cvt_pk_bf16_f32 v42, v46, v47
	v_cvt_pk_bf16_f32 v43, v44, v43
	v_mov_b32_e32 v44, 0
	s_and_b64 vcc, exec, s[8:9]
	v_mov_b32_e32 v45, 0
	global_store_dwordx4 v[48:49], v[40:43], off
	s_cbranch_vccnz .LBB0_255
	v_and_b32_e32 v45, 16, v40
	v_and_b32_e32 v44, 0xffff0000, v40
	v_lshlrev_b32_e32 v53, 16, v41
	v_lshlrev_b32_e32 v52, 16, v42
	v_and_b32_e32 v46, 0xffff0000, v41
	v_mov_b32_e32 v47, v44
	v_pk_mov_b32 v[58:59], v[52:53], v[44:45] op_sel:[1,0]
	v_lshlrev_b32_e32 v40, 16, v40
	v_and_b32_e32 v54, 0xffff0000, v43
	v_mov_b32_e32 v55, v46
	v_and_b32_e32 v42, 0xffff0000, v42
	v_lshlrev_b32_e32 v56, 16, v43
	v_mov_b32_e32 v43, v53
	v_mov_b32_e32 v41, v46
	v_mov_b32_e32 v57, v46
	v_add_f32_e32 v60, v46, v58
	v_add_f32_e32 v61, v47, v59
	v_mul_f32_e32 v46, v46, v58
	v_mul_f32_e32 v47, v47, v59
	v_add_f32_e32 v44, v40, v44
	v_add_f32_e32 v45, v40, v45
	v_mov_b32_e32 v61, v47
	v_add_f32_e32 v46, v52, v42
	v_add_f32_e32 v47, v53, v43
	v_mul_f32_e32 v58, v52, v52
	v_mul_f32_e32 v59, v53, v53
	v_mov_b32_e32 v43, v54
	v_mul_f32_e32 v45, v40, v40
	v_mov_b32_e32 v47, v59
	v_add_f32_e32 v58, v54, v56
	v_add_f32_e32 v59, v55, v57
	v_mul_f32_e32 v40, v54, v40
	v_mul_f32_e32 v41, v55, v41
	v_mov_b32_e32 v53, v56
	v_mul_f32_e32 v42, v42, v42
	v_mul_f32_e32 v43, v43, v43
	v_mov_b32_e32 v59, v41
	v_fma_f32 v42, v52, v52, v42
	v_fma_f32 v43, v53, v53, v43
	v_add_f32_e32 v44, v44, v60
	v_add_f32_e32 v45, v45, v61
	v_add_f32_e32 v40, v46, v58
	v_add_f32_e32 v41, v47, v59
	v_add_f32_e32 v43, v42, v43
	v_add_f32_e32 v42, v42, v42
	v_add_f32_e32 v40, v44, v40
	v_add_f32_e32 v41, v45, v41
	v_mov_b32_e32 v137, v43
	v_add_f32_e32 v44, v40, v136
	v_add_f32_e32 v45, v41, v137
.LBB0_255:
	v_mov_b32_e32 v51, v50
	v_mul_f32_e32 v36, v36, v50
	v_mul_f32_e32 v37, v37, v51
	v_mov_b32_e32 v40, v50
	v_and_b32_e32 v43, 0x7fffffff, v37
	v_and_b32_e32 v42, 0x7fffffff, v36
	v_fma_f32 v42, v42, s26, 1.0
	v_fma_f32 v43, v43, s26, 1.0
	v_mov_b32_e32 v41, v50
	v_rcp_f32_e32 v42, v42
	v_rcp_f32_e32 v43, v43
	v_mul_f32_e32 v38, v38, v40
	v_mul_f32_e32 v39, v39, v41
	v_mul_f32_e32 v34, v34, v40
	v_mul_f32_e32 v35, v35, v41
	v_mul_f32_e32 v32, v32, v50
	v_mul_f32_e32 v33, v33, v51
	v_mov_b64_e32 v[40:41], s[30:31]
	v_mul_f32_e32 v50, v36, v36
	v_mul_f32_e32 v51, v37, v37
	v_fma_f32 v46, v42, s28, v40
	v_fma_f32 v47, v43, s28, v40
	v_mul_f32_e32 v50, s40, v50
	v_mul_f32_e32 v51, s40, v51
	v_fma_f32 v46, v42, v46, s34
	v_fma_f32 v47, v43, v47, s34
	v_exp_f32_e32 v50, v50
	v_exp_f32_e32 v51, v51
	v_fma_f32 v46, v42, v46, s36
	v_fma_f32 v47, v43, v47, s36
	v_and_b32_e32 v53, 0x7fffffff, v39
	v_and_b32_e32 v52, 0x7fffffff, v38
	v_fma_f32 v46, v42, v46, s38
	v_fma_f32 v47, v43, v47, s38
	v_fma_f32 v52, v52, s26, 1.0
	v_fma_f32 v53, v53, s26, 1.0
	v_mul_f32_e32 v42, v42, v46
	v_mul_f32_e32 v43, v43, v47
	v_rcp_f32_e32 v52, v52
	v_rcp_f32_e32 v53, v53
	v_mul_f32_e32 v42, v50, v42
	v_mul_f32_e32 v43, v51, v43
	v_cmp_gt_f32_e32 vcc, 0, v36
	v_mul_f32_e32 v50, v36, v42
	v_mul_f32_e32 v51, v37, v43
	v_fma_f32 v42, -v36, v42, v36
	v_fma_f32 v43, -v37, v43, v37
	v_mul_f32_e32 v46, v38, v38
	v_mul_f32_e32 v47, v39, v39
	v_cndmask_b32_e32 v50, v42, v50, vcc
	v_cmp_gt_f32_e32 vcc, 0, v37
	v_fma_f32 v36, v52, s28, v40
	v_fma_f32 v37, v53, s28, v40
	s_nop 0
	v_cndmask_b32_e32 v51, v43, v51, vcc
	v_mul_f32_e32 v42, s40, v46
	v_mul_f32_e32 v43, s40, v47
	v_fma_f32 v36, v52, v36, s34
	v_fma_f32 v37, v53, v37, s34
	v_exp_f32_e32 v42, v42
	v_exp_f32_e32 v43, v43
	v_fma_f32 v36, v52, v36, s36
	v_fma_f32 v37, v53, v37, s36
	v_and_b32_e32 v47, 0x7fffffff, v33
	v_and_b32_e32 v46, 0x7fffffff, v32
	v_fma_f32 v36, v52, v36, s38
	v_fma_f32 v37, v53, v37, s38
	v_fma_f32 v46, v46, s26, 1.0
	v_fma_f32 v47, v47, s26, 1.0
	v_mul_f32_e32 v36, v52, v36
	v_mul_f32_e32 v37, v53, v37
	v_rcp_f32_e32 v46, v46
	v_rcp_f32_e32 v47, v47
	v_mul_f32_e32 v36, v42, v36
	v_mul_f32_e32 v37, v43, v37
	v_cmp_gt_f32_e32 vcc, 0, v38
	v_mul_f32_e32 v42, v38, v36
	v_mul_f32_e32 v43, v39, v37
	v_fma_f32 v36, -v38, v36, v38
	v_fma_f32 v37, -v39, v37, v39
	s_nop 0
	v_cndmask_b32_e32 v52, v36, v42, vcc
	v_cmp_gt_f32_e32 vcc, 0, v39
	v_mul_f32_e32 v38, v32, v32
	v_mul_f32_e32 v39, v33, v33
	s_nop 0
	v_cndmask_b32_e32 v53, v37, v43, vcc
	v_fma_f32 v36, v46, s28, v40
	v_fma_f32 v37, v47, s28, v40
	v_mul_f32_e32 v38, s40, v38
	v_mul_f32_e32 v39, s40, v39
	v_fma_f32 v36, v46, v36, s34
	v_fma_f32 v37, v47, v37, s34
	v_exp_f32_e32 v38, v38
	v_fma_f32 v36, v46, v36, s36
	v_fma_f32 v37, v47, v37, s36
	v_exp_f32_e32 v39, v39
	v_fma_f32 v36, v46, v36, s38
	v_fma_f32 v37, v47, v37, s38
	v_cmp_gt_f32_e32 vcc, 0, v32
	v_mul_f32_e32 v36, v46, v36
	v_mul_f32_e32 v37, v47, v37
	v_and_b32_e32 v47, 0x7fffffff, v35
	v_and_b32_e32 v46, 0x7fffffff, v34
	v_fma_f32 v46, v46, s26, 1.0
	v_fma_f32 v47, v47, s26, 1.0
	v_mul_f32_e32 v36, v38, v36
	v_mul_f32_e32 v37, v39, v37
	v_rcp_f32_e32 v46, v46
	v_rcp_f32_e32 v47, v47
	v_mul_f32_e32 v38, v32, v36
	v_mul_f32_e32 v39, v33, v37
	v_fma_f32 v36, -v32, v36, v32
	v_fma_f32 v37, -v33, v37, v33
	v_mul_f32_e32 v42, v34, v34
	v_mul_f32_e32 v43, v35, v35
	v_cndmask_b32_e32 v38, v36, v38, vcc
	v_cmp_gt_f32_e32 vcc, 0, v33
	v_fma_f32 v32, v46, s28, v40
	v_fma_f32 v33, v47, s28, v40
	s_nop 0
	v_cndmask_b32_e32 v39, v37, v39, vcc
	v_mul_f32_e32 v36, s40, v42
	v_mul_f32_e32 v37, s40, v43
	v_fma_f32 v32, v46, v32, s34
	v_fma_f32 v33, v47, v33, s34
	v_exp_f32_e32 v36, v36
	v_exp_f32_e32 v37, v37
	v_fma_f32 v32, v46, v32, s36
	v_fma_f32 v33, v47, v33, s36
	v_cmp_gt_f32_e32 vcc, 0, v34
	v_fma_f32 v32, v46, v32, s38
	v_fma_f32 v33, v47, v33, s38
	s_nop 0
	v_mul_f32_e32 v32, v46, v32
	v_mul_f32_e32 v33, v47, v33
	s_nop 0
	v_mul_f32_e32 v32, v36, v32
	v_mul_f32_e32 v33, v37, v33
	s_nop 0
	v_mul_f32_e32 v36, v34, v32
	v_mul_f32_e32 v37, v35, v33
	v_fma_f32 v32, -v34, v32, v34
	v_fma_f32 v33, -v35, v33, v35
	s_nop 0
	v_cndmask_b32_e32 v36, v32, v36, vcc
	v_cmp_gt_f32_e32 vcc, 0, v35
	v_cvt_pk_bf16_f32 v32, v50, v51
	s_nop 1
	v_cndmask_b32_e32 v35, v33, v37, vcc
	s_and_b64 vcc, exec, s[8:9]
	v_cvt_pk_bf16_f32 v33, v52, v53
	v_cvt_pk_bf16_f32 v34, v38, v39
	v_cvt_pk_bf16_f32 v35, v36, v35
	global_store_dwordx4 v[48:49], v[32:35], off offset:256
	s_cbranch_vccnz .LBB0_259
	v_lshlrev_b32_e32 v36, 16, v32
	v_and_b32_e32 v32, 0xffff0000, v32
	v_lshlrev_b32_e32 v38, 16, v33
	v_and_b32_e32 v40, 0xffff0000, v33
	v_lshlrev_b32_e32 v42, 16, v34
	v_and_b32_e32 v34, 0xffff0000, v34
	v_lshlrev_b32_e32 v46, 16, v35
	v_and_b32_e32 v48, 0xffff0000, v35
	v_mul_f32_e32 v37, v36, v36
	v_mul_f32_e32 v33, v32, v32
	v_mul_f32_e32 v39, v38, v38
	v_mul_f32_e32 v41, v40, v40
	v_mul_f32_e32 v43, v42, v42
	v_mul_f32_e32 v35, v34, v34
	v_mul_f32_e32 v47, v46, v46
	v_mul_f32_e32 v49, v48, v48
	v_add_f32_e32 v32, v36, v32
	v_add_f32_e32 v33, v37, v33
	v_add_f32_e32 v36, v38, v40
	v_add_f32_e32 v37, v39, v41
	v_add_f32_e32 v34, v42, v34
	v_add_f32_e32 v35, v43, v35
	v_add_f32_e32 v32, v32, v36
	v_add_f32_e32 v33, v33, v37
	v_add_f32_e32 v36, v46, v48
	v_add_f32_e32 v37, v47, v49
	s_nop 0
	v_add_f32_e32 v34, v34, v36
	v_add_f32_e32 v35, v35, v37
	s_nop 0
	v_add_f32_e32 v32, v32, v34
	v_add_f32_e32 v33, v33, v35
	s_nop 0
	v_add_f32_e32 v32, v44, v32
	v_add_f32_e32 v33, v45, v33
	ds_bpermute_b32 v34, v180, v32
	ds_bpermute_b32 v35, v180, v33
	s_waitcnt lgkmcnt(0)
	v_add_f32_e32 v32, v32, v34
	v_add_f32_e32 v33, v33, v35
	ds_bpermute_b32 v34, v179, v32
	ds_bpermute_b32 v35, v179, v33
	s_and_saveexec_b64 s[10:11], s[4:5]
	s_cbranch_execz .LBB0_258
	v_lshlrev_b64 v[36:37], 8, v[154:155]
	v_lshl_add_u64 v[36:37], s[16:17], 0, v[36:37]
	v_lshl_add_u64 v[36:37], s[50:51], 2, v[36:37]
	s_waitcnt lgkmcnt(0)
	v_add_f32_e32 v32, v32, v34
	v_add_f32_e32 v33, v33, v35
	global_store_dwordx2 v[36:37], v[32:33], off

.LBB0_259:
	s_nop 0
	v_add_f32_e32 v32, v183, v184
	v_fmamk_f32 v32, v32, 0x3a800000, v177
	v_mov_b64_e32 v[38:39], s[30:31]
	s_waitcnt lgkmcnt(1)
	s_waitcnt lgkmcnt(0)
	v_rsq_f32_e32 v34, v32
	s_nop 0
	v_mul_f32_e32 v28, v28, v34
	v_mul_f32_e32 v29, v29, v34
	v_mul_f32_e32 v30, v30, v34
	v_mul_f32_e32 v31, v31, v34
	v_and_b32_e32 v37, 0x7fffffff, v29
	v_and_b32_e32 v36, 0x7fffffff, v28
	v_fma_f32 v36, v36, s26, 1.0
	v_fma_f32 v37, v37, s26, 1.0
	v_mul_f32_e32 v42, v28, v28
	v_mul_f32_e32 v43, v29, v29
	v_rcp_f32_e32 v36, v36
	v_rcp_f32_e32 v37, v37
	v_mul_f32_e32 v42, s40, v42
	v_mul_f32_e32 v43, s40, v43
	v_and_b32_e32 v45, 0x7fffffff, v31
	v_exp_f32_e32 v42, v42
	v_fma_f32 v40, v36, s28, v38
	v_fma_f32 v41, v37, s28, v38
	v_exp_f32_e32 v43, v43
	v_fma_f32 v40, v36, v40, s34
	v_fma_f32 v41, v37, v41, s34
	v_and_b32_e32 v44, 0x7fffffff, v30
	v_fma_f32 v40, v36, v40, s36
	v_fma_f32 v41, v37, v41, s36
	v_fma_f32 v44, v44, s26, 1.0
	v_fma_f32 v45, v45, s26, 1.0
	v_fma_f32 v40, v36, v40, s38
	v_fma_f32 v41, v37, v41, s38
	v_rcp_f32_e32 v44, v44
	v_mul_f32_e32 v36, v36, v40
	v_mul_f32_e32 v37, v37, v41
	v_rcp_f32_e32 v45, v45
	v_mul_f32_e32 v36, v42, v36
	v_mul_f32_e32 v37, v43, v37
	v_cmp_gt_f32_e32 vcc, 0, v28
	v_mul_f32_e32 v42, v28, v36
	v_mul_f32_e32 v43, v29, v37
	v_fma_f32 v36, -v28, v36, v28
	v_fma_f32 v37, -v29, v37, v29
	v_mul_f32_e32 v26, v26, v34
	v_mul_f32_e32 v27, v27, v34
	v_mul_f32_e32 v24, v24, v34
	v_mul_f32_e32 v25, v25, v34
	v_mul_f32_e32 v40, v30, v30
	v_mul_f32_e32 v41, v31, v31
	v_cndmask_b32_e32 v35, v36, v42, vcc
	v_cmp_gt_f32_e32 vcc, 0, v29
	v_fma_f32 v28, v44, s28, v38
	v_fma_f32 v29, v45, s28, v38
	v_lshlrev_b64 v[32:33], 12, v[150:151]
	v_cndmask_b32_e32 v42, v37, v43, vcc
	v_mul_f32_e32 v36, s40, v40
	v_mul_f32_e32 v37, s40, v41
	v_fma_f32 v28, v44, v28, s34
	v_fma_f32 v29, v45, v29, s34
	v_exp_f32_e32 v36, v36
	v_exp_f32_e32 v37, v37
	v_fma_f32 v28, v44, v28, s36
	v_fma_f32 v29, v45, v29, s36
	v_and_b32_e32 v41, 0x7fffffff, v25
	v_and_b32_e32 v40, 0x7fffffff, v24
	v_fma_f32 v28, v44, v28, s38
	v_fma_f32 v29, v45, v29, s38
	v_fma_f32 v40, v40, s26, 1.0
	v_fma_f32 v41, v41, s26, 1.0
	v_mul_f32_e32 v28, v44, v28
	v_mul_f32_e32 v29, v45, v29
	v_rcp_f32_e32 v40, v40
	v_rcp_f32_e32 v41, v41
	v_mul_f32_e32 v28, v36, v28
	v_mul_f32_e32 v29, v37, v29
	v_cmp_gt_f32_e32 vcc, 0, v30
	v_mul_f32_e32 v36, v30, v28
	v_mul_f32_e32 v37, v31, v29
	v_fma_f32 v28, -v30, v28, v30
	v_fma_f32 v29, -v31, v29, v31
	v_lshl_add_u64 v[32:33], v[152:153], 0, v[32:33]
	v_cndmask_b32_e32 v43, v28, v36, vcc
	v_cmp_gt_f32_e32 vcc, 0, v31
	v_mul_f32_e32 v30, v24, v24
	v_mul_f32_e32 v31, v25, v25
	s_nop 0
	v_cndmask_b32_e32 v44, v29, v37, vcc
	v_fma_f32 v28, v40, s28, v38
	v_fma_f32 v29, v41, s28, v38
	v_mul_f32_e32 v30, s40, v30
	v_mul_f32_e32 v31, s40, v31
	v_fma_f32 v28, v40, v28, s34
	v_fma_f32 v29, v41, v29, s34
	v_exp_f32_e32 v30, v30
	v_fma_f32 v28, v40, v28, s36
	v_fma_f32 v29, v41, v29, s36
	v_exp_f32_e32 v31, v31
	v_fma_f32 v28, v40, v28, s38
	v_fma_f32 v29, v41, v29, s38
	v_cmp_gt_f32_e32 vcc, 0, v24
	v_mul_f32_e32 v28, v40, v28
	v_mul_f32_e32 v29, v41, v29
	v_and_b32_e32 v41, 0x7fffffff, v27
	v_and_b32_e32 v40, 0x7fffffff, v26
	v_fma_f32 v40, v40, s26, 1.0
	v_fma_f32 v41, v41, s26, 1.0
	v_mul_f32_e32 v28, v30, v28
	v_mul_f32_e32 v29, v31, v29
	v_rcp_f32_e32 v40, v40
	v_rcp_f32_e32 v41, v41
	v_mul_f32_e32 v30, v24, v28
	v_mul_f32_e32 v31, v25, v29
	v_fma_f32 v28, -v24, v28, v24
	v_fma_f32 v29, -v25, v29, v25
	v_mul_f32_e32 v36, v26, v26
	v_mul_f32_e32 v37, v27, v27
	v_cndmask_b32_e32 v30, v28, v30, vcc
	v_cmp_gt_f32_e32 vcc, 0, v25
	v_fma_f32 v24, v40, s28, v38
	v_fma_f32 v25, v41, s28, v38
	s_nop 0
	v_cndmask_b32_e32 v31, v29, v31, vcc
	v_mul_f32_e32 v28, s40, v36
	v_mul_f32_e32 v29, s40, v37
	v_fma_f32 v24, v40, v24, s34
	v_fma_f32 v25, v41, v25, s34
	v_exp_f32_e32 v28, v28
	v_exp_f32_e32 v29, v29
	v_fma_f32 v24, v40, v24, s36
	v_fma_f32 v25, v41, v25, s36
	v_cmp_gt_f32_e32 vcc, 0, v26
	v_fma_f32 v24, v40, v24, s38
	v_fma_f32 v25, v41, v25, s38
	s_nop 0
	v_mul_f32_e32 v24, v40, v24
	v_mul_f32_e32 v25, v41, v25
	s_nop 0
	v_mul_f32_e32 v24, v28, v24
	v_mul_f32_e32 v25, v29, v25
	s_nop 0
	v_mul_f32_e32 v28, v26, v24
	v_mul_f32_e32 v29, v27, v25
	v_fma_f32 v24, -v26, v24, v26
	v_fma_f32 v25, -v27, v25, v27
	s_nop 0
	v_cndmask_b32_e32 v28, v24, v28, vcc
	v_cmp_gt_f32_e32 vcc, 0, v27
	v_cvt_pk_bf16_f32 v24, v35, v42
	s_nop 1
	v_cndmask_b32_e32 v27, v25, v29, vcc
	v_cvt_pk_bf16_f32 v25, v43, v44
	v_cvt_pk_bf16_f32 v26, v30, v31
	v_cvt_pk_bf16_f32 v27, v28, v27
	v_mov_b32_e32 v28, 0
	s_and_b64 vcc, exec, s[8:9]
	v_mov_b32_e32 v29, 0
	global_store_dwordx4 v[32:33], v[24:27], off
	s_cbranch_vccnz .LBB0_261
	v_and_b32_e32 v29, 16, v24
	v_and_b32_e32 v28, 0xffff0000, v24
	v_lshlrev_b32_e32 v37, 16, v25
	v_lshlrev_b32_e32 v36, 16, v26
	v_and_b32_e32 v30, 0xffff0000, v25
	v_mov_b32_e32 v31, v28
	v_pk_mov_b32 v[42:43], v[36:37], v[28:29] op_sel:[1,0]
	v_lshlrev_b32_e32 v24, 16, v24
	v_and_b32_e32 v38, 0xffff0000, v27
	v_mov_b32_e32 v39, v30
	v_and_b32_e32 v26, 0xffff0000, v26
	v_lshlrev_b32_e32 v40, 16, v27
	v_mov_b32_e32 v27, v37
	v_mov_b32_e32 v25, v30
	v_mov_b32_e32 v41, v30
	v_add_f32_e32 v44, v30, v42
	v_add_f32_e32 v45, v31, v43
	v_mul_f32_e32 v30, v30, v42
	v_mul_f32_e32 v31, v31, v43
	v_add_f32_e32 v28, v24, v28
	v_add_f32_e32 v29, v24, v29
	v_mov_b32_e32 v45, v31
	v_add_f32_e32 v30, v36, v26
	v_add_f32_e32 v31, v37, v27
	v_mul_f32_e32 v42, v36, v36
	v_mul_f32_e32 v43, v37, v37
	v_mov_b32_e32 v27, v38
	v_mul_f32_e32 v29, v24, v24
	v_mov_b32_e32 v31, v43
	v_add_f32_e32 v42, v38, v40
	v_add_f32_e32 v43, v39, v41
	v_mul_f32_e32 v24, v38, v24
	v_mul_f32_e32 v25, v39, v25
	v_mov_b32_e32 v37, v40
	v_mul_f32_e32 v26, v26, v26
	v_mul_f32_e32 v27, v27, v27
	v_mov_b32_e32 v43, v25
	v_fma_f32 v26, v36, v36, v26
	v_fma_f32 v27, v37, v37, v27
	v_add_f32_e32 v28, v28, v44
	v_add_f32_e32 v29, v29, v45
	v_add_f32_e32 v24, v30, v42
	v_add_f32_e32 v25, v31, v43
	v_add_f32_e32 v27, v26, v27
	v_add_f32_e32 v26, v26, v26
	v_add_f32_e32 v24, v28, v24
	v_add_f32_e32 v25, v29, v25
	v_mov_b32_e32 v137, v27
	v_add_f32_e32 v28, v24, v136
	v_add_f32_e32 v29, v25, v137
.LBB0_261:
	v_mov_b32_e32 v35, v34
	v_mul_f32_e32 v20, v20, v34
	v_mul_f32_e32 v21, v21, v35
	v_mov_b32_e32 v24, v34
	v_and_b32_e32 v27, 0x7fffffff, v21
	v_and_b32_e32 v26, 0x7fffffff, v20
	v_fma_f32 v26, v26, s26, 1.0
	v_fma_f32 v27, v27, s26, 1.0
	v_mov_b32_e32 v25, v34
	v_rcp_f32_e32 v26, v26
	v_rcp_f32_e32 v27, v27
	v_mul_f32_e32 v22, v22, v24
	v_mul_f32_e32 v23, v23, v25
	v_mul_f32_e32 v18, v18, v24
	v_mul_f32_e32 v19, v19, v25
	v_mul_f32_e32 v16, v16, v34
	v_mul_f32_e32 v17, v17, v35
	v_mov_b64_e32 v[24:25], s[30:31]
	v_mul_f32_e32 v34, v20, v20
	v_mul_f32_e32 v35, v21, v21
	v_fma_f32 v30, v26, s28, v24
	v_fma_f32 v31, v27, s28, v24
	v_mul_f32_e32 v34, s40, v34
	v_mul_f32_e32 v35, s40, v35
	v_fma_f32 v30, v26, v30, s34
	v_fma_f32 v31, v27, v31, s34
	v_exp_f32_e32 v34, v34
	v_exp_f32_e32 v35, v35
	v_fma_f32 v30, v26, v30, s36
	v_fma_f32 v31, v27, v31, s36
	v_and_b32_e32 v37, 0x7fffffff, v23
	v_and_b32_e32 v36, 0x7fffffff, v22
	v_fma_f32 v30, v26, v30, s38
	v_fma_f32 v31, v27, v31, s38
	v_fma_f32 v36, v36, s26, 1.0
	v_fma_f32 v37, v37, s26, 1.0
	v_mul_f32_e32 v26, v26, v30
	v_mul_f32_e32 v27, v27, v31
	v_rcp_f32_e32 v36, v36
	v_rcp_f32_e32 v37, v37
	v_mul_f32_e32 v26, v34, v26
	v_mul_f32_e32 v27, v35, v27
	v_cmp_gt_f32_e32 vcc, 0, v20
	v_mul_f32_e32 v34, v20, v26
	v_mul_f32_e32 v35, v21, v27
	v_fma_f32 v26, -v20, v26, v20
	v_fma_f32 v27, -v21, v27, v21
	v_mul_f32_e32 v30, v22, v22
	v_mul_f32_e32 v31, v23, v23
	v_cndmask_b32_e32 v34, v26, v34, vcc
	v_cmp_gt_f32_e32 vcc, 0, v21
	v_fma_f32 v20, v36, s28, v24
	v_fma_f32 v21, v37, s28, v24
	s_nop 0
	v_cndmask_b32_e32 v35, v27, v35, vcc
	v_mul_f32_e32 v26, s40, v30
	v_mul_f32_e32 v27, s40, v31
	v_fma_f32 v20, v36, v20, s34
	v_fma_f32 v21, v37, v21, s34
	v_exp_f32_e32 v26, v26
	v_exp_f32_e32 v27, v27
	v_fma_f32 v20, v36, v20, s36
	v_fma_f32 v21, v37, v21, s36
	v_and_b32_e32 v31, 0x7fffffff, v17
	v_and_b32_e32 v30, 0x7fffffff, v16
	v_fma_f32 v20, v36, v20, s38
	v_fma_f32 v21, v37, v21, s38
	v_fma_f32 v30, v30, s26, 1.0
	v_fma_f32 v31, v31, s26, 1.0
	v_mul_f32_e32 v20, v36, v20
	v_mul_f32_e32 v21, v37, v21
	v_rcp_f32_e32 v30, v30
	v_rcp_f32_e32 v31, v31
	v_mul_f32_e32 v20, v26, v20
	v_mul_f32_e32 v21, v27, v21
	v_cmp_gt_f32_e32 vcc, 0, v22
	v_mul_f32_e32 v26, v22, v20
	v_mul_f32_e32 v27, v23, v21
	v_fma_f32 v20, -v22, v20, v22
	v_fma_f32 v21, -v23, v21, v23
	s_nop 0
	v_cndmask_b32_e32 v36, v20, v26, vcc
	v_cmp_gt_f32_e32 vcc, 0, v23
	v_mul_f32_e32 v22, v16, v16
	v_mul_f32_e32 v23, v17, v17
	s_nop 0
	v_cndmask_b32_e32 v37, v21, v27, vcc
	v_fma_f32 v20, v30, s28, v24
	v_fma_f32 v21, v31, s28, v24
	v_mul_f32_e32 v22, s40, v22
	v_mul_f32_e32 v23, s40, v23
	v_fma_f32 v20, v30, v20, s34
	v_fma_f32 v21, v31, v21, s34
	v_exp_f32_e32 v22, v22
	v_fma_f32 v20, v30, v20, s36
	v_fma_f32 v21, v31, v21, s36
	v_exp_f32_e32 v23, v23
	v_fma_f32 v20, v30, v20, s38
	v_fma_f32 v21, v31, v21, s38
	v_cmp_gt_f32_e32 vcc, 0, v16
	v_mul_f32_e32 v20, v30, v20
	v_mul_f32_e32 v21, v31, v21
	v_and_b32_e32 v31, 0x7fffffff, v19
	v_and_b32_e32 v30, 0x7fffffff, v18
	v_fma_f32 v30, v30, s26, 1.0
	v_fma_f32 v31, v31, s26, 1.0
	v_mul_f32_e32 v20, v22, v20
	v_mul_f32_e32 v21, v23, v21
	v_rcp_f32_e32 v30, v30
	v_rcp_f32_e32 v31, v31
	v_mul_f32_e32 v22, v16, v20
	v_mul_f32_e32 v23, v17, v21
	v_fma_f32 v20, -v16, v20, v16
	v_fma_f32 v21, -v17, v21, v17
	v_mul_f32_e32 v26, v18, v18
	v_mul_f32_e32 v27, v19, v19
	v_cndmask_b32_e32 v22, v20, v22, vcc
	v_cmp_gt_f32_e32 vcc, 0, v17
	v_fma_f32 v16, v30, s28, v24
	v_fma_f32 v17, v31, s28, v24
	s_nop 0
	v_cndmask_b32_e32 v23, v21, v23, vcc
	v_mul_f32_e32 v20, s40, v26
	v_mul_f32_e32 v21, s40, v27
	v_fma_f32 v16, v30, v16, s34
	v_fma_f32 v17, v31, v17, s34
	v_exp_f32_e32 v20, v20
	v_exp_f32_e32 v21, v21
	v_fma_f32 v16, v30, v16, s36
	v_fma_f32 v17, v31, v17, s36
	v_cmp_gt_f32_e32 vcc, 0, v18
	v_fma_f32 v16, v30, v16, s38
	v_fma_f32 v17, v31, v17, s38
	s_nop 0
	v_mul_f32_e32 v16, v30, v16
	v_mul_f32_e32 v17, v31, v17
	s_nop 0
	v_mul_f32_e32 v16, v20, v16
	v_mul_f32_e32 v17, v21, v17
	s_nop 0
	v_mul_f32_e32 v20, v18, v16
	v_mul_f32_e32 v21, v19, v17
	v_fma_f32 v16, -v18, v16, v18
	v_fma_f32 v17, -v19, v17, v19
	s_nop 0
	v_cndmask_b32_e32 v20, v16, v20, vcc
	v_cmp_gt_f32_e32 vcc, 0, v19
	v_cvt_pk_bf16_f32 v16, v34, v35
	s_nop 1
	v_cndmask_b32_e32 v19, v17, v21, vcc
	s_and_b64 vcc, exec, s[8:9]
	v_cvt_pk_bf16_f32 v17, v36, v37
	v_cvt_pk_bf16_f32 v18, v22, v23
	v_cvt_pk_bf16_f32 v19, v20, v19
	global_store_dwordx4 v[32:33], v[16:19], off offset:256
	s_cbranch_vccnz .LBB0_265
	v_lshlrev_b32_e32 v20, 16, v16
	v_and_b32_e32 v16, 0xffff0000, v16
	v_lshlrev_b32_e32 v22, 16, v17
	v_and_b32_e32 v24, 0xffff0000, v17
	v_lshlrev_b32_e32 v26, 16, v18
	v_and_b32_e32 v18, 0xffff0000, v18
	v_lshlrev_b32_e32 v30, 16, v19
	v_and_b32_e32 v32, 0xffff0000, v19
	v_mul_f32_e32 v21, v20, v20
	v_mul_f32_e32 v17, v16, v16
	v_mul_f32_e32 v23, v22, v22
	v_mul_f32_e32 v25, v24, v24
	v_mul_f32_e32 v27, v26, v26
	v_mul_f32_e32 v19, v18, v18
	v_mul_f32_e32 v31, v30, v30
	v_mul_f32_e32 v33, v32, v32
	v_add_f32_e32 v16, v20, v16
	v_add_f32_e32 v17, v21, v17
	v_add_f32_e32 v20, v22, v24
	v_add_f32_e32 v21, v23, v25
	v_add_f32_e32 v18, v26, v18
	v_add_f32_e32 v19, v27, v19
	v_add_f32_e32 v16, v16, v20
	v_add_f32_e32 v17, v17, v21
	v_add_f32_e32 v20, v30, v32
	v_add_f32_e32 v21, v31, v33
	s_nop 0
	v_add_f32_e32 v18, v18, v20
	v_add_f32_e32 v19, v19, v21
	s_nop 0
	v_add_f32_e32 v16, v16, v18
	v_add_f32_e32 v17, v17, v19
	s_nop 0
	v_add_f32_e32 v16, v28, v16
	v_add_f32_e32 v17, v29, v17
	ds_bpermute_b32 v18, v180, v16
	ds_bpermute_b32 v19, v180, v17
	s_waitcnt lgkmcnt(0)
	v_add_f32_e32 v16, v16, v18
	v_add_f32_e32 v17, v17, v19
	ds_bpermute_b32 v18, v179, v16
	ds_bpermute_b32 v19, v179, v17
	s_and_saveexec_b64 s[10:11], s[4:5]
	s_cbranch_execz .LBB0_264
	v_lshlrev_b64 v[20:21], 8, v[150:151]
	v_lshl_add_u64 v[20:21], s[16:17], 0, v[20:21]
	v_lshl_add_u64 v[20:21], s[50:51], 2, v[20:21]
	s_waitcnt lgkmcnt(0)
	v_add_f32_e32 v16, v16, v18
	v_add_f32_e32 v17, v17, v19
	global_store_dwordx2 v[20:21], v[16:17], off

.LBB0_265:
	s_nop 0
	v_add_f32_e32 v16, v181, v182
	v_fmamk_f32 v16, v16, 0x3a800000, v177
	v_mov_b64_e32 v[22:23], s[30:31]
	s_waitcnt lgkmcnt(1)
	s_waitcnt lgkmcnt(0)
	v_rsq_f32_e32 v18, v16
	s_nop 0
	v_mul_f32_e32 v12, v12, v18
	v_mul_f32_e32 v13, v13, v18
	v_mul_f32_e32 v14, v14, v18
	v_mul_f32_e32 v15, v15, v18
	v_and_b32_e32 v21, 0x7fffffff, v13
	v_and_b32_e32 v20, 0x7fffffff, v12
	v_fma_f32 v20, v20, s26, 1.0
	v_fma_f32 v21, v21, s26, 1.0
	v_mul_f32_e32 v26, v12, v12
	v_mul_f32_e32 v27, v13, v13
	v_rcp_f32_e32 v20, v20
	v_rcp_f32_e32 v21, v21
	v_mul_f32_e32 v26, s40, v26
	v_mul_f32_e32 v27, s40, v27
	v_and_b32_e32 v29, 0x7fffffff, v15
	v_exp_f32_e32 v26, v26
	v_fma_f32 v24, v20, s28, v22
	v_fma_f32 v25, v21, s28, v22
	v_exp_f32_e32 v27, v27
	v_fma_f32 v24, v20, v24, s34
	v_fma_f32 v25, v21, v25, s34
	v_and_b32_e32 v28, 0x7fffffff, v14
	v_fma_f32 v24, v20, v24, s36
	v_fma_f32 v25, v21, v25, s36
	v_fma_f32 v28, v28, s26, 1.0
	v_fma_f32 v29, v29, s26, 1.0
	v_fma_f32 v24, v20, v24, s38
	v_fma_f32 v25, v21, v25, s38
	v_rcp_f32_e32 v28, v28
	v_mul_f32_e32 v20, v20, v24
	v_mul_f32_e32 v21, v21, v25
	v_rcp_f32_e32 v29, v29
	v_mul_f32_e32 v20, v26, v20
	v_mul_f32_e32 v21, v27, v21
	v_cmp_gt_f32_e32 vcc, 0, v12
	v_mul_f32_e32 v26, v12, v20
	v_mul_f32_e32 v27, v13, v21
	v_fma_f32 v20, -v12, v20, v12
	v_fma_f32 v21, -v13, v21, v13
	v_mul_f32_e32 v10, v10, v18
	v_mul_f32_e32 v11, v11, v18
	v_mul_f32_e32 v8, v8, v18
	v_mul_f32_e32 v9, v9, v18
	v_mul_f32_e32 v24, v14, v14
	v_mul_f32_e32 v25, v15, v15
	v_cndmask_b32_e32 v19, v20, v26, vcc
	v_cmp_gt_f32_e32 vcc, 0, v13
	v_fma_f32 v12, v28, s28, v22
	v_fma_f32 v13, v29, s28, v22
	v_lshlrev_b64 v[16:17], 12, v[148:149]
	v_cndmask_b32_e32 v26, v21, v27, vcc
	v_mul_f32_e32 v20, s40, v24
	v_mul_f32_e32 v21, s40, v25
	v_fma_f32 v12, v28, v12, s34
	v_fma_f32 v13, v29, v13, s34
	v_exp_f32_e32 v20, v20
	v_exp_f32_e32 v21, v21
	v_fma_f32 v12, v28, v12, s36
	v_fma_f32 v13, v29, v13, s36
	v_and_b32_e32 v25, 0x7fffffff, v9
	v_and_b32_e32 v24, 0x7fffffff, v8
	v_fma_f32 v12, v28, v12, s38
	v_fma_f32 v13, v29, v13, s38
	v_fma_f32 v24, v24, s26, 1.0
	v_fma_f32 v25, v25, s26, 1.0
	v_mul_f32_e32 v12, v28, v12
	v_mul_f32_e32 v13, v29, v13
	v_rcp_f32_e32 v24, v24
	v_rcp_f32_e32 v25, v25
	v_mul_f32_e32 v12, v20, v12
	v_mul_f32_e32 v13, v21, v13
	v_cmp_gt_f32_e32 vcc, 0, v14
	v_mul_f32_e32 v20, v14, v12
	v_mul_f32_e32 v21, v15, v13
	v_fma_f32 v12, -v14, v12, v14
	v_fma_f32 v13, -v15, v13, v15
	v_lshl_add_u64 v[16:17], v[152:153], 0, v[16:17]
	v_cndmask_b32_e32 v27, v12, v20, vcc
	v_cmp_gt_f32_e32 vcc, 0, v15
	v_mul_f32_e32 v14, v8, v8
	v_mul_f32_e32 v15, v9, v9
	s_nop 0
	v_cndmask_b32_e32 v28, v13, v21, vcc
	v_fma_f32 v12, v24, s28, v22
	v_fma_f32 v13, v25, s28, v22
	v_mul_f32_e32 v14, s40, v14
	v_mul_f32_e32 v15, s40, v15
	v_fma_f32 v12, v24, v12, s34
	v_fma_f32 v13, v25, v13, s34
	v_exp_f32_e32 v14, v14
	v_fma_f32 v12, v24, v12, s36
	v_fma_f32 v13, v25, v13, s36
	v_exp_f32_e32 v15, v15
	v_fma_f32 v12, v24, v12, s38
	v_fma_f32 v13, v25, v13, s38
	v_cmp_gt_f32_e32 vcc, 0, v8
	v_mul_f32_e32 v12, v24, v12
	v_mul_f32_e32 v13, v25, v13
	v_and_b32_e32 v25, 0x7fffffff, v11
	v_and_b32_e32 v24, 0x7fffffff, v10
	v_fma_f32 v24, v24, s26, 1.0
	v_fma_f32 v25, v25, s26, 1.0
	v_mul_f32_e32 v12, v14, v12
	v_mul_f32_e32 v13, v15, v13
	v_rcp_f32_e32 v24, v24
	v_rcp_f32_e32 v25, v25
	v_mul_f32_e32 v14, v8, v12
	v_mul_f32_e32 v15, v9, v13
	v_fma_f32 v12, -v8, v12, v8
	v_fma_f32 v13, -v9, v13, v9
	v_mul_f32_e32 v20, v10, v10
	v_mul_f32_e32 v21, v11, v11
	v_cndmask_b32_e32 v14, v12, v14, vcc
	v_cmp_gt_f32_e32 vcc, 0, v9
	v_fma_f32 v8, v24, s28, v22
	v_fma_f32 v9, v25, s28, v22
	s_nop 0
	v_cndmask_b32_e32 v15, v13, v15, vcc
	v_mul_f32_e32 v12, s40, v20
	v_mul_f32_e32 v13, s40, v21
	v_fma_f32 v8, v24, v8, s34
	v_fma_f32 v9, v25, v9, s34
	v_exp_f32_e32 v12, v12
	v_exp_f32_e32 v13, v13
	v_fma_f32 v8, v24, v8, s36
	v_fma_f32 v9, v25, v9, s36
	v_cmp_gt_f32_e32 vcc, 0, v10
	v_fma_f32 v8, v24, v8, s38
	v_fma_f32 v9, v25, v9, s38
	s_nop 0
	v_mul_f32_e32 v8, v24, v8
	v_mul_f32_e32 v9, v25, v9
	s_nop 0
	v_mul_f32_e32 v8, v12, v8
	v_mul_f32_e32 v9, v13, v9
	s_nop 0
	v_mul_f32_e32 v12, v10, v8
	v_mul_f32_e32 v13, v11, v9
	v_fma_f32 v8, -v10, v8, v10
	v_fma_f32 v9, -v11, v9, v11
	s_nop 0
	v_cndmask_b32_e32 v12, v8, v12, vcc
	v_cmp_gt_f32_e32 vcc, 0, v11
	v_cvt_pk_bf16_f32 v8, v19, v26
	s_nop 1
	v_cndmask_b32_e32 v11, v9, v13, vcc
	v_cvt_pk_bf16_f32 v9, v27, v28
	v_cvt_pk_bf16_f32 v10, v14, v15
	v_cvt_pk_bf16_f32 v11, v12, v11
	v_mov_b32_e32 v12, 0
	s_and_b64 vcc, exec, s[8:9]
	v_mov_b32_e32 v13, 0
	global_store_dwordx4 v[16:17], v[8:11], off
	s_cbranch_vccnz .LBB0_267
	v_and_b32_e32 v13, 16, v8
	v_and_b32_e32 v12, 0xffff0000, v8
	v_lshlrev_b32_e32 v21, 16, v9
	v_lshlrev_b32_e32 v20, 16, v10
	v_and_b32_e32 v14, 0xffff0000, v9
	v_mov_b32_e32 v15, v12
	v_pk_mov_b32 v[26:27], v[20:21], v[12:13] op_sel:[1,0]
	v_lshlrev_b32_e32 v8, 16, v8
	v_and_b32_e32 v22, 0xffff0000, v11
	v_mov_b32_e32 v23, v14
	v_and_b32_e32 v10, 0xffff0000, v10
	v_lshlrev_b32_e32 v24, 16, v11
	v_mov_b32_e32 v11, v21
	v_mov_b32_e32 v9, v14
	v_mov_b32_e32 v25, v14
	v_add_f32_e32 v28, v14, v26
	v_add_f32_e32 v29, v15, v27
	v_mul_f32_e32 v14, v14, v26
	v_mul_f32_e32 v15, v15, v27
	v_add_f32_e32 v12, v8, v12
	v_add_f32_e32 v13, v8, v13
	v_mov_b32_e32 v29, v15
	v_add_f32_e32 v14, v20, v10
	v_add_f32_e32 v15, v21, v11
	v_mul_f32_e32 v26, v20, v20
	v_mul_f32_e32 v27, v21, v21
	v_mov_b32_e32 v11, v22
	v_mul_f32_e32 v13, v8, v8
	v_mov_b32_e32 v15, v27
	v_add_f32_e32 v26, v22, v24
	v_add_f32_e32 v27, v23, v25
	v_mul_f32_e32 v8, v22, v8
	v_mul_f32_e32 v9, v23, v9
	v_mov_b32_e32 v21, v24
	v_mul_f32_e32 v10, v10, v10
	v_mul_f32_e32 v11, v11, v11
	v_mov_b32_e32 v27, v9
	v_fma_f32 v10, v20, v20, v10
	v_fma_f32 v11, v21, v21, v11
	v_add_f32_e32 v12, v12, v28
	v_add_f32_e32 v13, v13, v29
	v_add_f32_e32 v8, v14, v26
	v_add_f32_e32 v9, v15, v27
	v_add_f32_e32 v11, v10, v11
	v_add_f32_e32 v10, v10, v10
	v_add_f32_e32 v8, v12, v8
	v_add_f32_e32 v9, v13, v9
	v_mov_b32_e32 v137, v11
	v_add_f32_e32 v12, v8, v136
	v_add_f32_e32 v13, v9, v137
.LBB0_267:
	v_mov_b32_e32 v19, v18
	v_mul_f32_e32 v4, v4, v18
	v_mul_f32_e32 v5, v5, v19
	v_mov_b32_e32 v8, v18
	v_and_b32_e32 v11, 0x7fffffff, v5
	v_and_b32_e32 v10, 0x7fffffff, v4
	v_fma_f32 v10, v10, s26, 1.0
	v_fma_f32 v11, v11, s26, 1.0
	v_mov_b32_e32 v9, v18
	v_rcp_f32_e32 v10, v10
	v_rcp_f32_e32 v11, v11
	v_mul_f32_e32 v6, v6, v8
	v_mul_f32_e32 v7, v7, v9
	v_mul_f32_e32 v2, v2, v8
	v_mul_f32_e32 v3, v3, v9
	v_mul_f32_e32 v0, v0, v18
	v_mul_f32_e32 v1, v1, v19
	v_mov_b64_e32 v[8:9], s[30:31]
	v_mul_f32_e32 v18, v4, v4
	v_mul_f32_e32 v19, v5, v5
	v_fma_f32 v14, v10, s28, v8
	v_fma_f32 v15, v11, s28, v8
	v_mul_f32_e32 v18, s40, v18
	v_mul_f32_e32 v19, s40, v19
	v_fma_f32 v14, v10, v14, s34
	v_fma_f32 v15, v11, v15, s34
	v_exp_f32_e32 v18, v18
	v_exp_f32_e32 v19, v19
	v_fma_f32 v14, v10, v14, s36
	v_fma_f32 v15, v11, v15, s36
	v_and_b32_e32 v21, 0x7fffffff, v7
	v_and_b32_e32 v20, 0x7fffffff, v6
	v_fma_f32 v14, v10, v14, s38
	v_fma_f32 v15, v11, v15, s38
	v_fma_f32 v20, v20, s26, 1.0
	v_fma_f32 v21, v21, s26, 1.0
	v_mul_f32_e32 v10, v10, v14
	v_mul_f32_e32 v11, v11, v15
	v_rcp_f32_e32 v20, v20
	v_rcp_f32_e32 v21, v21
	v_mul_f32_e32 v10, v18, v10
	v_mul_f32_e32 v11, v19, v11
	v_cmp_gt_f32_e32 vcc, 0, v4
	v_mul_f32_e32 v18, v4, v10
	v_mul_f32_e32 v19, v5, v11
	v_fma_f32 v10, -v4, v10, v4
	v_fma_f32 v11, -v5, v11, v5
	v_mul_f32_e32 v14, v6, v6
	v_mul_f32_e32 v15, v7, v7
	v_cndmask_b32_e32 v18, v10, v18, vcc
	v_cmp_gt_f32_e32 vcc, 0, v5
	v_fma_f32 v4, v20, s28, v8
	v_fma_f32 v5, v21, s28, v8
	s_nop 0
	v_cndmask_b32_e32 v19, v11, v19, vcc
	v_mul_f32_e32 v10, s40, v14
	v_mul_f32_e32 v11, s40, v15
	v_fma_f32 v4, v20, v4, s34
	v_fma_f32 v5, v21, v5, s34
	v_exp_f32_e32 v10, v10
	v_exp_f32_e32 v11, v11
	v_fma_f32 v4, v20, v4, s36
	v_fma_f32 v5, v21, v5, s36
	v_and_b32_e32 v15, 0x7fffffff, v1
	v_and_b32_e32 v14, 0x7fffffff, v0
	v_fma_f32 v4, v20, v4, s38
	v_fma_f32 v5, v21, v5, s38
	v_fma_f32 v14, v14, s26, 1.0
	v_fma_f32 v15, v15, s26, 1.0
	v_mul_f32_e32 v4, v20, v4
	v_mul_f32_e32 v5, v21, v5
	v_rcp_f32_e32 v14, v14
	v_rcp_f32_e32 v15, v15
	v_mul_f32_e32 v4, v10, v4
	v_mul_f32_e32 v5, v11, v5
	v_cmp_gt_f32_e32 vcc, 0, v6
	v_mul_f32_e32 v10, v6, v4
	v_mul_f32_e32 v11, v7, v5
	v_fma_f32 v4, -v6, v4, v6
	v_fma_f32 v5, -v7, v5, v7
	s_nop 0
	v_cndmask_b32_e32 v20, v4, v10, vcc
	v_cmp_gt_f32_e32 vcc, 0, v7
	v_mul_f32_e32 v6, v0, v0
	v_mul_f32_e32 v7, v1, v1
	s_nop 0
	v_cndmask_b32_e32 v21, v5, v11, vcc
	v_fma_f32 v4, v14, s28, v8
	v_fma_f32 v5, v15, s28, v8
	v_mul_f32_e32 v6, s40, v6
	v_mul_f32_e32 v7, s40, v7
	v_fma_f32 v4, v14, v4, s34
	v_fma_f32 v5, v15, v5, s34
	v_exp_f32_e32 v6, v6
	v_fma_f32 v4, v14, v4, s36
	v_fma_f32 v5, v15, v5, s36
	v_exp_f32_e32 v7, v7
	v_fma_f32 v4, v14, v4, s38
	v_fma_f32 v5, v15, v5, s38
	v_cmp_gt_f32_e32 vcc, 0, v0
	v_mul_f32_e32 v4, v14, v4
	v_mul_f32_e32 v5, v15, v5
	v_and_b32_e32 v15, 0x7fffffff, v3
	v_and_b32_e32 v14, 0x7fffffff, v2
	v_fma_f32 v14, v14, s26, 1.0
	v_fma_f32 v15, v15, s26, 1.0
	v_mul_f32_e32 v4, v6, v4
	v_mul_f32_e32 v5, v7, v5
	v_rcp_f32_e32 v14, v14
	v_rcp_f32_e32 v15, v15
	v_mul_f32_e32 v6, v0, v4
	v_mul_f32_e32 v7, v1, v5
	v_fma_f32 v4, -v0, v4, v0
	v_fma_f32 v5, -v1, v5, v1
	v_mul_f32_e32 v10, v2, v2
	v_mul_f32_e32 v11, v3, v3
	v_cndmask_b32_e32 v6, v4, v6, vcc
	v_cmp_gt_f32_e32 vcc, 0, v1
	v_fma_f32 v0, v14, s28, v8
	v_fma_f32 v1, v15, s28, v8
	s_nop 0
	v_cndmask_b32_e32 v7, v5, v7, vcc
	v_mul_f32_e32 v4, s40, v10
	v_mul_f32_e32 v5, s40, v11
	v_fma_f32 v0, v14, v0, s34
	v_fma_f32 v1, v15, v1, s34
	v_exp_f32_e32 v4, v4
	v_exp_f32_e32 v5, v5
	v_fma_f32 v0, v14, v0, s36
	v_fma_f32 v1, v15, v1, s36
	v_cmp_gt_f32_e32 vcc, 0, v2
	v_fma_f32 v0, v14, v0, s38
	v_fma_f32 v1, v15, v1, s38
	s_nop 0
	v_mul_f32_e32 v0, v14, v0
	v_mul_f32_e32 v1, v15, v1
	s_nop 0
	v_mul_f32_e32 v0, v4, v0
	v_mul_f32_e32 v1, v5, v1
	s_nop 0
	v_mul_f32_e32 v4, v2, v0
	v_mul_f32_e32 v5, v3, v1
	v_fma_f32 v0, -v2, v0, v2
	v_fma_f32 v1, -v3, v1, v3
	s_nop 0
	v_cndmask_b32_e32 v4, v0, v4, vcc
	v_cmp_gt_f32_e32 vcc, 0, v3
	v_cvt_pk_bf16_f32 v0, v18, v19
	s_nop 1
	v_cndmask_b32_e32 v3, v1, v5, vcc
	s_and_b64 vcc, exec, s[8:9]
	v_cvt_pk_bf16_f32 v1, v20, v21
	v_cvt_pk_bf16_f32 v2, v6, v7
	v_cvt_pk_bf16_f32 v3, v4, v3
	global_store_dwordx4 v[16:17], v[0:3], off offset:256
	s_cbranch_vccnz .LBB0_271
	v_lshlrev_b32_e32 v4, 16, v0
	v_and_b32_e32 v0, 0xffff0000, v0
	v_lshlrev_b32_e32 v6, 16, v1
	v_and_b32_e32 v8, 0xffff0000, v1
	v_lshlrev_b32_e32 v10, 16, v2
	v_and_b32_e32 v2, 0xffff0000, v2
	v_lshlrev_b32_e32 v14, 16, v3
	v_and_b32_e32 v16, 0xffff0000, v3
	v_mul_f32_e32 v5, v4, v4
	v_mul_f32_e32 v1, v0, v0
	v_mul_f32_e32 v7, v6, v6
	v_mul_f32_e32 v9, v8, v8
	v_mul_f32_e32 v11, v10, v10
	v_mul_f32_e32 v3, v2, v2
	v_mul_f32_e32 v15, v14, v14
	v_mul_f32_e32 v17, v16, v16
	v_add_f32_e32 v0, v4, v0
	v_add_f32_e32 v1, v5, v1
	v_add_f32_e32 v4, v6, v8
	v_add_f32_e32 v5, v7, v9
	v_add_f32_e32 v2, v10, v2
	v_add_f32_e32 v3, v11, v3
	v_add_f32_e32 v0, v0, v4
	v_add_f32_e32 v1, v1, v5
	v_add_f32_e32 v4, v14, v16
	v_add_f32_e32 v5, v15, v17
	s_nop 0
	v_add_f32_e32 v2, v2, v4
	v_add_f32_e32 v3, v3, v5
	s_nop 0
	v_add_f32_e32 v0, v0, v2
	v_add_f32_e32 v1, v1, v3
	s_nop 0
	v_add_f32_e32 v0, v12, v0
	v_add_f32_e32 v1, v13, v1
	ds_bpermute_b32 v2, v180, v0
	ds_bpermute_b32 v3, v180, v1
	s_waitcnt lgkmcnt(0)
	v_add_f32_e32 v0, v0, v2
	v_add_f32_e32 v1, v1, v3
	ds_bpermute_b32 v2, v179, v0
	ds_bpermute_b32 v3, v179, v1
	s_and_saveexec_b64 s[8:9], s[4:5]
	s_cbranch_execz .LBB0_270
	v_lshlrev_b64 v[4:5], 8, v[148:149]
	v_lshl_add_u64 v[4:5], s[16:17], 0, v[4:5]
	v_lshl_add_u64 v[4:5], s[50:51], 2, v[4:5]
	s_waitcnt lgkmcnt(0)
	v_add_f32_e32 v0, v0, v2
	v_add_f32_e32 v1, v1, v3
	global_store_dwordx2 v[4:5], v[0:1], off

.LBB0_334:
	s_or_b64 exec, exec, s[10:11]
	s_waitcnt lgkmcnt(0)
	s_barrier
	s_waitcnt lgkmcnt(1)
	ds_read_b64 v[0:1], v229
	s_waitcnt vmcnt(7)
	v_lshlrev_b32_e32 v2, 16, v85
	s_waitcnt lgkmcnt(1)
	v_and_b32_e32 v3, 0xffff0000, v85
	v_lshlrev_b32_e32 v4, 16, v84
	v_and_b32_e32 v5, 0xffff0000, v84
	v_lshlrev_b32_e32 v8, 16, v86
	v_and_b32_e32 v9, 0xffff0000, v86
	v_lshlrev_b32_e32 v6, 16, v87
	v_and_b32_e32 v7, 0xffff0000, v87
	s_waitcnt lgkmcnt(0)
	v_sub_f32_e32 v3, v3, v0
	v_sub_f32_e32 v2, v2, v0
	v_sub_f32_e32 v5, v5, v0
	v_sub_f32_e32 v4, v4, v0
	v_mul_f32_e32 v2, v1, v2
	v_mul_f32_e32 v3, v1, v3
	v_sub_f32_e32 v7, v7, v0
	v_sub_f32_e32 v6, v6, v0
	v_sub_f32_e32 v9, v9, v0
	v_sub_f32_e32 v8, v8, v0
	v_mul_f32_e32 v4, v1, v4
	v_mul_f32_e32 v5, v1, v5
	s_waitcnt vmcnt(0)
	v_fma_f32 v2, v82, v2, v122
	v_fma_f32 v3, v83, v3, v123
	v_mul_f32_e32 v8, v1, v8
	v_mul_f32_e32 v9, v1, v9
	v_mul_f32_e32 v0, v1, v6
	v_mul_f32_e32 v1, v1, v7
	v_fma_f32 v4, v80, v4, v120
	v_fma_f32 v5, v81, v5, v121
	v_fma_f32 v6, v118, v0, v126
	v_fma_f32 v7, v119, v1, v127
	v_fma_f32 v8, v116, v8, v124
	v_fma_f32 v9, v117, v9, v125
	v_cvt_pk_bf16_f32 v0, v4, v5
	v_cvt_pk_bf16_f32 v1, v2, v3
	v_lshlrev_b32_e32 v4, 16, v88
	v_cvt_pk_bf16_f32 v2, v8, v9
	v_cvt_pk_bf16_f32 v3, v6, v7
	ds_write_b128 v230, v[0:3]
	ds_read_b64 v[0:1], v231
	v_lshlrev_b32_e32 v2, 16, v89
	v_and_b32_e32 v3, 0xffff0000, v89
	v_and_b32_e32 v5, 0xffff0000, v88
	v_lshlrev_b32_e32 v8, 16, v90
	v_and_b32_e32 v9, 0xffff0000, v90
	v_lshlrev_b32_e32 v6, 16, v91
	v_and_b32_e32 v7, 0xffff0000, v91
	s_waitcnt lgkmcnt(0)
	v_sub_f32_e32 v3, v3, v0
	v_sub_f32_e32 v2, v2, v0
	v_sub_f32_e32 v5, v5, v0
	v_sub_f32_e32 v4, v4, v0
	v_mul_f32_e32 v2, v1, v2
	v_mul_f32_e32 v3, v1, v3
	v_sub_f32_e32 v7, v7, v0
	v_sub_f32_e32 v6, v6, v0
	v_sub_f32_e32 v9, v9, v0
	v_sub_f32_e32 v8, v8, v0
	v_mul_f32_e32 v4, v1, v4
	v_mul_f32_e32 v5, v1, v5
	v_fma_f32 v2, v82, v2, v122
	v_fma_f32 v3, v83, v3, v123
	v_mul_f32_e32 v8, v1, v8
	v_mul_f32_e32 v9, v1, v9
	v_mul_f32_e32 v0, v1, v6
	v_mul_f32_e32 v1, v1, v7
	v_fma_f32 v4, v80, v4, v120
	v_fma_f32 v5, v81, v5, v121
	v_fma_f32 v6, v118, v0, v126
	v_fma_f32 v7, v119, v1, v127
	v_fma_f32 v8, v116, v8, v124
	v_fma_f32 v9, v117, v9, v125
	v_cvt_pk_bf16_f32 v0, v4, v5
	v_cvt_pk_bf16_f32 v1, v2, v3
	v_lshlrev_b32_e32 v4, 16, v92
	v_cvt_pk_bf16_f32 v2, v8, v9
	v_cvt_pk_bf16_f32 v3, v6, v7
	ds_write_b128 v230, v[0:3] offset:8448
	ds_read_b64 v[0:1], v232
	v_lshlrev_b32_e32 v2, 16, v93
	v_and_b32_e32 v3, 0xffff0000, v93
	v_and_b32_e32 v5, 0xffff0000, v92
	v_lshlrev_b32_e32 v8, 16, v94
	v_and_b32_e32 v9, 0xffff0000, v94
	v_lshlrev_b32_e32 v6, 16, v95
	v_and_b32_e32 v7, 0xffff0000, v95
	s_waitcnt lgkmcnt(0)
	v_sub_f32_e32 v3, v3, v0
	v_sub_f32_e32 v2, v2, v0
	v_sub_f32_e32 v5, v5, v0
	v_sub_f32_e32 v4, v4, v0
	v_mul_f32_e32 v2, v1, v2
	v_mul_f32_e32 v3, v1, v3
	v_sub_f32_e32 v7, v7, v0
	v_sub_f32_e32 v6, v6, v0
	v_sub_f32_e32 v9, v9, v0
	v_sub_f32_e32 v8, v8, v0
	v_mul_f32_e32 v4, v1, v4
	v_mul_f32_e32 v5, v1, v5
	v_fma_f32 v2, v82, v2, v122
	v_fma_f32 v3, v83, v3, v123
	v_mul_f32_e32 v8, v1, v8
	v_mul_f32_e32 v9, v1, v9
	v_mul_f32_e32 v0, v1, v6
	v_mul_f32_e32 v1, v1, v7
	v_fma_f32 v4, v80, v4, v120
	v_fma_f32 v5, v81, v5, v121
	v_fma_f32 v6, v118, v0, v126
	v_fma_f32 v7, v119, v1, v127
	v_fma_f32 v8, v116, v8, v124
	v_fma_f32 v9, v117, v9, v125
	v_cvt_pk_bf16_f32 v0, v4, v5
	v_cvt_pk_bf16_f32 v1, v2, v3
	v_lshlrev_b32_e32 v4, 16, v96
	v_cvt_pk_bf16_f32 v2, v8, v9
	v_cvt_pk_bf16_f32 v3, v6, v7
	ds_write_b128 v230, v[0:3] offset:16896
	ds_read_b64 v[0:1], v233
	v_lshlrev_b32_e32 v2, 16, v97
	v_and_b32_e32 v3, 0xffff0000, v97
	v_and_b32_e32 v5, 0xffff0000, v96
	v_lshlrev_b32_e32 v8, 16, v98
	v_and_b32_e32 v9, 0xffff0000, v98
	v_lshlrev_b32_e32 v6, 16, v99
	v_and_b32_e32 v7, 0xffff0000, v99
	s_waitcnt lgkmcnt(0)
	v_sub_f32_e32 v3, v3, v0
	v_sub_f32_e32 v2, v2, v0
	v_sub_f32_e32 v5, v5, v0
	v_sub_f32_e32 v4, v4, v0
	v_mul_f32_e32 v2, v1, v2
	v_mul_f32_e32 v3, v1, v3
	v_sub_f32_e32 v7, v7, v0
	v_sub_f32_e32 v6, v6, v0
	v_sub_f32_e32 v9, v9, v0
	v_sub_f32_e32 v8, v8, v0
	v_mul_f32_e32 v4, v1, v4
	v_mul_f32_e32 v5, v1, v5
	v_fma_f32 v2, v82, v2, v122
	v_fma_f32 v3, v83, v3, v123
	v_mul_f32_e32 v8, v1, v8
	v_mul_f32_e32 v9, v1, v9
	v_mul_f32_e32 v0, v1, v6
	v_mul_f32_e32 v1, v1, v7
	v_fma_f32 v4, v80, v4, v120
	v_fma_f32 v5, v81, v5, v121
	v_fma_f32 v6, v118, v0, v126
	v_fma_f32 v7, v119, v1, v127
	v_fma_f32 v8, v116, v8, v124
	v_fma_f32 v9, v117, v9, v125
	v_cvt_pk_bf16_f32 v0, v4, v5
	v_cvt_pk_bf16_f32 v1, v2, v3
	v_lshlrev_b32_e32 v4, 16, v100
	v_cvt_pk_bf16_f32 v2, v8, v9
	v_cvt_pk_bf16_f32 v3, v6, v7
	ds_write_b128 v230, v[0:3] offset:25344
	ds_read_b64 v[0:1], v234
	v_lshlrev_b32_e32 v2, 16, v101
	v_and_b32_e32 v3, 0xffff0000, v101
	v_and_b32_e32 v5, 0xffff0000, v100
	v_lshlrev_b32_e32 v8, 16, v102
	v_and_b32_e32 v9, 0xffff0000, v102
	v_lshlrev_b32_e32 v6, 16, v103
	v_and_b32_e32 v7, 0xffff0000, v103
	s_waitcnt lgkmcnt(0)
	v_sub_f32_e32 v3, v3, v0
	v_sub_f32_e32 v2, v2, v0
	v_sub_f32_e32 v5, v5, v0
	v_sub_f32_e32 v4, v4, v0
	v_mul_f32_e32 v2, v1, v2
	v_mul_f32_e32 v3, v1, v3
	v_sub_f32_e32 v7, v7, v0
	v_sub_f32_e32 v6, v6, v0
	v_sub_f32_e32 v9, v9, v0
	v_sub_f32_e32 v8, v8, v0
	v_mul_f32_e32 v4, v1, v4
	v_mul_f32_e32 v5, v1, v5
	v_fma_f32 v2, v82, v2, v122
	v_fma_f32 v3, v83, v3, v123
	v_mul_f32_e32 v8, v1, v8
	v_mul_f32_e32 v9, v1, v9
	v_mul_f32_e32 v0, v1, v6
	v_mul_f32_e32 v1, v1, v7
	v_fma_f32 v4, v80, v4, v120
	v_fma_f32 v5, v81, v5, v121
	v_fma_f32 v6, v118, v0, v126
	v_fma_f32 v7, v119, v1, v127
	v_fma_f32 v8, v116, v8, v124
	v_fma_f32 v9, v117, v9, v125
	v_cvt_pk_bf16_f32 v0, v4, v5
	v_cvt_pk_bf16_f32 v1, v2, v3
	v_lshlrev_b32_e32 v4, 16, v104
	v_cvt_pk_bf16_f32 v2, v8, v9
	v_cvt_pk_bf16_f32 v3, v6, v7
	ds_write_b128 v230, v[0:3] offset:33792
	ds_read_b64 v[0:1], v235
	v_lshlrev_b32_e32 v2, 16, v105
	v_and_b32_e32 v3, 0xffff0000, v105
	v_and_b32_e32 v5, 0xffff0000, v104
	v_lshlrev_b32_e32 v8, 16, v106
	v_and_b32_e32 v9, 0xffff0000, v106
	v_lshlrev_b32_e32 v6, 16, v107
	v_and_b32_e32 v7, 0xffff0000, v107
	s_waitcnt lgkmcnt(0)
	v_sub_f32_e32 v3, v3, v0
	v_sub_f32_e32 v2, v2, v0
	v_sub_f32_e32 v5, v5, v0
	v_sub_f32_e32 v4, v4, v0
	v_mul_f32_e32 v2, v1, v2
	v_mul_f32_e32 v3, v1, v3
	v_sub_f32_e32 v7, v7, v0
	v_sub_f32_e32 v6, v6, v0
	v_sub_f32_e32 v9, v9, v0
	v_sub_f32_e32 v8, v8, v0
	v_mul_f32_e32 v4, v1, v4
	v_mul_f32_e32 v5, v1, v5
	v_fma_f32 v2, v82, v2, v122
	v_fma_f32 v3, v83, v3, v123
	v_mul_f32_e32 v8, v1, v8
	v_mul_f32_e32 v9, v1, v9
	v_mul_f32_e32 v0, v1, v6
	v_mul_f32_e32 v1, v1, v7
	v_fma_f32 v4, v80, v4, v120
	v_fma_f32 v5, v81, v5, v121
	v_fma_f32 v6, v118, v0, v126
	v_fma_f32 v7, v119, v1, v127
	v_fma_f32 v8, v116, v8, v124
	v_fma_f32 v9, v117, v9, v125
	v_cvt_pk_bf16_f32 v0, v4, v5
	v_cvt_pk_bf16_f32 v1, v2, v3
	v_lshlrev_b32_e32 v4, 16, v108
	v_cvt_pk_bf16_f32 v2, v8, v9
	v_cvt_pk_bf16_f32 v3, v6, v7
	ds_write_b128 v230, v[0:3] offset:42240
	ds_read_b64 v[0:1], v236
	v_lshlrev_b32_e32 v2, 16, v109
	v_and_b32_e32 v3, 0xffff0000, v109
	v_and_b32_e32 v5, 0xffff0000, v108
	v_lshlrev_b32_e32 v8, 16, v110
	v_and_b32_e32 v9, 0xffff0000, v110
	v_lshlrev_b32_e32 v6, 16, v111
	v_and_b32_e32 v7, 0xffff0000, v111
	s_waitcnt lgkmcnt(0)
	v_sub_f32_e32 v3, v3, v0
	v_sub_f32_e32 v2, v2, v0
	v_sub_f32_e32 v5, v5, v0
	v_sub_f32_e32 v4, v4, v0
	v_mul_f32_e32 v2, v1, v2
	v_mul_f32_e32 v3, v1, v3
	v_sub_f32_e32 v7, v7, v0
	v_sub_f32_e32 v6, v6, v0
	v_sub_f32_e32 v9, v9, v0
	v_sub_f32_e32 v8, v8, v0
	v_mul_f32_e32 v4, v1, v4
	v_mul_f32_e32 v5, v1, v5
	v_fma_f32 v2, v82, v2, v122
	v_fma_f32 v3, v83, v3, v123
	v_mul_f32_e32 v8, v1, v8
	v_mul_f32_e32 v9, v1, v9
	v_mul_f32_e32 v0, v1, v6
	v_mul_f32_e32 v1, v1, v7
	v_fma_f32 v4, v80, v4, v120
	v_fma_f32 v5, v81, v5, v121
	v_fma_f32 v6, v118, v0, v126
	v_fma_f32 v7, v119, v1, v127
	v_fma_f32 v8, v116, v8, v124
	v_fma_f32 v9, v117, v9, v125
	v_cvt_pk_bf16_f32 v0, v4, v5
	v_cvt_pk_bf16_f32 v1, v2, v3
	v_lshlrev_b32_e32 v4, 16, v112
	v_cvt_pk_bf16_f32 v2, v8, v9
	v_cvt_pk_bf16_f32 v3, v6, v7
	ds_write_b128 v230, v[0:3] offset:50688
	ds_read_b64 v[0:1], v237
	v_lshlrev_b32_e32 v2, 16, v113
	v_and_b32_e32 v3, 0xffff0000, v113
	v_and_b32_e32 v5, 0xffff0000, v112
	v_lshlrev_b32_e32 v8, 16, v114
	v_and_b32_e32 v9, 0xffff0000, v114
	v_lshlrev_b32_e32 v6, 16, v115
	v_and_b32_e32 v7, 0xffff0000, v115
	s_waitcnt lgkmcnt(0)
	v_sub_f32_e32 v3, v3, v0
	v_sub_f32_e32 v2, v2, v0
	v_sub_f32_e32 v5, v5, v0
	v_sub_f32_e32 v4, v4, v0
	v_mul_f32_e32 v2, v1, v2
	v_mul_f32_e32 v3, v1, v3
	v_sub_f32_e32 v7, v7, v0
	v_sub_f32_e32 v6, v6, v0
	v_sub_f32_e32 v9, v9, v0
	v_sub_f32_e32 v8, v8, v0
	v_mul_f32_e32 v4, v1, v4
	v_mul_f32_e32 v5, v1, v5
	v_fma_f32 v2, v82, v2, v122
	v_fma_f32 v3, v83, v3, v123
	v_mul_f32_e32 v8, v1, v8
	v_mul_f32_e32 v9, v1, v9
	v_mul_f32_e32 v0, v1, v6
	v_mul_f32_e32 v1, v1, v7
	v_fma_f32 v4, v80, v4, v120
	v_fma_f32 v5, v81, v5, v121
	v_fma_f32 v6, v118, v0, v126
	v_fma_f32 v7, v119, v1, v127
	v_fma_f32 v8, v116, v8, v124
	v_fma_f32 v9, v117, v9, v125
	v_cvt_pk_bf16_f32 v0, v4, v5
	v_cvt_pk_bf16_f32 v1, v2, v3
	s_add_i32 s29, s35, s18
	v_cvt_pk_bf16_f32 v2, v8, v9
	v_cvt_pk_bf16_f32 v3, v6, v7
	ds_write_b128 v230, v[0:3] offset:59136
	s_waitcnt lgkmcnt(0)
	s_barrier
	s_cmpk_gt_i32 s29, 0x7ff
	s_cselect_b64 s[8:9], -1, 0
	s_and_b64 vcc, exec, s[8:9]
	s_cbranch_vccnz .LBB0_327
	s_ashr_i32 s10, s29, 3
	s_ashr_i32 s11, s10, 31
	s_lshl_b64 s[10:11], s[10:11], 7
	v_lshl_add_u64 v[0:1], s[10:11], 0, v[162:163]
	v_lshlrev_b64 v[0:1], 8, v[0:1]
	v_lshl_add_u64 v[0:1], v[170:171], 0, v[0:1]
	global_load_dwordx4 v[64:67], v[0:1], off offset:48
	global_load_dwordx4 v[68:71], v[0:1], off offset:32
	global_load_dwordx4 v[72:75], v[0:1], off offset:16
	global_load_dwordx4 v[76:79], v[0:1], off
	v_lshl_add_u64 v[0:1], s[10:11], 0, v[160:161]
	s_and_b32 s10, s22, 0x700
	s_lshl_b32 s16, s10, 1
	v_lshl_add_u64 v[2:3], v[172:173], 0, s[16:17]
	v_lshlrev_b64 v[0:1], 12, v[0:1]
	v_lshl_add_u64 v[0:1], v[2:3], 0, v[0:1]
	v_add_co_u32_e32 v2, vcc, s14, v0
	s_nop 1
	v_addc_co_u32_e32 v3, vcc, 0, v1, vcc
	global_load_dwordx4 v[84:87], v[0:1], off
	global_load_dwordx4 v[88:91], v[2:3], off
	v_add_co_u32_e32 v2, vcc, s15, v0
	s_nop 1
	v_addc_co_u32_e32 v3, vcc, 0, v1, vcc
	v_add_co_u32_e32 v4, vcc, s20, v0
	s_nop 1
	v_addc_co_u32_e32 v5, vcc, 0, v1, vcc
	global_load_dwordx4 v[92:95], v[2:3], off
	global_load_dwordx4 v[96:99], v[4:5], off
	v_add_co_u32_e32 v2, vcc, s25, v0
	s_nop 1
	v_addc_co_u32_e32 v3, vcc, 0, v1, vcc
	v_add_co_u32_e32 v4, vcc, 0x50000, v0
	s_nop 1
	v_addc_co_u32_e32 v5, vcc, 0, v1, vcc
	global_load_dwordx4 v[100:103], v[2:3], off
	global_load_dwordx4 v[104:107], v[4:5], off
	v_add_co_u32_e32 v2, vcc, 0x60000, v0
	s_nop 1
	v_addc_co_u32_e32 v3, vcc, 0, v1, vcc
	v_add_co_u32_e32 v0, vcc, 0x70000, v0
	s_nop 1
	v_addc_co_u32_e32 v1, vcc, 0, v1, vcc
	global_load_dwordx4 v[108:111], v[2:3], off
	global_load_dwordx4 v[112:115], v[0:1], off
	s_branch .LBB0_327

.LBB0_404:
	v_lshl_or_b32 v168, s10, 8, v188
	v_lshl_add_u32 v172, s40, 8, v186
	v_ashrrev_i32_e32 v169, 31, v168
	v_lshlrev_b64 v[204:205], 1, v[168:169]
	v_ashrrev_i32_e32 v173, 31, v172
	v_lshl_add_u64 v[170:171], s[16:17], 0, v[204:205]
	v_lshlrev_b64 v[206:207], 11, v[172:173]
	v_lshl_add_u64 v[128:129], v[170:171], 0, v[206:207]
	global_load_dwordx4 v[194:197], v[128:129], off
	global_load_dwordx4 v[198:201], v[128:129], off offset:256
	v_or_b32_e32 v182, 16, v172
	v_or_b32_e32 v178, 32, v172
	v_or_b32_e32 v174, 48, v172
	v_ashrrev_i32_e32 v183, 31, v182
	v_ashrrev_i32_e32 v179, 31, v178
	v_ashrrev_i32_e32 v175, 31, v174
	v_lshlrev_b64 v[184:185], 11, v[182:183]
	v_lshlrev_b64 v[180:181], 11, v[178:179]
	v_lshlrev_b64 v[176:177], 11, v[174:175]
	v_lshl_add_u64 v[128:129], v[170:171], 0, v[184:185]
	v_lshl_add_u64 v[130:131], v[170:171], 0, v[180:181]
	v_lshl_add_u64 v[208:209], v[170:171], 0, v[176:177]
	global_load_dwordx4 v[148:151], v[128:129], off
	global_load_dwordx4 v[144:147], v[128:129], off offset:256
	global_load_dwordx4 v[140:143], v[130:131], off
	global_load_dwordx4 v[136:139], v[130:131], off offset:256
	global_load_dwordx4 v[132:135], v[208:209], off
	s_nop 0
	global_load_dwordx4 v[128:131], v[208:209], off offset:256
	v_and_b32_e32 v208, 64, v192
	v_xor_b32_e32 v193, 16, v192
	v_add_u32_e32 v208, 64, v208
	v_xor_b32_e32 v209, 32, v192
	v_cmp_lt_i32_e32 vcc, v193, v208
	v_lshl_add_u64 v[206:207], s[16:17], 0, v[206:207]
	v_lshl_add_u64 v[204:205], v[206:207], 0, v[204:205]
	v_cndmask_b32_e32 v193, v192, v193, vcc
	v_cmp_lt_i32_e32 vcc, v209, v208
	v_lshlrev_b32_e32 v193, 2, v193
	s_lshl_b32 s40, s10, 2
	v_cndmask_b32_e32 v214, v192, v209, vcc
	s_ashr_i32 s41, s40, 31
	s_waitcnt vmcnt(0)
	v_lshlrev_b32_e32 v206, 16, v194
	v_and_b32_e32 v207, 0xffff0000, v194
	v_lshlrev_b32_e32 v194, 16, v195
	v_and_b32_e32 v195, 0xffff0000, v195
	v_lshlrev_b32_e32 v208, 16, v196
	v_and_b32_e32 v209, 0xffff0000, v196
	v_lshlrev_b32_e32 v196, 16, v197
	v_and_b32_e32 v197, 0xffff0000, v197
	v_lshlrev_b32_e32 v210, 16, v198
	v_and_b32_e32 v211, 0xffff0000, v198
	v_lshlrev_b32_e32 v198, 16, v199
	v_and_b32_e32 v199, 0xffff0000, v199
	v_lshlrev_b32_e32 v212, 16, v200
	v_and_b32_e32 v213, 0xffff0000, v200
	v_lshlrev_b32_e32 v200, 16, v201
	v_and_b32_e32 v201, 0xffff0000, v201
	v_add_f32_e32 v126, v126, v194
	v_add_f32_e32 v127, v127, v195
	v_add_f32_e32 v124, v124, v206
	v_add_f32_e32 v125, v125, v207
	v_add_f32_e32 v122, v122, v196
	v_add_f32_e32 v123, v123, v197
	v_add_f32_e32 v120, v120, v208
	v_add_f32_e32 v121, v121, v209
	v_add_f32_e32 v118, v118, v198
	v_add_f32_e32 v119, v119, v199
	v_add_f32_e32 v116, v116, v210
	v_add_f32_e32 v117, v117, v211
	v_add_f32_e32 v194, v114, v200
	v_add_f32_e32 v195, v115, v201
	v_add_f32_e32 v196, v112, v212
	v_add_f32_e32 v197, v113, v213
	v_mul_f32_e32 v114, v125, v125
	v_mul_f32_e32 v115, v127, v127
	v_mul_f32_e32 v198, v121, v121
	v_mul_f32_e32 v199, v123, v123
	v_cvt_pk_bf16_f32 v112, v124, v125
	v_cvt_pk_bf16_f32 v113, v126, v127
	v_mul_f32_e32 v125, v117, v117
	v_mul_f32_e32 v127, v119, v119
	v_mul_f32_e32 v200, v197, v197
	v_mul_f32_e32 v201, v195, v195
	v_fmac_f32_e32 v114, v124, v124
	v_fmac_f32_e32 v115, v126, v126
	v_fmac_f32_e32 v198, v120, v120
	v_fmac_f32_e32 v199, v122, v122
	v_fmac_f32_e32 v125, v116, v116
	v_fmac_f32_e32 v127, v118, v118
	v_fmac_f32_e32 v200, v196, v196
	v_fmac_f32_e32 v201, v194, v194
	v_add_f32_e32 v114, v114, v115
	v_add_f32_e32 v115, v198, v199
	v_add_f32_e32 v124, v125, v127
	v_add_f32_e32 v125, v200, v201
	v_add_f32_e32 v114, v114, v115
	v_add_f32_e32 v115, v124, v125
	v_add_f32_e32 v124, v114, v115
	ds_bpermute_b32 v125, v193, v124
	v_cvt_pk_bf16_f32 v114, v120, v121
	v_cvt_pk_bf16_f32 v115, v122, v123
	global_store_dwordx4 v[204:205], v[112:115], off
	v_cvt_pk_bf16_f32 v116, v116, v117
	v_cvt_pk_bf16_f32 v117, v118, v119
	v_cvt_pk_bf16_f32 v118, v196, v197
	v_cvt_pk_bf16_f32 v119, v194, v195
	global_store_dwordx4 v[204:205], v[116:119], off offset:256
	s_waitcnt lgkmcnt(0)
	v_add_f32_e32 v113, v124, v125
	v_lshlrev_b32_e32 v112, 2, v214
	ds_bpermute_b32 v114, v112, v113
	s_and_saveexec_b64 s[4:5], s[6:7]
	s_cbranch_execz .LBB0_406
	v_lshlrev_b64 v[116:117], 6, v[172:173]
	v_lshl_add_u64 v[116:117], s[22:23], 0, v[116:117]
	v_lshl_add_u64 v[116:117], s[40:41], 2, v[116:117]
	s_lshl_b32 s10, s51, 2
	v_lshl_add_u64 v[116:117], v[116:117], 0, s[10:11]
	s_waitcnt lgkmcnt(0)
	v_add_f32_e32 v113, v113, v114
	global_store_dword v[116:117], v113, off
.LBB0_406:
	s_or_b64 exec, exec, s[4:5]
	s_waitcnt lgkmcnt(0)
	v_lshlrev_b32_e32 v114, 16, v148
	v_and_b32_e32 v115, 0xffff0000, v148
	v_lshlrev_b32_e32 v116, 16, v149
	v_and_b32_e32 v117, 0xffff0000, v149
	v_lshlrev_b32_e32 v118, 16, v150
	v_and_b32_e32 v119, 0xffff0000, v150
	v_lshlrev_b32_e32 v120, 16, v151
	v_and_b32_e32 v121, 0xffff0000, v151
	v_add_f32_e32 v110, v110, v116
	v_add_f32_e32 v111, v111, v117
	v_add_f32_e32 v108, v108, v114
	v_add_f32_e32 v109, v109, v115
	v_add_f32_e32 v114, v106, v120
	v_add_f32_e32 v115, v107, v121
	v_add_f32_e32 v106, v104, v118
	v_add_f32_e32 v107, v105, v119
	v_mul_f32_e32 v104, v109, v109
	v_mul_f32_e32 v105, v111, v111
	v_fmac_f32_e32 v104, v108, v108
	v_fmac_f32_e32 v105, v110, v110
	v_add_f32_e32 v104, v104, v105
	v_mul_f32_e32 v105, v107, v107
	v_mul_f32_e32 v113, v115, v115
	v_fmac_f32_e32 v105, v106, v106
	v_fmac_f32_e32 v113, v114, v114
	v_add_f32_e32 v105, v105, v113
	v_add_f32_e32 v113, v104, v105
	v_cvt_pk_bf16_f32 v104, v108, v109
	v_cvt_pk_bf16_f32 v105, v110, v111
	v_lshlrev_b32_e32 v108, 16, v144
	v_and_b32_e32 v109, 0xffff0000, v144
	v_lshlrev_b32_e32 v110, 16, v145
	v_and_b32_e32 v111, 0xffff0000, v145
	v_cvt_pk_bf16_f32 v106, v106, v107
	v_cvt_pk_bf16_f32 v107, v114, v115
	v_lshlrev_b32_e32 v114, 16, v146
	v_and_b32_e32 v115, 0xffff0000, v146
	v_add_f32_e32 v102, v102, v110
	v_add_f32_e32 v103, v103, v111
	v_add_f32_e32 v100, v100, v108
	v_add_f32_e32 v101, v101, v109
	v_lshlrev_b32_e32 v116, 16, v147
	v_and_b32_e32 v117, 0xffff0000, v147
	v_add_f32_e32 v110, v96, v114
	v_add_f32_e32 v111, v97, v115
	v_mul_f32_e32 v96, v101, v101
	v_mul_f32_e32 v97, v103, v103
	v_add_f32_e32 v108, v98, v116
	v_add_f32_e32 v109, v99, v117
	v_fmac_f32_e32 v96, v100, v100
	v_fmac_f32_e32 v97, v102, v102
	v_add_f32_e32 v96, v96, v97
	v_mul_f32_e32 v97, v111, v111
	v_mul_f32_e32 v98, v109, v109
	v_fmac_f32_e32 v97, v110, v110
	v_fmac_f32_e32 v98, v108, v108
	v_add_f32_e32 v97, v97, v98
	v_add_f32_e32 v96, v96, v97
	v_add_f32_e32 v99, v113, v96
	ds_bpermute_b32 v113, v193, v99
	v_lshl_add_u64 v[96:97], s[16:17], 0, v[184:185]
	v_lshl_add_u64 v[114:115], v[168:169], 1, v[96:97]
	global_store_dwordx4 v[114:115], v[104:107], off
	v_cvt_pk_bf16_f32 v98, v100, v101
	s_waitcnt lgkmcnt(0)
	v_add_f32_e32 v96, v99, v113
	ds_bpermute_b32 v97, v112, v96
	v_cvt_pk_bf16_f32 v99, v102, v103
	v_cvt_pk_bf16_f32 v100, v110, v111
	v_cvt_pk_bf16_f32 v101, v108, v109
	global_store_dwordx4 v[114:115], v[98:101], off offset:256
	s_and_saveexec_b64 s[4:5], s[6:7]
	s_cbranch_execz .LBB0_408
	v_lshlrev_b64 v[98:99], 6, v[182:183]
	v_lshl_add_u64 v[98:99], s[22:23], 0, v[98:99]
	v_lshl_add_u64 v[98:99], s[40:41], 2, v[98:99]
	s_lshl_b32 s10, s51, 2
	v_lshl_add_u64 v[98:99], v[98:99], 0, s[10:11]
	s_waitcnt lgkmcnt(0)
	v_add_f32_e32 v96, v96, v97
	global_store_dword v[98:99], v96, off
.LBB0_408:
	s_or_b64 exec, exec, s[4:5]
	v_lshlrev_b32_e32 v96, 16, v140
	s_waitcnt lgkmcnt(0)
	v_and_b32_e32 v97, 0xffff0000, v140
	v_lshlrev_b32_e32 v98, 16, v141
	v_and_b32_e32 v99, 0xffff0000, v141
	v_lshlrev_b32_e32 v100, 16, v142
	v_and_b32_e32 v101, 0xffff0000, v142
	v_lshlrev_b32_e32 v102, 16, v143
	v_and_b32_e32 v103, 0xffff0000, v143
	v_add_f32_e32 v94, v94, v98
	v_add_f32_e32 v95, v95, v99
	v_add_f32_e32 v92, v92, v96
	v_add_f32_e32 v93, v93, v97
	v_add_f32_e32 v96, v90, v102
	v_add_f32_e32 v97, v91, v103
	v_add_f32_e32 v90, v88, v100
	v_add_f32_e32 v91, v89, v101
	v_mul_f32_e32 v88, v93, v93
	v_mul_f32_e32 v89, v95, v95
	v_fmac_f32_e32 v88, v92, v92
	v_fmac_f32_e32 v89, v94, v94
	v_add_f32_e32 v88, v88, v89
	v_mul_f32_e32 v89, v91, v91
	v_mul_f32_e32 v98, v97, v97
	v_fmac_f32_e32 v89, v90, v90
	v_fmac_f32_e32 v98, v96, v96
	v_add_f32_e32 v89, v89, v98
	v_add_f32_e32 v100, v88, v89
	v_cvt_pk_bf16_f32 v88, v92, v93
	v_cvt_pk_bf16_f32 v89, v94, v95
	v_lshlrev_b32_e32 v92, 16, v136
	v_and_b32_e32 v93, 0xffff0000, v136
	v_lshlrev_b32_e32 v94, 16, v137
	v_and_b32_e32 v95, 0xffff0000, v137
	v_cvt_pk_bf16_f32 v90, v90, v91
	v_cvt_pk_bf16_f32 v91, v96, v97
	v_lshlrev_b32_e32 v96, 16, v138
	v_and_b32_e32 v97, 0xffff0000, v138
	v_add_f32_e32 v86, v86, v94
	v_add_f32_e32 v87, v87, v95
	v_add_f32_e32 v84, v84, v92
	v_add_f32_e32 v85, v85, v93
	v_lshlrev_b32_e32 v98, 16, v139
	v_and_b32_e32 v99, 0xffff0000, v139
	v_add_f32_e32 v94, v80, v96
	v_add_f32_e32 v95, v81, v97
	v_mul_f32_e32 v80, v85, v85
	v_mul_f32_e32 v81, v87, v87
	v_add_f32_e32 v92, v82, v98
	v_add_f32_e32 v93, v83, v99
	v_fmac_f32_e32 v80, v84, v84
	v_fmac_f32_e32 v81, v86, v86
	v_add_f32_e32 v80, v80, v81
	v_mul_f32_e32 v81, v95, v95
	v_mul_f32_e32 v82, v93, v93
	v_fmac_f32_e32 v81, v94, v94
	v_fmac_f32_e32 v82, v92, v92
	v_add_f32_e32 v81, v81, v82
	v_add_f32_e32 v80, v80, v81
	v_add_f32_e32 v83, v100, v80
	ds_bpermute_b32 v98, v193, v83
	v_lshl_add_u64 v[80:81], s[16:17], 0, v[180:181]
	v_lshl_add_u64 v[96:97], v[168:169], 1, v[80:81]
	global_store_dwordx4 v[96:97], v[88:91], off
	v_cvt_pk_bf16_f32 v82, v84, v85
	s_waitcnt lgkmcnt(0)
	v_add_f32_e32 v80, v83, v98
	ds_bpermute_b32 v81, v112, v80
	v_cvt_pk_bf16_f32 v83, v86, v87
	v_cvt_pk_bf16_f32 v84, v94, v95
	v_cvt_pk_bf16_f32 v85, v92, v93
	global_store_dwordx4 v[96:97], v[82:85], off offset:256
	s_and_saveexec_b64 s[4:5], s[6:7]
	s_cbranch_execz .LBB0_410
	v_lshlrev_b64 v[82:83], 6, v[178:179]
	v_lshl_add_u64 v[82:83], s[22:23], 0, v[82:83]
	v_lshl_add_u64 v[82:83], s[40:41], 2, v[82:83]
	s_lshl_b32 s10, s51, 2
	v_lshl_add_u64 v[82:83], v[82:83], 0, s[10:11]
	s_waitcnt lgkmcnt(0)
	v_add_f32_e32 v80, v80, v81
	global_store_dword v[82:83], v80, off
.LBB0_410:
	s_or_b64 exec, exec, s[4:5]
	v_lshlrev_b32_e32 v80, 16, v132
	s_waitcnt lgkmcnt(0)
	v_and_b32_e32 v81, 0xffff0000, v132
	v_lshlrev_b32_e32 v82, 16, v133
	v_and_b32_e32 v83, 0xffff0000, v133
	v_lshlrev_b32_e32 v84, 16, v134
	v_and_b32_e32 v85, 0xffff0000, v134
	v_lshlrev_b32_e32 v86, 16, v135
	v_and_b32_e32 v87, 0xffff0000, v135
	v_add_f32_e32 v78, v78, v82
	v_add_f32_e32 v79, v79, v83
	v_add_f32_e32 v76, v76, v80
	v_add_f32_e32 v77, v77, v81
	v_add_f32_e32 v80, v74, v86
	v_add_f32_e32 v81, v75, v87
	v_add_f32_e32 v74, v72, v84
	v_add_f32_e32 v75, v73, v85
	v_mul_f32_e32 v72, v77, v77
	v_mul_f32_e32 v73, v79, v79
	v_fmac_f32_e32 v72, v76, v76
	v_fmac_f32_e32 v73, v78, v78
	v_add_f32_e32 v72, v72, v73
	v_mul_f32_e32 v73, v75, v75
	v_mul_f32_e32 v82, v81, v81
	v_fmac_f32_e32 v73, v74, v74
	v_fmac_f32_e32 v82, v80, v80
	v_add_f32_e32 v73, v73, v82
	v_add_f32_e32 v84, v72, v73
	v_cvt_pk_bf16_f32 v72, v76, v77
	v_cvt_pk_bf16_f32 v73, v78, v79
	v_lshlrev_b32_e32 v76, 16, v128
	v_and_b32_e32 v77, 0xffff0000, v128
	v_lshlrev_b32_e32 v78, 16, v129
	v_and_b32_e32 v79, 0xffff0000, v129
	v_cvt_pk_bf16_f32 v74, v74, v75
	v_cvt_pk_bf16_f32 v75, v80, v81
	v_lshlrev_b32_e32 v80, 16, v130
	v_and_b32_e32 v81, 0xffff0000, v130
	v_add_f32_e32 v70, v70, v78
	v_add_f32_e32 v71, v71, v79
	v_add_f32_e32 v68, v68, v76
	v_add_f32_e32 v69, v69, v77
	v_lshlrev_b32_e32 v82, 16, v131
	v_and_b32_e32 v83, 0xffff0000, v131
	v_add_f32_e32 v78, v64, v80
	v_add_f32_e32 v79, v65, v81
	v_mul_f32_e32 v64, v69, v69
	v_mul_f32_e32 v65, v71, v71
	v_add_f32_e32 v76, v66, v82
	v_add_f32_e32 v77, v67, v83
	v_fmac_f32_e32 v64, v68, v68
	v_fmac_f32_e32 v65, v70, v70
	v_add_f32_e32 v64, v64, v65
	v_mul_f32_e32 v65, v79, v79
	v_mul_f32_e32 v66, v77, v77
	v_fmac_f32_e32 v65, v78, v78
	v_fmac_f32_e32 v66, v76, v76
	v_add_f32_e32 v65, v65, v66
	v_add_f32_e32 v64, v64, v65
	v_add_f32_e32 v67, v84, v64
	ds_bpermute_b32 v82, v193, v67
	v_lshl_add_u64 v[64:65], s[16:17], 0, v[176:177]
	v_lshl_add_u64 v[80:81], v[168:169], 1, v[64:65]
	global_store_dwordx4 v[80:81], v[72:75], off
	v_cvt_pk_bf16_f32 v66, v68, v69
	s_waitcnt lgkmcnt(0)
	v_add_f32_e32 v64, v67, v82
	ds_bpermute_b32 v65, v112, v64
	v_cvt_pk_bf16_f32 v67, v70, v71
	v_cvt_pk_bf16_f32 v68, v78, v79
	v_cvt_pk_bf16_f32 v69, v76, v77
	global_store_dwordx4 v[80:81], v[66:69], off offset:256
	s_and_saveexec_b64 s[4:5], s[6:7]
	s_cbranch_execz .LBB0_412
	v_lshlrev_b64 v[66:67], 6, v[174:175]
	v_lshl_add_u64 v[66:67], s[22:23], 0, v[66:67]
	v_lshl_add_u64 v[66:67], s[40:41], 2, v[66:67]
	s_lshl_b32 s10, s51, 2
	v_lshl_add_u64 v[66:67], v[66:67], 0, s[10:11]
	s_waitcnt lgkmcnt(0)
	v_add_f32_e32 v64, v64, v65
	global_store_dword v[66:67], v64, off
.LBB0_412:
	s_or_b64 exec, exec, s[4:5]
	v_add_u32_e32 v100, 0x80, v172
	v_ashrrev_i32_e32 v101, 31, v100
	v_lshlrev_b64 v[110:111], 11, v[100:101]
	s_waitcnt lgkmcnt(0)
	v_lshl_add_u64 v[64:65], v[170:171], 0, v[110:111]
	global_load_dwordx4 v[102:105], v[64:65], off
	global_load_dwordx4 v[106:109], v[64:65], off offset:256
	v_add_u32_e32 v96, 0x90, v172
	v_add_u32_e32 v92, 0xa0, v172
	v_add_u32_e32 v88, 0xb0, v172
	v_ashrrev_i32_e32 v97, 31, v96
	v_ashrrev_i32_e32 v93, 31, v92
	v_ashrrev_i32_e32 v89, 31, v88
	v_lshlrev_b64 v[98:99], 11, v[96:97]
	v_lshlrev_b64 v[94:95], 11, v[92:93]
	v_lshlrev_b64 v[90:91], 11, v[88:89]
	v_lshl_add_u64 v[64:65], v[170:171], 0, v[98:99]
	v_lshl_add_u64 v[66:67], v[170:171], 0, v[94:95]
	v_lshl_add_u64 v[114:115], v[170:171], 0, v[90:91]
	global_load_dwordx4 v[84:87], v[64:65], off
	global_load_dwordx4 v[80:83], v[64:65], off offset:256
	global_load_dwordx4 v[76:79], v[66:67], off
	global_load_dwordx4 v[72:75], v[66:67], off offset:256
	global_load_dwordx4 v[68:71], v[114:115], off
	s_nop 0
	global_load_dwordx4 v[64:67], v[114:115], off offset:256
	s_waitcnt vmcnt(7)
	v_lshlrev_b32_e32 v114, 16, v102
	v_and_b32_e32 v115, 0xffff0000, v102
	v_lshlrev_b32_e32 v102, 16, v103
	v_and_b32_e32 v103, 0xffff0000, v103
	v_lshlrev_b32_e32 v116, 16, v104
	v_and_b32_e32 v117, 0xffff0000, v104
	v_lshlrev_b32_e32 v104, 16, v105
	v_and_b32_e32 v105, 0xffff0000, v105
	s_waitcnt vmcnt(6)
	v_lshlrev_b32_e32 v118, 16, v106
	v_and_b32_e32 v119, 0xffff0000, v106
	v_lshlrev_b32_e32 v106, 16, v107
	v_and_b32_e32 v107, 0xffff0000, v107
	v_lshlrev_b32_e32 v120, 16, v108
	v_and_b32_e32 v121, 0xffff0000, v108
	v_lshlrev_b32_e32 v108, 16, v109
	v_and_b32_e32 v109, 0xffff0000, v109
	v_add_f32_e32 v62, v62, v102
	v_add_f32_e32 v63, v63, v103
	v_add_f32_e32 v60, v60, v114
	v_add_f32_e32 v61, v61, v115
	v_add_f32_e32 v58, v58, v104
	v_add_f32_e32 v59, v59, v105
	v_add_f32_e32 v56, v56, v116
	v_add_f32_e32 v57, v57, v117
	v_add_f32_e32 v54, v54, v106
	v_add_f32_e32 v55, v55, v107
	v_add_f32_e32 v52, v52, v118
	v_add_f32_e32 v53, v53, v119
	v_add_f32_e32 v102, v50, v108
	v_add_f32_e32 v103, v51, v109
	v_add_f32_e32 v104, v48, v120
	v_add_f32_e32 v105, v49, v121
	v_mul_f32_e32 v106, v61, v61
	v_mul_f32_e32 v107, v63, v63
	v_mul_f32_e32 v108, v57, v57
	v_mul_f32_e32 v109, v59, v59
	v_cvt_pk_bf16_f32 v48, v60, v61
	v_cvt_pk_bf16_f32 v49, v62, v63
	v_cvt_pk_bf16_f32 v50, v56, v57
	v_cvt_pk_bf16_f32 v51, v58, v59
	v_mul_f32_e32 v57, v53, v53
	v_mul_f32_e32 v59, v55, v55
	v_mul_f32_e32 v61, v105, v105
	v_mul_f32_e32 v63, v103, v103
	v_fmac_f32_e32 v106, v60, v60
	v_fmac_f32_e32 v107, v62, v62
	v_fmac_f32_e32 v108, v56, v56
	v_fmac_f32_e32 v109, v58, v58
	v_fmac_f32_e32 v57, v52, v52
	v_fmac_f32_e32 v59, v54, v54
	v_fmac_f32_e32 v61, v104, v104
	v_fmac_f32_e32 v63, v102, v102
	v_add_f32_e32 v56, v106, v107
	v_add_f32_e32 v58, v108, v109
	v_add_f32_e32 v57, v57, v59
	v_add_f32_e32 v59, v61, v63
	v_add_f32_e32 v56, v56, v58
	v_add_f32_e32 v57, v57, v59
	v_add_f32_e32 v58, v56, v57
	ds_bpermute_b32 v59, v193, v58
	v_lshl_add_u64 v[56:57], s[16:17], 0, v[110:111]
	v_lshl_add_u64 v[56:57], v[168:169], 1, v[56:57]
	global_store_dwordx4 v[56:57], v[48:51], off
	s_waitcnt lgkmcnt(0)
	s_nop 0
	v_add_f32_e32 v48, v58, v59
	ds_bpermute_b32 v49, v112, v48
	v_cvt_pk_bf16_f32 v50, v52, v53
	v_cvt_pk_bf16_f32 v51, v54, v55
	v_cvt_pk_bf16_f32 v52, v104, v105
	v_cvt_pk_bf16_f32 v53, v102, v103
	global_store_dwordx4 v[56:57], v[50:53], off offset:256
	s_and_saveexec_b64 s[4:5], s[6:7]
	s_cbranch_execz .LBB0_414
	v_lshlrev_b64 v[50:51], 6, v[100:101]
	v_lshl_add_u64 v[50:51], s[22:23], 0, v[50:51]
	v_lshl_add_u64 v[50:51], s[40:41], 2, v[50:51]
	s_lshl_b32 s10, s51, 2
	v_lshl_add_u64 v[50:51], v[50:51], 0, s[10:11]
	s_waitcnt lgkmcnt(0)
	v_add_f32_e32 v48, v48, v49
	global_store_dword v[50:51], v48, off
.LBB0_414:
	s_or_b64 exec, exec, s[4:5]
	s_waitcnt vmcnt(7)
	v_lshlrev_b32_e32 v48, 16, v84
	s_waitcnt lgkmcnt(0)
	v_and_b32_e32 v49, 0xffff0000, v84
	v_lshlrev_b32_e32 v50, 16, v85
	v_and_b32_e32 v51, 0xffff0000, v85
	v_lshlrev_b32_e32 v52, 16, v86
	v_and_b32_e32 v53, 0xffff0000, v86
	v_lshlrev_b32_e32 v54, 16, v87
	v_and_b32_e32 v55, 0xffff0000, v87
	v_add_f32_e32 v46, v46, v50
	v_add_f32_e32 v47, v47, v51
	v_add_f32_e32 v44, v44, v48
	v_add_f32_e32 v45, v45, v49
	v_add_f32_e32 v48, v42, v54
	v_add_f32_e32 v49, v43, v55
	v_add_f32_e32 v42, v40, v52
	v_add_f32_e32 v43, v41, v53
	v_mul_f32_e32 v40, v45, v45
	v_mul_f32_e32 v41, v47, v47
	v_fmac_f32_e32 v40, v44, v44
	v_fmac_f32_e32 v41, v46, v46
	v_add_f32_e32 v40, v40, v41
	v_mul_f32_e32 v41, v43, v43
	v_mul_f32_e32 v50, v49, v49
	v_fmac_f32_e32 v41, v42, v42
	v_fmac_f32_e32 v50, v48, v48
	v_add_f32_e32 v41, v41, v50
	v_add_f32_e32 v52, v40, v41
	v_cvt_pk_bf16_f32 v40, v44, v45
	v_cvt_pk_bf16_f32 v41, v46, v47
	s_waitcnt vmcnt(6)
	v_lshlrev_b32_e32 v44, 16, v80
	v_and_b32_e32 v45, 0xffff0000, v80
	v_lshlrev_b32_e32 v46, 16, v81
	v_and_b32_e32 v47, 0xffff0000, v81
	v_cvt_pk_bf16_f32 v42, v42, v43
	v_cvt_pk_bf16_f32 v43, v48, v49
	v_lshlrev_b32_e32 v48, 16, v82
	v_and_b32_e32 v49, 0xffff0000, v82
	v_add_f32_e32 v38, v38, v46
	v_add_f32_e32 v39, v39, v47
	v_add_f32_e32 v36, v36, v44
	v_add_f32_e32 v37, v37, v45
	v_lshlrev_b32_e32 v50, 16, v83
	v_and_b32_e32 v51, 0xffff0000, v83
	v_add_f32_e32 v46, v32, v48
	v_add_f32_e32 v47, v33, v49
	v_mul_f32_e32 v32, v37, v37
	v_mul_f32_e32 v33, v39, v39
	v_add_f32_e32 v44, v34, v50
	v_add_f32_e32 v45, v35, v51
	v_fmac_f32_e32 v32, v36, v36
	v_fmac_f32_e32 v33, v38, v38
	v_add_f32_e32 v32, v32, v33
	v_mul_f32_e32 v33, v47, v47
	v_mul_f32_e32 v34, v45, v45
	v_fmac_f32_e32 v33, v46, v46
	v_fmac_f32_e32 v34, v44, v44
	v_add_f32_e32 v33, v33, v34
	v_add_f32_e32 v32, v32, v33
	v_add_f32_e32 v35, v52, v32
	ds_bpermute_b32 v50, v193, v35
	v_lshl_add_u64 v[32:33], s[16:17], 0, v[98:99]
	v_lshl_add_u64 v[48:49], v[168:169], 1, v[32:33]
	global_store_dwordx4 v[48:49], v[40:43], off
	v_cvt_pk_bf16_f32 v34, v36, v37
	s_waitcnt lgkmcnt(0)
	v_add_f32_e32 v32, v35, v50
	ds_bpermute_b32 v33, v112, v32
	v_cvt_pk_bf16_f32 v35, v38, v39
	v_cvt_pk_bf16_f32 v36, v46, v47
	v_cvt_pk_bf16_f32 v37, v44, v45
	global_store_dwordx4 v[48:49], v[34:37], off offset:256
	s_and_saveexec_b64 s[4:5], s[6:7]
	s_cbranch_execz .LBB0_416
	v_lshlrev_b64 v[34:35], 6, v[96:97]
	v_lshl_add_u64 v[34:35], s[22:23], 0, v[34:35]
	v_lshl_add_u64 v[34:35], s[40:41], 2, v[34:35]
	s_lshl_b32 s10, s51, 2
	v_lshl_add_u64 v[34:35], v[34:35], 0, s[10:11]
	s_waitcnt lgkmcnt(0)
	v_add_f32_e32 v32, v32, v33
	global_store_dword v[34:35], v32, off
.LBB0_416:
	s_or_b64 exec, exec, s[4:5]
	s_waitcnt vmcnt(7)
	v_lshlrev_b32_e32 v32, 16, v76
	s_waitcnt lgkmcnt(0)
	v_and_b32_e32 v33, 0xffff0000, v76
	v_lshlrev_b32_e32 v34, 16, v77
	v_and_b32_e32 v35, 0xffff0000, v77
	v_lshlrev_b32_e32 v36, 16, v78
	v_and_b32_e32 v37, 0xffff0000, v78
	v_lshlrev_b32_e32 v38, 16, v79
	v_and_b32_e32 v39, 0xffff0000, v79
	v_add_f32_e32 v30, v30, v34
	v_add_f32_e32 v31, v31, v35
	v_add_f32_e32 v28, v28, v32
	v_add_f32_e32 v29, v29, v33
	v_add_f32_e32 v32, v26, v38
	v_add_f32_e32 v33, v27, v39
	v_add_f32_e32 v26, v24, v36
	v_add_f32_e32 v27, v25, v37
	v_mul_f32_e32 v24, v29, v29
	v_mul_f32_e32 v25, v31, v31
	v_fmac_f32_e32 v24, v28, v28
	v_fmac_f32_e32 v25, v30, v30
	v_add_f32_e32 v24, v24, v25
	v_mul_f32_e32 v25, v27, v27
	v_mul_f32_e32 v34, v33, v33
	v_fmac_f32_e32 v25, v26, v26
	v_fmac_f32_e32 v34, v32, v32
	v_add_f32_e32 v25, v25, v34
	v_add_f32_e32 v36, v24, v25
	v_cvt_pk_bf16_f32 v24, v28, v29
	v_cvt_pk_bf16_f32 v25, v30, v31
	s_waitcnt vmcnt(6)
	v_lshlrev_b32_e32 v28, 16, v72
	v_and_b32_e32 v29, 0xffff0000, v72
	v_lshlrev_b32_e32 v30, 16, v73
	v_and_b32_e32 v31, 0xffff0000, v73
	v_cvt_pk_bf16_f32 v26, v26, v27
	v_cvt_pk_bf16_f32 v27, v32, v33
	v_lshlrev_b32_e32 v32, 16, v74
	v_and_b32_e32 v33, 0xffff0000, v74
	v_add_f32_e32 v22, v22, v30
	v_add_f32_e32 v23, v23, v31
	v_add_f32_e32 v20, v20, v28
	v_add_f32_e32 v21, v21, v29
	v_lshlrev_b32_e32 v34, 16, v75
	v_and_b32_e32 v35, 0xffff0000, v75
	v_add_f32_e32 v30, v16, v32
	v_add_f32_e32 v31, v17, v33
	v_mul_f32_e32 v16, v21, v21
	v_mul_f32_e32 v17, v23, v23
	v_add_f32_e32 v28, v18, v34
	v_add_f32_e32 v29, v19, v35
	v_fmac_f32_e32 v16, v20, v20
	v_fmac_f32_e32 v17, v22, v22
	v_add_f32_e32 v16, v16, v17
	v_mul_f32_e32 v17, v31, v31
	v_mul_f32_e32 v18, v29, v29
	v_fmac_f32_e32 v17, v30, v30
	v_fmac_f32_e32 v18, v28, v28
	v_add_f32_e32 v17, v17, v18
	v_add_f32_e32 v16, v16, v17
	v_add_f32_e32 v19, v36, v16
	ds_bpermute_b32 v34, v193, v19
	v_lshl_add_u64 v[16:17], s[16:17], 0, v[94:95]
	v_lshl_add_u64 v[32:33], v[168:169], 1, v[16:17]
	global_store_dwordx4 v[32:33], v[24:27], off
	v_cvt_pk_bf16_f32 v18, v20, v21
	s_waitcnt lgkmcnt(0)
	v_add_f32_e32 v16, v19, v34
	ds_bpermute_b32 v17, v112, v16
	v_cvt_pk_bf16_f32 v19, v22, v23
	v_cvt_pk_bf16_f32 v20, v30, v31
	v_cvt_pk_bf16_f32 v21, v28, v29
	global_store_dwordx4 v[32:33], v[18:21], off offset:256
	s_and_saveexec_b64 s[4:5], s[6:7]
	s_cbranch_execz .LBB0_418
	v_lshlrev_b64 v[18:19], 6, v[92:93]
	v_lshl_add_u64 v[18:19], s[22:23], 0, v[18:19]
	v_lshl_add_u64 v[18:19], s[40:41], 2, v[18:19]
	s_lshl_b32 s10, s51, 2
	v_lshl_add_u64 v[18:19], v[18:19], 0, s[10:11]
	s_waitcnt lgkmcnt(0)
	v_add_f32_e32 v16, v16, v17
	global_store_dword v[18:19], v16, off
.LBB0_418:
	s_or_b64 exec, exec, s[4:5]
	s_waitcnt vmcnt(7)
	v_lshlrev_b32_e32 v16, 16, v68
	s_waitcnt lgkmcnt(0)
	v_and_b32_e32 v17, 0xffff0000, v68
	v_lshlrev_b32_e32 v18, 16, v69
	v_and_b32_e32 v19, 0xffff0000, v69
	v_lshlrev_b32_e32 v20, 16, v70
	v_and_b32_e32 v21, 0xffff0000, v70
	v_lshlrev_b32_e32 v22, 16, v71
	v_and_b32_e32 v23, 0xffff0000, v71
	v_add_f32_e32 v14, v14, v18
	v_add_f32_e32 v15, v15, v19
	v_add_f32_e32 v12, v12, v16
	v_add_f32_e32 v13, v13, v17
	v_add_f32_e32 v16, v10, v22
	v_add_f32_e32 v17, v11, v23
	v_add_f32_e32 v10, v8, v20
	v_add_f32_e32 v11, v9, v21
	v_mul_f32_e32 v8, v13, v13
	v_mul_f32_e32 v9, v15, v15
	v_fmac_f32_e32 v8, v12, v12
	v_fmac_f32_e32 v9, v14, v14
	v_add_f32_e32 v8, v8, v9
	v_mul_f32_e32 v9, v11, v11
	v_mul_f32_e32 v18, v17, v17
	v_fmac_f32_e32 v9, v10, v10
	v_fmac_f32_e32 v18, v16, v16
	v_add_f32_e32 v9, v9, v18
	v_add_f32_e32 v20, v8, v9
	v_cvt_pk_bf16_f32 v8, v12, v13
	v_cvt_pk_bf16_f32 v9, v14, v15
	s_waitcnt vmcnt(6)
	v_lshlrev_b32_e32 v12, 16, v64
	v_and_b32_e32 v13, 0xffff0000, v64
	v_lshlrev_b32_e32 v14, 16, v65
	v_and_b32_e32 v15, 0xffff0000, v65
	v_cvt_pk_bf16_f32 v10, v10, v11
	v_cvt_pk_bf16_f32 v11, v16, v17
	v_lshlrev_b32_e32 v16, 16, v66
	v_and_b32_e32 v17, 0xffff0000, v66
	v_add_f32_e32 v6, v6, v14
	v_add_f32_e32 v7, v7, v15
	v_add_f32_e32 v4, v4, v12
	v_add_f32_e32 v5, v5, v13
	v_lshlrev_b32_e32 v18, 16, v67
	v_and_b32_e32 v19, 0xffff0000, v67
	v_add_f32_e32 v14, v0, v16
	v_add_f32_e32 v15, v1, v17
	v_mul_f32_e32 v0, v5, v5
	v_mul_f32_e32 v1, v7, v7
	v_add_f32_e32 v12, v2, v18
	v_add_f32_e32 v13, v3, v19
	v_fmac_f32_e32 v0, v4, v4
	v_fmac_f32_e32 v1, v6, v6
	v_add_f32_e32 v0, v0, v1
	v_mul_f32_e32 v1, v15, v15
	v_mul_f32_e32 v2, v13, v13
	v_fmac_f32_e32 v1, v14, v14
	v_fmac_f32_e32 v2, v12, v12
	v_add_f32_e32 v1, v1, v2
	v_add_f32_e32 v0, v0, v1
	v_add_f32_e32 v3, v20, v0
	ds_bpermute_b32 v18, v193, v3
	v_lshl_add_u64 v[0:1], s[16:17], 0, v[90:91]
	v_lshl_add_u64 v[16:17], v[168:169], 1, v[0:1]
	global_store_dwordx4 v[16:17], v[8:11], off
	v_cvt_pk_bf16_f32 v2, v4, v5
	s_waitcnt lgkmcnt(0)
	v_add_f32_e32 v0, v3, v18
	ds_bpermute_b32 v1, v112, v0
	v_cvt_pk_bf16_f32 v3, v6, v7
	v_cvt_pk_bf16_f32 v4, v14, v15
	v_cvt_pk_bf16_f32 v5, v12, v13
	global_store_dwordx4 v[16:17], v[2:5], off offset:256
	s_and_saveexec_b64 s[4:5], s[6:7]
	s_cbranch_execz .LBB0_420
	v_lshlrev_b64 v[2:3], 6, v[88:89]
	v_lshl_add_u64 v[2:3], s[22:23], 0, v[2:3]
	v_lshl_add_u64 v[2:3], s[40:41], 2, v[2:3]
	s_lshl_b32 s10, s51, 2
	v_lshl_add_u64 v[2:3], v[2:3], 0, s[10:11]
	s_waitcnt lgkmcnt(0)
	v_add_f32_e32 v0, v0, v1
	global_store_dword v[2:3], v0, off

.LBB0_486:
	v_lshl_add_u32 v162, s8, 8, v159
	s_mov_b64 s[60:61], 0x2000
	v_lshlrev_b32_e32 v204, 6, v162
	v_mov_b32_e32 v205, 0
	v_mbcnt_lo_u32_b32 v248, -1, 0
	v_mbcnt_hi_u32_b32 v248, -1, v248
	v_xor_b32_e32 v248, 16, v248
	v_lshl_add_u64 v[204:205], v[136:137], 0, v[204:205]
	v_lshlrev_b32_e32 v248, 2, v248
	v_lshl_add_u64 v[206:207], v[204:205], 0, s[60:61]
	global_load_dwordx4 v[208:211], v[204:205], off
	global_load_dwordx4 v[212:215], v[204:205], off offset:1024
	global_load_dwordx4 v[216:219], v[204:205], off offset:2048
	global_load_dwordx4 v[220:223], v[204:205], off offset:3072
	global_load_dwordx4 v[224:227], v[206:207], off
	global_load_dwordx4 v[228:231], v[206:207], off offset:1024
	global_load_dwordx4 v[232:235], v[206:207], off offset:2048
	global_load_dwordx4 v[236:239], v[206:207], off offset:3072
	s_waitcnt vmcnt(0)
	v_add_f32_e32 v208, v208, v209
	v_add_f32_e32 v210, v210, v211
	v_add_f32_e32 v212, v212, v213
	v_add_f32_e32 v214, v214, v215
	v_add_f32_e32 v216, v216, v217
	v_add_f32_e32 v218, v218, v219
	v_add_f32_e32 v220, v220, v221
	v_add_f32_e32 v222, v222, v223
	v_add_f32_e32 v224, v224, v225
	v_add_f32_e32 v226, v226, v227
	v_add_f32_e32 v228, v228, v229
	v_add_f32_e32 v230, v230, v231
	v_add_f32_e32 v232, v232, v233
	v_add_f32_e32 v234, v234, v235
	v_add_f32_e32 v236, v236, v237
	v_add_f32_e32 v238, v238, v239
	v_add_f32_e32 v208, v208, v210
	v_add_f32_e32 v212, v212, v214
	v_add_f32_e32 v216, v216, v218
	v_add_f32_e32 v220, v220, v222
	v_add_f32_e32 v224, v224, v226
	v_add_f32_e32 v228, v228, v230
	v_add_f32_e32 v232, v232, v234
	v_add_f32_e32 v236, v236, v238
	ds_bpermute_b32 v209, v248, v208
	ds_bpermute_b32 v213, v248, v212
	ds_bpermute_b32 v217, v248, v216
	ds_bpermute_b32 v221, v248, v220
	ds_bpermute_b32 v225, v248, v224
	ds_bpermute_b32 v229, v248, v228
	ds_bpermute_b32 v233, v248, v232
	ds_bpermute_b32 v237, v248, v236
	s_waitcnt lgkmcnt(0)
	v_add_f32_e32 v208, v208, v209
	v_add_f32_e32 v212, v212, v213
	v_add_f32_e32 v216, v216, v217
	v_add_f32_e32 v220, v220, v221
	v_add_f32_e32 v224, v224, v225
	v_add_f32_e32 v228, v228, v229
	v_add_f32_e32 v232, v232, v233
	v_add_f32_e32 v236, v236, v237
	v_mov_b32_e32 v209, v208
	v_mov_b32_e32 v213, v212
	v_mov_b32_e32 v217, v216
	v_mov_b32_e32 v221, v220
	v_mov_b32_e32 v225, v224
	v_mov_b32_e32 v229, v228
	v_mov_b32_e32 v233, v232
	v_mov_b32_e32 v237, v236
	s_nop 1
	v_permlane32_swap_b32_e32 v208, v209
	v_permlane32_swap_b32_e32 v212, v213
	v_permlane32_swap_b32_e32 v216, v217
	v_permlane32_swap_b32_e32 v220, v221
	v_permlane32_swap_b32_e32 v224, v225
	v_permlane32_swap_b32_e32 v228, v229
	v_permlane32_swap_b32_e32 v232, v233
	v_permlane32_swap_b32_e32 v236, v237
	v_add_f32_e32 v208, v208, v209
	v_add_f32_e32 v212, v212, v213
	v_add_f32_e32 v216, v216, v217
	v_add_f32_e32 v220, v220, v221
	v_add_f32_e32 v224, v224, v225
	v_add_f32_e32 v228, v228, v229
	v_add_f32_e32 v232, v232, v233
	v_add_f32_e32 v236, v236, v237
	v_fmamk_f32 v208, v208, 0x3a800000, v177
	v_fmamk_f32 v212, v212, 0x3a800000, v177
	v_fmamk_f32 v216, v216, 0x3a800000, v177
	v_fmamk_f32 v220, v220, 0x3a800000, v177
	v_fmamk_f32 v224, v224, 0x3a800000, v177
	v_fmamk_f32 v228, v228, 0x3a800000, v177
	v_fmamk_f32 v232, v232, 0x3a800000, v177
	v_fmamk_f32 v236, v236, 0x3a800000, v177
	v_rsq_f32_e32 v176, v208
	v_rsq_f32_e32 v174, v212
	v_rsq_f32_e32 v172, v216
	v_rsq_f32_e32 v170, v220
	v_rsq_f32_e32 v168, v224
	v_rsq_f32_e32 v166, v228
	v_rsq_f32_e32 v164, v232
	v_rsq_f32_e32 v158, v236
	s_nop 0
	v_or_b32_e32 v160, 16, v162
	v_or_b32_e32 v156, 32, v162
	v_or_b32_e32 v154, 48, v162
	v_add_u32_e32 v148, 0x80, v162
	s_waitcnt vmcnt(0)
	s_waitcnt lgkmcnt(2)
	s_waitcnt lgkmcnt(2)
	s_waitcnt lgkmcnt(1)
	s_waitcnt lgkmcnt(2)
	s_waitcnt lgkmcnt(1)
	s_waitcnt lgkmcnt(0)
	s_nop 0
	s_nop 0
	v_add_u32_e32 v152, 0x90, v162
	s_waitcnt lgkmcnt(0)
	s_waitcnt lgkmcnt(0)
	s_waitcnt vmcnt(0)
	v_add_u32_e32 v150, 0xa0, v162
	s_waitcnt lgkmcnt(0)
	s_waitcnt lgkmcnt(0)
	s_nop 0
	s_nop 1
	v_add_u32_e32 v146, 0xb0, v162
	s_waitcnt lgkmcnt(0)
	s_waitcnt lgkmcnt(0)
	s_waitcnt vmcnt(1)
	s_waitcnt lgkmcnt(0)
	s_waitcnt lgkmcnt(0)
	s_waitcnt vmcnt(0)
	v_mov_b32_e32 v180, v120
	s_waitcnt lgkmcnt(0)
	s_waitcnt lgkmcnt(0)
	v_mov_b32_e32 v181, v124
	v_mul_f32_e32 v180, v180, v176
	v_mul_f32_e32 v181, v181, v176
	v_mov_b32_e32 v124, v121
	v_mul_f32_e32 v120, 0xbfb8aa3b, v181
	v_exp_f32_e32 v147, v120
	v_mul_f32_e32 v120, v124, v176
	v_mul_f32_e32 v121, v125, v176
	s_andn2_b64 vcc, exec, s[6:7]
	v_mul_f32_e32 v124, 0xbfb8aa3b, v121
	v_exp_f32_e32 v125, v124
	v_add_f32_e32 v147, 1.0, v147
	v_rcp_f32_e32 v147, v147
	v_lshl_or_b32 v124, s33, 7, v167
	v_add_f32_e32 v125, 1.0, v125
	v_rcp_f32_e32 v149, v125
	v_mul_f32_e32 v147, v181, v147
	v_mul_f32_e32 v147, v180, v147
	v_mov_b32_e32 v180, v122
	v_mov_b32_e32 v181, v126
	v_mul_f32_e32 v180, v180, v176
	v_mul_f32_e32 v181, v181, v176
	v_mov_b32_e32 v126, v123
	v_mul_f32_e32 v122, 0xbfb8aa3b, v181
	v_mul_f32_e32 v121, v121, v149
	v_exp_f32_e32 v149, v122
	v_mul_f32_e32 v122, v126, v176
	v_mul_f32_e32 v123, v127, v176
	v_mul_f32_e32 v127, v120, v121
	v_mul_f32_e32 v126, 0xbfb8aa3b, v123
	v_exp_f32_e32 v126, v126
	v_add_f32_e32 v120, 1.0, v149
	v_rcp_f32_e32 v149, v120
	v_mov_b32_e32 v121, v116
	v_add_f32_e32 v120, 1.0, v126
	v_rcp_f32_e32 v126, v120
	v_mov_b32_e32 v120, v112
	v_mul_f32_e32 v120, v120, v176
	v_mul_f32_e32 v121, v121, v176
	v_mul_f32_e32 v116, v181, v149
	v_mul_f32_e32 v112, 0xbfb8aa3b, v121
	v_exp_f32_e32 v112, v112
	v_mul_f32_e32 v149, v180, v116
	v_mov_b32_e32 v116, v113
	v_mul_f32_e32 v123, v123, v126
	v_add_f32_e32 v112, 1.0, v112
	v_rcp_f32_e32 v126, v112
	v_mul_f32_e32 v112, v116, v176
	v_mul_f32_e32 v113, v117, v176
	v_mul_f32_e32 v122, v122, v123
	v_mul_f32_e32 v116, 0xbfb8aa3b, v113
	v_exp_f32_e32 v116, v116
	v_mul_f32_e32 v117, v121, v126
	v_mul_f32_e32 v120, v120, v117
	v_mov_b32_e32 v117, v118
	v_add_f32_e32 v116, 1.0, v116
	v_rcp_f32_e32 v121, v116
	v_mov_b32_e32 v116, v114
	v_mul_f32_e32 v116, v116, v176
	v_mul_f32_e32 v117, v117, v176
	v_mov_b32_e32 v118, v115
	v_mul_f32_e32 v114, 0xbfb8aa3b, v117
	v_exp_f32_e32 v123, v114
	v_mul_f32_e32 v114, v118, v176
	v_mul_f32_e32 v115, v119, v176
	v_mul_f32_e32 v113, v113, v121
	v_mul_f32_e32 v118, 0xbfb8aa3b, v115
	v_exp_f32_e32 v118, v118
	v_add_f32_e32 v119, 1.0, v123
	v_rcp_f32_e32 v119, v119
	v_mul_f32_e32 v112, v112, v113
	v_add_f32_e32 v118, 1.0, v118
	v_rcp_f32_e32 v118, v118
	v_mul_f32_e32 v113, v117, v119
	v_mul_f32_e32 v113, v116, v113
	v_cvt_pk_bf16_f32 v116, v147, v127
	v_cvt_pk_bf16_f32 v117, v149, v122
	v_mov_b32_e32 v122, v104
	v_mov_b32_e32 v123, v108
	v_mul_f32_e32 v115, v115, v118
	v_mul_f32_e32 v122, v122, v174
	v_mul_f32_e32 v123, v123, v174
	v_ashrrev_i32_e32 v125, 31, v124
	v_mul_f32_e32 v114, v114, v115
	v_mul_f32_e32 v104, 0xbfb8aa3b, v123
	v_cvt_pk_bf16_f32 v118, v120, v112
	v_cvt_pk_bf16_f32 v119, v113, v114
	v_lshlrev_b64 v[114:115], 1, v[124:125]
	v_exp_f32_e32 v124, v104
	v_mov_b32_e32 v108, v105
	v_mov_b64_e32 v[112:113], s[26:27]
	v_mul_f32_e32 v104, v108, v174
	v_mul_f32_e32 v105, v109, v174
	v_mad_i64_i32 v[120:121], s[4:5], v162, s52, v[112:113]
	v_mul_f32_e32 v108, 0xbfb8aa3b, v105
	v_exp_f32_e32 v125, v108
	v_lshl_add_u64 v[108:109], v[120:121], 0, v[114:115]
	v_add_f32_e32 v120, 1.0, v124
	v_rcp_f32_e32 v120, v120
	global_store_dwordx4 v[108:109], v[116:119], off
	v_mov_b32_e32 v109, v110
	v_add_f32_e32 v121, 1.0, v125
	v_mul_f32_e32 v108, v123, v120
	v_mul_f32_e32 v116, v122, v108
	v_mov_b32_e32 v108, v106
	v_mul_f32_e32 v108, v108, v174
	v_mul_f32_e32 v109, v109, v174
	v_mov_b32_e32 v110, v107
	v_mul_f32_e32 v106, 0xbfb8aa3b, v109
	v_rcp_f32_e32 v121, v121
	v_exp_f32_e32 v117, v106
	v_mul_f32_e32 v106, v110, v174
	v_mul_f32_e32 v107, v111, v174
	v_mul_f32_e32 v105, v105, v121
	v_mul_f32_e32 v110, 0xbfb8aa3b, v107
	v_exp_f32_e32 v110, v110
	v_mul_f32_e32 v111, v104, v105
	v_add_f32_e32 v104, 1.0, v117
	v_rcp_f32_e32 v117, v104
	v_add_f32_e32 v104, 1.0, v110
	v_rcp_f32_e32 v110, v104
	v_mov_b32_e32 v104, v96
	v_mov_b32_e32 v105, v100
	v_mul_f32_e32 v104, v104, v174
	v_mul_f32_e32 v105, v105, v174
	v_mul_f32_e32 v100, v109, v117
	v_mul_f32_e32 v96, 0xbfb8aa3b, v105
	v_exp_f32_e32 v96, v96
	v_mul_f32_e32 v108, v108, v100
	v_mov_b32_e32 v100, v97
	v_mul_f32_e32 v107, v107, v110
	v_add_f32_e32 v96, 1.0, v96
	v_rcp_f32_e32 v109, v96
	v_mul_f32_e32 v96, v100, v174
	v_mul_f32_e32 v97, v101, v174
	v_mul_f32_e32 v106, v106, v107
	v_mul_f32_e32 v100, 0xbfb8aa3b, v97
	v_exp_f32_e32 v100, v100
	v_mul_f32_e32 v101, v105, v109
	v_mul_f32_e32 v104, v104, v101
	v_mov_b32_e32 v101, v102
	v_add_f32_e32 v100, 1.0, v100
	v_rcp_f32_e32 v105, v100
	v_mov_b32_e32 v100, v98
	v_mul_f32_e32 v100, v100, v174
	v_mul_f32_e32 v101, v101, v174
	v_mov_b32_e32 v102, v99
	v_mul_f32_e32 v98, 0xbfb8aa3b, v101
	v_exp_f32_e32 v107, v98
	v_mul_f32_e32 v98, v102, v174
	v_mul_f32_e32 v99, v103, v174
	v_mul_f32_e32 v97, v97, v105
	v_mul_f32_e32 v102, 0xbfb8aa3b, v99
	v_exp_f32_e32 v102, v102
	v_add_f32_e32 v103, 1.0, v107
	v_rcp_f32_e32 v103, v103
	v_mul_f32_e32 v105, v96, v97
	v_add_f32_e32 v102, 1.0, v102
	v_rcp_f32_e32 v102, v102
	v_mul_f32_e32 v96, v101, v103
	v_mul_f32_e32 v100, v100, v96
	v_mov_b32_e32 v103, v92
	v_mul_f32_e32 v96, v99, v102
	v_mov_b32_e32 v102, v88
	v_mul_f32_e32 v102, v102, v172
	v_mul_f32_e32 v103, v103, v172
	v_mul_f32_e32 v99, v98, v96
	v_mul_f32_e32 v88, 0xbfb8aa3b, v103
	v_cvt_pk_bf16_f32 v96, v116, v111
	v_cvt_pk_bf16_f32 v97, v108, v106
	v_cvt_pk_bf16_f32 v98, v104, v105
	v_exp_f32_e32 v104, v88
	v_mov_b32_e32 v92, v89
	v_mul_f32_e32 v88, v92, v172
	v_mul_f32_e32 v89, v93, v172
	v_cvt_pk_bf16_f32 v99, v100, v99
	v_mad_i64_i32 v[100:101], s[4:5], v160, s52, v[112:113]
	v_mul_f32_e32 v92, 0xbfb8aa3b, v89
	v_exp_f32_e32 v105, v92
	v_lshl_add_u64 v[92:93], v[100:101], 0, v[114:115]
	v_add_f32_e32 v100, 1.0, v104
	v_rcp_f32_e32 v100, v100
	global_store_dwordx4 v[92:93], v[96:99], off
	v_mov_b32_e32 v93, v94
	v_add_f32_e32 v101, 1.0, v105
	v_mul_f32_e32 v92, v103, v100
	v_mul_f32_e32 v96, v102, v92
	v_mov_b32_e32 v92, v90
	v_mul_f32_e32 v92, v92, v172
	v_mul_f32_e32 v93, v93, v172
	v_mov_b32_e32 v94, v91
	v_mul_f32_e32 v90, 0xbfb8aa3b, v93
	v_rcp_f32_e32 v101, v101
	v_exp_f32_e32 v97, v90
	v_mul_f32_e32 v90, v94, v172
	v_mul_f32_e32 v91, v95, v172
	v_mul_f32_e32 v89, v89, v101
	v_mul_f32_e32 v94, 0xbfb8aa3b, v91
	v_exp_f32_e32 v94, v94
	v_mul_f32_e32 v95, v88, v89
	v_add_f32_e32 v88, 1.0, v97
	v_rcp_f32_e32 v97, v88
	v_add_f32_e32 v88, 1.0, v94
	v_rcp_f32_e32 v94, v88
	v_mov_b32_e32 v88, v80
	v_mov_b32_e32 v89, v84
	v_mul_f32_e32 v88, v88, v172
	v_mul_f32_e32 v89, v89, v172
	v_mul_f32_e32 v84, v93, v97
	v_mul_f32_e32 v80, 0xbfb8aa3b, v89
	v_exp_f32_e32 v80, v80
	v_mul_f32_e32 v92, v92, v84
	v_mov_b32_e32 v84, v81
	v_mul_f32_e32 v91, v91, v94
	v_add_f32_e32 v80, 1.0, v80
	v_rcp_f32_e32 v93, v80
	v_mul_f32_e32 v80, v84, v172
	v_mul_f32_e32 v81, v85, v172
	v_mul_f32_e32 v90, v90, v91
	v_mul_f32_e32 v84, 0xbfb8aa3b, v81
	v_exp_f32_e32 v84, v84
	v_mul_f32_e32 v85, v89, v93
	v_mul_f32_e32 v88, v88, v85
	v_mov_b32_e32 v85, v86
	v_add_f32_e32 v84, 1.0, v84
	v_rcp_f32_e32 v89, v84
	v_mov_b32_e32 v84, v82
	v_mul_f32_e32 v84, v84, v172
	v_mul_f32_e32 v85, v85, v172
	v_mov_b32_e32 v86, v83
	v_mul_f32_e32 v82, 0xbfb8aa3b, v85
	v_exp_f32_e32 v91, v82
	v_mul_f32_e32 v82, v86, v172
	v_mul_f32_e32 v83, v87, v172
	v_mul_f32_e32 v81, v81, v89
	v_mul_f32_e32 v86, 0xbfb8aa3b, v83
	v_exp_f32_e32 v86, v86
	v_add_f32_e32 v87, 1.0, v91
	v_rcp_f32_e32 v87, v87
	v_mul_f32_e32 v89, v80, v81
	v_add_f32_e32 v86, 1.0, v86
	v_rcp_f32_e32 v86, v86
	v_mul_f32_e32 v80, v85, v87
	v_mul_f32_e32 v84, v84, v80
	v_mov_b32_e32 v87, v76
	v_mul_f32_e32 v80, v83, v86
	v_mov_b32_e32 v86, v72
	v_mul_f32_e32 v86, v86, v170
	v_mul_f32_e32 v87, v87, v170
	v_mul_f32_e32 v83, v82, v80
	v_mul_f32_e32 v72, 0xbfb8aa3b, v87
	v_cvt_pk_bf16_f32 v80, v96, v95
	v_cvt_pk_bf16_f32 v81, v92, v90
	v_cvt_pk_bf16_f32 v82, v88, v89
	v_exp_f32_e32 v88, v72
	v_mov_b32_e32 v76, v73
	v_mul_f32_e32 v72, v76, v170
	v_mul_f32_e32 v73, v77, v170
	v_cvt_pk_bf16_f32 v83, v84, v83
	v_mad_i64_i32 v[84:85], s[4:5], v156, s52, v[112:113]
	v_mul_f32_e32 v76, 0xbfb8aa3b, v73
	v_exp_f32_e32 v89, v76
	v_lshl_add_u64 v[76:77], v[84:85], 0, v[114:115]
	v_add_f32_e32 v84, 1.0, v88
	v_rcp_f32_e32 v84, v84
	global_store_dwordx4 v[76:77], v[80:83], off
	v_mov_b32_e32 v77, v78
	v_add_f32_e32 v85, 1.0, v89
	v_mul_f32_e32 v76, v87, v84
	v_mul_f32_e32 v80, v86, v76
	v_mov_b32_e32 v76, v74
	v_mul_f32_e32 v76, v76, v170
	v_mul_f32_e32 v77, v77, v170
	v_mov_b32_e32 v78, v75
	v_mul_f32_e32 v74, 0xbfb8aa3b, v77
	v_rcp_f32_e32 v85, v85
	v_exp_f32_e32 v81, v74
	v_mul_f32_e32 v74, v78, v170
	v_mul_f32_e32 v75, v79, v170
	v_mul_f32_e32 v73, v73, v85
	v_mul_f32_e32 v78, 0xbfb8aa3b, v75
	v_exp_f32_e32 v78, v78
	v_mul_f32_e32 v79, v72, v73
	v_add_f32_e32 v72, 1.0, v81
	v_rcp_f32_e32 v81, v72
	v_add_f32_e32 v72, 1.0, v78
	v_rcp_f32_e32 v78, v72
	v_mov_b32_e32 v72, v64
	v_mov_b32_e32 v73, v68
	v_mul_f32_e32 v72, v72, v170
	v_mul_f32_e32 v73, v73, v170
	v_mul_f32_e32 v68, v77, v81
	v_mul_f32_e32 v64, 0xbfb8aa3b, v73
	v_exp_f32_e32 v64, v64
	v_mul_f32_e32 v76, v76, v68
	v_mov_b32_e32 v68, v65
	v_mul_f32_e32 v75, v75, v78
	v_add_f32_e32 v64, 1.0, v64
	v_rcp_f32_e32 v77, v64
	v_mul_f32_e32 v64, v68, v170
	v_mul_f32_e32 v65, v69, v170
	v_mul_f32_e32 v74, v74, v75
	v_mul_f32_e32 v68, 0xbfb8aa3b, v65
	v_exp_f32_e32 v68, v68
	v_mul_f32_e32 v69, v73, v77
	v_mul_f32_e32 v72, v72, v69
	v_mov_b32_e32 v69, v70
	v_add_f32_e32 v68, 1.0, v68
	v_rcp_f32_e32 v73, v68
	v_mov_b32_e32 v68, v66
	v_mul_f32_e32 v68, v68, v170
	v_mul_f32_e32 v69, v69, v170
	v_mov_b32_e32 v70, v67
	v_mul_f32_e32 v66, 0xbfb8aa3b, v69
	v_exp_f32_e32 v75, v66
	v_mul_f32_e32 v66, v70, v170
	v_mul_f32_e32 v67, v71, v170
	v_mul_f32_e32 v65, v65, v73
	v_mul_f32_e32 v70, 0xbfb8aa3b, v67
	v_exp_f32_e32 v70, v70
	v_add_f32_e32 v71, 1.0, v75
	v_rcp_f32_e32 v71, v71
	v_mul_f32_e32 v73, v64, v65
	v_add_f32_e32 v70, 1.0, v70
	v_rcp_f32_e32 v70, v70
	v_mul_f32_e32 v64, v69, v71
	v_mul_f32_e32 v68, v68, v64
	v_mov_b32_e32 v71, v60
	v_mul_f32_e32 v64, v67, v70
	v_mov_b32_e32 v70, v56
	v_mul_f32_e32 v70, v70, v168
	v_mul_f32_e32 v71, v71, v168
	v_mul_f32_e32 v67, v66, v64
	v_mul_f32_e32 v56, 0xbfb8aa3b, v71
	v_cvt_pk_bf16_f32 v64, v80, v79
	v_cvt_pk_bf16_f32 v65, v76, v74
	v_cvt_pk_bf16_f32 v66, v72, v73
	v_exp_f32_e32 v72, v56
	v_mov_b32_e32 v60, v57
	v_mul_f32_e32 v56, v60, v168
	v_mul_f32_e32 v57, v61, v168
	v_cvt_pk_bf16_f32 v67, v68, v67
	v_mad_i64_i32 v[68:69], s[4:5], v154, s52, v[112:113]
	v_mul_f32_e32 v60, 0xbfb8aa3b, v57
	v_exp_f32_e32 v73, v60
	v_lshl_add_u64 v[60:61], v[68:69], 0, v[114:115]
	v_add_f32_e32 v68, 1.0, v72
	v_rcp_f32_e32 v68, v68
	global_store_dwordx4 v[60:61], v[64:67], off
	v_mov_b32_e32 v61, v62
	v_add_f32_e32 v69, 1.0, v73
	v_mul_f32_e32 v60, v71, v68
	v_mul_f32_e32 v64, v70, v60
	v_mov_b32_e32 v60, v58
	v_mul_f32_e32 v60, v60, v168
	v_mul_f32_e32 v61, v61, v168
	v_mov_b32_e32 v62, v59
	v_mul_f32_e32 v58, 0xbfb8aa3b, v61
	v_rcp_f32_e32 v69, v69
	v_exp_f32_e32 v65, v58
	v_mul_f32_e32 v58, v62, v168
	v_mul_f32_e32 v59, v63, v168
	v_mul_f32_e32 v57, v57, v69
	v_mul_f32_e32 v62, 0xbfb8aa3b, v59
	v_exp_f32_e32 v62, v62
	v_mul_f32_e32 v63, v56, v57
	v_add_f32_e32 v56, 1.0, v65
	v_rcp_f32_e32 v65, v56
	v_add_f32_e32 v56, 1.0, v62
	v_rcp_f32_e32 v62, v56
	v_mov_b32_e32 v56, v48
	v_mov_b32_e32 v57, v52
	v_mul_f32_e32 v56, v56, v168
	v_mul_f32_e32 v57, v57, v168
	v_mul_f32_e32 v52, v61, v65
	v_mul_f32_e32 v48, 0xbfb8aa3b, v57
	v_exp_f32_e32 v48, v48
	v_mul_f32_e32 v60, v60, v52
	v_mov_b32_e32 v52, v49
	v_mul_f32_e32 v59, v59, v62
	v_add_f32_e32 v48, 1.0, v48
	v_rcp_f32_e32 v61, v48
	v_mul_f32_e32 v48, v52, v168
	v_mul_f32_e32 v49, v53, v168
	v_mul_f32_e32 v58, v58, v59
	v_mul_f32_e32 v52, 0xbfb8aa3b, v49
	v_exp_f32_e32 v52, v52
	v_mul_f32_e32 v53, v57, v61
	v_mul_f32_e32 v56, v56, v53
	v_mov_b32_e32 v53, v54
	v_add_f32_e32 v52, 1.0, v52
	v_rcp_f32_e32 v57, v52
	v_mov_b32_e32 v52, v50
	v_mul_f32_e32 v52, v52, v168
	v_mul_f32_e32 v53, v53, v168
	v_mov_b32_e32 v54, v51
	v_mul_f32_e32 v50, 0xbfb8aa3b, v53
	v_exp_f32_e32 v59, v50
	v_mul_f32_e32 v50, v54, v168
	v_mul_f32_e32 v51, v55, v168
	v_mul_f32_e32 v49, v49, v57
	v_mul_f32_e32 v54, 0xbfb8aa3b, v51
	v_exp_f32_e32 v54, v54
	v_add_f32_e32 v55, 1.0, v59
	v_rcp_f32_e32 v55, v55
	v_mul_f32_e32 v57, v48, v49
	v_add_f32_e32 v54, 1.0, v54
	v_rcp_f32_e32 v54, v54
	v_mul_f32_e32 v48, v53, v55
	v_mul_f32_e32 v52, v52, v48
	v_mov_b32_e32 v55, v44
	v_mul_f32_e32 v48, v51, v54
	v_mov_b32_e32 v54, v40
	v_mul_f32_e32 v54, v54, v166
	v_mul_f32_e32 v55, v55, v166
	v_mul_f32_e32 v51, v50, v48
	v_mul_f32_e32 v40, 0xbfb8aa3b, v55
	v_cvt_pk_bf16_f32 v48, v64, v63
	v_cvt_pk_bf16_f32 v49, v60, v58
	v_cvt_pk_bf16_f32 v50, v56, v57
	v_exp_f32_e32 v56, v40
	v_mov_b32_e32 v44, v41
	v_mul_f32_e32 v40, v44, v166
	v_mul_f32_e32 v41, v45, v166
	v_cvt_pk_bf16_f32 v51, v52, v51
	v_mad_i64_i32 v[52:53], s[4:5], v148, s52, v[112:113]
	v_mul_f32_e32 v44, 0xbfb8aa3b, v41
	v_exp_f32_e32 v57, v44
	v_lshl_add_u64 v[44:45], v[52:53], 0, v[114:115]
	v_add_f32_e32 v52, 1.0, v56
	v_rcp_f32_e32 v52, v52
	global_store_dwordx4 v[44:45], v[48:51], off
	v_mov_b32_e32 v45, v46
	v_add_f32_e32 v53, 1.0, v57
	v_mul_f32_e32 v44, v55, v52
	v_mul_f32_e32 v48, v54, v44
	v_mov_b32_e32 v44, v42
	v_mul_f32_e32 v44, v44, v166
	v_mul_f32_e32 v45, v45, v166
	v_mov_b32_e32 v46, v43
	v_mul_f32_e32 v42, 0xbfb8aa3b, v45
	v_rcp_f32_e32 v53, v53
	v_exp_f32_e32 v49, v42
	v_mul_f32_e32 v42, v46, v166
	v_mul_f32_e32 v43, v47, v166
	v_mul_f32_e32 v41, v41, v53
	v_mul_f32_e32 v46, 0xbfb8aa3b, v43
	v_exp_f32_e32 v46, v46
	v_mul_f32_e32 v47, v40, v41
	v_add_f32_e32 v40, 1.0, v49
	v_rcp_f32_e32 v49, v40
	v_add_f32_e32 v40, 1.0, v46
	v_rcp_f32_e32 v46, v40
	v_mov_b32_e32 v40, v32
	v_mov_b32_e32 v41, v36
	v_mul_f32_e32 v40, v40, v166
	v_mul_f32_e32 v41, v41, v166
	v_mul_f32_e32 v36, v45, v49
	v_mul_f32_e32 v32, 0xbfb8aa3b, v41
	v_exp_f32_e32 v32, v32
	v_mul_f32_e32 v44, v44, v36
	v_mov_b32_e32 v36, v33
	v_mul_f32_e32 v43, v43, v46
	v_add_f32_e32 v32, 1.0, v32
	v_rcp_f32_e32 v45, v32
	v_mul_f32_e32 v32, v36, v166
	v_mul_f32_e32 v33, v37, v166
	v_mul_f32_e32 v42, v42, v43
	v_mul_f32_e32 v36, 0xbfb8aa3b, v33
	v_exp_f32_e32 v36, v36
	v_mul_f32_e32 v37, v41, v45
	v_mul_f32_e32 v40, v40, v37
	v_mov_b32_e32 v37, v38
	v_add_f32_e32 v36, 1.0, v36
	v_rcp_f32_e32 v41, v36
	v_mov_b32_e32 v36, v34
	v_mul_f32_e32 v36, v36, v166
	v_mul_f32_e32 v37, v37, v166
	v_mov_b32_e32 v38, v35
	v_mul_f32_e32 v34, 0xbfb8aa3b, v37
	v_exp_f32_e32 v43, v34
	v_mul_f32_e32 v34, v38, v166
	v_mul_f32_e32 v35, v39, v166
	v_mul_f32_e32 v33, v33, v41
	v_mul_f32_e32 v38, 0xbfb8aa3b, v35
	v_exp_f32_e32 v38, v38
	v_add_f32_e32 v39, 1.0, v43
	v_rcp_f32_e32 v39, v39
	v_mul_f32_e32 v41, v32, v33
	v_add_f32_e32 v38, 1.0, v38
	v_rcp_f32_e32 v38, v38
	v_mul_f32_e32 v32, v37, v39
	v_mul_f32_e32 v36, v36, v32
	v_mov_b32_e32 v39, v28
	v_mul_f32_e32 v32, v35, v38
	v_mov_b32_e32 v38, v24
	v_mul_f32_e32 v38, v38, v164
	v_mul_f32_e32 v39, v39, v164
	v_mul_f32_e32 v35, v34, v32
	v_mul_f32_e32 v24, 0xbfb8aa3b, v39
	v_cvt_pk_bf16_f32 v32, v48, v47
	v_cvt_pk_bf16_f32 v33, v44, v42
	v_cvt_pk_bf16_f32 v34, v40, v41
	v_exp_f32_e32 v40, v24
	v_mov_b32_e32 v28, v25
	v_mul_f32_e32 v24, v28, v164
	v_mul_f32_e32 v25, v29, v164
	v_cvt_pk_bf16_f32 v35, v36, v35
	v_mad_i64_i32 v[36:37], s[4:5], v152, s52, v[112:113]
	v_mul_f32_e32 v28, 0xbfb8aa3b, v25
	v_exp_f32_e32 v41, v28
	v_lshl_add_u64 v[28:29], v[36:37], 0, v[114:115]
	v_add_f32_e32 v36, 1.0, v40
	v_rcp_f32_e32 v36, v36
	global_store_dwordx4 v[28:29], v[32:35], off
	v_mov_b32_e32 v29, v30
	v_add_f32_e32 v37, 1.0, v41
	v_mul_f32_e32 v28, v39, v36
	v_mul_f32_e32 v32, v38, v28
	v_mov_b32_e32 v28, v26
	v_mul_f32_e32 v28, v28, v164
	v_mul_f32_e32 v29, v29, v164
	v_mov_b32_e32 v30, v27
	v_mul_f32_e32 v26, 0xbfb8aa3b, v29
	v_rcp_f32_e32 v37, v37
	v_exp_f32_e32 v33, v26
	v_mul_f32_e32 v26, v30, v164
	v_mul_f32_e32 v27, v31, v164
	v_mul_f32_e32 v25, v25, v37
	v_mul_f32_e32 v30, 0xbfb8aa3b, v27
	v_exp_f32_e32 v30, v30
	v_mul_f32_e32 v31, v24, v25
	v_add_f32_e32 v24, 1.0, v33
	v_rcp_f32_e32 v33, v24
	v_add_f32_e32 v24, 1.0, v30
	v_rcp_f32_e32 v30, v24
	v_mov_b32_e32 v24, v16
	v_mov_b32_e32 v25, v20
	v_mul_f32_e32 v24, v24, v164
	v_mul_f32_e32 v25, v25, v164
	v_mul_f32_e32 v20, v29, v33
	v_mul_f32_e32 v16, 0xbfb8aa3b, v25
	v_exp_f32_e32 v16, v16
	v_mul_f32_e32 v28, v28, v20
	v_mov_b32_e32 v20, v17
	v_mul_f32_e32 v27, v27, v30
	v_add_f32_e32 v16, 1.0, v16
	v_rcp_f32_e32 v29, v16
	v_mul_f32_e32 v16, v20, v164
	v_mul_f32_e32 v17, v21, v164
	v_mul_f32_e32 v26, v26, v27
	v_mul_f32_e32 v20, 0xbfb8aa3b, v17
	v_exp_f32_e32 v20, v20
	v_mul_f32_e32 v21, v25, v29
	v_mul_f32_e32 v24, v24, v21
	v_mov_b32_e32 v21, v22
	v_add_f32_e32 v20, 1.0, v20
	v_rcp_f32_e32 v25, v20
	v_mov_b32_e32 v20, v18
	v_mul_f32_e32 v20, v20, v164
	v_mul_f32_e32 v21, v21, v164
	v_mov_b32_e32 v22, v19
	v_mul_f32_e32 v18, 0xbfb8aa3b, v21
	v_exp_f32_e32 v27, v18
	v_mul_f32_e32 v18, v22, v164
	v_mul_f32_e32 v19, v23, v164
	v_mul_f32_e32 v17, v17, v25
	v_mul_f32_e32 v22, 0xbfb8aa3b, v19
	v_exp_f32_e32 v22, v22
	v_add_f32_e32 v23, 1.0, v27
	v_rcp_f32_e32 v23, v23
	v_mul_f32_e32 v25, v16, v17
	v_add_f32_e32 v22, 1.0, v22
	v_rcp_f32_e32 v22, v22
	v_mul_f32_e32 v16, v21, v23
	v_mul_f32_e32 v20, v20, v16
	v_mov_b32_e32 v23, v12
	v_mul_f32_e32 v16, v19, v22
	v_mov_b32_e32 v22, v8
	v_mul_f32_e32 v22, v22, v158
	v_mul_f32_e32 v23, v23, v158
	v_mul_f32_e32 v19, v18, v16
	v_mul_f32_e32 v8, 0xbfb8aa3b, v23
	v_cvt_pk_bf16_f32 v16, v32, v31
	v_cvt_pk_bf16_f32 v17, v28, v26
	v_cvt_pk_bf16_f32 v18, v24, v25
	v_exp_f32_e32 v24, v8
	v_mov_b32_e32 v12, v9
	v_mul_f32_e32 v8, v12, v158
	v_mul_f32_e32 v9, v13, v158
	v_cvt_pk_bf16_f32 v19, v20, v19
	v_mad_i64_i32 v[20:21], s[4:5], v150, s52, v[112:113]
	v_mul_f32_e32 v12, 0xbfb8aa3b, v9
	v_exp_f32_e32 v25, v12
	v_lshl_add_u64 v[12:13], v[20:21], 0, v[114:115]
	v_add_f32_e32 v20, 1.0, v24
	v_rcp_f32_e32 v20, v20
	global_store_dwordx4 v[12:13], v[16:19], off
	v_mov_b32_e32 v13, v14
	v_add_f32_e32 v21, 1.0, v25
	v_mul_f32_e32 v12, v23, v20
	v_mul_f32_e32 v16, v22, v12
	v_mov_b32_e32 v12, v10
	v_mul_f32_e32 v12, v12, v158
	v_mul_f32_e32 v13, v13, v158
	v_mov_b32_e32 v14, v11
	v_mul_f32_e32 v10, 0xbfb8aa3b, v13
	v_rcp_f32_e32 v21, v21
	v_exp_f32_e32 v17, v10
	v_mul_f32_e32 v10, v14, v158
	v_mul_f32_e32 v11, v15, v158
	v_mul_f32_e32 v9, v9, v21
	v_mul_f32_e32 v14, 0xbfb8aa3b, v11
	v_exp_f32_e32 v14, v14
	v_mul_f32_e32 v15, v8, v9
	v_add_f32_e32 v8, 1.0, v17
	v_rcp_f32_e32 v17, v8
	v_add_f32_e32 v8, 1.0, v14
	v_rcp_f32_e32 v14, v8
	v_mov_b32_e32 v8, v0
	v_mov_b32_e32 v9, v4
	v_mul_f32_e32 v8, v8, v158
	v_mul_f32_e32 v9, v9, v158
	v_mul_f32_e32 v4, v13, v17
	v_mul_f32_e32 v0, 0xbfb8aa3b, v9
	v_exp_f32_e32 v0, v0
	v_mul_f32_e32 v12, v12, v4
	v_mov_b32_e32 v4, v1
	v_mul_f32_e32 v11, v11, v14
	v_add_f32_e32 v0, 1.0, v0
	v_rcp_f32_e32 v13, v0
	v_mul_f32_e32 v0, v4, v158
	v_mul_f32_e32 v1, v5, v158
	v_mul_f32_e32 v10, v10, v11
	v_mul_f32_e32 v4, 0xbfb8aa3b, v1
	v_exp_f32_e32 v4, v4
	v_mul_f32_e32 v5, v9, v13
	v_mul_f32_e32 v8, v8, v5
	v_mov_b32_e32 v5, v6
	v_add_f32_e32 v4, 1.0, v4
	v_rcp_f32_e32 v9, v4
	v_mov_b32_e32 v4, v2
	v_mul_f32_e32 v4, v4, v158
	v_mul_f32_e32 v5, v5, v158
	v_mov_b32_e32 v6, v3
	v_mul_f32_e32 v2, 0xbfb8aa3b, v5
	v_exp_f32_e32 v11, v2
	v_mul_f32_e32 v2, v6, v158
	v_mul_f32_e32 v3, v7, v158
	v_mul_f32_e32 v1, v1, v9
	v_mul_f32_e32 v6, 0xbfb8aa3b, v3
	v_exp_f32_e32 v6, v6
	v_add_f32_e32 v7, 1.0, v11
	v_rcp_f32_e32 v7, v7
	v_mul_f32_e32 v9, v0, v1
	v_add_f32_e32 v6, 1.0, v6
	v_rcp_f32_e32 v6, v6
	v_mul_f32_e32 v0, v5, v7
	v_mul_f32_e32 v4, v4, v0
	v_mul_f32_e32 v0, v3, v6
	v_mul_f32_e32 v3, v2, v0
	v_cvt_pk_bf16_f32 v0, v16, v15
	v_cvt_pk_bf16_f32 v1, v12, v10
	v_cvt_pk_bf16_f32 v2, v8, v9
	v_cvt_pk_bf16_f32 v3, v4, v3
	v_mad_i64_i32 v[4:5], s[4:5], v146, s52, v[112:113]
	v_lshl_add_u64 v[4:5], v[4:5], 0, v[114:115]
	s_mov_b64 s[4:5], -1
	global_store_dwordx4 v[4:5], v[0:3], off
	s_cbranch_vccnz .LBB0_479
	s_andn2_b64 vcc, exec, s[16:17]
	s_cbranch_vccnz .LBB0_478
	s_barrier
	s_branch .LBB0_478

.LBB0_562:
	v_lshl_or_b32 v168, s12, 8, v188
	v_lshl_add_u32 v172, s54, 8, v186
	v_ashrrev_i32_e32 v169, 31, v168
	v_lshlrev_b64 v[204:205], 1, v[168:169]
	v_ashrrev_i32_e32 v173, 31, v172
	v_lshl_add_u64 v[170:171], s[26:27], 0, v[204:205]
	v_lshlrev_b64 v[206:207], 11, v[172:173]
	v_lshl_add_u64 v[128:129], v[170:171], 0, v[206:207]
	global_load_dwordx4 v[194:197], v[128:129], off
	global_load_dwordx4 v[198:201], v[128:129], off offset:256
	v_or_b32_e32 v182, 16, v172
	v_or_b32_e32 v178, 32, v172
	v_or_b32_e32 v174, 48, v172
	v_ashrrev_i32_e32 v183, 31, v182
	v_ashrrev_i32_e32 v179, 31, v178
	v_ashrrev_i32_e32 v175, 31, v174
	v_lshlrev_b64 v[184:185], 11, v[182:183]
	v_lshlrev_b64 v[180:181], 11, v[178:179]
	v_lshlrev_b64 v[176:177], 11, v[174:175]
	v_lshl_add_u64 v[128:129], v[170:171], 0, v[184:185]
	v_lshl_add_u64 v[130:131], v[170:171], 0, v[180:181]
	v_lshl_add_u64 v[208:209], v[170:171], 0, v[176:177]
	global_load_dwordx4 v[148:151], v[128:129], off
	global_load_dwordx4 v[144:147], v[128:129], off offset:256
	global_load_dwordx4 v[140:143], v[130:131], off
	global_load_dwordx4 v[136:139], v[130:131], off offset:256
	global_load_dwordx4 v[132:135], v[208:209], off
	s_nop 0
	global_load_dwordx4 v[128:131], v[208:209], off offset:256
	v_and_b32_e32 v208, 64, v192
	v_xor_b32_e32 v193, 16, v192
	v_add_u32_e32 v208, 64, v208
	v_xor_b32_e32 v209, 32, v192
	v_cmp_lt_i32_e32 vcc, v193, v208
	v_lshl_add_u64 v[206:207], s[26:27], 0, v[206:207]
	v_lshl_add_u64 v[204:205], v[206:207], 0, v[204:205]
	v_cndmask_b32_e32 v193, v192, v193, vcc
	v_cmp_lt_i32_e32 vcc, v209, v208
	v_lshlrev_b32_e32 v193, 2, v193
	s_lshl_b32 s38, s12, 2
	v_cndmask_b32_e32 v214, v192, v209, vcc
	s_ashr_i32 s39, s38, 31
	s_waitcnt vmcnt(0)
	v_lshlrev_b32_e32 v206, 16, v194
	v_and_b32_e32 v207, 0xffff0000, v194
	v_lshlrev_b32_e32 v194, 16, v195
	v_and_b32_e32 v195, 0xffff0000, v195
	v_lshlrev_b32_e32 v208, 16, v196
	v_and_b32_e32 v209, 0xffff0000, v196
	v_lshlrev_b32_e32 v196, 16, v197
	v_and_b32_e32 v197, 0xffff0000, v197
	v_lshlrev_b32_e32 v210, 16, v198
	v_and_b32_e32 v211, 0xffff0000, v198
	v_lshlrev_b32_e32 v198, 16, v199
	v_and_b32_e32 v199, 0xffff0000, v199
	v_lshlrev_b32_e32 v212, 16, v200
	v_and_b32_e32 v213, 0xffff0000, v200
	v_lshlrev_b32_e32 v200, 16, v201
	v_and_b32_e32 v201, 0xffff0000, v201
	v_add_f32_e32 v126, v126, v194
	v_add_f32_e32 v127, v127, v195
	v_add_f32_e32 v124, v124, v206
	v_add_f32_e32 v125, v125, v207
	v_add_f32_e32 v122, v122, v196
	v_add_f32_e32 v123, v123, v197
	v_add_f32_e32 v120, v120, v208
	v_add_f32_e32 v121, v121, v209
	v_add_f32_e32 v118, v118, v198
	v_add_f32_e32 v119, v119, v199
	v_add_f32_e32 v116, v116, v210
	v_add_f32_e32 v117, v117, v211
	v_add_f32_e32 v194, v114, v200
	v_add_f32_e32 v195, v115, v201
	v_add_f32_e32 v196, v112, v212
	v_add_f32_e32 v197, v113, v213
	v_mul_f32_e32 v114, v125, v125
	v_mul_f32_e32 v115, v127, v127
	v_mul_f32_e32 v198, v121, v121
	v_mul_f32_e32 v199, v123, v123
	v_cvt_pk_bf16_f32 v112, v124, v125
	v_cvt_pk_bf16_f32 v113, v126, v127
	v_mul_f32_e32 v125, v117, v117
	v_mul_f32_e32 v127, v119, v119
	v_mul_f32_e32 v200, v197, v197
	v_mul_f32_e32 v201, v195, v195
	v_fmac_f32_e32 v114, v124, v124
	v_fmac_f32_e32 v115, v126, v126
	v_fmac_f32_e32 v198, v120, v120
	v_fmac_f32_e32 v199, v122, v122
	v_fmac_f32_e32 v125, v116, v116
	v_fmac_f32_e32 v127, v118, v118
	v_fmac_f32_e32 v200, v196, v196
	v_fmac_f32_e32 v201, v194, v194
	v_add_f32_e32 v114, v114, v115
	v_add_f32_e32 v115, v198, v199
	v_add_f32_e32 v124, v125, v127
	v_add_f32_e32 v125, v200, v201
	v_add_f32_e32 v114, v114, v115
	v_add_f32_e32 v115, v124, v125
	v_add_f32_e32 v124, v114, v115
	ds_bpermute_b32 v125, v193, v124
	v_cvt_pk_bf16_f32 v114, v120, v121
	v_cvt_pk_bf16_f32 v115, v122, v123
	global_store_dwordx4 v[204:205], v[112:115], off
	v_cvt_pk_bf16_f32 v116, v116, v117
	v_cvt_pk_bf16_f32 v117, v118, v119
	v_cvt_pk_bf16_f32 v118, v196, v197
	v_cvt_pk_bf16_f32 v119, v194, v195
	global_store_dwordx4 v[204:205], v[116:119], off offset:256
	s_waitcnt lgkmcnt(0)
	v_add_f32_e32 v113, v124, v125
	v_lshlrev_b32_e32 v112, 2, v214
	ds_bpermute_b32 v114, v112, v113
	s_and_saveexec_b64 s[4:5], s[6:7]
	s_cbranch_execz .LBB0_564
	v_lshlrev_b64 v[116:117], 6, v[172:173]
	v_lshl_add_u64 v[116:117], s[28:29], 0, v[116:117]
	v_lshl_add_u64 v[116:117], s[38:39], 2, v[116:117]
	s_lshl_b32 s12, s47, 2
	v_lshl_add_u64 v[116:117], v[116:117], 0, s[12:13]
	s_waitcnt lgkmcnt(0)
	v_add_f32_e32 v113, v113, v114
	global_store_dword v[116:117], v113, off
.LBB0_564:
	s_or_b64 exec, exec, s[4:5]
	s_waitcnt lgkmcnt(0)
	v_lshlrev_b32_e32 v114, 16, v148
	v_and_b32_e32 v115, 0xffff0000, v148
	v_lshlrev_b32_e32 v116, 16, v149
	v_and_b32_e32 v117, 0xffff0000, v149
	v_lshlrev_b32_e32 v118, 16, v150
	v_and_b32_e32 v119, 0xffff0000, v150
	v_lshlrev_b32_e32 v120, 16, v151
	v_and_b32_e32 v121, 0xffff0000, v151
	v_add_f32_e32 v110, v110, v116
	v_add_f32_e32 v111, v111, v117
	v_add_f32_e32 v108, v108, v114
	v_add_f32_e32 v109, v109, v115
	v_add_f32_e32 v114, v106, v120
	v_add_f32_e32 v115, v107, v121
	v_add_f32_e32 v106, v104, v118
	v_add_f32_e32 v107, v105, v119
	v_mul_f32_e32 v104, v109, v109
	v_mul_f32_e32 v105, v111, v111
	v_fmac_f32_e32 v104, v108, v108
	v_fmac_f32_e32 v105, v110, v110
	v_add_f32_e32 v104, v104, v105
	v_mul_f32_e32 v105, v107, v107
	v_mul_f32_e32 v113, v115, v115
	v_fmac_f32_e32 v105, v106, v106
	v_fmac_f32_e32 v113, v114, v114
	v_add_f32_e32 v105, v105, v113
	v_add_f32_e32 v113, v104, v105
	v_cvt_pk_bf16_f32 v104, v108, v109
	v_cvt_pk_bf16_f32 v105, v110, v111
	v_lshlrev_b32_e32 v108, 16, v144
	v_and_b32_e32 v109, 0xffff0000, v144
	v_lshlrev_b32_e32 v110, 16, v145
	v_and_b32_e32 v111, 0xffff0000, v145
	v_cvt_pk_bf16_f32 v106, v106, v107
	v_cvt_pk_bf16_f32 v107, v114, v115
	v_lshlrev_b32_e32 v114, 16, v146
	v_and_b32_e32 v115, 0xffff0000, v146
	v_add_f32_e32 v102, v102, v110
	v_add_f32_e32 v103, v103, v111
	v_add_f32_e32 v100, v100, v108
	v_add_f32_e32 v101, v101, v109
	v_lshlrev_b32_e32 v116, 16, v147
	v_and_b32_e32 v117, 0xffff0000, v147
	v_add_f32_e32 v110, v96, v114
	v_add_f32_e32 v111, v97, v115
	v_mul_f32_e32 v96, v101, v101
	v_mul_f32_e32 v97, v103, v103
	v_add_f32_e32 v108, v98, v116
	v_add_f32_e32 v109, v99, v117
	v_fmac_f32_e32 v96, v100, v100
	v_fmac_f32_e32 v97, v102, v102
	v_add_f32_e32 v96, v96, v97
	v_mul_f32_e32 v97, v111, v111
	v_mul_f32_e32 v98, v109, v109
	v_fmac_f32_e32 v97, v110, v110
	v_fmac_f32_e32 v98, v108, v108
	v_add_f32_e32 v97, v97, v98
	v_add_f32_e32 v96, v96, v97
	v_add_f32_e32 v99, v113, v96
	ds_bpermute_b32 v113, v193, v99
	v_lshl_add_u64 v[96:97], s[26:27], 0, v[184:185]
	v_lshl_add_u64 v[114:115], v[168:169], 1, v[96:97]
	global_store_dwordx4 v[114:115], v[104:107], off
	v_cvt_pk_bf16_f32 v98, v100, v101
	s_waitcnt lgkmcnt(0)
	v_add_f32_e32 v96, v99, v113
	ds_bpermute_b32 v97, v112, v96
	v_cvt_pk_bf16_f32 v99, v102, v103
	v_cvt_pk_bf16_f32 v100, v110, v111
	v_cvt_pk_bf16_f32 v101, v108, v109
	global_store_dwordx4 v[114:115], v[98:101], off offset:256
	s_and_saveexec_b64 s[4:5], s[6:7]
	s_cbranch_execz .LBB0_566
	v_lshlrev_b64 v[98:99], 6, v[182:183]
	v_lshl_add_u64 v[98:99], s[28:29], 0, v[98:99]
	v_lshl_add_u64 v[98:99], s[38:39], 2, v[98:99]
	s_lshl_b32 s12, s47, 2
	v_lshl_add_u64 v[98:99], v[98:99], 0, s[12:13]
	s_waitcnt lgkmcnt(0)
	v_add_f32_e32 v96, v96, v97
	global_store_dword v[98:99], v96, off
.LBB0_566:
	s_or_b64 exec, exec, s[4:5]
	v_lshlrev_b32_e32 v96, 16, v140
	s_waitcnt lgkmcnt(0)
	v_and_b32_e32 v97, 0xffff0000, v140
	v_lshlrev_b32_e32 v98, 16, v141
	v_and_b32_e32 v99, 0xffff0000, v141
	v_lshlrev_b32_e32 v100, 16, v142
	v_and_b32_e32 v101, 0xffff0000, v142
	v_lshlrev_b32_e32 v102, 16, v143
	v_and_b32_e32 v103, 0xffff0000, v143
	v_add_f32_e32 v94, v94, v98
	v_add_f32_e32 v95, v95, v99
	v_add_f32_e32 v92, v92, v96
	v_add_f32_e32 v93, v93, v97
	v_add_f32_e32 v96, v90, v102
	v_add_f32_e32 v97, v91, v103
	v_add_f32_e32 v90, v88, v100
	v_add_f32_e32 v91, v89, v101
	v_mul_f32_e32 v88, v93, v93
	v_mul_f32_e32 v89, v95, v95
	v_fmac_f32_e32 v88, v92, v92
	v_fmac_f32_e32 v89, v94, v94
	v_add_f32_e32 v88, v88, v89
	v_mul_f32_e32 v89, v91, v91
	v_mul_f32_e32 v98, v97, v97
	v_fmac_f32_e32 v89, v90, v90
	v_fmac_f32_e32 v98, v96, v96
	v_add_f32_e32 v89, v89, v98
	v_add_f32_e32 v100, v88, v89
	v_cvt_pk_bf16_f32 v88, v92, v93
	v_cvt_pk_bf16_f32 v89, v94, v95
	v_lshlrev_b32_e32 v92, 16, v136
	v_and_b32_e32 v93, 0xffff0000, v136
	v_lshlrev_b32_e32 v94, 16, v137
	v_and_b32_e32 v95, 0xffff0000, v137
	v_cvt_pk_bf16_f32 v90, v90, v91
	v_cvt_pk_bf16_f32 v91, v96, v97
	v_lshlrev_b32_e32 v96, 16, v138
	v_and_b32_e32 v97, 0xffff0000, v138
	v_add_f32_e32 v86, v86, v94
	v_add_f32_e32 v87, v87, v95
	v_add_f32_e32 v84, v84, v92
	v_add_f32_e32 v85, v85, v93
	v_lshlrev_b32_e32 v98, 16, v139
	v_and_b32_e32 v99, 0xffff0000, v139
	v_add_f32_e32 v94, v80, v96
	v_add_f32_e32 v95, v81, v97
	v_mul_f32_e32 v80, v85, v85
	v_mul_f32_e32 v81, v87, v87
	v_add_f32_e32 v92, v82, v98
	v_add_f32_e32 v93, v83, v99
	v_fmac_f32_e32 v80, v84, v84
	v_fmac_f32_e32 v81, v86, v86
	v_add_f32_e32 v80, v80, v81
	v_mul_f32_e32 v81, v95, v95
	v_mul_f32_e32 v82, v93, v93
	v_fmac_f32_e32 v81, v94, v94
	v_fmac_f32_e32 v82, v92, v92
	v_add_f32_e32 v81, v81, v82
	v_add_f32_e32 v80, v80, v81
	v_add_f32_e32 v83, v100, v80
	ds_bpermute_b32 v98, v193, v83
	v_lshl_add_u64 v[80:81], s[26:27], 0, v[180:181]
	v_lshl_add_u64 v[96:97], v[168:169], 1, v[80:81]
	global_store_dwordx4 v[96:97], v[88:91], off
	v_cvt_pk_bf16_f32 v82, v84, v85
	s_waitcnt lgkmcnt(0)
	v_add_f32_e32 v80, v83, v98
	ds_bpermute_b32 v81, v112, v80
	v_cvt_pk_bf16_f32 v83, v86, v87
	v_cvt_pk_bf16_f32 v84, v94, v95
	v_cvt_pk_bf16_f32 v85, v92, v93
	global_store_dwordx4 v[96:97], v[82:85], off offset:256
	s_and_saveexec_b64 s[4:5], s[6:7]
	s_cbranch_execz .LBB0_568
	v_lshlrev_b64 v[82:83], 6, v[178:179]
	v_lshl_add_u64 v[82:83], s[28:29], 0, v[82:83]
	v_lshl_add_u64 v[82:83], s[38:39], 2, v[82:83]
	s_lshl_b32 s12, s47, 2
	v_lshl_add_u64 v[82:83], v[82:83], 0, s[12:13]
	s_waitcnt lgkmcnt(0)
	v_add_f32_e32 v80, v80, v81
	global_store_dword v[82:83], v80, off
.LBB0_568:
	s_or_b64 exec, exec, s[4:5]
	v_lshlrev_b32_e32 v80, 16, v132
	s_waitcnt lgkmcnt(0)
	v_and_b32_e32 v81, 0xffff0000, v132
	v_lshlrev_b32_e32 v82, 16, v133
	v_and_b32_e32 v83, 0xffff0000, v133
	v_lshlrev_b32_e32 v84, 16, v134
	v_and_b32_e32 v85, 0xffff0000, v134
	v_lshlrev_b32_e32 v86, 16, v135
	v_and_b32_e32 v87, 0xffff0000, v135
	v_add_f32_e32 v78, v78, v82
	v_add_f32_e32 v79, v79, v83
	v_add_f32_e32 v76, v76, v80
	v_add_f32_e32 v77, v77, v81
	v_add_f32_e32 v80, v74, v86
	v_add_f32_e32 v81, v75, v87
	v_add_f32_e32 v74, v72, v84
	v_add_f32_e32 v75, v73, v85
	v_mul_f32_e32 v72, v77, v77
	v_mul_f32_e32 v73, v79, v79
	v_fmac_f32_e32 v72, v76, v76
	v_fmac_f32_e32 v73, v78, v78
	v_add_f32_e32 v72, v72, v73
	v_mul_f32_e32 v73, v75, v75
	v_mul_f32_e32 v82, v81, v81
	v_fmac_f32_e32 v73, v74, v74
	v_fmac_f32_e32 v82, v80, v80
	v_add_f32_e32 v73, v73, v82
	v_add_f32_e32 v84, v72, v73
	v_cvt_pk_bf16_f32 v72, v76, v77
	v_cvt_pk_bf16_f32 v73, v78, v79
	v_lshlrev_b32_e32 v76, 16, v128
	v_and_b32_e32 v77, 0xffff0000, v128
	v_lshlrev_b32_e32 v78, 16, v129
	v_and_b32_e32 v79, 0xffff0000, v129
	v_cvt_pk_bf16_f32 v74, v74, v75
	v_cvt_pk_bf16_f32 v75, v80, v81
	v_lshlrev_b32_e32 v80, 16, v130
	v_and_b32_e32 v81, 0xffff0000, v130
	v_add_f32_e32 v70, v70, v78
	v_add_f32_e32 v71, v71, v79
	v_add_f32_e32 v68, v68, v76
	v_add_f32_e32 v69, v69, v77
	v_lshlrev_b32_e32 v82, 16, v131
	v_and_b32_e32 v83, 0xffff0000, v131
	v_add_f32_e32 v78, v64, v80
	v_add_f32_e32 v79, v65, v81
	v_mul_f32_e32 v64, v69, v69
	v_mul_f32_e32 v65, v71, v71
	v_add_f32_e32 v76, v66, v82
	v_add_f32_e32 v77, v67, v83
	v_fmac_f32_e32 v64, v68, v68
	v_fmac_f32_e32 v65, v70, v70
	v_add_f32_e32 v64, v64, v65
	v_mul_f32_e32 v65, v79, v79
	v_mul_f32_e32 v66, v77, v77
	v_fmac_f32_e32 v65, v78, v78
	v_fmac_f32_e32 v66, v76, v76
	v_add_f32_e32 v65, v65, v66
	v_add_f32_e32 v64, v64, v65
	v_add_f32_e32 v67, v84, v64
	ds_bpermute_b32 v82, v193, v67
	v_lshl_add_u64 v[64:65], s[26:27], 0, v[176:177]
	v_lshl_add_u64 v[80:81], v[168:169], 1, v[64:65]
	global_store_dwordx4 v[80:81], v[72:75], off
	v_cvt_pk_bf16_f32 v66, v68, v69
	s_waitcnt lgkmcnt(0)
	v_add_f32_e32 v64, v67, v82
	ds_bpermute_b32 v65, v112, v64
	v_cvt_pk_bf16_f32 v67, v70, v71
	v_cvt_pk_bf16_f32 v68, v78, v79
	v_cvt_pk_bf16_f32 v69, v76, v77
	global_store_dwordx4 v[80:81], v[66:69], off offset:256
	s_and_saveexec_b64 s[4:5], s[6:7]
	s_cbranch_execz .LBB0_570
	v_lshlrev_b64 v[66:67], 6, v[174:175]
	v_lshl_add_u64 v[66:67], s[28:29], 0, v[66:67]
	v_lshl_add_u64 v[66:67], s[38:39], 2, v[66:67]
	s_lshl_b32 s12, s47, 2
	v_lshl_add_u64 v[66:67], v[66:67], 0, s[12:13]
	s_waitcnt lgkmcnt(0)
	v_add_f32_e32 v64, v64, v65
	global_store_dword v[66:67], v64, off
.LBB0_570:
	s_or_b64 exec, exec, s[4:5]
	v_add_u32_e32 v100, 0x80, v172
	v_ashrrev_i32_e32 v101, 31, v100
	v_lshlrev_b64 v[110:111], 11, v[100:101]
	s_waitcnt lgkmcnt(0)
	v_lshl_add_u64 v[64:65], v[170:171], 0, v[110:111]
	global_load_dwordx4 v[102:105], v[64:65], off
	global_load_dwordx4 v[106:109], v[64:65], off offset:256
	v_add_u32_e32 v96, 0x90, v172
	v_add_u32_e32 v92, 0xa0, v172
	v_add_u32_e32 v88, 0xb0, v172
	v_ashrrev_i32_e32 v97, 31, v96
	v_ashrrev_i32_e32 v93, 31, v92
	v_ashrrev_i32_e32 v89, 31, v88
	v_lshlrev_b64 v[98:99], 11, v[96:97]
	v_lshlrev_b64 v[94:95], 11, v[92:93]
	v_lshlrev_b64 v[90:91], 11, v[88:89]
	v_lshl_add_u64 v[64:65], v[170:171], 0, v[98:99]
	v_lshl_add_u64 v[66:67], v[170:171], 0, v[94:95]
	v_lshl_add_u64 v[114:115], v[170:171], 0, v[90:91]
	global_load_dwordx4 v[84:87], v[64:65], off
	global_load_dwordx4 v[80:83], v[64:65], off offset:256
	global_load_dwordx4 v[76:79], v[66:67], off
	global_load_dwordx4 v[72:75], v[66:67], off offset:256
	global_load_dwordx4 v[68:71], v[114:115], off
	s_nop 0
	global_load_dwordx4 v[64:67], v[114:115], off offset:256
	s_waitcnt vmcnt(7)
	v_lshlrev_b32_e32 v114, 16, v102
	v_and_b32_e32 v115, 0xffff0000, v102
	v_lshlrev_b32_e32 v102, 16, v103
	v_and_b32_e32 v103, 0xffff0000, v103
	v_lshlrev_b32_e32 v116, 16, v104
	v_and_b32_e32 v117, 0xffff0000, v104
	v_lshlrev_b32_e32 v104, 16, v105
	v_and_b32_e32 v105, 0xffff0000, v105
	s_waitcnt vmcnt(6)
	v_lshlrev_b32_e32 v118, 16, v106
	v_and_b32_e32 v119, 0xffff0000, v106
	v_lshlrev_b32_e32 v106, 16, v107
	v_and_b32_e32 v107, 0xffff0000, v107
	v_lshlrev_b32_e32 v120, 16, v108
	v_and_b32_e32 v121, 0xffff0000, v108
	v_lshlrev_b32_e32 v108, 16, v109
	v_and_b32_e32 v109, 0xffff0000, v109
	v_add_f32_e32 v62, v62, v102
	v_add_f32_e32 v63, v63, v103
	v_add_f32_e32 v60, v60, v114
	v_add_f32_e32 v61, v61, v115
	v_add_f32_e32 v58, v58, v104
	v_add_f32_e32 v59, v59, v105
	v_add_f32_e32 v56, v56, v116
	v_add_f32_e32 v57, v57, v117
	v_add_f32_e32 v54, v54, v106
	v_add_f32_e32 v55, v55, v107
	v_add_f32_e32 v52, v52, v118
	v_add_f32_e32 v53, v53, v119
	v_add_f32_e32 v102, v50, v108
	v_add_f32_e32 v103, v51, v109
	v_add_f32_e32 v104, v48, v120
	v_add_f32_e32 v105, v49, v121
	v_mul_f32_e32 v106, v61, v61
	v_mul_f32_e32 v107, v63, v63
	v_mul_f32_e32 v108, v57, v57
	v_mul_f32_e32 v109, v59, v59
	v_cvt_pk_bf16_f32 v48, v60, v61
	v_cvt_pk_bf16_f32 v49, v62, v63
	v_cvt_pk_bf16_f32 v50, v56, v57
	v_cvt_pk_bf16_f32 v51, v58, v59
	v_mul_f32_e32 v57, v53, v53
	v_mul_f32_e32 v59, v55, v55
	v_mul_f32_e32 v61, v105, v105
	v_mul_f32_e32 v63, v103, v103
	v_fmac_f32_e32 v106, v60, v60
	v_fmac_f32_e32 v107, v62, v62
	v_fmac_f32_e32 v108, v56, v56
	v_fmac_f32_e32 v109, v58, v58
	v_fmac_f32_e32 v57, v52, v52
	v_fmac_f32_e32 v59, v54, v54
	v_fmac_f32_e32 v61, v104, v104
	v_fmac_f32_e32 v63, v102, v102
	v_add_f32_e32 v56, v106, v107
	v_add_f32_e32 v58, v108, v109
	v_add_f32_e32 v57, v57, v59
	v_add_f32_e32 v59, v61, v63
	v_add_f32_e32 v56, v56, v58
	v_add_f32_e32 v57, v57, v59
	v_add_f32_e32 v58, v56, v57
	ds_bpermute_b32 v59, v193, v58
	v_lshl_add_u64 v[56:57], s[26:27], 0, v[110:111]
	v_lshl_add_u64 v[56:57], v[168:169], 1, v[56:57]
	global_store_dwordx4 v[56:57], v[48:51], off
	s_waitcnt lgkmcnt(0)
	s_nop 0
	v_add_f32_e32 v48, v58, v59
	ds_bpermute_b32 v49, v112, v48
	v_cvt_pk_bf16_f32 v50, v52, v53
	v_cvt_pk_bf16_f32 v51, v54, v55
	v_cvt_pk_bf16_f32 v52, v104, v105
	v_cvt_pk_bf16_f32 v53, v102, v103
	global_store_dwordx4 v[56:57], v[50:53], off offset:256
	s_and_saveexec_b64 s[4:5], s[6:7]
	s_cbranch_execz .LBB0_572
	v_lshlrev_b64 v[50:51], 6, v[100:101]
	v_lshl_add_u64 v[50:51], s[28:29], 0, v[50:51]
	v_lshl_add_u64 v[50:51], s[38:39], 2, v[50:51]
	s_lshl_b32 s12, s47, 2
	v_lshl_add_u64 v[50:51], v[50:51], 0, s[12:13]
	s_waitcnt lgkmcnt(0)
	v_add_f32_e32 v48, v48, v49
	global_store_dword v[50:51], v48, off
.LBB0_572:
	s_or_b64 exec, exec, s[4:5]
	s_waitcnt vmcnt(7)
	v_lshlrev_b32_e32 v48, 16, v84
	s_waitcnt lgkmcnt(0)
	v_and_b32_e32 v49, 0xffff0000, v84
	v_lshlrev_b32_e32 v50, 16, v85
	v_and_b32_e32 v51, 0xffff0000, v85
	v_lshlrev_b32_e32 v52, 16, v86
	v_and_b32_e32 v53, 0xffff0000, v86
	v_lshlrev_b32_e32 v54, 16, v87
	v_and_b32_e32 v55, 0xffff0000, v87
	v_add_f32_e32 v46, v46, v50
	v_add_f32_e32 v47, v47, v51
	v_add_f32_e32 v44, v44, v48
	v_add_f32_e32 v45, v45, v49
	v_add_f32_e32 v48, v42, v54
	v_add_f32_e32 v49, v43, v55
	v_add_f32_e32 v42, v40, v52
	v_add_f32_e32 v43, v41, v53
	v_mul_f32_e32 v40, v45, v45
	v_mul_f32_e32 v41, v47, v47
	v_fmac_f32_e32 v40, v44, v44
	v_fmac_f32_e32 v41, v46, v46
	v_add_f32_e32 v40, v40, v41
	v_mul_f32_e32 v41, v43, v43
	v_mul_f32_e32 v50, v49, v49
	v_fmac_f32_e32 v41, v42, v42
	v_fmac_f32_e32 v50, v48, v48
	v_add_f32_e32 v41, v41, v50
	v_add_f32_e32 v52, v40, v41
	v_cvt_pk_bf16_f32 v40, v44, v45
	v_cvt_pk_bf16_f32 v41, v46, v47
	s_waitcnt vmcnt(6)
	v_lshlrev_b32_e32 v44, 16, v80
	v_and_b32_e32 v45, 0xffff0000, v80
	v_lshlrev_b32_e32 v46, 16, v81
	v_and_b32_e32 v47, 0xffff0000, v81
	v_cvt_pk_bf16_f32 v42, v42, v43
	v_cvt_pk_bf16_f32 v43, v48, v49
	v_lshlrev_b32_e32 v48, 16, v82
	v_and_b32_e32 v49, 0xffff0000, v82
	v_add_f32_e32 v38, v38, v46
	v_add_f32_e32 v39, v39, v47
	v_add_f32_e32 v36, v36, v44
	v_add_f32_e32 v37, v37, v45
	v_lshlrev_b32_e32 v50, 16, v83
	v_and_b32_e32 v51, 0xffff0000, v83
	v_add_f32_e32 v46, v32, v48
	v_add_f32_e32 v47, v33, v49
	v_mul_f32_e32 v32, v37, v37
	v_mul_f32_e32 v33, v39, v39
	v_add_f32_e32 v44, v34, v50
	v_add_f32_e32 v45, v35, v51
	v_fmac_f32_e32 v32, v36, v36
	v_fmac_f32_e32 v33, v38, v38
	v_add_f32_e32 v32, v32, v33
	v_mul_f32_e32 v33, v47, v47
	v_mul_f32_e32 v34, v45, v45
	v_fmac_f32_e32 v33, v46, v46
	v_fmac_f32_e32 v34, v44, v44
	v_add_f32_e32 v33, v33, v34
	v_add_f32_e32 v32, v32, v33
	v_add_f32_e32 v35, v52, v32
	ds_bpermute_b32 v50, v193, v35
	v_lshl_add_u64 v[32:33], s[26:27], 0, v[98:99]
	v_lshl_add_u64 v[48:49], v[168:169], 1, v[32:33]
	global_store_dwordx4 v[48:49], v[40:43], off
	v_cvt_pk_bf16_f32 v34, v36, v37
	s_waitcnt lgkmcnt(0)
	v_add_f32_e32 v32, v35, v50
	ds_bpermute_b32 v33, v112, v32
	v_cvt_pk_bf16_f32 v35, v38, v39
	v_cvt_pk_bf16_f32 v36, v46, v47
	v_cvt_pk_bf16_f32 v37, v44, v45
	global_store_dwordx4 v[48:49], v[34:37], off offset:256
	s_and_saveexec_b64 s[4:5], s[6:7]
	s_cbranch_execz .LBB0_574
	v_lshlrev_b64 v[34:35], 6, v[96:97]
	v_lshl_add_u64 v[34:35], s[28:29], 0, v[34:35]
	v_lshl_add_u64 v[34:35], s[38:39], 2, v[34:35]
	s_lshl_b32 s12, s47, 2
	v_lshl_add_u64 v[34:35], v[34:35], 0, s[12:13]
	s_waitcnt lgkmcnt(0)
	v_add_f32_e32 v32, v32, v33
	global_store_dword v[34:35], v32, off
.LBB0_574:
	s_or_b64 exec, exec, s[4:5]
	s_waitcnt vmcnt(7)
	v_lshlrev_b32_e32 v32, 16, v76
	s_waitcnt lgkmcnt(0)
	v_and_b32_e32 v33, 0xffff0000, v76
	v_lshlrev_b32_e32 v34, 16, v77
	v_and_b32_e32 v35, 0xffff0000, v77
	v_lshlrev_b32_e32 v36, 16, v78
	v_and_b32_e32 v37, 0xffff0000, v78
	v_lshlrev_b32_e32 v38, 16, v79
	v_and_b32_e32 v39, 0xffff0000, v79
	v_add_f32_e32 v30, v30, v34
	v_add_f32_e32 v31, v31, v35
	v_add_f32_e32 v28, v28, v32
	v_add_f32_e32 v29, v29, v33
	v_add_f32_e32 v32, v26, v38
	v_add_f32_e32 v33, v27, v39
	v_add_f32_e32 v26, v24, v36
	v_add_f32_e32 v27, v25, v37
	v_mul_f32_e32 v24, v29, v29
	v_mul_f32_e32 v25, v31, v31
	v_fmac_f32_e32 v24, v28, v28
	v_fmac_f32_e32 v25, v30, v30
	v_add_f32_e32 v24, v24, v25
	v_mul_f32_e32 v25, v27, v27
	v_mul_f32_e32 v34, v33, v33
	v_fmac_f32_e32 v25, v26, v26
	v_fmac_f32_e32 v34, v32, v32
	v_add_f32_e32 v25, v25, v34
	v_add_f32_e32 v36, v24, v25
	v_cvt_pk_bf16_f32 v24, v28, v29
	v_cvt_pk_bf16_f32 v25, v30, v31
	s_waitcnt vmcnt(6)
	v_lshlrev_b32_e32 v28, 16, v72
	v_and_b32_e32 v29, 0xffff0000, v72
	v_lshlrev_b32_e32 v30, 16, v73
	v_and_b32_e32 v31, 0xffff0000, v73
	v_cvt_pk_bf16_f32 v26, v26, v27
	v_cvt_pk_bf16_f32 v27, v32, v33
	v_lshlrev_b32_e32 v32, 16, v74
	v_and_b32_e32 v33, 0xffff0000, v74
	v_add_f32_e32 v22, v22, v30
	v_add_f32_e32 v23, v23, v31
	v_add_f32_e32 v20, v20, v28
	v_add_f32_e32 v21, v21, v29
	v_lshlrev_b32_e32 v34, 16, v75
	v_and_b32_e32 v35, 0xffff0000, v75
	v_add_f32_e32 v30, v16, v32
	v_add_f32_e32 v31, v17, v33
	v_mul_f32_e32 v16, v21, v21
	v_mul_f32_e32 v17, v23, v23
	v_add_f32_e32 v28, v18, v34
	v_add_f32_e32 v29, v19, v35
	v_fmac_f32_e32 v16, v20, v20
	v_fmac_f32_e32 v17, v22, v22
	v_add_f32_e32 v16, v16, v17
	v_mul_f32_e32 v17, v31, v31
	v_mul_f32_e32 v18, v29, v29
	v_fmac_f32_e32 v17, v30, v30
	v_fmac_f32_e32 v18, v28, v28
	v_add_f32_e32 v17, v17, v18
	v_add_f32_e32 v16, v16, v17
	v_add_f32_e32 v19, v36, v16
	ds_bpermute_b32 v34, v193, v19
	v_lshl_add_u64 v[16:17], s[26:27], 0, v[94:95]
	v_lshl_add_u64 v[32:33], v[168:169], 1, v[16:17]
	global_store_dwordx4 v[32:33], v[24:27], off
	v_cvt_pk_bf16_f32 v18, v20, v21
	s_waitcnt lgkmcnt(0)
	v_add_f32_e32 v16, v19, v34
	ds_bpermute_b32 v17, v112, v16
	v_cvt_pk_bf16_f32 v19, v22, v23
	v_cvt_pk_bf16_f32 v20, v30, v31
	v_cvt_pk_bf16_f32 v21, v28, v29
	global_store_dwordx4 v[32:33], v[18:21], off offset:256
	s_and_saveexec_b64 s[4:5], s[6:7]
	s_cbranch_execz .LBB0_576
	v_lshlrev_b64 v[18:19], 6, v[92:93]
	v_lshl_add_u64 v[18:19], s[28:29], 0, v[18:19]
	v_lshl_add_u64 v[18:19], s[38:39], 2, v[18:19]
	s_lshl_b32 s12, s47, 2
	v_lshl_add_u64 v[18:19], v[18:19], 0, s[12:13]
	s_waitcnt lgkmcnt(0)
	v_add_f32_e32 v16, v16, v17
	global_store_dword v[18:19], v16, off
.LBB0_576:
	s_or_b64 exec, exec, s[4:5]
	s_waitcnt vmcnt(7)
	v_lshlrev_b32_e32 v16, 16, v68
	s_waitcnt lgkmcnt(0)
	v_and_b32_e32 v17, 0xffff0000, v68
	v_lshlrev_b32_e32 v18, 16, v69
	v_and_b32_e32 v19, 0xffff0000, v69
	v_lshlrev_b32_e32 v20, 16, v70
	v_and_b32_e32 v21, 0xffff0000, v70
	v_lshlrev_b32_e32 v22, 16, v71
	v_and_b32_e32 v23, 0xffff0000, v71
	v_add_f32_e32 v14, v14, v18
	v_add_f32_e32 v15, v15, v19
	v_add_f32_e32 v12, v12, v16
	v_add_f32_e32 v13, v13, v17
	v_add_f32_e32 v16, v10, v22
	v_add_f32_e32 v17, v11, v23
	v_add_f32_e32 v10, v8, v20
	v_add_f32_e32 v11, v9, v21
	v_mul_f32_e32 v8, v13, v13
	v_mul_f32_e32 v9, v15, v15
	v_fmac_f32_e32 v8, v12, v12
	v_fmac_f32_e32 v9, v14, v14
	v_add_f32_e32 v8, v8, v9
	v_mul_f32_e32 v9, v11, v11
	v_mul_f32_e32 v18, v17, v17
	v_fmac_f32_e32 v9, v10, v10
	v_fmac_f32_e32 v18, v16, v16
	v_add_f32_e32 v9, v9, v18
	v_add_f32_e32 v20, v8, v9
	v_cvt_pk_bf16_f32 v8, v12, v13
	v_cvt_pk_bf16_f32 v9, v14, v15
	s_waitcnt vmcnt(6)
	v_lshlrev_b32_e32 v12, 16, v64
	v_and_b32_e32 v13, 0xffff0000, v64
	v_lshlrev_b32_e32 v14, 16, v65
	v_and_b32_e32 v15, 0xffff0000, v65
	v_cvt_pk_bf16_f32 v10, v10, v11
	v_cvt_pk_bf16_f32 v11, v16, v17
	v_lshlrev_b32_e32 v16, 16, v66
	v_and_b32_e32 v17, 0xffff0000, v66
	v_add_f32_e32 v6, v6, v14
	v_add_f32_e32 v7, v7, v15
	v_add_f32_e32 v4, v4, v12
	v_add_f32_e32 v5, v5, v13
	v_lshlrev_b32_e32 v18, 16, v67
	v_and_b32_e32 v19, 0xffff0000, v67
	v_add_f32_e32 v14, v0, v16
	v_add_f32_e32 v15, v1, v17
	v_mul_f32_e32 v0, v5, v5
	v_mul_f32_e32 v1, v7, v7
	v_add_f32_e32 v12, v2, v18
	v_add_f32_e32 v13, v3, v19
	v_fmac_f32_e32 v0, v4, v4
	v_fmac_f32_e32 v1, v6, v6
	v_add_f32_e32 v0, v0, v1
	v_mul_f32_e32 v1, v15, v15
	v_mul_f32_e32 v2, v13, v13
	v_fmac_f32_e32 v1, v14, v14
	v_fmac_f32_e32 v2, v12, v12
	v_add_f32_e32 v1, v1, v2
	v_add_f32_e32 v0, v0, v1
	v_add_f32_e32 v3, v20, v0
	ds_bpermute_b32 v18, v193, v3
	v_lshl_add_u64 v[0:1], s[26:27], 0, v[90:91]
	v_lshl_add_u64 v[16:17], v[168:169], 1, v[0:1]
	global_store_dwordx4 v[16:17], v[8:11], off
	v_cvt_pk_bf16_f32 v2, v4, v5
	s_waitcnt lgkmcnt(0)
	v_add_f32_e32 v0, v3, v18
	ds_bpermute_b32 v1, v112, v0
	v_cvt_pk_bf16_f32 v3, v6, v7
	v_cvt_pk_bf16_f32 v4, v14, v15
	v_cvt_pk_bf16_f32 v5, v12, v13
	global_store_dwordx4 v[16:17], v[2:5], off offset:256
	s_and_saveexec_b64 s[4:5], s[6:7]
	s_cbranch_execz .LBB0_578
	v_lshlrev_b64 v[2:3], 6, v[88:89]
	v_lshl_add_u64 v[2:3], s[28:29], 0, v[2:3]
	v_lshl_add_u64 v[2:3], s[38:39], 2, v[2:3]
	s_lshl_b32 s12, s47, 2
	v_lshl_add_u64 v[2:3], v[2:3], 0, s[12:13]
	s_waitcnt lgkmcnt(0)
	v_add_f32_e32 v0, v0, v1
	global_store_dword v[2:3], v0, off

.LBB0_648:
	s_or_b64 exec, exec, s[12:13]
	s_waitcnt lgkmcnt(7)
	v_add_f32_e32 v144, v144, v180
	v_fmamk_f32 v144, v144, 0x3a800000, v195
	v_rsq_f32_e32 v180, v144
	s_nop 0
	v_mul_f32_e32 v184, v122, v180
	v_mul_f32_e32 v185, v123, v180
	v_cndmask_b32_e64 v122, 0, 1, s[22:23]
	v_mul_f32_e32 v126, v126, v180
	v_mul_f32_e32 v127, v127, v180
	v_mul_f32_e32 v182, v124, v180
	v_mul_f32_e32 v183, v125, v180
	v_cmp_ne_u32_e64 s[12:13], 1, v122
	s_andn2_b64 vcc, exec, s[22:23]
	v_mul_f32_e32 v186, v120, v180
	v_mul_f32_e32 v187, v121, v180
	s_cbranch_vccnz .LBB0_650
	ds_bpermute_b32 v120, v198, v182
	ds_bpermute_b32 v121, v198, v183
	ds_bpermute_b32 v122, v198, v186
	ds_bpermute_b32 v124, v198, v126
	ds_bpermute_b32 v125, v198, v127
	ds_bpermute_b32 v123, v198, v187
	ds_bpermute_b32 v216, v198, v184
	ds_bpermute_b32 v217, v198, v185
	s_waitcnt lgkmcnt(6)
	v_mul_f32_e32 v120, v176, v120
	v_mul_f32_e32 v121, v177, v121
	s_waitcnt lgkmcnt(3)
	v_mul_f32_e32 v124, v178, v124
	v_mul_f32_e32 v125, v179, v125
	s_waitcnt vmcnt(1)
	v_fma_f32 v182, v182, v132, v120
	v_fma_f32 v183, v183, v133, v121
	s_waitcnt lgkmcnt(2)
	v_mul_f32_e32 v120, v174, v122
	v_mul_f32_e32 v121, v175, v123
	s_waitcnt lgkmcnt(0)
	v_mul_f32_e32 v122, v172, v216
	v_mul_f32_e32 v123, v173, v217
	v_fma_f32 v126, v126, v134, v124
	v_fma_f32 v127, v127, v135, v125
	s_waitcnt vmcnt(0)
	v_fma_f32 v184, v184, v130, v122
	v_fma_f32 v185, v185, v131, v123
	v_fma_f32 v186, v186, v128, v120
	v_fma_f32 v187, v187, v129, v121
.LBB0_650:
	s_lshl_b32 s22, s16, 8
	s_ashr_i32 s5, s4, 31
	s_lshl_b64 s[16:17], s[4:5], 26
	s_and_b32 s5, s22, 0x300
	s_add_u32 s16, s54, s16
	v_or_b32_e32 v120, s5, v190
	s_addc_u32 s17, s55, s17
	v_lshlrev_b32_e32 v144, 1, v120
	s_cmp_eq_u32 s4, 2
	v_lshl_add_u64 v[122:123], s[16:17], 0, v[144:145]
	v_lshlrev_b64 v[120:121], 11, v[170:171]
	s_cselect_b64 vcc, -1, 0
	v_lshl_add_u64 v[124:125], v[122:123], 0, v[120:121]
	v_cndmask_b32_e32 v120, 1.0, v197, vcc
	v_mul_f32_e32 v126, v120, v126
	v_mul_f32_e32 v127, v120, v127
	v_mov_b32_e32 v181, v180
	v_mul_f32_e32 v170, v120, v182
	v_mul_f32_e32 v171, v120, v183
	v_cvt_pk_bf16_f32 v182, v170, v171
	v_cvt_pk_bf16_f32 v183, v126, v127
	v_mov_b32_e32 v126, v180
	v_mov_b32_e32 v127, v180
	v_mul_f32_e32 v216, v120, v184
	v_mul_f32_e32 v217, v120, v185
	v_mul_f32_e32 v184, v120, v186
	v_mul_f32_e32 v185, v120, v187
	v_mul_f32_e32 v118, v118, v126
	v_mul_f32_e32 v119, v119, v127
	v_mul_f32_e32 v116, v116, v180
	v_mul_f32_e32 v117, v117, v181
	v_mul_f32_e32 v114, v114, v126
	v_mul_f32_e32 v115, v115, v127
	s_and_b64 vcc, exec, s[12:13]
	v_mul_f32_e32 v112, v112, v180
	v_mul_f32_e32 v113, v113, v181
	v_cvt_pk_bf16_f32 v184, v184, v185
	v_cvt_pk_bf16_f32 v185, v216, v217
	global_store_dwordx4 v[124:125], v[182:185], off
	s_cbranch_vccnz .LBB0_652
	ds_bpermute_b32 v126, v198, v116
	ds_bpermute_b32 v127, v198, v117
	ds_bpermute_b32 v170, v198, v112
	ds_bpermute_b32 v180, v198, v118
	ds_bpermute_b32 v181, v198, v119
	ds_bpermute_b32 v171, v198, v113
	ds_bpermute_b32 v182, v198, v114
	ds_bpermute_b32 v183, v198, v115
	s_waitcnt lgkmcnt(6)
	v_mul_f32_e32 v126, v176, v126
	v_mul_f32_e32 v127, v177, v127
	s_waitcnt lgkmcnt(3)
	v_mul_f32_e32 v176, v178, v180
	v_mul_f32_e32 v177, v179, v181
	s_waitcnt vmcnt(2)
	v_fma_f32 v116, v116, v132, v126
	v_fma_f32 v117, v117, v133, v127
	s_waitcnt lgkmcnt(2)
	v_mul_f32_e32 v126, v174, v170
	v_mul_f32_e32 v127, v175, v171
	s_waitcnt lgkmcnt(0)
	v_mul_f32_e32 v132, v172, v182
	v_mul_f32_e32 v133, v173, v183
	v_fma_f32 v118, v118, v134, v176
	v_fma_f32 v119, v119, v135, v177
	s_waitcnt vmcnt(1)
	v_fma_f32 v114, v114, v130, v132
	v_fma_f32 v115, v115, v131, v133
	v_fma_f32 v112, v112, v128, v126
	v_fma_f32 v113, v113, v129, v127
.LBB0_652:
	v_mov_b32_e32 v121, v120
	v_mov_b32_e32 v126, v120
	v_mov_b32_e32 v127, v120
	v_mul_f32_e32 v118, v126, v118
	v_mul_f32_e32 v119, v127, v119
	v_mul_f32_e32 v126, v126, v114
	v_mul_f32_e32 v127, v127, v115
	v_mul_f32_e32 v114, v120, v112
	v_mul_f32_e32 v115, v121, v113
	v_mul_f32_e32 v116, v120, v116
	v_mul_f32_e32 v117, v121, v117
	s_waitcnt vmcnt(1)
	v_mov_b32_e32 v128, 0
	v_cvt_pk_bf16_f32 v112, v116, v117
	v_cvt_pk_bf16_f32 v113, v118, v119
	v_cvt_pk_bf16_f32 v114, v114, v115
	v_cvt_pk_bf16_f32 v115, v126, v127
	global_store_dwordx4 v[124:125], v[112:115], off offset:256
	v_mov_b32_e32 v116, 1.0
	v_mov_b32_e32 v117, 1.0
	v_mov_b32_e32 v118, 1.0
	v_mov_b32_e32 v119, 1.0
	v_mov_b32_e32 v112, 1.0
	v_mov_b32_e32 v113, 1.0
	v_mov_b32_e32 v114, 1.0
	v_mov_b32_e32 v115, 1.0
	v_mov_b32_e32 v129, 0
	v_mov_b32_e32 v130, 0
	v_mov_b32_e32 v131, 0
	v_mov_b32_e32 v126, 0
	v_mov_b32_e32 v127, 0
	v_mov_b32_e32 v124, 0
	v_mov_b32_e32 v125, 0
	s_and_saveexec_b64 s[4:5], s[46:47]
	s_cbranch_execz .LBB0_654
	v_lshlrev_b32_e32 v112, 6, v168
	v_and_b32_e32 v112, 0x7f7c0, v112
	global_load_dwordx4 v[124:127], v112, s[28:29] offset:32
	global_load_dwordx4 v[132:135], v112, s[28:29] offset:48
	global_load_dwordx4 v[116:119], v112, s[28:29]
	s_nop 0
	global_load_dwordx4 v[112:115], v112, s[28:29] offset:16
	s_waitcnt vmcnt(3)
	v_xor_b32_e32 v131, 0x80000000, v127
	v_xor_b32_e32 v130, 0x80000000, v126
	v_xor_b32_e32 v129, 0x80000000, v125
	v_xor_b32_e32 v128, 0x80000000, v124
	s_waitcnt vmcnt(2)
	v_xor_b32_e32 v144, 0x80000000, v135
	v_xor_b32_e32 v170, 0x80000000, v134
	v_xor_b32_e32 v171, 0x80000000, v133
	v_xor_b32_e32 v172, 0x80000000, v132
	v_cndmask_b32_e64 v128, v124, v128, s[8:9]
	v_cndmask_b32_e64 v129, v125, v129, s[8:9]
	v_cndmask_b32_e64 v130, v126, v130, s[8:9]
	v_cndmask_b32_e64 v131, v127, v131, s[8:9]
	v_cndmask_b32_e64 v126, v132, v172, s[8:9]
	v_cndmask_b32_e64 v127, v133, v171, s[8:9]
	v_cndmask_b32_e64 v124, v134, v170, s[8:9]
	v_cndmask_b32_e64 v125, v135, v144, s[8:9]
.LBB0_654:
	s_or_b64 exec, exec, s[4:5]
	s_waitcnt lgkmcnt(6)
	v_add_f32_e32 v132, v213, v214
	v_fmamk_f32 v132, v132, 0x3a800000, v195
	v_rsq_f32_e32 v132, v132
	s_nop 0
	v_mul_f32_e32 v110, v110, v132
	v_mul_f32_e32 v111, v111, v132
	v_mul_f32_e32 v108, v108, v132
	v_mul_f32_e32 v109, v109, v132
	v_mul_f32_e32 v134, v106, v132
	v_mul_f32_e32 v135, v107, v132
	s_and_b64 vcc, exec, s[12:13]
	v_mul_f32_e32 v170, v104, v132
	v_mul_f32_e32 v171, v105, v132
	s_cbranch_vccnz .LBB0_656
	ds_bpermute_b32 v104, v198, v108
	ds_bpermute_b32 v105, v198, v109
	ds_bpermute_b32 v106, v198, v170
	ds_bpermute_b32 v172, v198, v110
	ds_bpermute_b32 v173, v198, v111
	ds_bpermute_b32 v107, v198, v171
	ds_bpermute_b32 v174, v198, v134
	ds_bpermute_b32 v175, v198, v135
	s_waitcnt lgkmcnt(6)
	v_mul_f32_e32 v104, v128, v104
	v_mul_f32_e32 v105, v129, v105
	s_waitcnt lgkmcnt(3)
	v_mul_f32_e32 v172, v130, v172
	v_mul_f32_e32 v173, v131, v173
	s_waitcnt vmcnt(1)
	v_fma_f32 v108, v108, v116, v104
	v_fma_f32 v109, v109, v117, v105
	s_waitcnt lgkmcnt(2)
	v_mul_f32_e32 v104, v126, v106
	v_mul_f32_e32 v105, v127, v107
	s_waitcnt lgkmcnt(0)
	v_mul_f32_e32 v106, v124, v174
	v_mul_f32_e32 v107, v125, v175
	v_fma_f32 v110, v110, v118, v172
	v_fma_f32 v111, v111, v119, v173
	s_waitcnt vmcnt(0)
	v_fma_f32 v134, v134, v114, v106
	v_fma_f32 v135, v135, v115, v107
	v_fma_f32 v170, v170, v112, v104
	v_fma_f32 v171, v171, v113, v105
.LBB0_656:
	v_lshlrev_b64 v[104:105], 11, v[168:169]
	v_mov_b32_e32 v106, v120
	v_mov_b32_e32 v107, v120
	v_mul_f32_e32 v108, v120, v108
	v_mul_f32_e32 v109, v121, v109
	v_lshl_add_u64 v[104:105], v[122:123], 0, v[104:105]
	v_mul_f32_e32 v110, v106, v110
	v_mul_f32_e32 v111, v107, v111
	v_cvt_pk_bf16_f32 v108, v108, v109
	v_mov_b32_e32 v133, v132
	v_cvt_pk_bf16_f32 v109, v110, v111
	v_mul_f32_e32 v134, v106, v134
	v_mul_f32_e32 v135, v107, v135
	v_mul_f32_e32 v168, v120, v170
	v_mul_f32_e32 v169, v121, v171
	v_mul_f32_e32 v100, v100, v132
	v_mul_f32_e32 v101, v101, v133
	v_cvt_pk_bf16_f32 v110, v168, v169
	v_cvt_pk_bf16_f32 v111, v134, v135
	global_store_dwordx4 v[104:105], v[108:111], off
	s_and_b64 vcc, exec, s[12:13]
	v_mul_f32_e32 v96, v96, v132
	v_mul_f32_e32 v97, v97, v133
	v_mov_b32_e32 v108, v132
	v_mov_b32_e32 v109, v132
	v_mul_f32_e32 v102, v102, v108
	v_mul_f32_e32 v103, v103, v109
	v_mul_f32_e32 v98, v98, v108
	v_mul_f32_e32 v99, v99, v109
	s_cbranch_vccnz .LBB0_658
	ds_bpermute_b32 v108, v198, v100
	ds_bpermute_b32 v109, v198, v101
	ds_bpermute_b32 v110, v198, v96
	ds_bpermute_b32 v132, v198, v102
	ds_bpermute_b32 v133, v198, v103
	ds_bpermute_b32 v111, v198, v97
	ds_bpermute_b32 v134, v198, v98
	ds_bpermute_b32 v135, v198, v99
	s_waitcnt lgkmcnt(6)
	v_mul_f32_e32 v108, v128, v108
	v_mul_f32_e32 v109, v129, v109
	s_waitcnt lgkmcnt(3)
	v_mul_f32_e32 v128, v130, v132
	v_mul_f32_e32 v129, v131, v133
	s_waitcnt vmcnt(2)
	v_fma_f32 v100, v100, v116, v108
	v_fma_f32 v101, v101, v117, v109
	s_waitcnt lgkmcnt(2)
	v_mul_f32_e32 v108, v126, v110
	v_mul_f32_e32 v109, v127, v111
	s_waitcnt lgkmcnt(0)
	v_mul_f32_e32 v110, v124, v134
	v_mul_f32_e32 v111, v125, v135
	v_fma_f32 v102, v102, v118, v128
	v_fma_f32 v103, v103, v119, v129
	s_waitcnt vmcnt(1)
	v_fma_f32 v98, v98, v114, v110
	v_fma_f32 v99, v99, v115, v111
	v_fma_f32 v96, v96, v112, v108
	v_fma_f32 v97, v97, v113, v109
.LBB0_658:
	v_mul_f32_e32 v102, v106, v102
	v_mul_f32_e32 v103, v107, v103
	v_mul_f32_e32 v106, v106, v98
	v_mul_f32_e32 v107, v107, v99
	v_mul_f32_e32 v98, v120, v96
	v_mul_f32_e32 v99, v121, v97
	v_mul_f32_e32 v100, v120, v100
	v_mul_f32_e32 v101, v121, v101
	v_mov_b32_e32 v108, 0
	v_cvt_pk_bf16_f32 v96, v100, v101
	v_cvt_pk_bf16_f32 v97, v102, v103
	v_cvt_pk_bf16_f32 v98, v98, v99
	v_cvt_pk_bf16_f32 v99, v106, v107
	global_store_dwordx4 v[104:105], v[96:99], off offset:256
	v_mov_b32_e32 v100, 1.0
	v_mov_b32_e32 v101, 1.0
	v_mov_b32_e32 v102, 1.0
	v_mov_b32_e32 v103, 1.0
	v_mov_b32_e32 v96, 1.0
	v_mov_b32_e32 v97, 1.0
	v_mov_b32_e32 v98, 1.0
	v_mov_b32_e32 v99, 1.0
	v_mov_b32_e32 v109, 0
	v_mov_b32_e32 v110, 0
	v_mov_b32_e32 v111, 0
	v_mov_b32_e32 v106, 0
	v_mov_b32_e32 v107, 0
	v_mov_b32_e32 v104, 0
	v_mov_b32_e32 v105, 0
	s_and_saveexec_b64 s[4:5], s[46:47]
	s_cbranch_execz .LBB0_660
	v_lshlrev_b32_e32 v96, 6, v166
	v_and_b32_e32 v96, 0x7fbc0, v96
	global_load_dwordx4 v[104:107], v96, s[28:29] offset:32
	global_load_dwordx4 v[112:115], v96, s[28:29] offset:48
	global_load_dwordx4 v[100:103], v96, s[28:29]
	s_nop 0
	global_load_dwordx4 v[96:99], v96, s[28:29] offset:16
	s_waitcnt vmcnt(3)
	v_xor_b32_e32 v111, 0x80000000, v107
	v_xor_b32_e32 v110, 0x80000000, v106
	v_xor_b32_e32 v109, 0x80000000, v105
	v_xor_b32_e32 v108, 0x80000000, v104
	s_waitcnt vmcnt(2)
	v_xor_b32_e32 v116, 0x80000000, v115
	v_xor_b32_e32 v117, 0x80000000, v114
	v_xor_b32_e32 v118, 0x80000000, v113
	v_xor_b32_e32 v119, 0x80000000, v112
	v_cndmask_b32_e64 v108, v104, v108, s[8:9]
	v_cndmask_b32_e64 v109, v105, v109, s[8:9]
	v_cndmask_b32_e64 v110, v106, v110, s[8:9]
	v_cndmask_b32_e64 v111, v107, v111, s[8:9]
	v_cndmask_b32_e64 v106, v112, v119, s[8:9]
	v_cndmask_b32_e64 v107, v113, v118, s[8:9]
	v_cndmask_b32_e64 v104, v114, v117, s[8:9]
	v_cndmask_b32_e64 v105, v115, v116, s[8:9]
.LBB0_660:
	s_or_b64 exec, exec, s[4:5]
	s_waitcnt vmcnt(2) lgkmcnt(5)
	v_add_f32_e32 v112, v211, v212
	v_fmamk_f32 v112, v112, 0x3a800000, v195
	v_rsq_f32_e32 v112, v112
	s_nop 0
	v_mul_f32_e32 v94, v94, v112
	v_mul_f32_e32 v95, v95, v112
	v_mul_f32_e32 v92, v92, v112
	v_mul_f32_e32 v93, v93, v112
	v_mul_f32_e32 v114, v90, v112
	v_mul_f32_e32 v115, v91, v112
	s_and_b64 vcc, exec, s[12:13]
	v_mul_f32_e32 v116, v88, v112
	v_mul_f32_e32 v117, v89, v112
	s_cbranch_vccnz .LBB0_662
	ds_bpermute_b32 v88, v198, v92
	ds_bpermute_b32 v89, v198, v93
	ds_bpermute_b32 v90, v198, v116
	ds_bpermute_b32 v118, v198, v94
	ds_bpermute_b32 v119, v198, v95
	ds_bpermute_b32 v91, v198, v117
	ds_bpermute_b32 v124, v198, v114
	ds_bpermute_b32 v125, v198, v115
	s_waitcnt lgkmcnt(6)
	v_mul_f32_e32 v88, v108, v88
	v_mul_f32_e32 v89, v109, v89
	s_waitcnt lgkmcnt(3)
	v_mul_f32_e32 v118, v110, v118
	v_mul_f32_e32 v119, v111, v119
	s_waitcnt vmcnt(1)
	v_fma_f32 v92, v92, v100, v88
	v_fma_f32 v93, v93, v101, v89
	s_waitcnt lgkmcnt(2)
	v_mul_f32_e32 v88, v106, v90
	v_mul_f32_e32 v89, v107, v91
	s_waitcnt lgkmcnt(0)
	v_mul_f32_e32 v90, v104, v124
	v_mul_f32_e32 v91, v105, v125
	v_fma_f32 v94, v94, v102, v118
	v_fma_f32 v95, v95, v103, v119
	s_waitcnt vmcnt(0)
	v_fma_f32 v114, v114, v98, v90
	v_fma_f32 v115, v115, v99, v91
	v_fma_f32 v116, v116, v96, v88
	v_fma_f32 v117, v117, v97, v89
.LBB0_662:
	v_lshlrev_b64 v[88:89], 11, v[166:167]
	v_mov_b32_e32 v90, v120
	v_mov_b32_e32 v91, v120
	v_mul_f32_e32 v92, v120, v92
	v_mul_f32_e32 v93, v121, v93
	v_lshl_add_u64 v[88:89], v[122:123], 0, v[88:89]
	v_mul_f32_e32 v94, v90, v94
	v_mul_f32_e32 v95, v91, v95
	v_cvt_pk_bf16_f32 v92, v92, v93
	v_mov_b32_e32 v113, v112
	v_cvt_pk_bf16_f32 v93, v94, v95
	v_mul_f32_e32 v114, v90, v114
	v_mul_f32_e32 v115, v91, v115
	v_mul_f32_e32 v116, v120, v116
	v_mul_f32_e32 v117, v121, v117
	v_mul_f32_e32 v84, v84, v112
	v_mul_f32_e32 v85, v85, v113
	v_cvt_pk_bf16_f32 v94, v116, v117
	v_cvt_pk_bf16_f32 v95, v114, v115
	global_store_dwordx4 v[88:89], v[92:95], off
	s_and_b64 vcc, exec, s[12:13]
	v_mul_f32_e32 v80, v80, v112
	v_mul_f32_e32 v81, v81, v113
	v_mov_b32_e32 v92, v112
	v_mov_b32_e32 v93, v112
	v_mul_f32_e32 v86, v86, v92
	v_mul_f32_e32 v87, v87, v93
	v_mul_f32_e32 v82, v82, v92
	v_mul_f32_e32 v83, v83, v93
	s_cbranch_vccnz .LBB0_664
	ds_bpermute_b32 v92, v198, v84
	ds_bpermute_b32 v93, v198, v85
	ds_bpermute_b32 v94, v198, v80
	ds_bpermute_b32 v112, v198, v86
	ds_bpermute_b32 v113, v198, v87
	ds_bpermute_b32 v95, v198, v81
	ds_bpermute_b32 v114, v198, v82
	ds_bpermute_b32 v115, v198, v83
	s_waitcnt lgkmcnt(6)
	v_mul_f32_e32 v92, v108, v92
	v_mul_f32_e32 v93, v109, v93
	s_waitcnt lgkmcnt(3)
	v_mul_f32_e32 v108, v110, v112
	v_mul_f32_e32 v109, v111, v113
	s_waitcnt vmcnt(2)
	v_fma_f32 v84, v84, v100, v92
	v_fma_f32 v85, v85, v101, v93
	s_waitcnt lgkmcnt(2)
	v_mul_f32_e32 v92, v106, v94
	v_mul_f32_e32 v93, v107, v95
	s_waitcnt lgkmcnt(0)
	v_mul_f32_e32 v94, v104, v114
	v_mul_f32_e32 v95, v105, v115
	v_fma_f32 v86, v86, v102, v108
	v_fma_f32 v87, v87, v103, v109
	s_waitcnt vmcnt(1)
	v_fma_f32 v82, v82, v98, v94
	v_fma_f32 v83, v83, v99, v95
	v_fma_f32 v80, v80, v96, v92
	v_fma_f32 v81, v81, v97, v93
.LBB0_664:
	v_mul_f32_e32 v86, v90, v86
	v_mul_f32_e32 v87, v91, v87
	v_mul_f32_e32 v90, v90, v82
	v_mul_f32_e32 v91, v91, v83
	v_mul_f32_e32 v82, v120, v80
	v_mul_f32_e32 v83, v121, v81
	v_mul_f32_e32 v84, v120, v84
	v_mul_f32_e32 v85, v121, v85
	v_mov_b32_e32 v92, 0
	v_cvt_pk_bf16_f32 v80, v84, v85
	v_cvt_pk_bf16_f32 v81, v86, v87
	v_cvt_pk_bf16_f32 v82, v82, v83
	v_cvt_pk_bf16_f32 v83, v90, v91
	global_store_dwordx4 v[88:89], v[80:83], off offset:256
	v_mov_b32_e32 v84, 1.0
	v_mov_b32_e32 v85, 1.0
	v_mov_b32_e32 v86, 1.0
	v_mov_b32_e32 v87, 1.0
	v_mov_b32_e32 v80, 1.0
	v_mov_b32_e32 v81, 1.0
	v_mov_b32_e32 v82, 1.0
	v_mov_b32_e32 v83, 1.0
	v_mov_b32_e32 v93, 0
	v_mov_b32_e32 v94, 0
	v_mov_b32_e32 v95, 0
	v_mov_b32_e32 v90, 0
	v_mov_b32_e32 v91, 0
	v_mov_b32_e32 v88, 0
	v_mov_b32_e32 v89, 0
	s_and_saveexec_b64 s[4:5], s[46:47]
	s_cbranch_execz .LBB0_666
	v_lshlrev_b32_e32 v80, 6, v164
	v_and_b32_e32 v80, 0x7ffc0, v80
	global_load_dwordx4 v[88:91], v80, s[28:29] offset:32
	global_load_dwordx4 v[96:99], v80, s[28:29] offset:48
	global_load_dwordx4 v[84:87], v80, s[28:29]
	s_nop 0
	global_load_dwordx4 v[80:83], v80, s[28:29] offset:16
	s_waitcnt vmcnt(3)
	v_xor_b32_e32 v95, 0x80000000, v91
	v_xor_b32_e32 v94, 0x80000000, v90
	v_xor_b32_e32 v93, 0x80000000, v89
	v_xor_b32_e32 v92, 0x80000000, v88
	s_waitcnt vmcnt(2)
	v_xor_b32_e32 v100, 0x80000000, v99
	v_xor_b32_e32 v101, 0x80000000, v98
	v_xor_b32_e32 v102, 0x80000000, v97
	v_xor_b32_e32 v103, 0x80000000, v96
	v_cndmask_b32_e64 v92, v88, v92, s[8:9]
	v_cndmask_b32_e64 v93, v89, v93, s[8:9]
	v_cndmask_b32_e64 v94, v90, v94, s[8:9]
	v_cndmask_b32_e64 v95, v91, v95, s[8:9]
	v_cndmask_b32_e64 v90, v96, v103, s[8:9]
	v_cndmask_b32_e64 v91, v97, v102, s[8:9]
	v_cndmask_b32_e64 v88, v98, v101, s[8:9]
	v_cndmask_b32_e64 v89, v99, v100, s[8:9]
.LBB0_666:
	s_or_b64 exec, exec, s[4:5]
	s_waitcnt vmcnt(2) lgkmcnt(4)
	v_add_f32_e32 v96, v209, v210
	v_fmamk_f32 v96, v96, 0x3a800000, v195
	v_rsq_f32_e32 v96, v96
	s_nop 0
	v_mul_f32_e32 v78, v78, v96
	v_mul_f32_e32 v79, v79, v96
	v_mul_f32_e32 v76, v76, v96
	v_mul_f32_e32 v77, v77, v96
	v_mul_f32_e32 v98, v74, v96
	v_mul_f32_e32 v99, v75, v96
	s_and_b64 vcc, exec, s[12:13]
	v_mul_f32_e32 v100, v72, v96
	v_mul_f32_e32 v101, v73, v96
	s_cbranch_vccnz .LBB0_668
	ds_bpermute_b32 v72, v198, v76
	ds_bpermute_b32 v73, v198, v77
	ds_bpermute_b32 v74, v198, v100
	ds_bpermute_b32 v102, v198, v78
	ds_bpermute_b32 v103, v198, v79
	ds_bpermute_b32 v75, v198, v101
	ds_bpermute_b32 v104, v198, v98
	ds_bpermute_b32 v105, v198, v99
	s_waitcnt lgkmcnt(6)
	v_mul_f32_e32 v72, v92, v72
	v_mul_f32_e32 v73, v93, v73
	s_waitcnt lgkmcnt(3)
	v_mul_f32_e32 v102, v94, v102
	v_mul_f32_e32 v103, v95, v103
	s_waitcnt vmcnt(1)
	v_fma_f32 v76, v76, v84, v72
	v_fma_f32 v77, v77, v85, v73
	s_waitcnt lgkmcnt(2)
	v_mul_f32_e32 v72, v90, v74
	v_mul_f32_e32 v73, v91, v75
	s_waitcnt lgkmcnt(0)
	v_mul_f32_e32 v74, v88, v104
	v_mul_f32_e32 v75, v89, v105
	v_fma_f32 v78, v78, v86, v102
	v_fma_f32 v79, v79, v87, v103
	s_waitcnt vmcnt(0)
	v_fma_f32 v98, v98, v82, v74
	v_fma_f32 v99, v99, v83, v75
	v_fma_f32 v100, v100, v80, v72
	v_fma_f32 v101, v101, v81, v73
.LBB0_668:
	v_lshlrev_b64 v[72:73], 11, v[164:165]
	v_mov_b32_e32 v74, v120
	v_mov_b32_e32 v75, v120
	v_mul_f32_e32 v76, v120, v76
	v_mul_f32_e32 v77, v121, v77
	v_lshl_add_u64 v[72:73], v[122:123], 0, v[72:73]
	v_mul_f32_e32 v78, v74, v78
	v_mul_f32_e32 v79, v75, v79
	v_cvt_pk_bf16_f32 v76, v76, v77
	v_mov_b32_e32 v97, v96
	v_cvt_pk_bf16_f32 v77, v78, v79
	v_mul_f32_e32 v98, v74, v98
	v_mul_f32_e32 v99, v75, v99
	v_mul_f32_e32 v100, v120, v100
	v_mul_f32_e32 v101, v121, v101
	v_mul_f32_e32 v68, v68, v96
	v_mul_f32_e32 v69, v69, v97
	v_cvt_pk_bf16_f32 v78, v100, v101
	v_cvt_pk_bf16_f32 v79, v98, v99
	global_store_dwordx4 v[72:73], v[76:79], off
	s_and_b64 vcc, exec, s[12:13]
	v_mul_f32_e32 v64, v64, v96
	v_mul_f32_e32 v65, v65, v97
	v_mov_b32_e32 v76, v96
	v_mov_b32_e32 v77, v96
	v_mul_f32_e32 v70, v70, v76
	v_mul_f32_e32 v71, v71, v77
	v_mul_f32_e32 v66, v66, v76
	v_mul_f32_e32 v67, v67, v77
	s_cbranch_vccnz .LBB0_670
	ds_bpermute_b32 v76, v198, v68
	ds_bpermute_b32 v77, v198, v69
	ds_bpermute_b32 v78, v198, v64
	ds_bpermute_b32 v96, v198, v70
	ds_bpermute_b32 v97, v198, v71
	ds_bpermute_b32 v79, v198, v65
	ds_bpermute_b32 v98, v198, v66
	ds_bpermute_b32 v99, v198, v67
	s_waitcnt lgkmcnt(6)
	v_mul_f32_e32 v76, v92, v76
	v_mul_f32_e32 v77, v93, v77
	s_waitcnt lgkmcnt(3)
	v_mul_f32_e32 v92, v94, v96
	v_mul_f32_e32 v93, v95, v97
	s_waitcnt vmcnt(2)
	v_fma_f32 v68, v68, v84, v76
	v_fma_f32 v69, v69, v85, v77
	s_waitcnt lgkmcnt(2)
	v_mul_f32_e32 v76, v90, v78
	v_mul_f32_e32 v77, v91, v79
	s_waitcnt lgkmcnt(0)
	v_mul_f32_e32 v78, v88, v98
	v_mul_f32_e32 v79, v89, v99
	v_fma_f32 v70, v70, v86, v92
	v_fma_f32 v71, v71, v87, v93
	s_waitcnt vmcnt(1)
	v_fma_f32 v66, v66, v82, v78
	v_fma_f32 v67, v67, v83, v79
	v_fma_f32 v64, v64, v80, v76
	v_fma_f32 v65, v65, v81, v77
.LBB0_670:
	v_mul_f32_e32 v70, v74, v70
	v_mul_f32_e32 v71, v75, v71
	v_mul_f32_e32 v74, v74, v66
	v_mul_f32_e32 v75, v75, v67
	v_mul_f32_e32 v66, v120, v64
	v_mul_f32_e32 v67, v121, v65
	v_mul_f32_e32 v68, v120, v68
	v_mul_f32_e32 v69, v121, v69
	v_mov_b32_e32 v76, 0
	v_cvt_pk_bf16_f32 v64, v68, v69
	v_cvt_pk_bf16_f32 v65, v70, v71
	v_cvt_pk_bf16_f32 v66, v66, v67
	v_cvt_pk_bf16_f32 v67, v74, v75
	global_store_dwordx4 v[72:73], v[64:67], off offset:256
	v_mov_b32_e32 v68, 1.0
	v_mov_b32_e32 v69, 1.0
	v_mov_b32_e32 v70, 1.0
	v_mov_b32_e32 v71, 1.0
	v_mov_b32_e32 v64, 1.0
	v_mov_b32_e32 v65, 1.0
	v_mov_b32_e32 v66, 1.0
	v_mov_b32_e32 v67, 1.0
	v_mov_b32_e32 v77, 0
	v_mov_b32_e32 v78, 0
	v_mov_b32_e32 v79, 0
	v_mov_b32_e32 v74, 0
	v_mov_b32_e32 v75, 0
	v_mov_b32_e32 v72, 0
	v_mov_b32_e32 v73, 0
	s_and_saveexec_b64 s[4:5], s[46:47]
	s_cbranch_execz .LBB0_672
	v_lshlrev_b32_e32 v64, 6, v162
	v_and_b32_e32 v64, 0x7f3c0, v64
	global_load_dwordx4 v[72:75], v64, s[28:29] offset:32
	global_load_dwordx4 v[80:83], v64, s[28:29] offset:48
	global_load_dwordx4 v[68:71], v64, s[28:29]
	s_nop 0
	global_load_dwordx4 v[64:67], v64, s[28:29] offset:16
	s_waitcnt vmcnt(3)
	v_xor_b32_e32 v79, 0x80000000, v75
	v_xor_b32_e32 v78, 0x80000000, v74
	v_xor_b32_e32 v77, 0x80000000, v73
	v_xor_b32_e32 v76, 0x80000000, v72
	s_waitcnt vmcnt(2)
	v_xor_b32_e32 v84, 0x80000000, v83
	v_xor_b32_e32 v85, 0x80000000, v82
	v_xor_b32_e32 v86, 0x80000000, v81
	v_xor_b32_e32 v87, 0x80000000, v80
	v_cndmask_b32_e64 v76, v72, v76, s[8:9]
	v_cndmask_b32_e64 v77, v73, v77, s[8:9]
	v_cndmask_b32_e64 v78, v74, v78, s[8:9]
	v_cndmask_b32_e64 v79, v75, v79, s[8:9]
	v_cndmask_b32_e64 v74, v80, v87, s[8:9]
	v_cndmask_b32_e64 v75, v81, v86, s[8:9]
	v_cndmask_b32_e64 v72, v82, v85, s[8:9]
	v_cndmask_b32_e64 v73, v83, v84, s[8:9]
.LBB0_672:
	s_or_b64 exec, exec, s[4:5]
	s_waitcnt vmcnt(2) lgkmcnt(3)
	v_add_f32_e32 v80, v207, v208
	v_fmamk_f32 v80, v80, 0x3a800000, v195
	v_rsq_f32_e32 v80, v80
	s_nop 0
	v_mul_f32_e32 v62, v62, v80
	v_mul_f32_e32 v63, v63, v80
	v_mul_f32_e32 v60, v60, v80
	v_mul_f32_e32 v61, v61, v80
	v_mul_f32_e32 v82, v58, v80
	v_mul_f32_e32 v83, v59, v80
	s_and_b64 vcc, exec, s[12:13]
	v_mul_f32_e32 v84, v56, v80
	v_mul_f32_e32 v85, v57, v80
	s_cbranch_vccnz .LBB0_674
	ds_bpermute_b32 v56, v198, v60
	ds_bpermute_b32 v57, v198, v61
	ds_bpermute_b32 v58, v198, v84
	ds_bpermute_b32 v86, v198, v62
	ds_bpermute_b32 v87, v198, v63
	ds_bpermute_b32 v59, v198, v85
	ds_bpermute_b32 v88, v198, v82
	ds_bpermute_b32 v89, v198, v83
	s_waitcnt lgkmcnt(6)
	v_mul_f32_e32 v56, v76, v56
	v_mul_f32_e32 v57, v77, v57
	s_waitcnt lgkmcnt(3)
	v_mul_f32_e32 v86, v78, v86
	v_mul_f32_e32 v87, v79, v87
	s_waitcnt vmcnt(1)
	v_fma_f32 v60, v60, v68, v56
	v_fma_f32 v61, v61, v69, v57
	s_waitcnt lgkmcnt(2)
	v_mul_f32_e32 v56, v74, v58
	v_mul_f32_e32 v57, v75, v59
	s_waitcnt lgkmcnt(0)
	v_mul_f32_e32 v58, v72, v88
	v_mul_f32_e32 v59, v73, v89
	v_fma_f32 v62, v62, v70, v86
	v_fma_f32 v63, v63, v71, v87
	s_waitcnt vmcnt(0)
	v_fma_f32 v82, v82, v66, v58
	v_fma_f32 v83, v83, v67, v59
	v_fma_f32 v84, v84, v64, v56
	v_fma_f32 v85, v85, v65, v57
.LBB0_674:
	v_lshlrev_b64 v[56:57], 11, v[162:163]
	v_mov_b32_e32 v58, v120
	v_mov_b32_e32 v59, v120
	v_mul_f32_e32 v60, v120, v60
	v_mul_f32_e32 v61, v121, v61
	v_lshl_add_u64 v[56:57], v[122:123], 0, v[56:57]
	v_mul_f32_e32 v62, v58, v62
	v_mul_f32_e32 v63, v59, v63
	v_cvt_pk_bf16_f32 v60, v60, v61
	v_mov_b32_e32 v81, v80
	v_cvt_pk_bf16_f32 v61, v62, v63
	v_mul_f32_e32 v82, v58, v82
	v_mul_f32_e32 v83, v59, v83
	v_mul_f32_e32 v84, v120, v84
	v_mul_f32_e32 v85, v121, v85
	v_mul_f32_e32 v52, v52, v80
	v_mul_f32_e32 v53, v53, v81
	v_cvt_pk_bf16_f32 v62, v84, v85
	v_cvt_pk_bf16_f32 v63, v82, v83
	global_store_dwordx4 v[56:57], v[60:63], off
	s_and_b64 vcc, exec, s[12:13]
	v_mul_f32_e32 v48, v48, v80
	v_mul_f32_e32 v49, v49, v81
	v_mov_b32_e32 v60, v80
	v_mov_b32_e32 v61, v80
	v_mul_f32_e32 v54, v54, v60
	v_mul_f32_e32 v55, v55, v61
	v_mul_f32_e32 v50, v50, v60
	v_mul_f32_e32 v51, v51, v61
	s_cbranch_vccnz .LBB0_676
	ds_bpermute_b32 v60, v198, v52
	ds_bpermute_b32 v61, v198, v53
	ds_bpermute_b32 v62, v198, v48
	ds_bpermute_b32 v80, v198, v54
	ds_bpermute_b32 v81, v198, v55
	ds_bpermute_b32 v63, v198, v49
	ds_bpermute_b32 v82, v198, v50
	ds_bpermute_b32 v83, v198, v51
	s_waitcnt lgkmcnt(6)
	v_mul_f32_e32 v60, v76, v60
	v_mul_f32_e32 v61, v77, v61
	s_waitcnt lgkmcnt(3)
	v_mul_f32_e32 v76, v78, v80
	v_mul_f32_e32 v77, v79, v81
	s_waitcnt vmcnt(2)
	v_fma_f32 v52, v52, v68, v60
	v_fma_f32 v53, v53, v69, v61
	s_waitcnt lgkmcnt(2)
	v_mul_f32_e32 v60, v74, v62
	v_mul_f32_e32 v61, v75, v63
	s_waitcnt lgkmcnt(0)
	v_mul_f32_e32 v62, v72, v82
	v_mul_f32_e32 v63, v73, v83
	v_fma_f32 v54, v54, v70, v76
	v_fma_f32 v55, v55, v71, v77
	s_waitcnt vmcnt(1)
	v_fma_f32 v50, v50, v66, v62
	v_fma_f32 v51, v51, v67, v63
	v_fma_f32 v48, v48, v64, v60
	v_fma_f32 v49, v49, v65, v61
.LBB0_676:
	v_mul_f32_e32 v54, v58, v54
	v_mul_f32_e32 v55, v59, v55
	v_mul_f32_e32 v58, v58, v50
	v_mul_f32_e32 v59, v59, v51
	v_mul_f32_e32 v50, v120, v48
	v_mul_f32_e32 v51, v121, v49
	v_mul_f32_e32 v52, v120, v52
	v_mul_f32_e32 v53, v121, v53
	v_mov_b32_e32 v60, 0
	v_cvt_pk_bf16_f32 v48, v52, v53
	v_cvt_pk_bf16_f32 v49, v54, v55
	v_cvt_pk_bf16_f32 v50, v50, v51
	v_cvt_pk_bf16_f32 v51, v58, v59
	global_store_dwordx4 v[56:57], v[48:51], off offset:256
	v_mov_b32_e32 v52, 1.0
	v_mov_b32_e32 v53, 1.0
	v_mov_b32_e32 v54, 1.0
	v_mov_b32_e32 v55, 1.0
	v_mov_b32_e32 v48, 1.0
	v_mov_b32_e32 v49, 1.0
	v_mov_b32_e32 v50, 1.0
	v_mov_b32_e32 v51, 1.0
	v_mov_b32_e32 v61, 0
	v_mov_b32_e32 v62, 0
	v_mov_b32_e32 v63, 0
	v_mov_b32_e32 v58, 0
	v_mov_b32_e32 v59, 0
	v_mov_b32_e32 v56, 0
	v_mov_b32_e32 v57, 0
	s_and_saveexec_b64 s[4:5], s[46:47]
	s_cbranch_execz .LBB0_678
	v_lshlrev_b32_e32 v48, 6, v160
	v_and_b32_e32 v48, 0x7f7c0, v48
	global_load_dwordx4 v[56:59], v48, s[28:29] offset:32
	global_load_dwordx4 v[64:67], v48, s[28:29] offset:48
	global_load_dwordx4 v[52:55], v48, s[28:29]
	s_nop 0
	global_load_dwordx4 v[48:51], v48, s[28:29] offset:16
	s_waitcnt vmcnt(3)
	v_xor_b32_e32 v63, 0x80000000, v59
	v_xor_b32_e32 v62, 0x80000000, v58
	v_xor_b32_e32 v61, 0x80000000, v57
	v_xor_b32_e32 v60, 0x80000000, v56
	s_waitcnt vmcnt(2)
	v_xor_b32_e32 v68, 0x80000000, v67
	v_xor_b32_e32 v69, 0x80000000, v66
	v_xor_b32_e32 v70, 0x80000000, v65
	v_xor_b32_e32 v71, 0x80000000, v64
	v_cndmask_b32_e64 v60, v56, v60, s[8:9]
	v_cndmask_b32_e64 v61, v57, v61, s[8:9]
	v_cndmask_b32_e64 v62, v58, v62, s[8:9]
	v_cndmask_b32_e64 v63, v59, v63, s[8:9]
	v_cndmask_b32_e64 v58, v64, v71, s[8:9]
	v_cndmask_b32_e64 v59, v65, v70, s[8:9]
	v_cndmask_b32_e64 v56, v66, v69, s[8:9]
	v_cndmask_b32_e64 v57, v67, v68, s[8:9]
.LBB0_678:
	s_or_b64 exec, exec, s[4:5]
	s_waitcnt vmcnt(2) lgkmcnt(2)
	v_add_f32_e32 v64, v205, v206
	v_fmamk_f32 v64, v64, 0x3a800000, v195
	v_rsq_f32_e32 v64, v64
	s_nop 0
	v_mul_f32_e32 v46, v46, v64
	v_mul_f32_e32 v47, v47, v64
	v_mul_f32_e32 v44, v44, v64
	v_mul_f32_e32 v45, v45, v64
	v_mul_f32_e32 v66, v42, v64
	v_mul_f32_e32 v67, v43, v64
	s_and_b64 vcc, exec, s[12:13]
	v_mul_f32_e32 v68, v40, v64
	v_mul_f32_e32 v69, v41, v64
	s_cbranch_vccnz .LBB0_680
	ds_bpermute_b32 v40, v198, v44
	ds_bpermute_b32 v41, v198, v45
	ds_bpermute_b32 v42, v198, v68
	ds_bpermute_b32 v70, v198, v46
	ds_bpermute_b32 v71, v198, v47
	ds_bpermute_b32 v43, v198, v69
	ds_bpermute_b32 v72, v198, v66
	ds_bpermute_b32 v73, v198, v67
	s_waitcnt lgkmcnt(6)
	v_mul_f32_e32 v40, v60, v40
	v_mul_f32_e32 v41, v61, v41
	s_waitcnt lgkmcnt(3)
	v_mul_f32_e32 v70, v62, v70
	v_mul_f32_e32 v71, v63, v71
	s_waitcnt vmcnt(1)
	v_fma_f32 v44, v44, v52, v40
	v_fma_f32 v45, v45, v53, v41
	s_waitcnt lgkmcnt(2)
	v_mul_f32_e32 v40, v58, v42
	v_mul_f32_e32 v41, v59, v43
	s_waitcnt lgkmcnt(0)
	v_mul_f32_e32 v42, v56, v72
	v_mul_f32_e32 v43, v57, v73
	v_fma_f32 v46, v46, v54, v70
	v_fma_f32 v47, v47, v55, v71
	s_waitcnt vmcnt(0)
	v_fma_f32 v66, v66, v50, v42
	v_fma_f32 v67, v67, v51, v43
	v_fma_f32 v68, v68, v48, v40
	v_fma_f32 v69, v69, v49, v41
.LBB0_680:
	v_lshlrev_b64 v[40:41], 11, v[160:161]
	v_mov_b32_e32 v42, v120
	v_mov_b32_e32 v43, v120
	v_mul_f32_e32 v44, v120, v44
	v_mul_f32_e32 v45, v121, v45
	v_lshl_add_u64 v[40:41], v[122:123], 0, v[40:41]
	v_mul_f32_e32 v46, v42, v46
	v_mul_f32_e32 v47, v43, v47
	v_cvt_pk_bf16_f32 v44, v44, v45
	v_mov_b32_e32 v65, v64
	v_cvt_pk_bf16_f32 v45, v46, v47
	v_mul_f32_e32 v66, v42, v66
	v_mul_f32_e32 v67, v43, v67
	v_mul_f32_e32 v68, v120, v68
	v_mul_f32_e32 v69, v121, v69
	v_mul_f32_e32 v36, v36, v64
	v_mul_f32_e32 v37, v37, v65
	v_cvt_pk_bf16_f32 v46, v68, v69
	v_cvt_pk_bf16_f32 v47, v66, v67
	global_store_dwordx4 v[40:41], v[44:47], off
	s_and_b64 vcc, exec, s[12:13]
	v_mul_f32_e32 v32, v32, v64
	v_mul_f32_e32 v33, v33, v65
	v_mov_b32_e32 v44, v64
	v_mov_b32_e32 v45, v64
	v_mul_f32_e32 v38, v38, v44
	v_mul_f32_e32 v39, v39, v45
	v_mul_f32_e32 v34, v34, v44
	v_mul_f32_e32 v35, v35, v45
	s_cbranch_vccnz .LBB0_682
	ds_bpermute_b32 v44, v198, v36
	ds_bpermute_b32 v45, v198, v37
	ds_bpermute_b32 v46, v198, v32
	ds_bpermute_b32 v64, v198, v38
	ds_bpermute_b32 v65, v198, v39
	ds_bpermute_b32 v47, v198, v33
	ds_bpermute_b32 v66, v198, v34
	ds_bpermute_b32 v67, v198, v35
	s_waitcnt lgkmcnt(6)
	v_mul_f32_e32 v44, v60, v44
	v_mul_f32_e32 v45, v61, v45
	s_waitcnt lgkmcnt(3)
	v_mul_f32_e32 v60, v62, v64
	v_mul_f32_e32 v61, v63, v65
	s_waitcnt vmcnt(2)
	v_fma_f32 v36, v36, v52, v44
	v_fma_f32 v37, v37, v53, v45
	s_waitcnt lgkmcnt(2)
	v_mul_f32_e32 v44, v58, v46
	v_mul_f32_e32 v45, v59, v47
	s_waitcnt lgkmcnt(0)
	v_mul_f32_e32 v46, v56, v66
	v_mul_f32_e32 v47, v57, v67
	v_fma_f32 v38, v38, v54, v60
	v_fma_f32 v39, v39, v55, v61
	s_waitcnt vmcnt(1)
	v_fma_f32 v34, v34, v50, v46
	v_fma_f32 v35, v35, v51, v47
	v_fma_f32 v32, v32, v48, v44
	v_fma_f32 v33, v33, v49, v45
.LBB0_682:
	v_mul_f32_e32 v38, v42, v38
	v_mul_f32_e32 v39, v43, v39
	v_mul_f32_e32 v42, v42, v34
	v_mul_f32_e32 v43, v43, v35
	v_mul_f32_e32 v34, v120, v32
	v_mul_f32_e32 v35, v121, v33
	v_mul_f32_e32 v36, v120, v36
	v_mul_f32_e32 v37, v121, v37
	v_mov_b32_e32 v44, 0
	v_cvt_pk_bf16_f32 v32, v36, v37
	v_cvt_pk_bf16_f32 v33, v38, v39
	v_cvt_pk_bf16_f32 v34, v34, v35
	v_cvt_pk_bf16_f32 v35, v42, v43
	global_store_dwordx4 v[40:41], v[32:35], off offset:256
	v_mov_b32_e32 v36, 1.0
	v_mov_b32_e32 v37, 1.0
	v_mov_b32_e32 v38, 1.0
	v_mov_b32_e32 v39, 1.0
	v_mov_b32_e32 v32, 1.0
	v_mov_b32_e32 v33, 1.0
	v_mov_b32_e32 v34, 1.0
	v_mov_b32_e32 v35, 1.0
	v_mov_b32_e32 v45, 0
	v_mov_b32_e32 v46, 0
	v_mov_b32_e32 v47, 0
	v_mov_b32_e32 v42, 0
	v_mov_b32_e32 v43, 0
	v_mov_b32_e32 v40, 0
	v_mov_b32_e32 v41, 0
	s_and_saveexec_b64 s[4:5], s[46:47]
	s_cbranch_execz .LBB0_684
	v_lshlrev_b32_e32 v32, 6, v158
	v_and_b32_e32 v32, 0x7fbc0, v32
	global_load_dwordx4 v[40:43], v32, s[28:29] offset:32
	global_load_dwordx4 v[48:51], v32, s[28:29] offset:48
	global_load_dwordx4 v[36:39], v32, s[28:29]
	s_nop 0
	global_load_dwordx4 v[32:35], v32, s[28:29] offset:16
	s_waitcnt vmcnt(3)
	v_xor_b32_e32 v47, 0x80000000, v43
	v_xor_b32_e32 v46, 0x80000000, v42
	v_xor_b32_e32 v45, 0x80000000, v41
	v_xor_b32_e32 v44, 0x80000000, v40
	s_waitcnt vmcnt(2)
	v_xor_b32_e32 v52, 0x80000000, v51
	v_xor_b32_e32 v53, 0x80000000, v50
	v_xor_b32_e32 v54, 0x80000000, v49
	v_xor_b32_e32 v55, 0x80000000, v48
	v_cndmask_b32_e64 v44, v40, v44, s[8:9]
	v_cndmask_b32_e64 v45, v41, v45, s[8:9]
	v_cndmask_b32_e64 v46, v42, v46, s[8:9]
	v_cndmask_b32_e64 v47, v43, v47, s[8:9]
	v_cndmask_b32_e64 v42, v48, v55, s[8:9]
	v_cndmask_b32_e64 v43, v49, v54, s[8:9]
	v_cndmask_b32_e64 v40, v50, v53, s[8:9]
	v_cndmask_b32_e64 v41, v51, v52, s[8:9]
.LBB0_684:
	s_or_b64 exec, exec, s[4:5]
	s_waitcnt vmcnt(2) lgkmcnt(1)
	v_add_f32_e32 v48, v201, v204
	v_fmamk_f32 v48, v48, 0x3a800000, v195
	v_rsq_f32_e32 v48, v48
	s_nop 0
	v_mul_f32_e32 v30, v30, v48
	v_mul_f32_e32 v31, v31, v48
	v_mul_f32_e32 v28, v28, v48
	v_mul_f32_e32 v29, v29, v48
	v_mul_f32_e32 v50, v26, v48
	v_mul_f32_e32 v51, v27, v48
	s_and_b64 vcc, exec, s[12:13]
	v_mul_f32_e32 v52, v24, v48
	v_mul_f32_e32 v53, v25, v48
	s_cbranch_vccnz .LBB0_686
	ds_bpermute_b32 v24, v198, v28
	ds_bpermute_b32 v25, v198, v29
	ds_bpermute_b32 v26, v198, v52
	ds_bpermute_b32 v54, v198, v30
	ds_bpermute_b32 v55, v198, v31
	ds_bpermute_b32 v27, v198, v53
	ds_bpermute_b32 v56, v198, v50
	ds_bpermute_b32 v57, v198, v51
	s_waitcnt lgkmcnt(6)
	v_mul_f32_e32 v24, v44, v24
	v_mul_f32_e32 v25, v45, v25
	s_waitcnt lgkmcnt(3)
	v_mul_f32_e32 v54, v46, v54
	v_mul_f32_e32 v55, v47, v55
	s_waitcnt vmcnt(1)
	v_fma_f32 v28, v28, v36, v24
	v_fma_f32 v29, v29, v37, v25
	s_waitcnt lgkmcnt(2)
	v_mul_f32_e32 v24, v42, v26
	v_mul_f32_e32 v25, v43, v27
	s_waitcnt lgkmcnt(0)
	v_mul_f32_e32 v26, v40, v56
	v_mul_f32_e32 v27, v41, v57
	v_fma_f32 v30, v30, v38, v54
	v_fma_f32 v31, v31, v39, v55
	s_waitcnt vmcnt(0)
	v_fma_f32 v50, v50, v34, v26
	v_fma_f32 v51, v51, v35, v27
	v_fma_f32 v52, v52, v32, v24
	v_fma_f32 v53, v53, v33, v25
.LBB0_686:
	v_lshlrev_b64 v[24:25], 11, v[158:159]
	v_mov_b32_e32 v26, v120
	v_mov_b32_e32 v27, v120
	v_mul_f32_e32 v28, v120, v28
	v_mul_f32_e32 v29, v121, v29
	v_lshl_add_u64 v[24:25], v[122:123], 0, v[24:25]
	v_mul_f32_e32 v30, v26, v30
	v_mul_f32_e32 v31, v27, v31
	v_cvt_pk_bf16_f32 v28, v28, v29
	v_mov_b32_e32 v49, v48
	v_cvt_pk_bf16_f32 v29, v30, v31
	v_mul_f32_e32 v50, v26, v50
	v_mul_f32_e32 v51, v27, v51
	v_mul_f32_e32 v52, v120, v52
	v_mul_f32_e32 v53, v121, v53
	v_mul_f32_e32 v20, v20, v48
	v_mul_f32_e32 v21, v21, v49
	v_cvt_pk_bf16_f32 v30, v52, v53
	v_cvt_pk_bf16_f32 v31, v50, v51
	global_store_dwordx4 v[24:25], v[28:31], off
	s_and_b64 vcc, exec, s[12:13]
	v_mul_f32_e32 v16, v16, v48
	v_mul_f32_e32 v17, v17, v49
	v_mov_b32_e32 v28, v48
	v_mov_b32_e32 v29, v48
	v_mul_f32_e32 v22, v22, v28
	v_mul_f32_e32 v23, v23, v29
	v_mul_f32_e32 v18, v18, v28
	v_mul_f32_e32 v19, v19, v29
	s_cbranch_vccnz .LBB0_688
	ds_bpermute_b32 v28, v198, v20
	ds_bpermute_b32 v29, v198, v21
	ds_bpermute_b32 v30, v198, v16
	ds_bpermute_b32 v48, v198, v22
	ds_bpermute_b32 v49, v198, v23
	ds_bpermute_b32 v31, v198, v17
	ds_bpermute_b32 v50, v198, v18
	ds_bpermute_b32 v51, v198, v19
	s_waitcnt lgkmcnt(6)
	v_mul_f32_e32 v28, v44, v28
	v_mul_f32_e32 v29, v45, v29
	s_waitcnt lgkmcnt(3)
	v_mul_f32_e32 v44, v46, v48
	v_mul_f32_e32 v45, v47, v49
	s_waitcnt vmcnt(2)
	v_fma_f32 v20, v20, v36, v28
	v_fma_f32 v21, v21, v37, v29
	s_waitcnt lgkmcnt(2)
	v_mul_f32_e32 v28, v42, v30
	v_mul_f32_e32 v29, v43, v31
	s_waitcnt lgkmcnt(0)
	v_mul_f32_e32 v30, v40, v50
	v_mul_f32_e32 v31, v41, v51
	v_fma_f32 v22, v22, v38, v44
	v_fma_f32 v23, v23, v39, v45
	s_waitcnt vmcnt(1)
	v_fma_f32 v18, v18, v34, v30
	v_fma_f32 v19, v19, v35, v31
	v_fma_f32 v16, v16, v32, v28
	v_fma_f32 v17, v17, v33, v29
.LBB0_688:
	v_mul_f32_e32 v22, v26, v22
	v_mul_f32_e32 v23, v27, v23
	v_mul_f32_e32 v26, v26, v18
	v_mul_f32_e32 v27, v27, v19
	v_mul_f32_e32 v18, v120, v16
	v_mul_f32_e32 v19, v121, v17
	v_mul_f32_e32 v20, v120, v20
	v_mul_f32_e32 v21, v121, v21
	v_mov_b32_e32 v28, 0
	v_cvt_pk_bf16_f32 v16, v20, v21
	v_cvt_pk_bf16_f32 v17, v22, v23
	v_cvt_pk_bf16_f32 v18, v18, v19
	v_cvt_pk_bf16_f32 v19, v26, v27
	global_store_dwordx4 v[24:25], v[16:19], off offset:256
	v_mov_b32_e32 v20, 1.0
	v_mov_b32_e32 v21, 1.0
	v_mov_b32_e32 v22, 1.0
	v_mov_b32_e32 v23, 1.0
	v_mov_b32_e32 v16, 1.0
	v_mov_b32_e32 v17, 1.0
	v_mov_b32_e32 v18, 1.0
	v_mov_b32_e32 v19, 1.0
	v_mov_b32_e32 v29, 0
	v_mov_b32_e32 v30, 0
	v_mov_b32_e32 v31, 0
	v_mov_b32_e32 v26, 0
	v_mov_b32_e32 v27, 0
	v_mov_b32_e32 v24, 0
	v_mov_b32_e32 v25, 0
	s_and_saveexec_b64 s[4:5], s[46:47]
	s_cbranch_execz .LBB0_690
	v_lshlrev_b32_e32 v16, 6, v156
	v_and_b32_e32 v16, 0x7ffc0, v16
	global_load_dwordx4 v[24:27], v16, s[28:29] offset:32
	global_load_dwordx4 v[32:35], v16, s[28:29] offset:48
	global_load_dwordx4 v[20:23], v16, s[28:29]
	s_nop 0
	global_load_dwordx4 v[16:19], v16, s[28:29] offset:16
	s_waitcnt vmcnt(3)
	v_xor_b32_e32 v31, 0x80000000, v27
	v_xor_b32_e32 v30, 0x80000000, v26
	v_xor_b32_e32 v29, 0x80000000, v25
	v_xor_b32_e32 v28, 0x80000000, v24
	s_waitcnt vmcnt(2)
	v_xor_b32_e32 v36, 0x80000000, v35
	v_xor_b32_e32 v37, 0x80000000, v34
	v_xor_b32_e32 v38, 0x80000000, v33
	v_xor_b32_e32 v39, 0x80000000, v32
	v_cndmask_b32_e64 v28, v24, v28, s[8:9]
	v_cndmask_b32_e64 v29, v25, v29, s[8:9]
	v_cndmask_b32_e64 v30, v26, v30, s[8:9]
	v_cndmask_b32_e64 v31, v27, v31, s[8:9]
	v_cndmask_b32_e64 v26, v32, v39, s[8:9]
	v_cndmask_b32_e64 v27, v33, v38, s[8:9]
	v_cndmask_b32_e64 v24, v34, v37, s[8:9]
	v_cndmask_b32_e64 v25, v35, v36, s[8:9]
.LBB0_690:
	s_or_b64 exec, exec, s[4:5]
	s_waitcnt vmcnt(2) lgkmcnt(0)
	v_add_f32_e32 v32, v199, v200
	v_fmamk_f32 v32, v32, 0x3a800000, v195
	v_rsq_f32_e32 v32, v32
	s_nop 0
	v_mul_f32_e32 v14, v14, v32
	v_mul_f32_e32 v15, v15, v32
	v_mul_f32_e32 v12, v12, v32
	v_mul_f32_e32 v13, v13, v32
	v_mul_f32_e32 v34, v10, v32
	v_mul_f32_e32 v35, v11, v32
	s_and_b64 vcc, exec, s[12:13]
	v_mul_f32_e32 v36, v8, v32
	v_mul_f32_e32 v37, v9, v32
	s_cbranch_vccnz .LBB0_692
	ds_bpermute_b32 v8, v198, v12
	ds_bpermute_b32 v9, v198, v13
	ds_bpermute_b32 v10, v198, v36
	ds_bpermute_b32 v38, v198, v14
	ds_bpermute_b32 v39, v198, v15
	ds_bpermute_b32 v11, v198, v37
	ds_bpermute_b32 v40, v198, v34
	ds_bpermute_b32 v41, v198, v35
	s_waitcnt lgkmcnt(6)
	v_mul_f32_e32 v8, v28, v8
	v_mul_f32_e32 v9, v29, v9
	s_waitcnt lgkmcnt(3)
	v_mul_f32_e32 v38, v30, v38
	v_mul_f32_e32 v39, v31, v39
	s_waitcnt vmcnt(1)
	v_fma_f32 v12, v12, v20, v8
	v_fma_f32 v13, v13, v21, v9
	s_waitcnt lgkmcnt(2)
	v_mul_f32_e32 v8, v26, v10
	v_mul_f32_e32 v9, v27, v11
	s_waitcnt lgkmcnt(0)
	v_mul_f32_e32 v10, v24, v40
	v_mul_f32_e32 v11, v25, v41
	v_fma_f32 v14, v14, v22, v38
	v_fma_f32 v15, v15, v23, v39
	s_waitcnt vmcnt(0)
	v_fma_f32 v34, v34, v18, v10
	v_fma_f32 v35, v35, v19, v11
	v_fma_f32 v36, v36, v16, v8
	v_fma_f32 v37, v37, v17, v9
.LBB0_692:
	v_lshlrev_b64 v[8:9], 11, v[156:157]
	v_mov_b32_e32 v10, v120
	v_mov_b32_e32 v11, v120
	v_mul_f32_e32 v12, v120, v12
	v_mul_f32_e32 v13, v121, v13
	v_lshl_add_u64 v[8:9], v[122:123], 0, v[8:9]
	v_mul_f32_e32 v14, v10, v14
	v_mul_f32_e32 v15, v11, v15
	v_cvt_pk_bf16_f32 v12, v12, v13
	v_mov_b32_e32 v33, v32
	v_cvt_pk_bf16_f32 v13, v14, v15
	v_mul_f32_e32 v34, v10, v34
	v_mul_f32_e32 v35, v11, v35
	v_mul_f32_e32 v36, v120, v36
	v_mul_f32_e32 v37, v121, v37
	v_mul_f32_e32 v4, v4, v32
	v_mul_f32_e32 v5, v5, v33
	v_cvt_pk_bf16_f32 v14, v36, v37
	v_cvt_pk_bf16_f32 v15, v34, v35
	global_store_dwordx4 v[8:9], v[12:15], off
	s_and_b64 vcc, exec, s[12:13]
	v_mul_f32_e32 v0, v0, v32
	v_mul_f32_e32 v1, v1, v33
	v_mov_b32_e32 v12, v32
	v_mov_b32_e32 v13, v32
	v_mul_f32_e32 v6, v6, v12
	v_mul_f32_e32 v7, v7, v13
	v_mul_f32_e32 v2, v2, v12
	v_mul_f32_e32 v3, v3, v13
	s_cbranch_vccnz .LBB0_694
	ds_bpermute_b32 v12, v198, v4
	ds_bpermute_b32 v13, v198, v5
	ds_bpermute_b32 v14, v198, v0
	ds_bpermute_b32 v32, v198, v6
	ds_bpermute_b32 v33, v198, v7
	ds_bpermute_b32 v15, v198, v1
	ds_bpermute_b32 v34, v198, v2
	ds_bpermute_b32 v35, v198, v3
	s_waitcnt lgkmcnt(6)
	v_mul_f32_e32 v12, v28, v12
	v_mul_f32_e32 v13, v29, v13
	s_waitcnt lgkmcnt(3)
	v_mul_f32_e32 v28, v30, v32
	v_mul_f32_e32 v29, v31, v33
	s_waitcnt vmcnt(2)
	v_fma_f32 v4, v4, v20, v12
	v_fma_f32 v5, v5, v21, v13
	s_waitcnt lgkmcnt(2)
	v_mul_f32_e32 v12, v26, v14
	v_mul_f32_e32 v13, v27, v15
	s_waitcnt lgkmcnt(0)
	v_mul_f32_e32 v14, v24, v34
	v_mul_f32_e32 v15, v25, v35
	v_fma_f32 v6, v6, v22, v28
	v_fma_f32 v7, v7, v23, v29
	s_waitcnt vmcnt(1)
	v_fma_f32 v2, v2, v18, v14
	v_fma_f32 v3, v3, v19, v15
	v_fma_f32 v0, v0, v16, v12
	v_fma_f32 v1, v1, v17, v13
.LBB0_694:
	v_mul_f32_e32 v6, v10, v6
	v_mul_f32_e32 v7, v11, v7
	v_mul_f32_e32 v10, v10, v2
	v_mul_f32_e32 v11, v11, v3
	v_mul_f32_e32 v2, v120, v0
	v_mul_f32_e32 v3, v121, v1
	s_andn2_b64 vcc, exec, s[10:11]
	s_mov_b64 s[4:5], -1
	v_mul_f32_e32 v4, v120, v4
	v_mul_f32_e32 v5, v121, v5
	s_nop 0
	v_cvt_pk_bf16_f32 v0, v4, v5
	v_cvt_pk_bf16_f32 v1, v6, v7
	v_cvt_pk_bf16_f32 v2, v2, v3
	v_cvt_pk_bf16_f32 v3, v10, v11
	global_store_dwordx4 v[8:9], v[0:3], off offset:256
	s_cbranch_vccnz .LBB0_639
	s_andn2_b64 vcc, exec, s[26:27]
	s_cbranch_vccnz .LBB0_638
	s_barrier
	s_branch .LBB0_638

.LBB0_969:
	v_lshl_or_b32 v168, s10, 8, v188
	v_lshl_add_u32 v172, s40, 8, v186
	v_ashrrev_i32_e32 v169, 31, v168
	v_lshlrev_b64 v[204:205], 1, v[168:169]
	v_ashrrev_i32_e32 v173, 31, v172
	v_lshl_add_u64 v[170:171], s[16:17], 0, v[204:205]
	v_lshlrev_b64 v[206:207], 11, v[172:173]
	v_lshl_add_u64 v[128:129], v[170:171], 0, v[206:207]
	global_load_dwordx4 v[192:195], v[128:129], off
	global_load_dwordx4 v[198:201], v[128:129], off offset:256
	v_or_b32_e32 v182, 16, v172
	v_or_b32_e32 v178, 32, v172
	v_or_b32_e32 v174, 48, v172
	v_ashrrev_i32_e32 v183, 31, v182
	v_ashrrev_i32_e32 v179, 31, v178
	v_ashrrev_i32_e32 v175, 31, v174
	v_lshlrev_b64 v[184:185], 11, v[182:183]
	v_lshlrev_b64 v[180:181], 11, v[178:179]
	v_lshlrev_b64 v[176:177], 11, v[174:175]
	v_lshl_add_u64 v[128:129], v[170:171], 0, v[184:185]
	v_lshl_add_u64 v[130:131], v[170:171], 0, v[180:181]
	v_lshl_add_u64 v[208:209], v[170:171], 0, v[176:177]
	global_load_dwordx4 v[148:151], v[128:129], off
	global_load_dwordx4 v[144:147], v[128:129], off offset:256
	global_load_dwordx4 v[140:143], v[130:131], off
	global_load_dwordx4 v[136:139], v[130:131], off offset:256
	global_load_dwordx4 v[132:135], v[208:209], off
	s_nop 0
	global_load_dwordx4 v[128:131], v[208:209], off offset:256
	s_lshl_b32 s40, s10, 2
	s_ashr_i32 s41, s40, 31
	s_waitcnt vmcnt(0)
	v_lshlrev_b32_e32 v208, 16, v192
	v_and_b32_e32 v209, 0xffff0000, v192
	v_lshlrev_b32_e32 v192, 16, v193
	v_and_b32_e32 v193, 0xffff0000, v193
	v_lshlrev_b32_e32 v210, 16, v194
	v_and_b32_e32 v211, 0xffff0000, v194
	v_lshlrev_b32_e32 v194, 16, v195
	v_and_b32_e32 v195, 0xffff0000, v195
	v_lshlrev_b32_e32 v212, 16, v198
	v_and_b32_e32 v213, 0xffff0000, v198
	v_lshlrev_b32_e32 v198, 16, v199
	v_and_b32_e32 v199, 0xffff0000, v199
	v_lshlrev_b32_e32 v214, 16, v200
	v_and_b32_e32 v215, 0xffff0000, v200
	v_lshlrev_b32_e32 v200, 16, v201
	v_and_b32_e32 v201, 0xffff0000, v201
	v_add_f32_e32 v126, v126, v192
	v_add_f32_e32 v127, v127, v193
	v_add_f32_e32 v124, v124, v208
	v_add_f32_e32 v125, v125, v209
	v_add_f32_e32 v122, v122, v194
	v_add_f32_e32 v123, v123, v195
	v_add_f32_e32 v120, v120, v210
	v_add_f32_e32 v121, v121, v211
	v_add_f32_e32 v118, v118, v198
	v_add_f32_e32 v119, v119, v199
	v_add_f32_e32 v116, v116, v212
	v_add_f32_e32 v117, v117, v213
	v_add_f32_e32 v192, v114, v200
	v_add_f32_e32 v193, v115, v201
	v_add_f32_e32 v194, v112, v214
	v_add_f32_e32 v195, v113, v215
	v_mul_f32_e32 v198, v125, v125
	v_mul_f32_e32 v199, v127, v127
	v_mul_f32_e32 v200, v121, v121
	v_mul_f32_e32 v201, v123, v123
	v_cvt_pk_bf16_f32 v112, v124, v125
	v_cvt_pk_bf16_f32 v113, v126, v127
	v_cvt_pk_bf16_f32 v114, v120, v121
	v_cvt_pk_bf16_f32 v115, v122, v123
	v_mul_f32_e32 v121, v117, v117
	v_mul_f32_e32 v123, v119, v119
	v_mul_f32_e32 v125, v195, v195
	v_mul_f32_e32 v127, v193, v193
	v_fmac_f32_e32 v198, v124, v124
	v_fmac_f32_e32 v199, v126, v126
	v_fmac_f32_e32 v200, v120, v120
	v_fmac_f32_e32 v201, v122, v122
	v_fmac_f32_e32 v121, v116, v116
	v_fmac_f32_e32 v123, v118, v118
	v_fmac_f32_e32 v125, v194, v194
	v_fmac_f32_e32 v127, v192, v192
	v_add_f32_e32 v120, v198, v199
	v_add_f32_e32 v122, v200, v201
	v_add_f32_e32 v121, v121, v123
	v_add_f32_e32 v123, v125, v127
	v_add_f32_e32 v120, v120, v122
	v_add_f32_e32 v121, v121, v123
	v_add_f32_e32 v122, v120, v121
	ds_bpermute_b32 v123, v196, v122
	v_lshl_add_u64 v[120:121], s[16:17], 0, v[206:207]
	v_lshl_add_u64 v[120:121], v[120:121], 0, v[204:205]
	global_store_dwordx4 v[120:121], v[112:115], off
	s_waitcnt lgkmcnt(0)
	s_nop 0
	v_add_f32_e32 v112, v122, v123
	ds_bpermute_b32 v113, v197, v112
	v_cvt_pk_bf16_f32 v114, v116, v117
	v_cvt_pk_bf16_f32 v115, v118, v119
	v_cvt_pk_bf16_f32 v116, v194, v195
	v_cvt_pk_bf16_f32 v117, v192, v193
	global_store_dwordx4 v[120:121], v[114:117], off offset:256
	s_and_saveexec_b64 s[4:5], s[6:7]
	s_cbranch_execz .LBB0_971
	v_lshlrev_b64 v[114:115], 6, v[172:173]
	v_lshl_add_u64 v[114:115], s[24:25], 0, v[114:115]
	v_lshl_add_u64 v[114:115], s[40:41], 2, v[114:115]
	s_lshl_b32 s10, s49, 2
	v_lshl_add_u64 v[114:115], v[114:115], 0, s[10:11]
	s_waitcnt lgkmcnt(0)
	v_add_f32_e32 v112, v112, v113
	global_store_dword v[114:115], v112, off
.LBB0_971:
	s_or_b64 exec, exec, s[4:5]
	v_lshlrev_b32_e32 v112, 16, v148
	s_waitcnt lgkmcnt(0)
	v_and_b32_e32 v113, 0xffff0000, v148
	v_lshlrev_b32_e32 v114, 16, v149
	v_and_b32_e32 v115, 0xffff0000, v149
	v_lshlrev_b32_e32 v116, 16, v150
	v_and_b32_e32 v117, 0xffff0000, v150
	v_lshlrev_b32_e32 v118, 16, v151
	v_and_b32_e32 v119, 0xffff0000, v151
	v_add_f32_e32 v110, v110, v114
	v_add_f32_e32 v111, v111, v115
	v_add_f32_e32 v108, v108, v112
	v_add_f32_e32 v109, v109, v113
	v_add_f32_e32 v112, v106, v118
	v_add_f32_e32 v113, v107, v119
	v_add_f32_e32 v106, v104, v116
	v_add_f32_e32 v107, v105, v117
	v_mul_f32_e32 v104, v109, v109
	v_mul_f32_e32 v105, v111, v111
	v_fmac_f32_e32 v104, v108, v108
	v_fmac_f32_e32 v105, v110, v110
	v_add_f32_e32 v104, v104, v105
	v_mul_f32_e32 v105, v107, v107
	v_mul_f32_e32 v114, v113, v113
	v_fmac_f32_e32 v105, v106, v106
	v_fmac_f32_e32 v114, v112, v112
	v_add_f32_e32 v105, v105, v114
	v_add_f32_e32 v116, v104, v105
	v_cvt_pk_bf16_f32 v104, v108, v109
	v_cvt_pk_bf16_f32 v105, v110, v111
	v_lshlrev_b32_e32 v108, 16, v144
	v_and_b32_e32 v109, 0xffff0000, v144
	v_lshlrev_b32_e32 v110, 16, v145
	v_and_b32_e32 v111, 0xffff0000, v145
	v_cvt_pk_bf16_f32 v106, v106, v107
	v_cvt_pk_bf16_f32 v107, v112, v113
	v_lshlrev_b32_e32 v112, 16, v146
	v_and_b32_e32 v113, 0xffff0000, v146
	v_add_f32_e32 v102, v102, v110
	v_add_f32_e32 v103, v103, v111
	v_add_f32_e32 v100, v100, v108
	v_add_f32_e32 v101, v101, v109
	v_lshlrev_b32_e32 v114, 16, v147
	v_and_b32_e32 v115, 0xffff0000, v147
	v_add_f32_e32 v110, v96, v112
	v_add_f32_e32 v111, v97, v113
	v_mul_f32_e32 v96, v101, v101
	v_mul_f32_e32 v97, v103, v103
	v_add_f32_e32 v108, v98, v114
	v_add_f32_e32 v109, v99, v115
	v_fmac_f32_e32 v96, v100, v100
	v_fmac_f32_e32 v97, v102, v102
	v_add_f32_e32 v96, v96, v97
	v_mul_f32_e32 v97, v111, v111
	v_mul_f32_e32 v98, v109, v109
	v_fmac_f32_e32 v97, v110, v110
	v_fmac_f32_e32 v98, v108, v108
	v_add_f32_e32 v97, v97, v98
	v_add_f32_e32 v96, v96, v97
	v_add_f32_e32 v99, v116, v96
	ds_bpermute_b32 v114, v196, v99
	v_lshl_add_u64 v[96:97], s[16:17], 0, v[184:185]
	v_lshl_add_u64 v[112:113], v[168:169], 1, v[96:97]
	global_store_dwordx4 v[112:113], v[104:107], off
	v_cvt_pk_bf16_f32 v98, v100, v101
	s_waitcnt lgkmcnt(0)
	v_add_f32_e32 v96, v99, v114
	ds_bpermute_b32 v97, v197, v96
	v_cvt_pk_bf16_f32 v99, v102, v103
	v_cvt_pk_bf16_f32 v100, v110, v111
	v_cvt_pk_bf16_f32 v101, v108, v109
	global_store_dwordx4 v[112:113], v[98:101], off offset:256
	s_and_saveexec_b64 s[4:5], s[6:7]
	s_cbranch_execz .LBB0_973
	v_lshlrev_b64 v[98:99], 6, v[182:183]
	v_lshl_add_u64 v[98:99], s[24:25], 0, v[98:99]
	v_lshl_add_u64 v[98:99], s[40:41], 2, v[98:99]
	s_lshl_b32 s10, s49, 2
	v_lshl_add_u64 v[98:99], v[98:99], 0, s[10:11]
	s_waitcnt lgkmcnt(0)
	v_add_f32_e32 v96, v96, v97
	global_store_dword v[98:99], v96, off
.LBB0_973:
	s_or_b64 exec, exec, s[4:5]
	v_lshlrev_b32_e32 v96, 16, v140
	s_waitcnt lgkmcnt(0)
	v_and_b32_e32 v97, 0xffff0000, v140
	v_lshlrev_b32_e32 v98, 16, v141
	v_and_b32_e32 v99, 0xffff0000, v141
	v_lshlrev_b32_e32 v100, 16, v142
	v_and_b32_e32 v101, 0xffff0000, v142
	v_lshlrev_b32_e32 v102, 16, v143
	v_and_b32_e32 v103, 0xffff0000, v143
	v_add_f32_e32 v94, v94, v98
	v_add_f32_e32 v95, v95, v99
	v_add_f32_e32 v92, v92, v96
	v_add_f32_e32 v93, v93, v97
	v_add_f32_e32 v96, v90, v102
	v_add_f32_e32 v97, v91, v103
	v_add_f32_e32 v90, v88, v100
	v_add_f32_e32 v91, v89, v101
	v_mul_f32_e32 v88, v93, v93
	v_mul_f32_e32 v89, v95, v95
	v_fmac_f32_e32 v88, v92, v92
	v_fmac_f32_e32 v89, v94, v94
	v_add_f32_e32 v88, v88, v89
	v_mul_f32_e32 v89, v91, v91
	v_mul_f32_e32 v98, v97, v97
	v_fmac_f32_e32 v89, v90, v90
	v_fmac_f32_e32 v98, v96, v96
	v_add_f32_e32 v89, v89, v98
	v_add_f32_e32 v100, v88, v89
	v_cvt_pk_bf16_f32 v88, v92, v93
	v_cvt_pk_bf16_f32 v89, v94, v95
	v_lshlrev_b32_e32 v92, 16, v136
	v_and_b32_e32 v93, 0xffff0000, v136
	v_lshlrev_b32_e32 v94, 16, v137
	v_and_b32_e32 v95, 0xffff0000, v137
	v_cvt_pk_bf16_f32 v90, v90, v91
	v_cvt_pk_bf16_f32 v91, v96, v97
	v_lshlrev_b32_e32 v96, 16, v138
	v_and_b32_e32 v97, 0xffff0000, v138
	v_add_f32_e32 v86, v86, v94
	v_add_f32_e32 v87, v87, v95
	v_add_f32_e32 v84, v84, v92
	v_add_f32_e32 v85, v85, v93
	v_lshlrev_b32_e32 v98, 16, v139
	v_and_b32_e32 v99, 0xffff0000, v139
	v_add_f32_e32 v94, v80, v96
	v_add_f32_e32 v95, v81, v97
	v_mul_f32_e32 v80, v85, v85
	v_mul_f32_e32 v81, v87, v87
	v_add_f32_e32 v92, v82, v98
	v_add_f32_e32 v93, v83, v99
	v_fmac_f32_e32 v80, v84, v84
	v_fmac_f32_e32 v81, v86, v86
	v_add_f32_e32 v80, v80, v81
	v_mul_f32_e32 v81, v95, v95
	v_mul_f32_e32 v82, v93, v93
	v_fmac_f32_e32 v81, v94, v94
	v_fmac_f32_e32 v82, v92, v92
	v_add_f32_e32 v81, v81, v82
	v_add_f32_e32 v80, v80, v81
	v_add_f32_e32 v83, v100, v80
	ds_bpermute_b32 v98, v196, v83
	v_lshl_add_u64 v[80:81], s[16:17], 0, v[180:181]
	v_lshl_add_u64 v[96:97], v[168:169], 1, v[80:81]
	global_store_dwordx4 v[96:97], v[88:91], off
	v_cvt_pk_bf16_f32 v82, v84, v85
	s_waitcnt lgkmcnt(0)
	v_add_f32_e32 v80, v83, v98
	ds_bpermute_b32 v81, v197, v80
	v_cvt_pk_bf16_f32 v83, v86, v87
	v_cvt_pk_bf16_f32 v84, v94, v95
	v_cvt_pk_bf16_f32 v85, v92, v93
	global_store_dwordx4 v[96:97], v[82:85], off offset:256
	s_and_saveexec_b64 s[4:5], s[6:7]
	s_cbranch_execz .LBB0_975
	v_lshlrev_b64 v[82:83], 6, v[178:179]
	v_lshl_add_u64 v[82:83], s[24:25], 0, v[82:83]
	v_lshl_add_u64 v[82:83], s[40:41], 2, v[82:83]
	s_lshl_b32 s10, s49, 2
	v_lshl_add_u64 v[82:83], v[82:83], 0, s[10:11]
	s_waitcnt lgkmcnt(0)
	v_add_f32_e32 v80, v80, v81
	global_store_dword v[82:83], v80, off
.LBB0_975:
	s_or_b64 exec, exec, s[4:5]
	v_lshlrev_b32_e32 v80, 16, v132
	s_waitcnt lgkmcnt(0)
	v_and_b32_e32 v81, 0xffff0000, v132
	v_lshlrev_b32_e32 v82, 16, v133
	v_and_b32_e32 v83, 0xffff0000, v133
	v_lshlrev_b32_e32 v84, 16, v134
	v_and_b32_e32 v85, 0xffff0000, v134
	v_lshlrev_b32_e32 v86, 16, v135
	v_and_b32_e32 v87, 0xffff0000, v135
	v_add_f32_e32 v78, v78, v82
	v_add_f32_e32 v79, v79, v83
	v_add_f32_e32 v76, v76, v80
	v_add_f32_e32 v77, v77, v81
	v_add_f32_e32 v80, v74, v86
	v_add_f32_e32 v81, v75, v87
	v_add_f32_e32 v74, v72, v84
	v_add_f32_e32 v75, v73, v85
	v_mul_f32_e32 v72, v77, v77
	v_mul_f32_e32 v73, v79, v79
	v_fmac_f32_e32 v72, v76, v76
	v_fmac_f32_e32 v73, v78, v78
	v_add_f32_e32 v72, v72, v73
	v_mul_f32_e32 v73, v75, v75
	v_mul_f32_e32 v82, v81, v81
	v_fmac_f32_e32 v73, v74, v74
	v_fmac_f32_e32 v82, v80, v80
	v_add_f32_e32 v73, v73, v82
	v_add_f32_e32 v84, v72, v73
	v_cvt_pk_bf16_f32 v72, v76, v77
	v_cvt_pk_bf16_f32 v73, v78, v79
	v_lshlrev_b32_e32 v76, 16, v128
	v_and_b32_e32 v77, 0xffff0000, v128
	v_lshlrev_b32_e32 v78, 16, v129
	v_and_b32_e32 v79, 0xffff0000, v129
	v_cvt_pk_bf16_f32 v74, v74, v75
	v_cvt_pk_bf16_f32 v75, v80, v81
	v_lshlrev_b32_e32 v80, 16, v130
	v_and_b32_e32 v81, 0xffff0000, v130
	v_add_f32_e32 v70, v70, v78
	v_add_f32_e32 v71, v71, v79
	v_add_f32_e32 v68, v68, v76
	v_add_f32_e32 v69, v69, v77
	v_lshlrev_b32_e32 v82, 16, v131
	v_and_b32_e32 v83, 0xffff0000, v131
	v_add_f32_e32 v78, v64, v80
	v_add_f32_e32 v79, v65, v81
	v_mul_f32_e32 v64, v69, v69
	v_mul_f32_e32 v65, v71, v71
	v_add_f32_e32 v76, v66, v82
	v_add_f32_e32 v77, v67, v83
	v_fmac_f32_e32 v64, v68, v68
	v_fmac_f32_e32 v65, v70, v70
	v_add_f32_e32 v64, v64, v65
	v_mul_f32_e32 v65, v79, v79
	v_mul_f32_e32 v66, v77, v77
	v_fmac_f32_e32 v65, v78, v78
	v_fmac_f32_e32 v66, v76, v76
	v_add_f32_e32 v65, v65, v66
	v_add_f32_e32 v64, v64, v65
	v_add_f32_e32 v67, v84, v64
	ds_bpermute_b32 v82, v196, v67
	v_lshl_add_u64 v[64:65], s[16:17], 0, v[176:177]
	v_lshl_add_u64 v[80:81], v[168:169], 1, v[64:65]
	global_store_dwordx4 v[80:81], v[72:75], off
	v_cvt_pk_bf16_f32 v66, v68, v69
	s_waitcnt lgkmcnt(0)
	v_add_f32_e32 v64, v67, v82
	ds_bpermute_b32 v65, v197, v64
	v_cvt_pk_bf16_f32 v67, v70, v71
	v_cvt_pk_bf16_f32 v68, v78, v79
	v_cvt_pk_bf16_f32 v69, v76, v77
	global_store_dwordx4 v[80:81], v[66:69], off offset:256
	s_and_saveexec_b64 s[4:5], s[6:7]
	s_cbranch_execz .LBB0_977
	v_lshlrev_b64 v[66:67], 6, v[174:175]
	v_lshl_add_u64 v[66:67], s[24:25], 0, v[66:67]
	v_lshl_add_u64 v[66:67], s[40:41], 2, v[66:67]
	s_lshl_b32 s10, s49, 2
	v_lshl_add_u64 v[66:67], v[66:67], 0, s[10:11]
	s_waitcnt lgkmcnt(0)
	v_add_f32_e32 v64, v64, v65
	global_store_dword v[66:67], v64, off
.LBB0_977:
	s_or_b64 exec, exec, s[4:5]
	v_add_u32_e32 v100, 0x80, v172
	v_ashrrev_i32_e32 v101, 31, v100
	v_lshlrev_b64 v[110:111], 11, v[100:101]
	s_waitcnt lgkmcnt(0)
	v_lshl_add_u64 v[64:65], v[170:171], 0, v[110:111]
	global_load_dwordx4 v[102:105], v[64:65], off
	global_load_dwordx4 v[106:109], v[64:65], off offset:256
	v_add_u32_e32 v96, 0x90, v172
	v_add_u32_e32 v92, 0xa0, v172
	v_add_u32_e32 v88, 0xb0, v172
	v_ashrrev_i32_e32 v97, 31, v96
	v_ashrrev_i32_e32 v93, 31, v92
	v_ashrrev_i32_e32 v89, 31, v88
	v_lshlrev_b64 v[98:99], 11, v[96:97]
	v_lshlrev_b64 v[94:95], 11, v[92:93]
	v_lshlrev_b64 v[90:91], 11, v[88:89]
	v_lshl_add_u64 v[64:65], v[170:171], 0, v[98:99]
	v_lshl_add_u64 v[66:67], v[170:171], 0, v[94:95]
	v_lshl_add_u64 v[112:113], v[170:171], 0, v[90:91]
	global_load_dwordx4 v[84:87], v[64:65], off
	global_load_dwordx4 v[80:83], v[64:65], off offset:256
	global_load_dwordx4 v[76:79], v[66:67], off
	global_load_dwordx4 v[72:75], v[66:67], off offset:256
	global_load_dwordx4 v[68:71], v[112:113], off
	s_nop 0
	global_load_dwordx4 v[64:67], v[112:113], off offset:256
	s_waitcnt vmcnt(7)
	v_lshlrev_b32_e32 v112, 16, v102
	v_and_b32_e32 v113, 0xffff0000, v102
	v_lshlrev_b32_e32 v102, 16, v103
	v_and_b32_e32 v103, 0xffff0000, v103
	v_lshlrev_b32_e32 v114, 16, v104
	v_and_b32_e32 v115, 0xffff0000, v104
	v_lshlrev_b32_e32 v104, 16, v105
	v_and_b32_e32 v105, 0xffff0000, v105
	s_waitcnt vmcnt(6)
	v_lshlrev_b32_e32 v116, 16, v106
	v_and_b32_e32 v117, 0xffff0000, v106
	v_lshlrev_b32_e32 v106, 16, v107
	v_and_b32_e32 v107, 0xffff0000, v107
	v_lshlrev_b32_e32 v118, 16, v108
	v_and_b32_e32 v119, 0xffff0000, v108
	v_lshlrev_b32_e32 v108, 16, v109
	v_and_b32_e32 v109, 0xffff0000, v109
	v_add_f32_e32 v62, v62, v102
	v_add_f32_e32 v63, v63, v103
	v_add_f32_e32 v60, v60, v112
	v_add_f32_e32 v61, v61, v113
	v_add_f32_e32 v58, v58, v104
	v_add_f32_e32 v59, v59, v105
	v_add_f32_e32 v56, v56, v114
	v_add_f32_e32 v57, v57, v115
	v_add_f32_e32 v54, v54, v106
	v_add_f32_e32 v55, v55, v107
	v_add_f32_e32 v52, v52, v116
	v_add_f32_e32 v53, v53, v117
	v_add_f32_e32 v102, v50, v108
	v_add_f32_e32 v103, v51, v109
	v_add_f32_e32 v104, v48, v118
	v_add_f32_e32 v105, v49, v119
	v_mul_f32_e32 v106, v61, v61
	v_mul_f32_e32 v107, v63, v63
	v_mul_f32_e32 v108, v57, v57
	v_mul_f32_e32 v109, v59, v59
	v_cvt_pk_bf16_f32 v48, v60, v61
	v_cvt_pk_bf16_f32 v49, v62, v63
	v_cvt_pk_bf16_f32 v50, v56, v57
	v_cvt_pk_bf16_f32 v51, v58, v59
	v_mul_f32_e32 v57, v53, v53
	v_mul_f32_e32 v59, v55, v55
	v_mul_f32_e32 v61, v105, v105
	v_mul_f32_e32 v63, v103, v103
	v_fmac_f32_e32 v106, v60, v60
	v_fmac_f32_e32 v107, v62, v62
	v_fmac_f32_e32 v108, v56, v56
	v_fmac_f32_e32 v109, v58, v58
	v_fmac_f32_e32 v57, v52, v52
	v_fmac_f32_e32 v59, v54, v54
	v_fmac_f32_e32 v61, v104, v104
	v_fmac_f32_e32 v63, v102, v102
	v_add_f32_e32 v56, v106, v107
	v_add_f32_e32 v58, v108, v109
	v_add_f32_e32 v57, v57, v59
	v_add_f32_e32 v59, v61, v63
	v_add_f32_e32 v56, v56, v58
	v_add_f32_e32 v57, v57, v59
	v_add_f32_e32 v58, v56, v57
	ds_bpermute_b32 v59, v196, v58
	v_lshl_add_u64 v[56:57], s[16:17], 0, v[110:111]
	v_lshl_add_u64 v[56:57], v[168:169], 1, v[56:57]
	global_store_dwordx4 v[56:57], v[48:51], off
	s_waitcnt lgkmcnt(0)
	s_nop 0
	v_add_f32_e32 v48, v58, v59
	ds_bpermute_b32 v49, v197, v48
	v_cvt_pk_bf16_f32 v50, v52, v53
	v_cvt_pk_bf16_f32 v51, v54, v55
	v_cvt_pk_bf16_f32 v52, v104, v105
	v_cvt_pk_bf16_f32 v53, v102, v103
	global_store_dwordx4 v[56:57], v[50:53], off offset:256
	s_and_saveexec_b64 s[4:5], s[6:7]
	s_cbranch_execz .LBB0_979
	v_lshlrev_b64 v[50:51], 6, v[100:101]
	v_lshl_add_u64 v[50:51], s[24:25], 0, v[50:51]
	v_lshl_add_u64 v[50:51], s[40:41], 2, v[50:51]
	s_lshl_b32 s10, s49, 2
	v_lshl_add_u64 v[50:51], v[50:51], 0, s[10:11]
	s_waitcnt lgkmcnt(0)
	v_add_f32_e32 v48, v48, v49
	global_store_dword v[50:51], v48, off
.LBB0_979:
	s_or_b64 exec, exec, s[4:5]
	s_waitcnt vmcnt(7)
	v_lshlrev_b32_e32 v48, 16, v84
	s_waitcnt lgkmcnt(0)
	v_and_b32_e32 v49, 0xffff0000, v84
	v_lshlrev_b32_e32 v50, 16, v85
	v_and_b32_e32 v51, 0xffff0000, v85
	v_lshlrev_b32_e32 v52, 16, v86
	v_and_b32_e32 v53, 0xffff0000, v86
	v_lshlrev_b32_e32 v54, 16, v87
	v_and_b32_e32 v55, 0xffff0000, v87
	v_add_f32_e32 v46, v46, v50
	v_add_f32_e32 v47, v47, v51
	v_add_f32_e32 v44, v44, v48
	v_add_f32_e32 v45, v45, v49
	v_add_f32_e32 v48, v42, v54
	v_add_f32_e32 v49, v43, v55
	v_add_f32_e32 v42, v40, v52
	v_add_f32_e32 v43, v41, v53
	v_mul_f32_e32 v40, v45, v45
	v_mul_f32_e32 v41, v47, v47
	v_fmac_f32_e32 v40, v44, v44
	v_fmac_f32_e32 v41, v46, v46
	v_add_f32_e32 v40, v40, v41
	v_mul_f32_e32 v41, v43, v43
	v_mul_f32_e32 v50, v49, v49
	v_fmac_f32_e32 v41, v42, v42
	v_fmac_f32_e32 v50, v48, v48
	v_add_f32_e32 v41, v41, v50
	v_add_f32_e32 v52, v40, v41
	v_cvt_pk_bf16_f32 v40, v44, v45
	v_cvt_pk_bf16_f32 v41, v46, v47
	s_waitcnt vmcnt(6)
	v_lshlrev_b32_e32 v44, 16, v80
	v_and_b32_e32 v45, 0xffff0000, v80
	v_lshlrev_b32_e32 v46, 16, v81
	v_and_b32_e32 v47, 0xffff0000, v81
	v_cvt_pk_bf16_f32 v42, v42, v43
	v_cvt_pk_bf16_f32 v43, v48, v49
	v_lshlrev_b32_e32 v48, 16, v82
	v_and_b32_e32 v49, 0xffff0000, v82
	v_add_f32_e32 v38, v38, v46
	v_add_f32_e32 v39, v39, v47
	v_add_f32_e32 v36, v36, v44
	v_add_f32_e32 v37, v37, v45
	v_lshlrev_b32_e32 v50, 16, v83
	v_and_b32_e32 v51, 0xffff0000, v83
	v_add_f32_e32 v46, v32, v48
	v_add_f32_e32 v47, v33, v49
	v_mul_f32_e32 v32, v37, v37
	v_mul_f32_e32 v33, v39, v39
	v_add_f32_e32 v44, v34, v50
	v_add_f32_e32 v45, v35, v51
	v_fmac_f32_e32 v32, v36, v36
	v_fmac_f32_e32 v33, v38, v38
	v_add_f32_e32 v32, v32, v33
	v_mul_f32_e32 v33, v47, v47
	v_mul_f32_e32 v34, v45, v45
	v_fmac_f32_e32 v33, v46, v46
	v_fmac_f32_e32 v34, v44, v44
	v_add_f32_e32 v33, v33, v34
	v_add_f32_e32 v32, v32, v33
	v_add_f32_e32 v35, v52, v32
	ds_bpermute_b32 v50, v196, v35
	v_lshl_add_u64 v[32:33], s[16:17], 0, v[98:99]
	v_lshl_add_u64 v[48:49], v[168:169], 1, v[32:33]
	global_store_dwordx4 v[48:49], v[40:43], off
	v_cvt_pk_bf16_f32 v34, v36, v37
	s_waitcnt lgkmcnt(0)
	v_add_f32_e32 v32, v35, v50
	ds_bpermute_b32 v33, v197, v32
	v_cvt_pk_bf16_f32 v35, v38, v39
	v_cvt_pk_bf16_f32 v36, v46, v47
	v_cvt_pk_bf16_f32 v37, v44, v45
	global_store_dwordx4 v[48:49], v[34:37], off offset:256
	s_and_saveexec_b64 s[4:5], s[6:7]
	s_cbranch_execz .LBB0_981
	v_lshlrev_b64 v[34:35], 6, v[96:97]
	v_lshl_add_u64 v[34:35], s[24:25], 0, v[34:35]
	v_lshl_add_u64 v[34:35], s[40:41], 2, v[34:35]
	s_lshl_b32 s10, s49, 2
	v_lshl_add_u64 v[34:35], v[34:35], 0, s[10:11]
	s_waitcnt lgkmcnt(0)
	v_add_f32_e32 v32, v32, v33
	global_store_dword v[34:35], v32, off
.LBB0_981:
	s_or_b64 exec, exec, s[4:5]
	s_waitcnt vmcnt(7)
	v_lshlrev_b32_e32 v32, 16, v76
	s_waitcnt lgkmcnt(0)
	v_and_b32_e32 v33, 0xffff0000, v76
	v_lshlrev_b32_e32 v34, 16, v77
	v_and_b32_e32 v35, 0xffff0000, v77
	v_lshlrev_b32_e32 v36, 16, v78
	v_and_b32_e32 v37, 0xffff0000, v78
	v_lshlrev_b32_e32 v38, 16, v79
	v_and_b32_e32 v39, 0xffff0000, v79
	v_add_f32_e32 v30, v30, v34
	v_add_f32_e32 v31, v31, v35
	v_add_f32_e32 v28, v28, v32
	v_add_f32_e32 v29, v29, v33
	v_add_f32_e32 v32, v26, v38
	v_add_f32_e32 v33, v27, v39
	v_add_f32_e32 v26, v24, v36
	v_add_f32_e32 v27, v25, v37
	v_mul_f32_e32 v24, v29, v29
	v_mul_f32_e32 v25, v31, v31
	v_fmac_f32_e32 v24, v28, v28
	v_fmac_f32_e32 v25, v30, v30
	v_add_f32_e32 v24, v24, v25
	v_mul_f32_e32 v25, v27, v27
	v_mul_f32_e32 v34, v33, v33
	v_fmac_f32_e32 v25, v26, v26
	v_fmac_f32_e32 v34, v32, v32
	v_add_f32_e32 v25, v25, v34
	v_add_f32_e32 v36, v24, v25
	v_cvt_pk_bf16_f32 v24, v28, v29
	v_cvt_pk_bf16_f32 v25, v30, v31
	s_waitcnt vmcnt(6)
	v_lshlrev_b32_e32 v28, 16, v72
	v_and_b32_e32 v29, 0xffff0000, v72
	v_lshlrev_b32_e32 v30, 16, v73
	v_and_b32_e32 v31, 0xffff0000, v73
	v_cvt_pk_bf16_f32 v26, v26, v27
	v_cvt_pk_bf16_f32 v27, v32, v33
	v_lshlrev_b32_e32 v32, 16, v74
	v_and_b32_e32 v33, 0xffff0000, v74
	v_add_f32_e32 v22, v22, v30
	v_add_f32_e32 v23, v23, v31
	v_add_f32_e32 v20, v20, v28
	v_add_f32_e32 v21, v21, v29
	v_lshlrev_b32_e32 v34, 16, v75
	v_and_b32_e32 v35, 0xffff0000, v75
	v_add_f32_e32 v30, v16, v32
	v_add_f32_e32 v31, v17, v33
	v_mul_f32_e32 v16, v21, v21
	v_mul_f32_e32 v17, v23, v23
	v_add_f32_e32 v28, v18, v34
	v_add_f32_e32 v29, v19, v35
	v_fmac_f32_e32 v16, v20, v20
	v_fmac_f32_e32 v17, v22, v22
	v_add_f32_e32 v16, v16, v17
	v_mul_f32_e32 v17, v31, v31
	v_mul_f32_e32 v18, v29, v29
	v_fmac_f32_e32 v17, v30, v30
	v_fmac_f32_e32 v18, v28, v28
	v_add_f32_e32 v17, v17, v18
	v_add_f32_e32 v16, v16, v17
	v_add_f32_e32 v19, v36, v16
	ds_bpermute_b32 v34, v196, v19
	v_lshl_add_u64 v[16:17], s[16:17], 0, v[94:95]
	v_lshl_add_u64 v[32:33], v[168:169], 1, v[16:17]
	global_store_dwordx4 v[32:33], v[24:27], off
	v_cvt_pk_bf16_f32 v18, v20, v21
	s_waitcnt lgkmcnt(0)
	v_add_f32_e32 v16, v19, v34
	ds_bpermute_b32 v17, v197, v16
	v_cvt_pk_bf16_f32 v19, v22, v23
	v_cvt_pk_bf16_f32 v20, v30, v31
	v_cvt_pk_bf16_f32 v21, v28, v29
	global_store_dwordx4 v[32:33], v[18:21], off offset:256
	s_and_saveexec_b64 s[4:5], s[6:7]
	s_cbranch_execz .LBB0_983
	v_lshlrev_b64 v[18:19], 6, v[92:93]
	v_lshl_add_u64 v[18:19], s[24:25], 0, v[18:19]
	v_lshl_add_u64 v[18:19], s[40:41], 2, v[18:19]
	s_lshl_b32 s10, s49, 2
	v_lshl_add_u64 v[18:19], v[18:19], 0, s[10:11]
	s_waitcnt lgkmcnt(0)
	v_add_f32_e32 v16, v16, v17
	global_store_dword v[18:19], v16, off
.LBB0_983:
	s_or_b64 exec, exec, s[4:5]
	s_waitcnt vmcnt(7)
	v_lshlrev_b32_e32 v16, 16, v68
	s_waitcnt lgkmcnt(0)
	v_and_b32_e32 v17, 0xffff0000, v68
	v_lshlrev_b32_e32 v18, 16, v69
	v_and_b32_e32 v19, 0xffff0000, v69
	v_lshlrev_b32_e32 v20, 16, v70
	v_and_b32_e32 v21, 0xffff0000, v70
	v_lshlrev_b32_e32 v22, 16, v71
	v_and_b32_e32 v23, 0xffff0000, v71
	v_add_f32_e32 v14, v14, v18
	v_add_f32_e32 v15, v15, v19
	v_add_f32_e32 v12, v12, v16
	v_add_f32_e32 v13, v13, v17
	v_add_f32_e32 v16, v10, v22
	v_add_f32_e32 v17, v11, v23
	v_add_f32_e32 v10, v8, v20
	v_add_f32_e32 v11, v9, v21
	v_mul_f32_e32 v8, v13, v13
	v_mul_f32_e32 v9, v15, v15
	v_fmac_f32_e32 v8, v12, v12
	v_fmac_f32_e32 v9, v14, v14
	v_add_f32_e32 v8, v8, v9
	v_mul_f32_e32 v9, v11, v11
	v_mul_f32_e32 v18, v17, v17
	v_fmac_f32_e32 v9, v10, v10
	v_fmac_f32_e32 v18, v16, v16
	v_add_f32_e32 v9, v9, v18
	v_add_f32_e32 v20, v8, v9
	v_cvt_pk_bf16_f32 v8, v12, v13
	v_cvt_pk_bf16_f32 v9, v14, v15
	s_waitcnt vmcnt(6)
	v_lshlrev_b32_e32 v12, 16, v64
	v_and_b32_e32 v13, 0xffff0000, v64
	v_lshlrev_b32_e32 v14, 16, v65
	v_and_b32_e32 v15, 0xffff0000, v65
	v_cvt_pk_bf16_f32 v10, v10, v11
	v_cvt_pk_bf16_f32 v11, v16, v17
	v_lshlrev_b32_e32 v16, 16, v66
	v_and_b32_e32 v17, 0xffff0000, v66
	v_add_f32_e32 v6, v6, v14
	v_add_f32_e32 v7, v7, v15
	v_add_f32_e32 v4, v4, v12
	v_add_f32_e32 v5, v5, v13
	v_lshlrev_b32_e32 v18, 16, v67
	v_and_b32_e32 v19, 0xffff0000, v67
	v_add_f32_e32 v14, v0, v16
	v_add_f32_e32 v15, v1, v17
	v_mul_f32_e32 v0, v5, v5
	v_mul_f32_e32 v1, v7, v7
	v_add_f32_e32 v12, v2, v18
	v_add_f32_e32 v13, v3, v19
	v_fmac_f32_e32 v0, v4, v4
	v_fmac_f32_e32 v1, v6, v6
	v_add_f32_e32 v0, v0, v1
	v_mul_f32_e32 v1, v15, v15
	v_mul_f32_e32 v2, v13, v13
	v_fmac_f32_e32 v1, v14, v14
	v_fmac_f32_e32 v2, v12, v12
	v_add_f32_e32 v1, v1, v2
	v_add_f32_e32 v0, v0, v1
	v_add_f32_e32 v3, v20, v0
	ds_bpermute_b32 v18, v196, v3
	v_lshl_add_u64 v[0:1], s[16:17], 0, v[90:91]
	v_lshl_add_u64 v[16:17], v[168:169], 1, v[0:1]
	global_store_dwordx4 v[16:17], v[8:11], off
	v_cvt_pk_bf16_f32 v2, v4, v5
	s_waitcnt lgkmcnt(0)
	v_add_f32_e32 v0, v3, v18
	ds_bpermute_b32 v1, v197, v0
	v_cvt_pk_bf16_f32 v3, v6, v7
	v_cvt_pk_bf16_f32 v4, v14, v15
	v_cvt_pk_bf16_f32 v5, v12, v13
	global_store_dwordx4 v[16:17], v[2:5], off offset:256
	s_and_saveexec_b64 s[4:5], s[6:7]
	s_cbranch_execz .LBB0_985
	v_lshlrev_b64 v[2:3], 6, v[88:89]
	v_lshl_add_u64 v[2:3], s[24:25], 0, v[2:3]
	v_lshl_add_u64 v[2:3], s[40:41], 2, v[2:3]
	s_lshl_b32 s10, s49, 2
	v_lshl_add_u64 v[2:3], v[2:3], 0, s[10:11]
	s_waitcnt lgkmcnt(0)
	v_add_f32_e32 v0, v0, v1
	global_store_dword v[2:3], v0, off

.LBB0_1051:
	v_lshl_add_u32 v162, s8, 8, v159
	s_mov_b64 s[60:61], 0x2000
	v_lshlrev_b32_e32 v204, 6, v162
	v_mov_b32_e32 v205, 0
	v_mbcnt_lo_u32_b32 v248, -1, 0
	v_mbcnt_hi_u32_b32 v248, -1, v248
	v_xor_b32_e32 v248, 16, v248
	v_lshl_add_u64 v[204:205], v[136:137], 0, v[204:205]
	v_lshlrev_b32_e32 v248, 2, v248
	v_lshl_add_u64 v[206:207], v[204:205], 0, s[60:61]
	global_load_dwordx4 v[208:211], v[204:205], off
	global_load_dwordx4 v[212:215], v[204:205], off offset:1024
	global_load_dwordx4 v[216:219], v[204:205], off offset:2048
	global_load_dwordx4 v[220:223], v[204:205], off offset:3072
	global_load_dwordx4 v[224:227], v[206:207], off
	global_load_dwordx4 v[228:231], v[206:207], off offset:1024
	global_load_dwordx4 v[232:235], v[206:207], off offset:2048
	global_load_dwordx4 v[236:239], v[206:207], off offset:3072
	s_waitcnt vmcnt(0)
	v_add_f32_e32 v208, v208, v209
	v_add_f32_e32 v210, v210, v211
	v_add_f32_e32 v212, v212, v213
	v_add_f32_e32 v214, v214, v215
	v_add_f32_e32 v216, v216, v217
	v_add_f32_e32 v218, v218, v219
	v_add_f32_e32 v220, v220, v221
	v_add_f32_e32 v222, v222, v223
	v_add_f32_e32 v224, v224, v225
	v_add_f32_e32 v226, v226, v227
	v_add_f32_e32 v228, v228, v229
	v_add_f32_e32 v230, v230, v231
	v_add_f32_e32 v232, v232, v233
	v_add_f32_e32 v234, v234, v235
	v_add_f32_e32 v236, v236, v237
	v_add_f32_e32 v238, v238, v239
	v_add_f32_e32 v208, v208, v210
	v_add_f32_e32 v212, v212, v214
	v_add_f32_e32 v216, v216, v218
	v_add_f32_e32 v220, v220, v222
	v_add_f32_e32 v224, v224, v226
	v_add_f32_e32 v228, v228, v230
	v_add_f32_e32 v232, v232, v234
	v_add_f32_e32 v236, v236, v238
	ds_bpermute_b32 v209, v248, v208
	ds_bpermute_b32 v213, v248, v212
	ds_bpermute_b32 v217, v248, v216
	ds_bpermute_b32 v221, v248, v220
	ds_bpermute_b32 v225, v248, v224
	ds_bpermute_b32 v229, v248, v228
	ds_bpermute_b32 v233, v248, v232
	ds_bpermute_b32 v237, v248, v236
	s_waitcnt lgkmcnt(0)
	v_add_f32_e32 v208, v208, v209
	v_add_f32_e32 v212, v212, v213
	v_add_f32_e32 v216, v216, v217
	v_add_f32_e32 v220, v220, v221
	v_add_f32_e32 v224, v224, v225
	v_add_f32_e32 v228, v228, v229
	v_add_f32_e32 v232, v232, v233
	v_add_f32_e32 v236, v236, v237
	v_mov_b32_e32 v209, v208
	v_mov_b32_e32 v213, v212
	v_mov_b32_e32 v217, v216
	v_mov_b32_e32 v221, v220
	v_mov_b32_e32 v225, v224
	v_mov_b32_e32 v229, v228
	v_mov_b32_e32 v233, v232
	v_mov_b32_e32 v237, v236
	s_nop 1
	v_permlane32_swap_b32_e32 v208, v209
	v_permlane32_swap_b32_e32 v212, v213
	v_permlane32_swap_b32_e32 v216, v217
	v_permlane32_swap_b32_e32 v220, v221
	v_permlane32_swap_b32_e32 v224, v225
	v_permlane32_swap_b32_e32 v228, v229
	v_permlane32_swap_b32_e32 v232, v233
	v_permlane32_swap_b32_e32 v236, v237
	v_add_f32_e32 v208, v208, v209
	v_add_f32_e32 v212, v212, v213
	v_add_f32_e32 v216, v216, v217
	v_add_f32_e32 v220, v220, v221
	v_add_f32_e32 v224, v224, v225
	v_add_f32_e32 v228, v228, v229
	v_add_f32_e32 v232, v232, v233
	v_add_f32_e32 v236, v236, v237
	v_fmamk_f32 v208, v208, 0x3a800000, v175
	v_fmamk_f32 v212, v212, 0x3a800000, v175
	v_fmamk_f32 v216, v216, 0x3a800000, v175
	v_fmamk_f32 v220, v220, 0x3a800000, v175
	v_fmamk_f32 v224, v224, 0x3a800000, v175
	v_fmamk_f32 v228, v228, 0x3a800000, v175
	v_fmamk_f32 v232, v232, 0x3a800000, v175
	v_fmamk_f32 v236, v236, 0x3a800000, v175
	v_rsq_f32_e32 v176, v208
	v_rsq_f32_e32 v174, v212
	v_rsq_f32_e32 v172, v216
	v_rsq_f32_e32 v170, v220
	v_rsq_f32_e32 v168, v224
	v_rsq_f32_e32 v166, v228
	v_rsq_f32_e32 v164, v232
	v_rsq_f32_e32 v158, v236
	s_nop 0
	v_or_b32_e32 v160, 16, v162
	v_or_b32_e32 v156, 32, v162
	v_or_b32_e32 v154, 48, v162
	v_add_u32_e32 v148, 0x80, v162
	s_waitcnt vmcnt(0)
	s_waitcnt lgkmcnt(2)
	s_waitcnt lgkmcnt(2)
	s_waitcnt lgkmcnt(1)
	s_waitcnt lgkmcnt(2)
	s_waitcnt lgkmcnt(1)
	s_waitcnt lgkmcnt(0)
	s_nop 0
	v_add_u32_e32 v152, 0x90, v162
	s_waitcnt lgkmcnt(0)
	s_waitcnt lgkmcnt(0)
	s_waitcnt vmcnt(0)
	v_add_u32_e32 v150, 0xa0, v162
	s_waitcnt lgkmcnt(0)
	s_waitcnt lgkmcnt(0)
	s_nop 0
	s_nop 1
	v_add_u32_e32 v146, 0xb0, v162
	s_waitcnt lgkmcnt(0)
	s_waitcnt lgkmcnt(0)
	s_waitcnt vmcnt(1)
	s_waitcnt lgkmcnt(0)
	s_waitcnt lgkmcnt(0)
	s_waitcnt vmcnt(0)
	v_mov_b32_e32 v178, v120
	s_waitcnt lgkmcnt(0)
	s_waitcnt lgkmcnt(0)
	v_mov_b32_e32 v179, v124
	v_mul_f32_e32 v178, v178, v176
	v_mul_f32_e32 v179, v179, v176
	v_mov_b32_e32 v124, v121
	v_mul_f32_e32 v120, 0xbfb8aa3b, v179
	v_exp_f32_e32 v147, v120
	v_mul_f32_e32 v120, v124, v176
	v_mul_f32_e32 v121, v125, v176
	s_andn2_b64 vcc, exec, s[6:7]
	v_mul_f32_e32 v124, 0xbfb8aa3b, v121
	v_exp_f32_e32 v125, v124
	v_add_f32_e32 v147, 1.0, v147
	v_rcp_f32_e32 v147, v147
	v_lshl_or_b32 v124, s33, 7, v167
	v_add_f32_e32 v125, 1.0, v125
	v_rcp_f32_e32 v149, v125
	v_mul_f32_e32 v147, v179, v147
	v_mul_f32_e32 v147, v178, v147
	v_mov_b32_e32 v178, v122
	v_mov_b32_e32 v179, v126
	v_mul_f32_e32 v178, v178, v176
	v_mul_f32_e32 v179, v179, v176
	v_mov_b32_e32 v126, v123
	v_mul_f32_e32 v122, 0xbfb8aa3b, v179
	v_mul_f32_e32 v121, v121, v149
	v_exp_f32_e32 v149, v122
	v_mul_f32_e32 v122, v126, v176
	v_mul_f32_e32 v123, v127, v176
	v_mul_f32_e32 v127, v120, v121
	v_mul_f32_e32 v126, 0xbfb8aa3b, v123
	v_exp_f32_e32 v126, v126
	v_add_f32_e32 v120, 1.0, v149
	v_rcp_f32_e32 v149, v120
	v_mov_b32_e32 v121, v116
	v_add_f32_e32 v120, 1.0, v126
	v_rcp_f32_e32 v126, v120
	v_mov_b32_e32 v120, v112
	v_mul_f32_e32 v120, v120, v176
	v_mul_f32_e32 v121, v121, v176
	v_mul_f32_e32 v116, v179, v149
	v_mul_f32_e32 v112, 0xbfb8aa3b, v121
	v_exp_f32_e32 v112, v112
	v_mul_f32_e32 v149, v178, v116
	v_mov_b32_e32 v116, v113
	v_mul_f32_e32 v123, v123, v126
	v_add_f32_e32 v112, 1.0, v112
	v_rcp_f32_e32 v126, v112
	v_mul_f32_e32 v112, v116, v176
	v_mul_f32_e32 v113, v117, v176
	v_mul_f32_e32 v122, v122, v123
	v_mul_f32_e32 v116, 0xbfb8aa3b, v113
	v_exp_f32_e32 v116, v116
	v_mul_f32_e32 v117, v121, v126
	v_mul_f32_e32 v120, v120, v117
	v_mov_b32_e32 v117, v118
	v_add_f32_e32 v116, 1.0, v116
	v_rcp_f32_e32 v121, v116
	v_mov_b32_e32 v116, v114
	v_mul_f32_e32 v116, v116, v176
	v_mul_f32_e32 v117, v117, v176
	v_mov_b32_e32 v118, v115
	v_mul_f32_e32 v114, 0xbfb8aa3b, v117
	v_exp_f32_e32 v123, v114
	v_mul_f32_e32 v114, v118, v176
	v_mul_f32_e32 v115, v119, v176
	v_mul_f32_e32 v113, v113, v121
	v_mul_f32_e32 v118, 0xbfb8aa3b, v115
	v_exp_f32_e32 v118, v118
	v_add_f32_e32 v119, 1.0, v123
	v_rcp_f32_e32 v119, v119
	v_mul_f32_e32 v112, v112, v113
	v_add_f32_e32 v118, 1.0, v118
	v_rcp_f32_e32 v118, v118
	v_mul_f32_e32 v113, v117, v119
	v_mul_f32_e32 v113, v116, v113
	v_cvt_pk_bf16_f32 v116, v147, v127
	v_cvt_pk_bf16_f32 v117, v149, v122
	v_mov_b32_e32 v122, v104
	v_mov_b32_e32 v123, v108
	v_mul_f32_e32 v115, v115, v118
	v_mul_f32_e32 v122, v122, v174
	v_mul_f32_e32 v123, v123, v174
	v_ashrrev_i32_e32 v125, 31, v124
	v_mul_f32_e32 v114, v114, v115
	v_mul_f32_e32 v104, 0xbfb8aa3b, v123
	v_cvt_pk_bf16_f32 v118, v120, v112
	v_cvt_pk_bf16_f32 v119, v113, v114
	v_lshlrev_b64 v[114:115], 1, v[124:125]
	v_exp_f32_e32 v124, v104
	v_mov_b32_e32 v108, v105
	v_mov_b64_e32 v[112:113], s[22:23]
	v_mul_f32_e32 v104, v108, v174
	v_mul_f32_e32 v105, v109, v174
	v_mad_i64_i32 v[120:121], s[4:5], v162, s51, v[112:113]
	v_mul_f32_e32 v108, 0xbfb8aa3b, v105
	v_exp_f32_e32 v125, v108
	v_lshl_add_u64 v[108:109], v[120:121], 0, v[114:115]
	v_add_f32_e32 v120, 1.0, v124
	v_rcp_f32_e32 v120, v120
	global_store_dwordx4 v[108:109], v[116:119], off
	v_mov_b32_e32 v109, v110
	v_add_f32_e32 v121, 1.0, v125
	v_mul_f32_e32 v108, v123, v120
	v_mul_f32_e32 v116, v122, v108
	v_mov_b32_e32 v108, v106
	v_mul_f32_e32 v108, v108, v174
	v_mul_f32_e32 v109, v109, v174
	v_mov_b32_e32 v110, v107
	v_mul_f32_e32 v106, 0xbfb8aa3b, v109
	v_rcp_f32_e32 v121, v121
	v_exp_f32_e32 v117, v106
	v_mul_f32_e32 v106, v110, v174
	v_mul_f32_e32 v107, v111, v174
	v_mul_f32_e32 v105, v105, v121
	v_mul_f32_e32 v110, 0xbfb8aa3b, v107
	v_exp_f32_e32 v110, v110
	v_mul_f32_e32 v111, v104, v105
	v_add_f32_e32 v104, 1.0, v117
	v_rcp_f32_e32 v117, v104
	v_add_f32_e32 v104, 1.0, v110
	v_rcp_f32_e32 v110, v104
	v_mov_b32_e32 v104, v96
	v_mov_b32_e32 v105, v100
	v_mul_f32_e32 v104, v104, v174
	v_mul_f32_e32 v105, v105, v174
	v_mul_f32_e32 v100, v109, v117
	v_mul_f32_e32 v96, 0xbfb8aa3b, v105
	v_exp_f32_e32 v96, v96
	v_mul_f32_e32 v108, v108, v100
	v_mov_b32_e32 v100, v97
	v_mul_f32_e32 v107, v107, v110
	v_add_f32_e32 v96, 1.0, v96
	v_rcp_f32_e32 v109, v96
	v_mul_f32_e32 v96, v100, v174
	v_mul_f32_e32 v97, v101, v174
	v_mul_f32_e32 v106, v106, v107
	v_mul_f32_e32 v100, 0xbfb8aa3b, v97
	v_exp_f32_e32 v100, v100
	v_mul_f32_e32 v101, v105, v109
	v_mul_f32_e32 v104, v104, v101
	v_mov_b32_e32 v101, v102
	v_add_f32_e32 v100, 1.0, v100
	v_rcp_f32_e32 v105, v100
	v_mov_b32_e32 v100, v98
	v_mul_f32_e32 v100, v100, v174
	v_mul_f32_e32 v101, v101, v174
	v_mov_b32_e32 v102, v99
	v_mul_f32_e32 v98, 0xbfb8aa3b, v101
	v_exp_f32_e32 v107, v98
	v_mul_f32_e32 v98, v102, v174
	v_mul_f32_e32 v99, v103, v174
	v_mul_f32_e32 v97, v97, v105
	v_mul_f32_e32 v102, 0xbfb8aa3b, v99
	v_exp_f32_e32 v102, v102
	v_add_f32_e32 v103, 1.0, v107
	v_rcp_f32_e32 v103, v103
	v_mul_f32_e32 v105, v96, v97
	v_add_f32_e32 v102, 1.0, v102
	v_rcp_f32_e32 v102, v102
	v_mul_f32_e32 v96, v101, v103
	v_mul_f32_e32 v100, v100, v96
	v_mov_b32_e32 v103, v92
	v_mul_f32_e32 v96, v99, v102
	v_mov_b32_e32 v102, v88
	v_mul_f32_e32 v102, v102, v172
	v_mul_f32_e32 v103, v103, v172
	v_mul_f32_e32 v99, v98, v96
	v_mul_f32_e32 v88, 0xbfb8aa3b, v103
	v_cvt_pk_bf16_f32 v96, v116, v111
	v_cvt_pk_bf16_f32 v97, v108, v106
	v_cvt_pk_bf16_f32 v98, v104, v105
	v_exp_f32_e32 v104, v88
	v_mov_b32_e32 v92, v89
	v_mul_f32_e32 v88, v92, v172
	v_mul_f32_e32 v89, v93, v172
	v_cvt_pk_bf16_f32 v99, v100, v99
	v_mad_i64_i32 v[100:101], s[4:5], v160, s51, v[112:113]
	v_mul_f32_e32 v92, 0xbfb8aa3b, v89
	v_exp_f32_e32 v105, v92
	v_lshl_add_u64 v[92:93], v[100:101], 0, v[114:115]
	v_add_f32_e32 v100, 1.0, v104
	v_rcp_f32_e32 v100, v100
	global_store_dwordx4 v[92:93], v[96:99], off
	v_mov_b32_e32 v93, v94
	v_add_f32_e32 v101, 1.0, v105
	v_mul_f32_e32 v92, v103, v100
	v_mul_f32_e32 v96, v102, v92
	v_mov_b32_e32 v92, v90
	v_mul_f32_e32 v92, v92, v172
	v_mul_f32_e32 v93, v93, v172
	v_mov_b32_e32 v94, v91
	v_mul_f32_e32 v90, 0xbfb8aa3b, v93
	v_rcp_f32_e32 v101, v101
	v_exp_f32_e32 v97, v90
	v_mul_f32_e32 v90, v94, v172
	v_mul_f32_e32 v91, v95, v172
	v_mul_f32_e32 v89, v89, v101
	v_mul_f32_e32 v94, 0xbfb8aa3b, v91
	v_exp_f32_e32 v94, v94
	v_mul_f32_e32 v95, v88, v89
	v_add_f32_e32 v88, 1.0, v97
	v_rcp_f32_e32 v97, v88
	v_add_f32_e32 v88, 1.0, v94
	v_rcp_f32_e32 v94, v88
	v_mov_b32_e32 v88, v80
	v_mov_b32_e32 v89, v84
	v_mul_f32_e32 v88, v88, v172
	v_mul_f32_e32 v89, v89, v172
	v_mul_f32_e32 v84, v93, v97
	v_mul_f32_e32 v80, 0xbfb8aa3b, v89
	v_exp_f32_e32 v80, v80
	v_mul_f32_e32 v92, v92, v84
	v_mov_b32_e32 v84, v81
	v_mul_f32_e32 v91, v91, v94
	v_add_f32_e32 v80, 1.0, v80
	v_rcp_f32_e32 v93, v80
	v_mul_f32_e32 v80, v84, v172
	v_mul_f32_e32 v81, v85, v172
	v_mul_f32_e32 v90, v90, v91
	v_mul_f32_e32 v84, 0xbfb8aa3b, v81
	v_exp_f32_e32 v84, v84
	v_mul_f32_e32 v85, v89, v93
	v_mul_f32_e32 v88, v88, v85
	v_mov_b32_e32 v85, v86
	v_add_f32_e32 v84, 1.0, v84
	v_rcp_f32_e32 v89, v84
	v_mov_b32_e32 v84, v82
	v_mul_f32_e32 v84, v84, v172
	v_mul_f32_e32 v85, v85, v172
	v_mov_b32_e32 v86, v83
	v_mul_f32_e32 v82, 0xbfb8aa3b, v85
	v_exp_f32_e32 v91, v82
	v_mul_f32_e32 v82, v86, v172
	v_mul_f32_e32 v83, v87, v172
	v_mul_f32_e32 v81, v81, v89
	v_mul_f32_e32 v86, 0xbfb8aa3b, v83
	v_exp_f32_e32 v86, v86
	v_add_f32_e32 v87, 1.0, v91
	v_rcp_f32_e32 v87, v87
	v_mul_f32_e32 v89, v80, v81
	v_add_f32_e32 v86, 1.0, v86
	v_rcp_f32_e32 v86, v86
	v_mul_f32_e32 v80, v85, v87
	v_mul_f32_e32 v84, v84, v80
	v_mov_b32_e32 v87, v76
	v_mul_f32_e32 v80, v83, v86
	v_mov_b32_e32 v86, v72
	v_mul_f32_e32 v86, v86, v170
	v_mul_f32_e32 v87, v87, v170
	v_mul_f32_e32 v83, v82, v80
	v_mul_f32_e32 v72, 0xbfb8aa3b, v87
	v_cvt_pk_bf16_f32 v80, v96, v95
	v_cvt_pk_bf16_f32 v81, v92, v90
	v_cvt_pk_bf16_f32 v82, v88, v89
	v_exp_f32_e32 v88, v72
	v_mov_b32_e32 v76, v73
	v_mul_f32_e32 v72, v76, v170
	v_mul_f32_e32 v73, v77, v170
	v_cvt_pk_bf16_f32 v83, v84, v83
	v_mad_i64_i32 v[84:85], s[4:5], v156, s51, v[112:113]
	v_mul_f32_e32 v76, 0xbfb8aa3b, v73
	v_exp_f32_e32 v89, v76
	v_lshl_add_u64 v[76:77], v[84:85], 0, v[114:115]
	v_add_f32_e32 v84, 1.0, v88
	v_rcp_f32_e32 v84, v84
	global_store_dwordx4 v[76:77], v[80:83], off
	v_mov_b32_e32 v77, v78
	v_add_f32_e32 v85, 1.0, v89
	v_mul_f32_e32 v76, v87, v84
	v_mul_f32_e32 v80, v86, v76
	v_mov_b32_e32 v76, v74
	v_mul_f32_e32 v76, v76, v170
	v_mul_f32_e32 v77, v77, v170
	v_mov_b32_e32 v78, v75
	v_mul_f32_e32 v74, 0xbfb8aa3b, v77
	v_rcp_f32_e32 v85, v85
	v_exp_f32_e32 v81, v74
	v_mul_f32_e32 v74, v78, v170
	v_mul_f32_e32 v75, v79, v170
	v_mul_f32_e32 v73, v73, v85
	v_mul_f32_e32 v78, 0xbfb8aa3b, v75
	v_exp_f32_e32 v78, v78
	v_mul_f32_e32 v79, v72, v73
	v_add_f32_e32 v72, 1.0, v81
	v_rcp_f32_e32 v81, v72
	v_add_f32_e32 v72, 1.0, v78
	v_rcp_f32_e32 v78, v72
	v_mov_b32_e32 v72, v64
	v_mov_b32_e32 v73, v68
	v_mul_f32_e32 v72, v72, v170
	v_mul_f32_e32 v73, v73, v170
	v_mul_f32_e32 v68, v77, v81
	v_mul_f32_e32 v64, 0xbfb8aa3b, v73
	v_exp_f32_e32 v64, v64
	v_mul_f32_e32 v76, v76, v68
	v_mov_b32_e32 v68, v65
	v_mul_f32_e32 v75, v75, v78
	v_add_f32_e32 v64, 1.0, v64
	v_rcp_f32_e32 v77, v64
	v_mul_f32_e32 v64, v68, v170
	v_mul_f32_e32 v65, v69, v170
	v_mul_f32_e32 v74, v74, v75
	v_mul_f32_e32 v68, 0xbfb8aa3b, v65
	v_exp_f32_e32 v68, v68
	v_mul_f32_e32 v69, v73, v77
	v_mul_f32_e32 v72, v72, v69
	v_mov_b32_e32 v69, v70
	v_add_f32_e32 v68, 1.0, v68
	v_rcp_f32_e32 v73, v68
	v_mov_b32_e32 v68, v66
	v_mul_f32_e32 v68, v68, v170
	v_mul_f32_e32 v69, v69, v170
	v_mov_b32_e32 v70, v67
	v_mul_f32_e32 v66, 0xbfb8aa3b, v69
	v_exp_f32_e32 v75, v66
	v_mul_f32_e32 v66, v70, v170
	v_mul_f32_e32 v67, v71, v170
	v_mul_f32_e32 v65, v65, v73
	v_mul_f32_e32 v70, 0xbfb8aa3b, v67
	v_exp_f32_e32 v70, v70
	v_add_f32_e32 v71, 1.0, v75
	v_rcp_f32_e32 v71, v71
	v_mul_f32_e32 v73, v64, v65
	v_add_f32_e32 v70, 1.0, v70
	v_rcp_f32_e32 v70, v70
	v_mul_f32_e32 v64, v69, v71
	v_mul_f32_e32 v68, v68, v64
	v_mov_b32_e32 v71, v60
	v_mul_f32_e32 v64, v67, v70
	v_mov_b32_e32 v70, v56
	v_mul_f32_e32 v70, v70, v168
	v_mul_f32_e32 v71, v71, v168
	v_mul_f32_e32 v67, v66, v64
	v_mul_f32_e32 v56, 0xbfb8aa3b, v71
	v_cvt_pk_bf16_f32 v64, v80, v79
	v_cvt_pk_bf16_f32 v65, v76, v74
	v_cvt_pk_bf16_f32 v66, v72, v73
	v_exp_f32_e32 v72, v56
	v_mov_b32_e32 v60, v57
	v_mul_f32_e32 v56, v60, v168
	v_mul_f32_e32 v57, v61, v168
	v_cvt_pk_bf16_f32 v67, v68, v67
	v_mad_i64_i32 v[68:69], s[4:5], v154, s51, v[112:113]
	v_mul_f32_e32 v60, 0xbfb8aa3b, v57
	v_exp_f32_e32 v73, v60
	v_lshl_add_u64 v[60:61], v[68:69], 0, v[114:115]
	v_add_f32_e32 v68, 1.0, v72
	v_rcp_f32_e32 v68, v68
	global_store_dwordx4 v[60:61], v[64:67], off
	v_mov_b32_e32 v61, v62
	v_add_f32_e32 v69, 1.0, v73
	v_mul_f32_e32 v60, v71, v68
	v_mul_f32_e32 v64, v70, v60
	v_mov_b32_e32 v60, v58
	v_mul_f32_e32 v60, v60, v168
	v_mul_f32_e32 v61, v61, v168
	v_mov_b32_e32 v62, v59
	v_mul_f32_e32 v58, 0xbfb8aa3b, v61
	v_rcp_f32_e32 v69, v69
	v_exp_f32_e32 v65, v58
	v_mul_f32_e32 v58, v62, v168
	v_mul_f32_e32 v59, v63, v168
	v_mul_f32_e32 v57, v57, v69
	v_mul_f32_e32 v62, 0xbfb8aa3b, v59
	v_exp_f32_e32 v62, v62
	v_mul_f32_e32 v63, v56, v57
	v_add_f32_e32 v56, 1.0, v65
	v_rcp_f32_e32 v65, v56
	v_add_f32_e32 v56, 1.0, v62
	v_rcp_f32_e32 v62, v56
	v_mov_b32_e32 v56, v48
	v_mov_b32_e32 v57, v52
	v_mul_f32_e32 v56, v56, v168
	v_mul_f32_e32 v57, v57, v168
	v_mul_f32_e32 v52, v61, v65
	v_mul_f32_e32 v48, 0xbfb8aa3b, v57
	v_exp_f32_e32 v48, v48
	v_mul_f32_e32 v60, v60, v52
	v_mov_b32_e32 v52, v49
	v_mul_f32_e32 v59, v59, v62
	v_add_f32_e32 v48, 1.0, v48
	v_rcp_f32_e32 v61, v48
	v_mul_f32_e32 v48, v52, v168
	v_mul_f32_e32 v49, v53, v168
	v_mul_f32_e32 v58, v58, v59
	v_mul_f32_e32 v52, 0xbfb8aa3b, v49
	v_exp_f32_e32 v52, v52
	v_mul_f32_e32 v53, v57, v61
	v_mul_f32_e32 v56, v56, v53
	v_mov_b32_e32 v53, v54
	v_add_f32_e32 v52, 1.0, v52
	v_rcp_f32_e32 v57, v52
	v_mov_b32_e32 v52, v50
	v_mul_f32_e32 v52, v52, v168
	v_mul_f32_e32 v53, v53, v168
	v_mov_b32_e32 v54, v51
	v_mul_f32_e32 v50, 0xbfb8aa3b, v53
	v_exp_f32_e32 v59, v50
	v_mul_f32_e32 v50, v54, v168
	v_mul_f32_e32 v51, v55, v168
	v_mul_f32_e32 v49, v49, v57
	v_mul_f32_e32 v54, 0xbfb8aa3b, v51
	v_exp_f32_e32 v54, v54
	v_add_f32_e32 v55, 1.0, v59
	v_rcp_f32_e32 v55, v55
	v_mul_f32_e32 v57, v48, v49
	v_add_f32_e32 v54, 1.0, v54
	v_rcp_f32_e32 v54, v54
	v_mul_f32_e32 v48, v53, v55
	v_mul_f32_e32 v52, v52, v48
	v_mov_b32_e32 v55, v44
	v_mul_f32_e32 v48, v51, v54
	v_mov_b32_e32 v54, v40
	v_mul_f32_e32 v54, v54, v166
	v_mul_f32_e32 v55, v55, v166
	v_mul_f32_e32 v51, v50, v48
	v_mul_f32_e32 v40, 0xbfb8aa3b, v55
	v_cvt_pk_bf16_f32 v48, v64, v63
	v_cvt_pk_bf16_f32 v49, v60, v58
	v_cvt_pk_bf16_f32 v50, v56, v57
	v_exp_f32_e32 v56, v40
	v_mov_b32_e32 v44, v41
	v_mul_f32_e32 v40, v44, v166
	v_mul_f32_e32 v41, v45, v166
	v_cvt_pk_bf16_f32 v51, v52, v51
	v_mad_i64_i32 v[52:53], s[4:5], v148, s51, v[112:113]
	v_mul_f32_e32 v44, 0xbfb8aa3b, v41
	v_exp_f32_e32 v57, v44
	v_lshl_add_u64 v[44:45], v[52:53], 0, v[114:115]
	v_add_f32_e32 v52, 1.0, v56
	v_rcp_f32_e32 v52, v52
	global_store_dwordx4 v[44:45], v[48:51], off
	v_mov_b32_e32 v45, v46
	v_add_f32_e32 v53, 1.0, v57
	v_mul_f32_e32 v44, v55, v52
	v_mul_f32_e32 v48, v54, v44
	v_mov_b32_e32 v44, v42
	v_mul_f32_e32 v44, v44, v166
	v_mul_f32_e32 v45, v45, v166
	v_mov_b32_e32 v46, v43
	v_mul_f32_e32 v42, 0xbfb8aa3b, v45
	v_rcp_f32_e32 v53, v53
	v_exp_f32_e32 v49, v42
	v_mul_f32_e32 v42, v46, v166
	v_mul_f32_e32 v43, v47, v166
	v_mul_f32_e32 v41, v41, v53
	v_mul_f32_e32 v46, 0xbfb8aa3b, v43
	v_exp_f32_e32 v46, v46
	v_mul_f32_e32 v47, v40, v41
	v_add_f32_e32 v40, 1.0, v49
	v_rcp_f32_e32 v49, v40
	v_add_f32_e32 v40, 1.0, v46
	v_rcp_f32_e32 v46, v40
	v_mov_b32_e32 v40, v32
	v_mov_b32_e32 v41, v36
	v_mul_f32_e32 v40, v40, v166
	v_mul_f32_e32 v41, v41, v166
	v_mul_f32_e32 v36, v45, v49
	v_mul_f32_e32 v32, 0xbfb8aa3b, v41
	v_exp_f32_e32 v32, v32
	v_mul_f32_e32 v44, v44, v36
	v_mov_b32_e32 v36, v33
	v_mul_f32_e32 v43, v43, v46
	v_add_f32_e32 v32, 1.0, v32
	v_rcp_f32_e32 v45, v32
	v_mul_f32_e32 v32, v36, v166
	v_mul_f32_e32 v33, v37, v166
	v_mul_f32_e32 v42, v42, v43
	v_mul_f32_e32 v36, 0xbfb8aa3b, v33
	v_exp_f32_e32 v36, v36
	v_mul_f32_e32 v37, v41, v45
	v_mul_f32_e32 v40, v40, v37
	v_mov_b32_e32 v37, v38
	v_add_f32_e32 v36, 1.0, v36
	v_rcp_f32_e32 v41, v36
	v_mov_b32_e32 v36, v34
	v_mul_f32_e32 v36, v36, v166
	v_mul_f32_e32 v37, v37, v166
	v_mov_b32_e32 v38, v35
	v_mul_f32_e32 v34, 0xbfb8aa3b, v37
	v_exp_f32_e32 v43, v34
	v_mul_f32_e32 v34, v38, v166
	v_mul_f32_e32 v35, v39, v166
	v_mul_f32_e32 v33, v33, v41
	v_mul_f32_e32 v38, 0xbfb8aa3b, v35
	v_exp_f32_e32 v38, v38
	v_add_f32_e32 v39, 1.0, v43
	v_rcp_f32_e32 v39, v39
	v_mul_f32_e32 v41, v32, v33
	v_add_f32_e32 v38, 1.0, v38
	v_rcp_f32_e32 v38, v38
	v_mul_f32_e32 v32, v37, v39
	v_mul_f32_e32 v36, v36, v32
	v_mov_b32_e32 v39, v28
	v_mul_f32_e32 v32, v35, v38
	v_mov_b32_e32 v38, v24
	v_mul_f32_e32 v38, v38, v164
	v_mul_f32_e32 v39, v39, v164
	v_mul_f32_e32 v35, v34, v32
	v_mul_f32_e32 v24, 0xbfb8aa3b, v39
	v_cvt_pk_bf16_f32 v32, v48, v47
	v_cvt_pk_bf16_f32 v33, v44, v42
	v_cvt_pk_bf16_f32 v34, v40, v41
	v_exp_f32_e32 v40, v24
	v_mov_b32_e32 v28, v25
	v_mul_f32_e32 v24, v28, v164
	v_mul_f32_e32 v25, v29, v164
	v_cvt_pk_bf16_f32 v35, v36, v35
	v_mad_i64_i32 v[36:37], s[4:5], v152, s51, v[112:113]
	v_mul_f32_e32 v28, 0xbfb8aa3b, v25
	v_exp_f32_e32 v41, v28
	v_lshl_add_u64 v[28:29], v[36:37], 0, v[114:115]
	v_add_f32_e32 v36, 1.0, v40
	v_rcp_f32_e32 v36, v36
	global_store_dwordx4 v[28:29], v[32:35], off
	v_mov_b32_e32 v29, v30
	v_add_f32_e32 v37, 1.0, v41
	v_mul_f32_e32 v28, v39, v36
	v_mul_f32_e32 v32, v38, v28
	v_mov_b32_e32 v28, v26
	v_mul_f32_e32 v28, v28, v164
	v_mul_f32_e32 v29, v29, v164
	v_mov_b32_e32 v30, v27
	v_mul_f32_e32 v26, 0xbfb8aa3b, v29
	v_rcp_f32_e32 v37, v37
	v_exp_f32_e32 v33, v26
	v_mul_f32_e32 v26, v30, v164
	v_mul_f32_e32 v27, v31, v164
	v_mul_f32_e32 v25, v25, v37
	v_mul_f32_e32 v30, 0xbfb8aa3b, v27
	v_exp_f32_e32 v30, v30
	v_mul_f32_e32 v31, v24, v25
	v_add_f32_e32 v24, 1.0, v33
	v_rcp_f32_e32 v33, v24
	v_add_f32_e32 v24, 1.0, v30
	v_rcp_f32_e32 v30, v24
	v_mov_b32_e32 v24, v16
	v_mov_b32_e32 v25, v20
	v_mul_f32_e32 v24, v24, v164
	v_mul_f32_e32 v25, v25, v164
	v_mul_f32_e32 v20, v29, v33
	v_mul_f32_e32 v16, 0xbfb8aa3b, v25
	v_exp_f32_e32 v16, v16
	v_mul_f32_e32 v28, v28, v20
	v_mov_b32_e32 v20, v17
	v_mul_f32_e32 v27, v27, v30
	v_add_f32_e32 v16, 1.0, v16
	v_rcp_f32_e32 v29, v16
	v_mul_f32_e32 v16, v20, v164
	v_mul_f32_e32 v17, v21, v164
	v_mul_f32_e32 v26, v26, v27
	v_mul_f32_e32 v20, 0xbfb8aa3b, v17
	v_exp_f32_e32 v20, v20
	v_mul_f32_e32 v21, v25, v29
	v_mul_f32_e32 v24, v24, v21
	v_mov_b32_e32 v21, v22
	v_add_f32_e32 v20, 1.0, v20
	v_rcp_f32_e32 v25, v20
	v_mov_b32_e32 v20, v18
	v_mul_f32_e32 v20, v20, v164
	v_mul_f32_e32 v21, v21, v164
	v_mov_b32_e32 v22, v19
	v_mul_f32_e32 v18, 0xbfb8aa3b, v21
	v_exp_f32_e32 v27, v18
	v_mul_f32_e32 v18, v22, v164
	v_mul_f32_e32 v19, v23, v164
	v_mul_f32_e32 v17, v17, v25
	v_mul_f32_e32 v22, 0xbfb8aa3b, v19
	v_exp_f32_e32 v22, v22
	v_add_f32_e32 v23, 1.0, v27
	v_rcp_f32_e32 v23, v23
	v_mul_f32_e32 v25, v16, v17
	v_add_f32_e32 v22, 1.0, v22
	v_rcp_f32_e32 v22, v22
	v_mul_f32_e32 v16, v21, v23
	v_mul_f32_e32 v20, v20, v16
	v_mov_b32_e32 v23, v12
	v_mul_f32_e32 v16, v19, v22
	v_mov_b32_e32 v22, v8
	v_mul_f32_e32 v22, v22, v158
	v_mul_f32_e32 v23, v23, v158
	v_mul_f32_e32 v19, v18, v16
	v_mul_f32_e32 v8, 0xbfb8aa3b, v23
	v_cvt_pk_bf16_f32 v16, v32, v31
	v_cvt_pk_bf16_f32 v17, v28, v26
	v_cvt_pk_bf16_f32 v18, v24, v25
	v_exp_f32_e32 v24, v8
	v_mov_b32_e32 v12, v9
	v_mul_f32_e32 v8, v12, v158
	v_mul_f32_e32 v9, v13, v158
	v_cvt_pk_bf16_f32 v19, v20, v19
	v_mad_i64_i32 v[20:21], s[4:5], v150, s51, v[112:113]
	v_mul_f32_e32 v12, 0xbfb8aa3b, v9
	v_exp_f32_e32 v25, v12
	v_lshl_add_u64 v[12:13], v[20:21], 0, v[114:115]
	v_add_f32_e32 v20, 1.0, v24
	v_rcp_f32_e32 v20, v20
	global_store_dwordx4 v[12:13], v[16:19], off
	v_mov_b32_e32 v13, v14
	v_add_f32_e32 v21, 1.0, v25
	v_mul_f32_e32 v12, v23, v20
	v_mul_f32_e32 v16, v22, v12
	v_mov_b32_e32 v12, v10
	v_mul_f32_e32 v12, v12, v158
	v_mul_f32_e32 v13, v13, v158
	v_mov_b32_e32 v14, v11
	v_mul_f32_e32 v10, 0xbfb8aa3b, v13
	v_rcp_f32_e32 v21, v21
	v_exp_f32_e32 v17, v10
	v_mul_f32_e32 v10, v14, v158
	v_mul_f32_e32 v11, v15, v158
	v_mul_f32_e32 v9, v9, v21
	v_mul_f32_e32 v14, 0xbfb8aa3b, v11
	v_exp_f32_e32 v14, v14
	v_mul_f32_e32 v15, v8, v9
	v_add_f32_e32 v8, 1.0, v17
	v_rcp_f32_e32 v17, v8
	v_add_f32_e32 v8, 1.0, v14
	v_rcp_f32_e32 v14, v8
	v_mov_b32_e32 v8, v0
	v_mov_b32_e32 v9, v4
	v_mul_f32_e32 v8, v8, v158
	v_mul_f32_e32 v9, v9, v158
	v_mul_f32_e32 v4, v13, v17
	v_mul_f32_e32 v0, 0xbfb8aa3b, v9
	v_exp_f32_e32 v0, v0
	v_mul_f32_e32 v12, v12, v4
	v_mov_b32_e32 v4, v1
	v_mul_f32_e32 v11, v11, v14
	v_add_f32_e32 v0, 1.0, v0
	v_rcp_f32_e32 v13, v0
	v_mul_f32_e32 v0, v4, v158
	v_mul_f32_e32 v1, v5, v158
	v_mul_f32_e32 v10, v10, v11
	v_mul_f32_e32 v4, 0xbfb8aa3b, v1
	v_exp_f32_e32 v4, v4
	v_mul_f32_e32 v5, v9, v13
	v_mul_f32_e32 v8, v8, v5
	v_mov_b32_e32 v5, v6
	v_add_f32_e32 v4, 1.0, v4
	v_rcp_f32_e32 v9, v4
	v_mov_b32_e32 v4, v2
	v_mul_f32_e32 v4, v4, v158
	v_mul_f32_e32 v5, v5, v158
	v_mov_b32_e32 v6, v3
	v_mul_f32_e32 v2, 0xbfb8aa3b, v5
	v_exp_f32_e32 v11, v2
	v_mul_f32_e32 v2, v6, v158
	v_mul_f32_e32 v3, v7, v158
	v_mul_f32_e32 v1, v1, v9
	v_mul_f32_e32 v6, 0xbfb8aa3b, v3
	v_exp_f32_e32 v6, v6
	v_add_f32_e32 v7, 1.0, v11
	v_rcp_f32_e32 v7, v7
	v_mul_f32_e32 v9, v0, v1
	v_add_f32_e32 v6, 1.0, v6
	v_rcp_f32_e32 v6, v6
	v_mul_f32_e32 v0, v5, v7
	v_mul_f32_e32 v4, v4, v0
	v_mul_f32_e32 v0, v3, v6
	v_mul_f32_e32 v3, v2, v0
	v_cvt_pk_bf16_f32 v0, v16, v15
	v_cvt_pk_bf16_f32 v1, v12, v10
	v_cvt_pk_bf16_f32 v2, v8, v9
	v_cvt_pk_bf16_f32 v3, v4, v3
	v_mad_i64_i32 v[4:5], s[4:5], v146, s51, v[112:113]
	v_lshl_add_u64 v[4:5], v[4:5], 0, v[114:115]
	s_mov_b64 s[4:5], -1
	global_store_dwordx4 v[4:5], v[0:3], off
	s_cbranch_vccnz .LBB0_1044
	s_andn2_b64 vcc, exec, s[16:17]
	s_cbranch_vccnz .LBB0_1043
	s_barrier
	s_branch .LBB0_1043

.LBB0_1127:
	v_lshl_or_b32 v168, s10, 8, v188
	v_lshl_add_u32 v172, s53, 8, v186
	v_ashrrev_i32_e32 v169, 31, v168
	v_lshlrev_b64 v[204:205], 1, v[168:169]
	v_ashrrev_i32_e32 v173, 31, v172
	v_lshl_add_u64 v[170:171], s[16:17], 0, v[204:205]
	v_lshlrev_b64 v[206:207], 11, v[172:173]
	v_lshl_add_u64 v[128:129], v[170:171], 0, v[206:207]
	global_load_dwordx4 v[192:195], v[128:129], off
	global_load_dwordx4 v[198:201], v[128:129], off offset:256
	v_or_b32_e32 v182, 16, v172
	v_or_b32_e32 v178, 32, v172
	v_or_b32_e32 v174, 48, v172
	v_ashrrev_i32_e32 v183, 31, v182
	v_ashrrev_i32_e32 v179, 31, v178
	v_ashrrev_i32_e32 v175, 31, v174
	v_lshlrev_b64 v[184:185], 11, v[182:183]
	v_lshlrev_b64 v[180:181], 11, v[178:179]
	v_lshlrev_b64 v[176:177], 11, v[174:175]
	v_lshl_add_u64 v[128:129], v[170:171], 0, v[184:185]
	v_lshl_add_u64 v[130:131], v[170:171], 0, v[180:181]
	v_lshl_add_u64 v[208:209], v[170:171], 0, v[176:177]
	global_load_dwordx4 v[148:151], v[128:129], off
	global_load_dwordx4 v[144:147], v[128:129], off offset:256
	global_load_dwordx4 v[140:143], v[130:131], off
	global_load_dwordx4 v[136:139], v[130:131], off offset:256
	global_load_dwordx4 v[132:135], v[208:209], off
	s_nop 0
	global_load_dwordx4 v[128:131], v[208:209], off offset:256
	s_lshl_b32 s30, s10, 2
	s_ashr_i32 s31, s30, 31
	s_waitcnt vmcnt(0)
	v_lshlrev_b32_e32 v208, 16, v192
	v_and_b32_e32 v209, 0xffff0000, v192
	v_lshlrev_b32_e32 v192, 16, v193
	v_and_b32_e32 v193, 0xffff0000, v193
	v_lshlrev_b32_e32 v210, 16, v194
	v_and_b32_e32 v211, 0xffff0000, v194
	v_lshlrev_b32_e32 v194, 16, v195
	v_and_b32_e32 v195, 0xffff0000, v195
	v_lshlrev_b32_e32 v212, 16, v198
	v_and_b32_e32 v213, 0xffff0000, v198
	v_lshlrev_b32_e32 v198, 16, v199
	v_and_b32_e32 v199, 0xffff0000, v199
	v_lshlrev_b32_e32 v214, 16, v200
	v_and_b32_e32 v215, 0xffff0000, v200
	v_lshlrev_b32_e32 v200, 16, v201
	v_and_b32_e32 v201, 0xffff0000, v201
	v_add_f32_e32 v126, v126, v192
	v_add_f32_e32 v127, v127, v193
	v_add_f32_e32 v124, v124, v208
	v_add_f32_e32 v125, v125, v209
	v_add_f32_e32 v122, v122, v194
	v_add_f32_e32 v123, v123, v195
	v_add_f32_e32 v120, v120, v210
	v_add_f32_e32 v121, v121, v211
	v_add_f32_e32 v118, v118, v198
	v_add_f32_e32 v119, v119, v199
	v_add_f32_e32 v116, v116, v212
	v_add_f32_e32 v117, v117, v213
	v_add_f32_e32 v192, v114, v200
	v_add_f32_e32 v193, v115, v201
	v_add_f32_e32 v194, v112, v214
	v_add_f32_e32 v195, v113, v215
	v_mul_f32_e32 v198, v125, v125
	v_mul_f32_e32 v199, v127, v127
	v_mul_f32_e32 v200, v121, v121
	v_mul_f32_e32 v201, v123, v123
	v_cvt_pk_bf16_f32 v112, v124, v125
	v_cvt_pk_bf16_f32 v113, v126, v127
	v_cvt_pk_bf16_f32 v114, v120, v121
	v_cvt_pk_bf16_f32 v115, v122, v123
	v_mul_f32_e32 v121, v117, v117
	v_mul_f32_e32 v123, v119, v119
	v_mul_f32_e32 v125, v195, v195
	v_mul_f32_e32 v127, v193, v193
	v_fmac_f32_e32 v198, v124, v124
	v_fmac_f32_e32 v199, v126, v126
	v_fmac_f32_e32 v200, v120, v120
	v_fmac_f32_e32 v201, v122, v122
	v_fmac_f32_e32 v121, v116, v116
	v_fmac_f32_e32 v123, v118, v118
	v_fmac_f32_e32 v125, v194, v194
	v_fmac_f32_e32 v127, v192, v192
	v_add_f32_e32 v120, v198, v199
	v_add_f32_e32 v122, v200, v201
	v_add_f32_e32 v121, v121, v123
	v_add_f32_e32 v123, v125, v127
	v_add_f32_e32 v120, v120, v122
	v_add_f32_e32 v121, v121, v123
	v_add_f32_e32 v122, v120, v121
	ds_bpermute_b32 v123, v196, v122
	v_lshl_add_u64 v[120:121], s[16:17], 0, v[206:207]
	v_lshl_add_u64 v[120:121], v[120:121], 0, v[204:205]
	global_store_dwordx4 v[120:121], v[112:115], off
	s_waitcnt lgkmcnt(0)
	s_nop 0
	v_add_f32_e32 v112, v122, v123
	ds_bpermute_b32 v113, v197, v112
	v_cvt_pk_bf16_f32 v114, v116, v117
	v_cvt_pk_bf16_f32 v115, v118, v119
	v_cvt_pk_bf16_f32 v116, v194, v195
	v_cvt_pk_bf16_f32 v117, v192, v193
	global_store_dwordx4 v[120:121], v[114:117], off offset:256
	s_and_saveexec_b64 s[34:35], s[4:5]
	s_cbranch_execz .LBB0_1129
	v_lshlrev_b64 v[114:115], 6, v[172:173]
	v_lshl_add_u64 v[114:115], s[22:23], 0, v[114:115]
	v_lshl_add_u64 v[114:115], s[30:31], 2, v[114:115]
	s_lshl_b32 s10, s45, 2
	v_lshl_add_u64 v[114:115], v[114:115], 0, s[10:11]
	s_waitcnt lgkmcnt(0)
	v_add_f32_e32 v112, v112, v113
	global_store_dword v[114:115], v112, off
.LBB0_1129:
	s_or_b64 exec, exec, s[34:35]
	v_lshlrev_b32_e32 v112, 16, v148
	s_waitcnt lgkmcnt(0)
	v_and_b32_e32 v113, 0xffff0000, v148
	v_lshlrev_b32_e32 v114, 16, v149
	v_and_b32_e32 v115, 0xffff0000, v149
	v_lshlrev_b32_e32 v116, 16, v150
	v_and_b32_e32 v117, 0xffff0000, v150
	v_lshlrev_b32_e32 v118, 16, v151
	v_and_b32_e32 v119, 0xffff0000, v151
	v_add_f32_e32 v110, v110, v114
	v_add_f32_e32 v111, v111, v115
	v_add_f32_e32 v108, v108, v112
	v_add_f32_e32 v109, v109, v113
	v_add_f32_e32 v112, v106, v118
	v_add_f32_e32 v113, v107, v119
	v_add_f32_e32 v106, v104, v116
	v_add_f32_e32 v107, v105, v117
	v_mul_f32_e32 v104, v109, v109
	v_mul_f32_e32 v105, v111, v111
	v_fmac_f32_e32 v104, v108, v108
	v_fmac_f32_e32 v105, v110, v110
	v_add_f32_e32 v104, v104, v105
	v_mul_f32_e32 v105, v107, v107
	v_mul_f32_e32 v114, v113, v113
	v_fmac_f32_e32 v105, v106, v106
	v_fmac_f32_e32 v114, v112, v112
	v_add_f32_e32 v105, v105, v114
	v_add_f32_e32 v116, v104, v105
	v_cvt_pk_bf16_f32 v104, v108, v109
	v_cvt_pk_bf16_f32 v105, v110, v111
	v_lshlrev_b32_e32 v108, 16, v144
	v_and_b32_e32 v109, 0xffff0000, v144
	v_lshlrev_b32_e32 v110, 16, v145
	v_and_b32_e32 v111, 0xffff0000, v145
	v_cvt_pk_bf16_f32 v106, v106, v107
	v_cvt_pk_bf16_f32 v107, v112, v113
	v_lshlrev_b32_e32 v112, 16, v146
	v_and_b32_e32 v113, 0xffff0000, v146
	v_add_f32_e32 v102, v102, v110
	v_add_f32_e32 v103, v103, v111
	v_add_f32_e32 v100, v100, v108
	v_add_f32_e32 v101, v101, v109
	v_lshlrev_b32_e32 v114, 16, v147
	v_and_b32_e32 v115, 0xffff0000, v147
	v_add_f32_e32 v110, v96, v112
	v_add_f32_e32 v111, v97, v113
	v_mul_f32_e32 v96, v101, v101
	v_mul_f32_e32 v97, v103, v103
	v_add_f32_e32 v108, v98, v114
	v_add_f32_e32 v109, v99, v115
	v_fmac_f32_e32 v96, v100, v100
	v_fmac_f32_e32 v97, v102, v102
	v_add_f32_e32 v96, v96, v97
	v_mul_f32_e32 v97, v111, v111
	v_mul_f32_e32 v98, v109, v109
	v_fmac_f32_e32 v97, v110, v110
	v_fmac_f32_e32 v98, v108, v108
	v_add_f32_e32 v97, v97, v98
	v_add_f32_e32 v96, v96, v97
	v_add_f32_e32 v99, v116, v96
	ds_bpermute_b32 v114, v196, v99
	v_lshl_add_u64 v[96:97], s[16:17], 0, v[184:185]
	v_lshl_add_u64 v[112:113], v[168:169], 1, v[96:97]
	global_store_dwordx4 v[112:113], v[104:107], off
	v_cvt_pk_bf16_f32 v98, v100, v101
	s_waitcnt lgkmcnt(0)
	v_add_f32_e32 v96, v99, v114
	ds_bpermute_b32 v97, v197, v96
	v_cvt_pk_bf16_f32 v99, v102, v103
	v_cvt_pk_bf16_f32 v100, v110, v111
	v_cvt_pk_bf16_f32 v101, v108, v109
	global_store_dwordx4 v[112:113], v[98:101], off offset:256
	s_and_saveexec_b64 s[34:35], s[4:5]
	s_cbranch_execz .LBB0_1131
	v_lshlrev_b64 v[98:99], 6, v[182:183]
	v_lshl_add_u64 v[98:99], s[22:23], 0, v[98:99]
	v_lshl_add_u64 v[98:99], s[30:31], 2, v[98:99]
	s_lshl_b32 s10, s45, 2
	v_lshl_add_u64 v[98:99], v[98:99], 0, s[10:11]
	s_waitcnt lgkmcnt(0)
	v_add_f32_e32 v96, v96, v97
	global_store_dword v[98:99], v96, off
.LBB0_1131:
	s_or_b64 exec, exec, s[34:35]
	v_lshlrev_b32_e32 v96, 16, v140
	s_waitcnt lgkmcnt(0)
	v_and_b32_e32 v97, 0xffff0000, v140
	v_lshlrev_b32_e32 v98, 16, v141
	v_and_b32_e32 v99, 0xffff0000, v141
	v_lshlrev_b32_e32 v100, 16, v142
	v_and_b32_e32 v101, 0xffff0000, v142
	v_lshlrev_b32_e32 v102, 16, v143
	v_and_b32_e32 v103, 0xffff0000, v143
	v_add_f32_e32 v94, v94, v98
	v_add_f32_e32 v95, v95, v99
	v_add_f32_e32 v92, v92, v96
	v_add_f32_e32 v93, v93, v97
	v_add_f32_e32 v96, v90, v102
	v_add_f32_e32 v97, v91, v103
	v_add_f32_e32 v90, v88, v100
	v_add_f32_e32 v91, v89, v101
	v_mul_f32_e32 v88, v93, v93
	v_mul_f32_e32 v89, v95, v95
	v_fmac_f32_e32 v88, v92, v92
	v_fmac_f32_e32 v89, v94, v94
	v_add_f32_e32 v88, v88, v89
	v_mul_f32_e32 v89, v91, v91
	v_mul_f32_e32 v98, v97, v97
	v_fmac_f32_e32 v89, v90, v90
	v_fmac_f32_e32 v98, v96, v96
	v_add_f32_e32 v89, v89, v98
	v_add_f32_e32 v100, v88, v89
	v_cvt_pk_bf16_f32 v88, v92, v93
	v_cvt_pk_bf16_f32 v89, v94, v95
	v_lshlrev_b32_e32 v92, 16, v136
	v_and_b32_e32 v93, 0xffff0000, v136
	v_lshlrev_b32_e32 v94, 16, v137
	v_and_b32_e32 v95, 0xffff0000, v137
	v_cvt_pk_bf16_f32 v90, v90, v91
	v_cvt_pk_bf16_f32 v91, v96, v97
	v_lshlrev_b32_e32 v96, 16, v138
	v_and_b32_e32 v97, 0xffff0000, v138
	v_add_f32_e32 v86, v86, v94
	v_add_f32_e32 v87, v87, v95
	v_add_f32_e32 v84, v84, v92
	v_add_f32_e32 v85, v85, v93
	v_lshlrev_b32_e32 v98, 16, v139
	v_and_b32_e32 v99, 0xffff0000, v139
	v_add_f32_e32 v94, v80, v96
	v_add_f32_e32 v95, v81, v97
	v_mul_f32_e32 v80, v85, v85
	v_mul_f32_e32 v81, v87, v87
	v_add_f32_e32 v92, v82, v98
	v_add_f32_e32 v93, v83, v99
	v_fmac_f32_e32 v80, v84, v84
	v_fmac_f32_e32 v81, v86, v86
	v_add_f32_e32 v80, v80, v81
	v_mul_f32_e32 v81, v95, v95
	v_mul_f32_e32 v82, v93, v93
	v_fmac_f32_e32 v81, v94, v94
	v_fmac_f32_e32 v82, v92, v92
	v_add_f32_e32 v81, v81, v82
	v_add_f32_e32 v80, v80, v81
	v_add_f32_e32 v83, v100, v80
	ds_bpermute_b32 v98, v196, v83
	v_lshl_add_u64 v[80:81], s[16:17], 0, v[180:181]
	v_lshl_add_u64 v[96:97], v[168:169], 1, v[80:81]
	global_store_dwordx4 v[96:97], v[88:91], off
	v_cvt_pk_bf16_f32 v82, v84, v85
	s_waitcnt lgkmcnt(0)
	v_add_f32_e32 v80, v83, v98
	ds_bpermute_b32 v81, v197, v80
	v_cvt_pk_bf16_f32 v83, v86, v87
	v_cvt_pk_bf16_f32 v84, v94, v95
	v_cvt_pk_bf16_f32 v85, v92, v93
	global_store_dwordx4 v[96:97], v[82:85], off offset:256
	s_and_saveexec_b64 s[34:35], s[4:5]
	s_cbranch_execz .LBB0_1133
	v_lshlrev_b64 v[82:83], 6, v[178:179]
	v_lshl_add_u64 v[82:83], s[22:23], 0, v[82:83]
	v_lshl_add_u64 v[82:83], s[30:31], 2, v[82:83]
	s_lshl_b32 s10, s45, 2
	v_lshl_add_u64 v[82:83], v[82:83], 0, s[10:11]
	s_waitcnt lgkmcnt(0)
	v_add_f32_e32 v80, v80, v81
	global_store_dword v[82:83], v80, off
.LBB0_1133:
	s_or_b64 exec, exec, s[34:35]
	v_lshlrev_b32_e32 v80, 16, v132
	s_waitcnt lgkmcnt(0)
	v_and_b32_e32 v81, 0xffff0000, v132
	v_lshlrev_b32_e32 v82, 16, v133
	v_and_b32_e32 v83, 0xffff0000, v133
	v_lshlrev_b32_e32 v84, 16, v134
	v_and_b32_e32 v85, 0xffff0000, v134
	v_lshlrev_b32_e32 v86, 16, v135
	v_and_b32_e32 v87, 0xffff0000, v135
	v_add_f32_e32 v78, v78, v82
	v_add_f32_e32 v79, v79, v83
	v_add_f32_e32 v76, v76, v80
	v_add_f32_e32 v77, v77, v81
	v_add_f32_e32 v80, v74, v86
	v_add_f32_e32 v81, v75, v87
	v_add_f32_e32 v74, v72, v84
	v_add_f32_e32 v75, v73, v85
	v_mul_f32_e32 v72, v77, v77
	v_mul_f32_e32 v73, v79, v79
	v_fmac_f32_e32 v72, v76, v76
	v_fmac_f32_e32 v73, v78, v78
	v_add_f32_e32 v72, v72, v73
	v_mul_f32_e32 v73, v75, v75
	v_mul_f32_e32 v82, v81, v81
	v_fmac_f32_e32 v73, v74, v74
	v_fmac_f32_e32 v82, v80, v80
	v_add_f32_e32 v73, v73, v82
	v_add_f32_e32 v84, v72, v73
	v_cvt_pk_bf16_f32 v72, v76, v77
	v_cvt_pk_bf16_f32 v73, v78, v79
	v_lshlrev_b32_e32 v76, 16, v128
	v_and_b32_e32 v77, 0xffff0000, v128
	v_lshlrev_b32_e32 v78, 16, v129
	v_and_b32_e32 v79, 0xffff0000, v129
	v_cvt_pk_bf16_f32 v74, v74, v75
	v_cvt_pk_bf16_f32 v75, v80, v81
	v_lshlrev_b32_e32 v80, 16, v130
	v_and_b32_e32 v81, 0xffff0000, v130
	v_add_f32_e32 v70, v70, v78
	v_add_f32_e32 v71, v71, v79
	v_add_f32_e32 v68, v68, v76
	v_add_f32_e32 v69, v69, v77
	v_lshlrev_b32_e32 v82, 16, v131
	v_and_b32_e32 v83, 0xffff0000, v131
	v_add_f32_e32 v78, v64, v80
	v_add_f32_e32 v79, v65, v81
	v_mul_f32_e32 v64, v69, v69
	v_mul_f32_e32 v65, v71, v71
	v_add_f32_e32 v76, v66, v82
	v_add_f32_e32 v77, v67, v83
	v_fmac_f32_e32 v64, v68, v68
	v_fmac_f32_e32 v65, v70, v70
	v_add_f32_e32 v64, v64, v65
	v_mul_f32_e32 v65, v79, v79
	v_mul_f32_e32 v66, v77, v77
	v_fmac_f32_e32 v65, v78, v78
	v_fmac_f32_e32 v66, v76, v76
	v_add_f32_e32 v65, v65, v66
	v_add_f32_e32 v64, v64, v65
	v_add_f32_e32 v67, v84, v64
	ds_bpermute_b32 v82, v196, v67
	v_lshl_add_u64 v[64:65], s[16:17], 0, v[176:177]
	v_lshl_add_u64 v[80:81], v[168:169], 1, v[64:65]
	global_store_dwordx4 v[80:81], v[72:75], off
	v_cvt_pk_bf16_f32 v66, v68, v69
	s_waitcnt lgkmcnt(0)
	v_add_f32_e32 v64, v67, v82
	ds_bpermute_b32 v65, v197, v64
	v_cvt_pk_bf16_f32 v67, v70, v71
	v_cvt_pk_bf16_f32 v68, v78, v79
	v_cvt_pk_bf16_f32 v69, v76, v77
	global_store_dwordx4 v[80:81], v[66:69], off offset:256
	s_and_saveexec_b64 s[34:35], s[4:5]
	s_cbranch_execz .LBB0_1135
	v_lshlrev_b64 v[66:67], 6, v[174:175]
	v_lshl_add_u64 v[66:67], s[22:23], 0, v[66:67]
	v_lshl_add_u64 v[66:67], s[30:31], 2, v[66:67]
	s_lshl_b32 s10, s45, 2
	v_lshl_add_u64 v[66:67], v[66:67], 0, s[10:11]
	s_waitcnt lgkmcnt(0)
	v_add_f32_e32 v64, v64, v65
	global_store_dword v[66:67], v64, off
.LBB0_1135:
	s_or_b64 exec, exec, s[34:35]
	v_add_u32_e32 v100, 0x80, v172
	v_ashrrev_i32_e32 v101, 31, v100
	v_lshlrev_b64 v[110:111], 11, v[100:101]
	s_waitcnt lgkmcnt(0)
	v_lshl_add_u64 v[64:65], v[170:171], 0, v[110:111]
	global_load_dwordx4 v[102:105], v[64:65], off
	global_load_dwordx4 v[106:109], v[64:65], off offset:256
	v_add_u32_e32 v96, 0x90, v172
	v_add_u32_e32 v92, 0xa0, v172
	v_add_u32_e32 v88, 0xb0, v172
	v_ashrrev_i32_e32 v97, 31, v96
	v_ashrrev_i32_e32 v93, 31, v92
	v_ashrrev_i32_e32 v89, 31, v88
	v_lshlrev_b64 v[98:99], 11, v[96:97]
	v_lshlrev_b64 v[94:95], 11, v[92:93]
	v_lshlrev_b64 v[90:91], 11, v[88:89]
	v_lshl_add_u64 v[64:65], v[170:171], 0, v[98:99]
	v_lshl_add_u64 v[66:67], v[170:171], 0, v[94:95]
	v_lshl_add_u64 v[112:113], v[170:171], 0, v[90:91]
	global_load_dwordx4 v[84:87], v[64:65], off
	global_load_dwordx4 v[80:83], v[64:65], off offset:256
	global_load_dwordx4 v[76:79], v[66:67], off
	global_load_dwordx4 v[72:75], v[66:67], off offset:256
	global_load_dwordx4 v[68:71], v[112:113], off
	s_nop 0
	global_load_dwordx4 v[64:67], v[112:113], off offset:256
	s_waitcnt vmcnt(7)
	v_lshlrev_b32_e32 v112, 16, v102
	v_and_b32_e32 v113, 0xffff0000, v102
	v_lshlrev_b32_e32 v102, 16, v103
	v_and_b32_e32 v103, 0xffff0000, v103
	v_lshlrev_b32_e32 v114, 16, v104
	v_and_b32_e32 v115, 0xffff0000, v104
	v_lshlrev_b32_e32 v104, 16, v105
	v_and_b32_e32 v105, 0xffff0000, v105
	s_waitcnt vmcnt(6)
	v_lshlrev_b32_e32 v116, 16, v106
	v_and_b32_e32 v117, 0xffff0000, v106
	v_lshlrev_b32_e32 v106, 16, v107
	v_and_b32_e32 v107, 0xffff0000, v107
	v_lshlrev_b32_e32 v118, 16, v108
	v_and_b32_e32 v119, 0xffff0000, v108
	v_lshlrev_b32_e32 v108, 16, v109
	v_and_b32_e32 v109, 0xffff0000, v109
	v_add_f32_e32 v62, v62, v102
	v_add_f32_e32 v63, v63, v103
	v_add_f32_e32 v60, v60, v112
	v_add_f32_e32 v61, v61, v113
	v_add_f32_e32 v58, v58, v104
	v_add_f32_e32 v59, v59, v105
	v_add_f32_e32 v56, v56, v114
	v_add_f32_e32 v57, v57, v115
	v_add_f32_e32 v54, v54, v106
	v_add_f32_e32 v55, v55, v107
	v_add_f32_e32 v52, v52, v116
	v_add_f32_e32 v53, v53, v117
	v_add_f32_e32 v102, v50, v108
	v_add_f32_e32 v103, v51, v109
	v_add_f32_e32 v104, v48, v118
	v_add_f32_e32 v105, v49, v119
	v_mul_f32_e32 v106, v61, v61
	v_mul_f32_e32 v107, v63, v63
	v_mul_f32_e32 v108, v57, v57
	v_mul_f32_e32 v109, v59, v59
	v_cvt_pk_bf16_f32 v48, v60, v61
	v_cvt_pk_bf16_f32 v49, v62, v63
	v_cvt_pk_bf16_f32 v50, v56, v57
	v_cvt_pk_bf16_f32 v51, v58, v59
	v_mul_f32_e32 v57, v53, v53
	v_mul_f32_e32 v59, v55, v55
	v_mul_f32_e32 v61, v105, v105
	v_mul_f32_e32 v63, v103, v103
	v_fmac_f32_e32 v106, v60, v60
	v_fmac_f32_e32 v107, v62, v62
	v_fmac_f32_e32 v108, v56, v56
	v_fmac_f32_e32 v109, v58, v58
	v_fmac_f32_e32 v57, v52, v52
	v_fmac_f32_e32 v59, v54, v54
	v_fmac_f32_e32 v61, v104, v104
	v_fmac_f32_e32 v63, v102, v102
	v_add_f32_e32 v56, v106, v107
	v_add_f32_e32 v58, v108, v109
	v_add_f32_e32 v57, v57, v59
	v_add_f32_e32 v59, v61, v63
	v_add_f32_e32 v56, v56, v58
	v_add_f32_e32 v57, v57, v59
	v_add_f32_e32 v58, v56, v57
	ds_bpermute_b32 v59, v196, v58
	v_lshl_add_u64 v[56:57], s[16:17], 0, v[110:111]
	v_lshl_add_u64 v[56:57], v[168:169], 1, v[56:57]
	global_store_dwordx4 v[56:57], v[48:51], off
	s_waitcnt lgkmcnt(0)
	s_nop 0
	v_add_f32_e32 v48, v58, v59
	ds_bpermute_b32 v49, v197, v48
	v_cvt_pk_bf16_f32 v50, v52, v53
	v_cvt_pk_bf16_f32 v51, v54, v55
	v_cvt_pk_bf16_f32 v52, v104, v105
	v_cvt_pk_bf16_f32 v53, v102, v103
	global_store_dwordx4 v[56:57], v[50:53], off offset:256
	s_and_saveexec_b64 s[34:35], s[4:5]
	s_cbranch_execz .LBB0_1137
	v_lshlrev_b64 v[50:51], 6, v[100:101]
	v_lshl_add_u64 v[50:51], s[22:23], 0, v[50:51]
	v_lshl_add_u64 v[50:51], s[30:31], 2, v[50:51]
	s_lshl_b32 s10, s45, 2
	v_lshl_add_u64 v[50:51], v[50:51], 0, s[10:11]
	s_waitcnt lgkmcnt(0)
	v_add_f32_e32 v48, v48, v49
	global_store_dword v[50:51], v48, off
.LBB0_1137:
	s_or_b64 exec, exec, s[34:35]
	s_waitcnt vmcnt(7)
	v_lshlrev_b32_e32 v48, 16, v84
	s_waitcnt lgkmcnt(0)
	v_and_b32_e32 v49, 0xffff0000, v84
	v_lshlrev_b32_e32 v50, 16, v85
	v_and_b32_e32 v51, 0xffff0000, v85
	v_lshlrev_b32_e32 v52, 16, v86
	v_and_b32_e32 v53, 0xffff0000, v86
	v_lshlrev_b32_e32 v54, 16, v87
	v_and_b32_e32 v55, 0xffff0000, v87
	v_add_f32_e32 v46, v46, v50
	v_add_f32_e32 v47, v47, v51
	v_add_f32_e32 v44, v44, v48
	v_add_f32_e32 v45, v45, v49
	v_add_f32_e32 v48, v42, v54
	v_add_f32_e32 v49, v43, v55
	v_add_f32_e32 v42, v40, v52
	v_add_f32_e32 v43, v41, v53
	v_mul_f32_e32 v40, v45, v45
	v_mul_f32_e32 v41, v47, v47
	v_fmac_f32_e32 v40, v44, v44
	v_fmac_f32_e32 v41, v46, v46
	v_add_f32_e32 v40, v40, v41
	v_mul_f32_e32 v41, v43, v43
	v_mul_f32_e32 v50, v49, v49
	v_fmac_f32_e32 v41, v42, v42
	v_fmac_f32_e32 v50, v48, v48
	v_add_f32_e32 v41, v41, v50
	v_add_f32_e32 v52, v40, v41
	v_cvt_pk_bf16_f32 v40, v44, v45
	v_cvt_pk_bf16_f32 v41, v46, v47
	s_waitcnt vmcnt(6)
	v_lshlrev_b32_e32 v44, 16, v80
	v_and_b32_e32 v45, 0xffff0000, v80
	v_lshlrev_b32_e32 v46, 16, v81
	v_and_b32_e32 v47, 0xffff0000, v81
	v_cvt_pk_bf16_f32 v42, v42, v43
	v_cvt_pk_bf16_f32 v43, v48, v49
	v_lshlrev_b32_e32 v48, 16, v82
	v_and_b32_e32 v49, 0xffff0000, v82
	v_add_f32_e32 v38, v38, v46
	v_add_f32_e32 v39, v39, v47
	v_add_f32_e32 v36, v36, v44
	v_add_f32_e32 v37, v37, v45
	v_lshlrev_b32_e32 v50, 16, v83
	v_and_b32_e32 v51, 0xffff0000, v83
	v_add_f32_e32 v46, v32, v48
	v_add_f32_e32 v47, v33, v49
	v_mul_f32_e32 v32, v37, v37
	v_mul_f32_e32 v33, v39, v39
	v_add_f32_e32 v44, v34, v50
	v_add_f32_e32 v45, v35, v51
	v_fmac_f32_e32 v32, v36, v36
	v_fmac_f32_e32 v33, v38, v38
	v_add_f32_e32 v32, v32, v33
	v_mul_f32_e32 v33, v47, v47
	v_mul_f32_e32 v34, v45, v45
	v_fmac_f32_e32 v33, v46, v46
	v_fmac_f32_e32 v34, v44, v44
	v_add_f32_e32 v33, v33, v34
	v_add_f32_e32 v32, v32, v33
	v_add_f32_e32 v35, v52, v32
	ds_bpermute_b32 v50, v196, v35
	v_lshl_add_u64 v[32:33], s[16:17], 0, v[98:99]
	v_lshl_add_u64 v[48:49], v[168:169], 1, v[32:33]
	global_store_dwordx4 v[48:49], v[40:43], off
	v_cvt_pk_bf16_f32 v34, v36, v37
	s_waitcnt lgkmcnt(0)
	v_add_f32_e32 v32, v35, v50
	ds_bpermute_b32 v33, v197, v32
	v_cvt_pk_bf16_f32 v35, v38, v39
	v_cvt_pk_bf16_f32 v36, v46, v47
	v_cvt_pk_bf16_f32 v37, v44, v45
	global_store_dwordx4 v[48:49], v[34:37], off offset:256
	s_and_saveexec_b64 s[34:35], s[4:5]
	s_cbranch_execz .LBB0_1139
	v_lshlrev_b64 v[34:35], 6, v[96:97]
	v_lshl_add_u64 v[34:35], s[22:23], 0, v[34:35]
	v_lshl_add_u64 v[34:35], s[30:31], 2, v[34:35]
	s_lshl_b32 s10, s45, 2
	v_lshl_add_u64 v[34:35], v[34:35], 0, s[10:11]
	s_waitcnt lgkmcnt(0)
	v_add_f32_e32 v32, v32, v33
	global_store_dword v[34:35], v32, off
.LBB0_1139:
	s_or_b64 exec, exec, s[34:35]
	s_waitcnt vmcnt(7)
	v_lshlrev_b32_e32 v32, 16, v76
	s_waitcnt lgkmcnt(0)
	v_and_b32_e32 v33, 0xffff0000, v76
	v_lshlrev_b32_e32 v34, 16, v77
	v_and_b32_e32 v35, 0xffff0000, v77
	v_lshlrev_b32_e32 v36, 16, v78
	v_and_b32_e32 v37, 0xffff0000, v78
	v_lshlrev_b32_e32 v38, 16, v79
	v_and_b32_e32 v39, 0xffff0000, v79
	v_add_f32_e32 v30, v30, v34
	v_add_f32_e32 v31, v31, v35
	v_add_f32_e32 v28, v28, v32
	v_add_f32_e32 v29, v29, v33
	v_add_f32_e32 v32, v26, v38
	v_add_f32_e32 v33, v27, v39
	v_add_f32_e32 v26, v24, v36
	v_add_f32_e32 v27, v25, v37
	v_mul_f32_e32 v24, v29, v29
	v_mul_f32_e32 v25, v31, v31
	v_fmac_f32_e32 v24, v28, v28
	v_fmac_f32_e32 v25, v30, v30
	v_add_f32_e32 v24, v24, v25
	v_mul_f32_e32 v25, v27, v27
	v_mul_f32_e32 v34, v33, v33
	v_fmac_f32_e32 v25, v26, v26
	v_fmac_f32_e32 v34, v32, v32
	v_add_f32_e32 v25, v25, v34
	v_add_f32_e32 v36, v24, v25
	v_cvt_pk_bf16_f32 v24, v28, v29
	v_cvt_pk_bf16_f32 v25, v30, v31
	s_waitcnt vmcnt(6)
	v_lshlrev_b32_e32 v28, 16, v72
	v_and_b32_e32 v29, 0xffff0000, v72
	v_lshlrev_b32_e32 v30, 16, v73
	v_and_b32_e32 v31, 0xffff0000, v73
	v_cvt_pk_bf16_f32 v26, v26, v27
	v_cvt_pk_bf16_f32 v27, v32, v33
	v_lshlrev_b32_e32 v32, 16, v74
	v_and_b32_e32 v33, 0xffff0000, v74
	v_add_f32_e32 v22, v22, v30
	v_add_f32_e32 v23, v23, v31
	v_add_f32_e32 v20, v20, v28
	v_add_f32_e32 v21, v21, v29
	v_lshlrev_b32_e32 v34, 16, v75
	v_and_b32_e32 v35, 0xffff0000, v75
	v_add_f32_e32 v30, v16, v32
	v_add_f32_e32 v31, v17, v33
	v_mul_f32_e32 v16, v21, v21
	v_mul_f32_e32 v17, v23, v23
	v_add_f32_e32 v28, v18, v34
	v_add_f32_e32 v29, v19, v35
	v_fmac_f32_e32 v16, v20, v20
	v_fmac_f32_e32 v17, v22, v22
	v_add_f32_e32 v16, v16, v17
	v_mul_f32_e32 v17, v31, v31
	v_mul_f32_e32 v18, v29, v29
	v_fmac_f32_e32 v17, v30, v30
	v_fmac_f32_e32 v18, v28, v28
	v_add_f32_e32 v17, v17, v18
	v_add_f32_e32 v16, v16, v17
	v_add_f32_e32 v19, v36, v16
	ds_bpermute_b32 v34, v196, v19
	v_lshl_add_u64 v[16:17], s[16:17], 0, v[94:95]
	v_lshl_add_u64 v[32:33], v[168:169], 1, v[16:17]
	global_store_dwordx4 v[32:33], v[24:27], off
	v_cvt_pk_bf16_f32 v18, v20, v21
	s_waitcnt lgkmcnt(0)
	v_add_f32_e32 v16, v19, v34
	ds_bpermute_b32 v17, v197, v16
	v_cvt_pk_bf16_f32 v19, v22, v23
	v_cvt_pk_bf16_f32 v20, v30, v31
	v_cvt_pk_bf16_f32 v21, v28, v29
	global_store_dwordx4 v[32:33], v[18:21], off offset:256
	s_and_saveexec_b64 s[34:35], s[4:5]
	s_cbranch_execz .LBB0_1141
	v_lshlrev_b64 v[18:19], 6, v[92:93]
	v_lshl_add_u64 v[18:19], s[22:23], 0, v[18:19]
	v_lshl_add_u64 v[18:19], s[30:31], 2, v[18:19]
	s_lshl_b32 s10, s45, 2
	v_lshl_add_u64 v[18:19], v[18:19], 0, s[10:11]
	s_waitcnt lgkmcnt(0)
	v_add_f32_e32 v16, v16, v17
	global_store_dword v[18:19], v16, off
.LBB0_1141:
	s_or_b64 exec, exec, s[34:35]
	s_waitcnt vmcnt(7)
	v_lshlrev_b32_e32 v16, 16, v68
	s_waitcnt lgkmcnt(0)
	v_and_b32_e32 v17, 0xffff0000, v68
	v_lshlrev_b32_e32 v18, 16, v69
	v_and_b32_e32 v19, 0xffff0000, v69
	v_lshlrev_b32_e32 v20, 16, v70
	v_and_b32_e32 v21, 0xffff0000, v70
	v_lshlrev_b32_e32 v22, 16, v71
	v_and_b32_e32 v23, 0xffff0000, v71
	v_add_f32_e32 v14, v14, v18
	v_add_f32_e32 v15, v15, v19
	v_add_f32_e32 v12, v12, v16
	v_add_f32_e32 v13, v13, v17
	v_add_f32_e32 v16, v10, v22
	v_add_f32_e32 v17, v11, v23
	v_add_f32_e32 v10, v8, v20
	v_add_f32_e32 v11, v9, v21
	v_mul_f32_e32 v8, v13, v13
	v_mul_f32_e32 v9, v15, v15
	v_fmac_f32_e32 v8, v12, v12
	v_fmac_f32_e32 v9, v14, v14
	v_add_f32_e32 v8, v8, v9
	v_mul_f32_e32 v9, v11, v11
	v_mul_f32_e32 v18, v17, v17
	v_fmac_f32_e32 v9, v10, v10
	v_fmac_f32_e32 v18, v16, v16
	v_add_f32_e32 v9, v9, v18
	v_add_f32_e32 v20, v8, v9
	v_cvt_pk_bf16_f32 v8, v12, v13
	v_cvt_pk_bf16_f32 v9, v14, v15
	s_waitcnt vmcnt(6)
	v_lshlrev_b32_e32 v12, 16, v64
	v_and_b32_e32 v13, 0xffff0000, v64
	v_lshlrev_b32_e32 v14, 16, v65
	v_and_b32_e32 v15, 0xffff0000, v65
	v_cvt_pk_bf16_f32 v10, v10, v11
	v_cvt_pk_bf16_f32 v11, v16, v17
	v_lshlrev_b32_e32 v16, 16, v66
	v_and_b32_e32 v17, 0xffff0000, v66
	v_add_f32_e32 v6, v6, v14
	v_add_f32_e32 v7, v7, v15
	v_add_f32_e32 v4, v4, v12
	v_add_f32_e32 v5, v5, v13
	v_lshlrev_b32_e32 v18, 16, v67
	v_and_b32_e32 v19, 0xffff0000, v67
	v_add_f32_e32 v14, v0, v16
	v_add_f32_e32 v15, v1, v17
	v_mul_f32_e32 v0, v5, v5
	v_mul_f32_e32 v1, v7, v7
	v_add_f32_e32 v12, v2, v18
	v_add_f32_e32 v13, v3, v19
	v_fmac_f32_e32 v0, v4, v4
	v_fmac_f32_e32 v1, v6, v6
	v_add_f32_e32 v0, v0, v1
	v_mul_f32_e32 v1, v15, v15
	v_mul_f32_e32 v2, v13, v13
	v_fmac_f32_e32 v1, v14, v14
	v_fmac_f32_e32 v2, v12, v12
	v_add_f32_e32 v1, v1, v2
	v_add_f32_e32 v0, v0, v1
	v_add_f32_e32 v3, v20, v0
	ds_bpermute_b32 v18, v196, v3
	v_lshl_add_u64 v[0:1], s[16:17], 0, v[90:91]
	v_lshl_add_u64 v[16:17], v[168:169], 1, v[0:1]
	global_store_dwordx4 v[16:17], v[8:11], off
	v_cvt_pk_bf16_f32 v2, v4, v5
	s_waitcnt lgkmcnt(0)
	v_add_f32_e32 v0, v3, v18
	ds_bpermute_b32 v1, v197, v0
	v_cvt_pk_bf16_f32 v3, v6, v7
	v_cvt_pk_bf16_f32 v4, v14, v15
	v_cvt_pk_bf16_f32 v5, v12, v13
	global_store_dwordx4 v[16:17], v[2:5], off offset:256
	s_and_saveexec_b64 s[34:35], s[4:5]
	s_cbranch_execz .LBB0_1143
	v_lshlrev_b64 v[2:3], 6, v[88:89]
	v_lshl_add_u64 v[2:3], s[22:23], 0, v[2:3]
	v_lshl_add_u64 v[2:3], s[30:31], 2, v[2:3]
	s_lshl_b32 s10, s45, 2
	v_lshl_add_u64 v[2:3], v[2:3], 0, s[10:11]
	s_waitcnt lgkmcnt(0)
	v_add_f32_e32 v0, v0, v1
	global_store_dword v[2:3], v0, off

.LBB0_1200:
	s_add_i32 s19, s94, s20
	s_cmp_lt_i32 s19, 0x8000
	s_cselect_b32 s50, s19, s20
	s_ashr_i32 s51, s50, 31
	s_lshl_b64 s[0:1], s[50:51], 11
	s_add_i32 s42, s72, s20
	s_cmp_lt_i32 s42, 0x8000
	s_cselect_b64 s[44:45], -1, 0
	s_and_b64 s[22:23], s[44:45], exec
	s_cselect_b32 s52, s42, s20
	s_ashr_i32 s53, s52, 31
	s_lshl_b64 s[46:47], s[52:53], 11
	s_add_i32 s38, s80, s20
	s_cmp_lt_i32 s38, 0x8000
	s_cselect_b64 s[40:41], -1, 0
	s_and_b64 s[22:23], s[40:41], exec
	s_cselect_b32 s62, s38, s20
	s_ashr_i32 s63, s62, 31
	s_lshl_b64 s[48:49], s[62:63], 11
	s_add_i32 s34, s73, s20
	s_cmp_lt_i32 s34, 0x8000
	s_cselect_b64 s[36:37], -1, 0
	s_and_b64 s[22:23], s[36:37], exec
	s_cselect_b32 s64, s34, s20
	s_ashr_i32 s65, s64, 31
	s_lshl_b64 s[54:55], s[64:65], 11
	s_add_i32 s28, s81, s20
	s_cmp_lt_i32 s28, 0x8000
	s_cselect_b64 s[30:31], -1, 0
	s_and_b64 s[22:23], s[30:31], exec
	s_cselect_b32 s66, s28, s20
	s_ashr_i32 s67, s66, 31
	s_lshl_b64 s[56:57], s[66:67], 11
	s_add_i32 s24, s82, s20
	s_cmp_lt_i32 s24, 0x8000
	s_cselect_b64 s[26:27], -1, 0
	s_and_b64 s[22:23], s[26:27], exec
	s_cselect_b32 s76, s24, s20
	s_ashr_i32 s77, s76, 31
	s_lshl_b64 s[68:69], s[76:77], 11
	s_add_i32 s18, s83, s20
	s_cmp_lt_i32 s18, 0x8000
	s_cselect_b64 s[22:23], -1, 0
	s_and_b64 s[58:59], s[22:23], exec
	s_cselect_b32 s78, s18, s20
	s_ashr_i32 s79, s78, 31
	s_lshl_b64 s[70:71], s[78:79], 11
	s_lshl_b64 s[50:51], s[50:51], 6
	s_add_u32 s58, s21, s50
	s_addc_u32 s59, s33, s51
	s_lshl_b64 s[50:51], s[52:53], 6
	s_add_u32 s60, s21, s50
	s_addc_u32 s61, s33, s51
	s_lshl_b64 s[50:51], s[62:63], 6
	s_add_u32 s62, s21, s50
	s_addc_u32 s63, s33, s51
	s_lshl_b64 s[50:51], s[64:65], 6
	s_add_u32 s64, s21, s50
	s_addc_u32 s65, s33, s51
	s_lshl_b64 s[50:51], s[66:67], 6
	s_add_u32 s66, s21, s50
	s_addc_u32 s67, s33, s51
	s_lshl_b64 s[50:51], s[76:77], 6
	s_add_u32 s50, s21, s50
	s_addc_u32 s51, s33, s51
	s_lshl_b64 s[52:53], s[78:79], 6
	s_add_u32 s52, s21, s52
	s_addc_u32 s53, s33, s53
	s_add_u32 s76, s2, s12
	s_addc_u32 s77, s3, s13
	global_load_dwordx4 v[32:35], v192, s[76:77]
	s_add_u32 s76, s76, 0x200000
	s_addc_u32 s77, s77, 0
	global_load_dwordx4 v[36:39], v185, s[76:77] offset:16
	global_load_dwordx4 v[40:43], v185, s[76:77] offset:32
	global_load_dwordx4 v[196:199], v185, s[76:77] offset:48
	v_lshl_add_u64 v[16:17], s[2:3], 0, v[190:191]
	s_waitcnt vmcnt(12)
	v_add_co_u32_e32 v26, vcc, s75, v16
	v_lshl_add_u64 v[24:25], v[16:17], 0, s[4:5]
	s_nop 0
	v_addc_co_u32_e32 v27, vcc, 0, v17, vcc
	s_waitcnt vmcnt(9)
	v_lshl_add_u64 v[64:65], v[186:187], 0, s[0:1]
	v_lshl_add_u64 v[16:17], v[186:187], 0, s[46:47]
	v_lshl_add_u64 v[18:19], v[186:187], 0, s[48:49]
	global_load_dwordx4 v[152:155], v[64:65], off offset:16
	global_load_dwordx4 v[140:143], v[16:17], off
	global_load_dwordx4 v[128:131], v[16:17], off offset:16
	global_load_dwordx4 v[116:119], v[18:19], off
	v_lshl_add_u64 v[16:17], v[186:187], 0, s[54:55]
	global_load_dwordx4 v[104:107], v[18:19], off offset:16
	global_load_dwordx4 v[92:95], v[16:17], off
	v_lshl_add_u64 v[18:19], v[186:187], 0, s[56:57]
	global_load_dwordx4 v[76:79], v[16:17], off offset:16
	global_load_dwordx4 v[68:71], v[18:19], off
	v_lshl_add_u64 v[16:17], v[186:187], 0, s[68:69]
	global_load_dwordx4 v[52:55], v[18:19], off offset:16
	global_load_dwordx4 v[44:47], v[16:17], off
	v_lshl_add_u64 v[18:19], v[186:187], 0, s[70:71]
	global_load_dwordx4 v[28:31], v[16:17], off offset:16
	global_load_dwordx4 v[20:23], v[18:19], off
	s_nop 0
	global_load_dwordx4 v[16:19], v[18:19], off offset:16
	s_nop 0
	global_load_dwordx4 v[200:203], v[24:25], off offset:16
	global_load_dwordx4 v[172:175], v185, s[58:59] offset:32
	global_load_dwordx4 v[176:179], v185, s[58:59] offset:16
	global_load_dwordx4 v[180:183], v185, s[58:59]
	global_load_dwordx4 v[204:207], v[26:27], off
	global_load_dwordx4 v[144:147], v185, s[60:61] offset:32
	global_load_dwordx4 v[156:159], v185, s[60:61] offset:16
	global_load_dwordx4 v[168:171], v185, s[58:59] offset:48
	global_load_dwordx4 v[160:163], v185, s[60:61]
	global_load_dwordx4 v[120:123], v185, s[62:63] offset:32
	global_load_dwordx4 v[132:135], v185, s[62:63] offset:16
	global_load_dwordx4 v[148:151], v185, s[60:61] offset:48
	global_load_dwordx4 v[136:139], v185, s[62:63]
	global_load_dwordx4 v[96:99], v185, s[64:65] offset:32
	global_load_dwordx4 v[108:111], v185, s[64:65] offset:16
	global_load_dwordx4 v[124:127], v185, s[62:63] offset:48
	global_load_dwordx4 v[112:115], v185, s[64:65]
	global_load_dwordx4 v[72:75], v185, s[66:67] offset:32
	global_load_dwordx4 v[84:87], v185, s[66:67] offset:16
	global_load_dwordx4 v[100:103], v185, s[64:65] offset:48
	global_load_dwordx4 v[88:91], v185, s[66:67]
	global_load_dwordx4 v[48:51], v185, s[50:51] offset:32
	global_load_dwordx4 v[56:59], v185, s[50:51] offset:16
	global_load_dwordx4 v[80:83], v185, s[66:67] offset:48
	global_load_dwordx4 v[60:63], v185, s[50:51]
	global_load_dwordx4 v[164:167], v[64:65], off
	global_load_dwordx4 v[24:27], v185, s[52:53] offset:48
	s_cmpk_gt_i32 s19, 0x7fff
	s_waitcnt vmcnt(43)
	v_mov_b32_e32 v64, v33
	v_mov_b32_e32 v65, v34
	v_mov_b32_e32 v33, v35
	s_waitcnt vmcnt(42)
	v_mov_b32_e32 v34, v37
	v_mov_b32_e32 v35, v38
	v_mov_b32_e32 v37, v39
	v_add_f32_e32 v32, v64, v32
	v_add_f32_e32 v33, v65, v33
	v_add_f32_e32 v34, v34, v36
	v_add_f32_e32 v35, v35, v37
	v_pk_add_f32 v[32:33], v[32:33], v[32:33] op_sel:[0,1] op_sel_hi:[1,0]
	v_pk_add_f32 v[34:35], v[34:35], v[34:35] op_sel:[0,1] op_sel_hi:[1,0]
	s_waitcnt vmcnt(40)
	v_mov_b32_e32 v33, v196
	v_mov_b32_e32 v35, v197
	v_add_f32_e32 v208, v40, v41
	v_add_f32_e32 v210, v42, v43
	v_add_f32_e32 v196, v32, v34
	v_add_f32_e32 v197, v33, v35
	global_load_dwordx4 v[32:35], v185, s[52:53] offset:32
	global_load_dwordx4 v[36:39], v185, s[52:53] offset:16
	global_load_dwordx4 v[64:67], v185, s[50:51] offset:48
	global_load_dwordx4 v[40:43], v185, s[52:53]
	v_mov_b32_e32 v209, v198
	v_mov_b32_e32 v211, v199
	v_add_f32_e32 v198, v208, v210
	v_add_f32_e32 v199, v209, v211
	v_lshl_add_u64 v[210:211], s[6:7], 0, v[184:185]
	v_add_f32_e32 v196, v196, v198
	v_add_f32_e32 v197, v197, v199
	s_nop 0
	v_add_f32_e32 v195, v196, v197
	v_fmamk_f32 v195, v195, 0x3a800000, v193
	v_mul_f32_e32 v196, 0x4f800000, v195
	v_cmp_gt_f32_e32 vcc, s74, v195
	s_nop 1
	v_cndmask_b32_e32 v195, v195, v196, vcc
	v_sqrt_f32_e32 v196, v195
	s_nop 0
	v_add_u32_e32 v198, -1, v196
	v_fma_f32 v199, -v198, v196, v195
	v_add_u32_e32 v197, 1, v196
	v_cmp_ge_f32_e64 s[0:1], 0, v199
	s_nop 1
	v_cndmask_b32_e64 v198, v196, v198, s[0:1]
	v_fma_f32 v196, -v197, v196, v195
	v_cmp_lt_f32_e64 s[0:1], 0, v196
	s_nop 1
	v_cndmask_b32_e64 v196, v198, v197, s[0:1]
	v_mul_f32_e32 v197, 0x37800000, v196
	v_cndmask_b32_e32 v196, v196, v197, vcc
	v_cmp_class_f32_e32 vcc, v195, v194
	s_nop 1
	v_cndmask_b32_e32 v195, v196, v195, vcc
	v_div_scale_f32 v196, s[0:1], v195, v195, 1.0
	v_rcp_f32_e32 v197, v196
	s_nop 0
	v_fma_f32 v198, -v196, v197, 1.0
	v_fmac_f32_e32 v197, v198, v197
	v_div_scale_f32 v198, vcc, 1.0, v195, 1.0
	v_mul_f32_e32 v199, v198, v197
	v_fma_f32 v208, -v196, v199, v198
	v_fmac_f32_e32 v199, v208, v197
	v_fma_f32 v196, -v196, v199, v198
	v_div_fmas_f32 v196, v196, v197, v199
	v_div_fixup_f32 v208, v196, v195, 1.0
	s_waitcnt vmcnt(26)
	v_lshlrev_b32_e32 v196, 16, v204
	v_and_b32_e32 v197, 0xffff0000, v204
	v_lshlrev_b32_e32 v198, 16, v205
	v_and_b32_e32 v199, 0xffff0000, v205
	v_mul_f32_e32 v196, v208, v196
	v_mul_f32_e32 v197, v208, v197
	v_mul_f32_e32 v198, v208, v198
	v_mul_f32_e32 v199, v208, v199
	v_mul_f32_e32 v198, v14, v198
	v_mul_f32_e32 v199, v15, v199
	v_mul_f32_e32 v196, v12, v196
	v_mul_f32_e32 v197, v13, v197
	global_store_dwordx4 v[210:211], v[196:199], off
	s_nop 1
	v_lshlrev_b32_e32 v196, 16, v206
	v_and_b32_e32 v197, 0xffff0000, v206
	v_lshlrev_b32_e32 v198, 16, v207
	v_and_b32_e32 v199, 0xffff0000, v207
	v_mul_f32_e32 v196, v208, v196
	v_mul_f32_e32 v197, v208, v197
	v_mul_f32_e32 v198, v208, v198
	v_mul_f32_e32 v199, v208, v199
	v_mul_f32_e32 v198, v10, v198
	v_mul_f32_e32 v199, v11, v199
	v_mul_f32_e32 v196, v8, v196
	v_mul_f32_e32 v197, v9, v197
	global_store_dwordx4 v[210:211], v[196:199], off offset:16
	s_nop 1
	v_lshlrev_b32_e32 v196, 16, v200
	v_and_b32_e32 v197, 0xffff0000, v200
	v_lshlrev_b32_e32 v198, 16, v201
	v_and_b32_e32 v199, 0xffff0000, v201
	v_mul_f32_e32 v196, v208, v196
	v_mul_f32_e32 v197, v208, v197
	v_mul_f32_e32 v198, v208, v198
	v_mul_f32_e32 v199, v208, v199
	v_mul_f32_e32 v198, v6, v198
	v_mul_f32_e32 v199, v7, v199
	v_mul_f32_e32 v196, v4, v196
	v_mul_f32_e32 v197, v5, v197
	global_store_dwordx4 v[210:211], v[196:199], off offset:32
	s_nop 1
	v_lshlrev_b32_e32 v196, 16, v202
	v_and_b32_e32 v197, 0xffff0000, v202
	v_lshlrev_b32_e32 v198, 16, v203
	v_and_b32_e32 v199, 0xffff0000, v203
	v_mul_f32_e32 v196, v208, v196
	v_mul_f32_e32 v197, v208, v197
	v_mul_f32_e32 v198, v208, v198
	v_mul_f32_e32 v199, v208, v199
	v_mul_f32_e32 v198, v2, v198
	v_mul_f32_e32 v199, v3, v199
	v_mul_f32_e32 v196, v0, v196
	v_mul_f32_e32 v197, v1, v197
	global_store_dwordx4 v[210:211], v[196:199], off offset:48
	s_cbranch_scc0 .LBB0_1207
	s_andn2_b64 vcc, exec, s[44:45]
	s_cbranch_vccz .LBB0_1208

.LBB0_1207:
	s_nop 0
	v_mov_b32_e32 v196, v181
	v_mov_b32_e32 v197, v182
	v_mov_b32_e32 v181, v183
	v_mov_b32_e32 v182, v177
	v_mov_b32_e32 v183, v178
	v_mov_b32_e32 v177, v179
	v_add_f32_e32 v180, v196, v180
	v_add_f32_e32 v181, v197, v181
	v_add_f32_e32 v176, v182, v176
	v_add_f32_e32 v177, v183, v177
	v_pk_add_f32 v[180:181], v[180:181], v[180:181] op_sel:[0,1] op_sel_hi:[1,0]
	v_pk_add_f32 v[176:177], v[176:177], v[176:177] op_sel:[0,1] op_sel_hi:[1,0]
	v_add_f32_e32 v172, v172, v173
	v_add_f32_e32 v174, v174, v175
	s_waitcnt vmcnt(27)
	v_mov_b32_e32 v181, v168
	v_mov_b32_e32 v177, v169
	v_mov_b32_e32 v173, v170
	v_mov_b32_e32 v175, v171
	v_add_f32_e32 v168, v180, v176
	v_add_f32_e32 v169, v181, v177
	v_add_f32_e32 v170, v172, v174
	v_add_f32_e32 v171, v173, v175
	v_lshl_add_u64 v[174:175], s[8:9], 0, v[184:185]
	v_add_f32_e32 v168, v168, v170
	v_add_f32_e32 v169, v169, v171
	s_nop 0
	v_add_f32_e32 v168, v168, v169
	v_fmamk_f32 v168, v168, 0x3a800000, v193
	v_mul_f32_e32 v169, 0x4f800000, v168
	v_cmp_gt_f32_e32 vcc, s74, v168
	s_nop 1
	v_cndmask_b32_e32 v168, v168, v169, vcc
	v_sqrt_f32_e32 v169, v168
	s_nop 0
	v_add_u32_e32 v170, -1, v169
	v_fma_f32 v171, -v170, v169, v168
	v_cmp_ge_f32_e64 s[0:1], 0, v171
	v_add_u32_e32 v171, 1, v169
	s_nop 0
	v_cndmask_b32_e64 v170, v169, v170, s[0:1]
	v_fma_f32 v169, -v171, v169, v168
	v_cmp_lt_f32_e64 s[0:1], 0, v169
	s_nop 1
	v_cndmask_b32_e64 v169, v170, v171, s[0:1]
	v_mul_f32_e32 v170, 0x37800000, v169
	v_cndmask_b32_e32 v169, v169, v170, vcc
	v_cmp_class_f32_e32 vcc, v168, v194
	s_nop 1
	v_cndmask_b32_e32 v168, v169, v168, vcc
	v_div_scale_f32 v169, s[0:1], v168, v168, 1.0
	v_rcp_f32_e32 v170, v169
	s_nop 0
	v_fma_f32 v171, -v169, v170, 1.0
	v_fmac_f32_e32 v170, v171, v170
	v_div_scale_f32 v171, vcc, 1.0, v168, 1.0
	v_mul_f32_e32 v172, v171, v170
	v_fma_f32 v173, -v169, v172, v171
	v_fmac_f32_e32 v172, v173, v170
	v_fma_f32 v169, -v169, v172, v171
	v_div_fmas_f32 v169, v169, v170, v172
	v_div_fixup_f32 v172, v169, v168, 1.0
	s_waitcnt vmcnt(9)
	v_lshlrev_b32_e32 v168, 16, v164
	v_and_b32_e32 v169, 0xffff0000, v164
	v_lshlrev_b32_e32 v164, 16, v165
	v_and_b32_e32 v165, 0xffff0000, v165
	v_mul_f32_e32 v164, v172, v164
	v_mul_f32_e32 v165, v172, v165
	v_mul_f32_e32 v170, v14, v164
	v_mul_f32_e32 v171, v15, v165
	v_lshlrev_b32_e32 v164, 16, v166
	v_and_b32_e32 v165, 0xffff0000, v166
	v_lshlrev_b32_e32 v166, 16, v167
	v_and_b32_e32 v167, 0xffff0000, v167
	v_mul_f32_e32 v164, v172, v164
	v_mul_f32_e32 v165, v172, v165
	v_mul_f32_e32 v166, v172, v166
	v_mul_f32_e32 v167, v172, v167
	v_mul_f32_e32 v166, v10, v166
	v_mul_f32_e32 v167, v11, v167
	v_mul_f32_e32 v164, v8, v164
	v_mul_f32_e32 v165, v9, v165
	global_store_dwordx4 v[174:175], v[164:167], off offset:16
	v_mul_f32_e32 v168, v172, v168
	v_mul_f32_e32 v169, v172, v169
	v_mul_f32_e32 v168, v12, v168
	v_mul_f32_e32 v169, v13, v169
	v_lshlrev_b32_e32 v164, 16, v152
	v_and_b32_e32 v165, 0xffff0000, v152
	v_lshlrev_b32_e32 v152, 16, v153
	v_and_b32_e32 v153, 0xffff0000, v153
	v_mul_f32_e32 v152, v172, v152
	v_mul_f32_e32 v153, v172, v153
	v_mul_f32_e32 v166, v6, v152
	v_mul_f32_e32 v167, v7, v153
	v_lshlrev_b32_e32 v152, 16, v154
	v_and_b32_e32 v153, 0xffff0000, v154
	v_lshlrev_b32_e32 v154, 16, v155
	v_and_b32_e32 v155, 0xffff0000, v155
	v_mul_f32_e32 v164, v172, v164
	v_mul_f32_e32 v165, v172, v165
	v_mul_f32_e32 v152, v172, v152
	v_mul_f32_e32 v153, v172, v153
	v_mul_f32_e32 v154, v172, v154
	v_mul_f32_e32 v155, v172, v155
	v_mul_f32_e32 v164, v4, v164
	v_mul_f32_e32 v165, v5, v165
	v_mul_f32_e32 v154, v2, v154
	v_mul_f32_e32 v155, v3, v155
	v_mul_f32_e32 v152, v0, v152
	v_mul_f32_e32 v153, v1, v153
	global_store_dwordx4 v[174:175], v[168:171], off
	global_store_dwordx4 v[174:175], v[164:167], off offset:32
	global_store_dwordx4 v[174:175], v[152:155], off offset:48
	s_andn2_b64 vcc, exec, s[44:45]
	s_cbranch_vccnz .LBB0_1202
.LBB0_1208:
	s_waitcnt vmcnt(26)
	v_add_f32_e32 v152, v160, v161
	v_add_f32_e32 v153, v162, v163
	v_add_f32_e32 v152, v152, v153
	v_add_f32_e32 v153, v156, v157
	v_add_f32_e32 v154, v158, v159
	v_add_f32_e32 v153, v153, v154
	v_add_f32_e32 v144, v144, v145
	v_add_f32_e32 v145, v146, v147
	v_add_f32_e32 v152, v152, v153
	v_add_f32_e32 v144, v144, v145
	s_waitcnt vmcnt(23)
	v_add_f32_e32 v145, v148, v149
	v_add_f32_e32 v146, v150, v151
	v_add_f32_e32 v144, v152, v144
	v_add_f32_e32 v145, v145, v146
	v_add_f32_e32 v144, v144, v145
	v_fmamk_f32 v144, v144, 0x3a800000, v193
	v_mul_f32_e32 v145, 0x4f800000, v144
	v_cmp_gt_f32_e32 vcc, s74, v144
	s_ashr_i32 s43, s42, 31
	s_nop 0
	v_cndmask_b32_e32 v144, v144, v145, vcc
	v_sqrt_f32_e32 v145, v144
	s_nop 0
	v_add_u32_e32 v146, -1, v145
	v_fma_f32 v147, -v146, v145, v144
	v_cmp_ge_f32_e64 s[0:1], 0, v147
	v_add_u32_e32 v147, 1, v145
	s_nop 0
	v_cndmask_b32_e64 v146, v145, v146, s[0:1]
	v_fma_f32 v145, -v147, v145, v144
	v_cmp_lt_f32_e64 s[0:1], 0, v145
	s_nop 1
	v_cndmask_b32_e64 v145, v146, v147, s[0:1]
	v_mul_f32_e32 v146, 0x37800000, v145
	v_cndmask_b32_e32 v145, v145, v146, vcc
	v_cmp_class_f32_e32 vcc, v144, v194
	s_nop 1
	v_cndmask_b32_e32 v144, v145, v144, vcc
	v_div_scale_f32 v145, s[0:1], v144, v144, 1.0
	v_rcp_f32_e32 v146, v145
	s_lshl_b64 s[0:1], s[42:43], 12
	v_lshl_add_u64 v[150:151], v[188:189], 0, s[0:1]
	v_fma_f32 v147, -v145, v146, 1.0
	v_fmac_f32_e32 v146, v147, v146
	v_div_scale_f32 v147, vcc, 1.0, v144, 1.0
	v_mul_f32_e32 v148, v147, v146
	v_fma_f32 v149, -v145, v148, v147
	v_fmac_f32_e32 v148, v149, v146
	v_fma_f32 v145, -v145, v148, v147
	v_div_fmas_f32 v145, v145, v146, v148
	v_div_fixup_f32 v148, v145, v144, 1.0
	v_lshlrev_b32_e32 v144, 16, v140
	v_and_b32_e32 v145, 0xffff0000, v140
	v_lshlrev_b32_e32 v140, 16, v141
	v_and_b32_e32 v141, 0xffff0000, v141
	v_mul_f32_e32 v140, v148, v140
	v_mul_f32_e32 v141, v148, v141
	v_mul_f32_e32 v146, v14, v140
	v_mul_f32_e32 v147, v15, v141
	v_lshlrev_b32_e32 v140, 16, v142
	v_and_b32_e32 v141, 0xffff0000, v142
	v_lshlrev_b32_e32 v142, 16, v143
	v_and_b32_e32 v143, 0xffff0000, v143
	v_mul_f32_e32 v140, v148, v140
	v_mul_f32_e32 v141, v148, v141
	v_mul_f32_e32 v142, v148, v142
	v_mul_f32_e32 v143, v148, v143
	v_mul_f32_e32 v142, v10, v142
	v_mul_f32_e32 v143, v11, v143
	v_mul_f32_e32 v140, v8, v140
	v_mul_f32_e32 v141, v9, v141
	global_store_dwordx4 v[150:151], v[140:143], off offset:16
	v_mul_f32_e32 v144, v148, v144
	v_mul_f32_e32 v145, v148, v145
	v_mul_f32_e32 v144, v12, v144
	v_mul_f32_e32 v145, v13, v145
	v_lshlrev_b32_e32 v140, 16, v128
	v_and_b32_e32 v141, 0xffff0000, v128
	v_lshlrev_b32_e32 v128, 16, v129
	v_and_b32_e32 v129, 0xffff0000, v129
	v_mul_f32_e32 v128, v148, v128
	v_mul_f32_e32 v129, v148, v129
	v_mul_f32_e32 v142, v6, v128
	v_mul_f32_e32 v143, v7, v129
	v_lshlrev_b32_e32 v128, 16, v130
	v_and_b32_e32 v129, 0xffff0000, v130
	v_lshlrev_b32_e32 v130, 16, v131
	v_and_b32_e32 v131, 0xffff0000, v131
	v_mul_f32_e32 v140, v148, v140
	v_mul_f32_e32 v141, v148, v141
	v_mul_f32_e32 v128, v148, v128
	v_mul_f32_e32 v129, v148, v129
	v_mul_f32_e32 v130, v148, v130
	v_mul_f32_e32 v131, v148, v131
	v_mul_f32_e32 v140, v4, v140
	v_mul_f32_e32 v141, v5, v141
	v_mul_f32_e32 v130, v2, v130
	v_mul_f32_e32 v131, v3, v131
	v_mul_f32_e32 v128, v0, v128
	v_mul_f32_e32 v129, v1, v129
	global_store_dwordx4 v[150:151], v[144:147], off
	global_store_dwordx4 v[150:151], v[140:143], off offset:32
	global_store_dwordx4 v[150:151], v[128:131], off offset:48
	s_andn2_b64 vcc, exec, s[40:41]
	s_cbranch_vccnz .LBB0_1203
.LBB0_1209:
	s_waitcnt vmcnt(22)
	v_add_f32_e32 v128, v136, v137
	v_add_f32_e32 v129, v138, v139
	v_add_f32_e32 v128, v128, v129
	v_add_f32_e32 v129, v132, v133
	v_add_f32_e32 v130, v134, v135
	v_add_f32_e32 v129, v129, v130
	v_add_f32_e32 v120, v120, v121
	v_add_f32_e32 v121, v122, v123
	v_add_f32_e32 v128, v128, v129
	v_add_f32_e32 v120, v120, v121
	s_waitcnt vmcnt(19)
	v_add_f32_e32 v121, v124, v125
	v_add_f32_e32 v122, v126, v127
	v_add_f32_e32 v120, v128, v120
	v_add_f32_e32 v121, v121, v122
	v_add_f32_e32 v120, v120, v121
	v_fmamk_f32 v120, v120, 0x3a800000, v193
	v_mul_f32_e32 v121, 0x4f800000, v120
	v_cmp_gt_f32_e32 vcc, s74, v120
	s_ashr_i32 s39, s38, 31
	s_nop 0
	v_cndmask_b32_e32 v120, v120, v121, vcc
	v_sqrt_f32_e32 v121, v120
	s_nop 0
	v_add_u32_e32 v122, -1, v121
	v_fma_f32 v123, -v122, v121, v120
	v_cmp_ge_f32_e64 s[0:1], 0, v123
	v_add_u32_e32 v123, 1, v121
	s_nop 0
	v_cndmask_b32_e64 v122, v121, v122, s[0:1]
	v_fma_f32 v121, -v123, v121, v120
	v_cmp_lt_f32_e64 s[0:1], 0, v121
	s_nop 1
	v_cndmask_b32_e64 v121, v122, v123, s[0:1]
	v_mul_f32_e32 v122, 0x37800000, v121
	v_cndmask_b32_e32 v121, v121, v122, vcc
	v_cmp_class_f32_e32 vcc, v120, v194
	s_nop 1
	v_cndmask_b32_e32 v120, v121, v120, vcc
	v_div_scale_f32 v121, s[0:1], v120, v120, 1.0
	v_rcp_f32_e32 v122, v121
	s_lshl_b64 s[0:1], s[38:39], 12
	v_lshl_add_u64 v[126:127], v[188:189], 0, s[0:1]
	v_fma_f32 v123, -v121, v122, 1.0
	v_fmac_f32_e32 v122, v123, v122
	v_div_scale_f32 v123, vcc, 1.0, v120, 1.0
	v_mul_f32_e32 v124, v123, v122
	v_fma_f32 v125, -v121, v124, v123
	v_fmac_f32_e32 v124, v125, v122
	v_fma_f32 v121, -v121, v124, v123
	v_div_fmas_f32 v121, v121, v122, v124
	v_div_fixup_f32 v124, v121, v120, 1.0
	v_lshlrev_b32_e32 v120, 16, v116
	v_and_b32_e32 v121, 0xffff0000, v116
	v_lshlrev_b32_e32 v116, 16, v117
	v_and_b32_e32 v117, 0xffff0000, v117
	v_mul_f32_e32 v116, v124, v116
	v_mul_f32_e32 v117, v124, v117
	v_mul_f32_e32 v122, v14, v116
	v_mul_f32_e32 v123, v15, v117
	v_lshlrev_b32_e32 v116, 16, v118
	v_and_b32_e32 v117, 0xffff0000, v118
	v_lshlrev_b32_e32 v118, 16, v119
	v_and_b32_e32 v119, 0xffff0000, v119
	v_mul_f32_e32 v116, v124, v116
	v_mul_f32_e32 v117, v124, v117
	v_mul_f32_e32 v118, v124, v118
	v_mul_f32_e32 v119, v124, v119
	v_mul_f32_e32 v118, v10, v118
	v_mul_f32_e32 v119, v11, v119
	v_mul_f32_e32 v116, v8, v116
	v_mul_f32_e32 v117, v9, v117
	global_store_dwordx4 v[126:127], v[116:119], off offset:16
	v_mul_f32_e32 v120, v124, v120
	v_mul_f32_e32 v121, v124, v121
	v_mul_f32_e32 v120, v12, v120
	v_mul_f32_e32 v121, v13, v121
	v_lshlrev_b32_e32 v116, 16, v104
	v_and_b32_e32 v117, 0xffff0000, v104
	v_lshlrev_b32_e32 v104, 16, v105
	v_and_b32_e32 v105, 0xffff0000, v105
	v_mul_f32_e32 v104, v124, v104
	v_mul_f32_e32 v105, v124, v105
	v_mul_f32_e32 v118, v6, v104
	v_mul_f32_e32 v119, v7, v105
	v_lshlrev_b32_e32 v104, 16, v106
	v_and_b32_e32 v105, 0xffff0000, v106
	v_lshlrev_b32_e32 v106, 16, v107
	v_and_b32_e32 v107, 0xffff0000, v107
	v_mul_f32_e32 v116, v124, v116
	v_mul_f32_e32 v117, v124, v117
	v_mul_f32_e32 v104, v124, v104
	v_mul_f32_e32 v105, v124, v105
	v_mul_f32_e32 v106, v124, v106
	v_mul_f32_e32 v107, v124, v107
	v_mul_f32_e32 v116, v4, v116
	v_mul_f32_e32 v117, v5, v117
	v_mul_f32_e32 v106, v2, v106
	v_mul_f32_e32 v107, v3, v107
	v_mul_f32_e32 v104, v0, v104
	v_mul_f32_e32 v105, v1, v105
	global_store_dwordx4 v[126:127], v[120:123], off
	global_store_dwordx4 v[126:127], v[116:119], off offset:32
	global_store_dwordx4 v[126:127], v[104:107], off offset:48
	s_andn2_b64 vcc, exec, s[36:37]
	s_cbranch_vccnz .LBB0_1204
.LBB0_1210:
	s_waitcnt vmcnt(18)
	v_add_f32_e32 v104, v112, v113
	v_add_f32_e32 v105, v114, v115
	v_add_f32_e32 v104, v104, v105
	v_add_f32_e32 v105, v108, v109
	v_add_f32_e32 v106, v110, v111
	v_add_f32_e32 v105, v105, v106
	v_add_f32_e32 v96, v96, v97
	v_add_f32_e32 v97, v98, v99
	v_add_f32_e32 v104, v104, v105
	v_add_f32_e32 v96, v96, v97
	s_waitcnt vmcnt(15)
	v_add_f32_e32 v97, v100, v101
	v_add_f32_e32 v98, v102, v103
	v_add_f32_e32 v96, v104, v96
	v_add_f32_e32 v97, v97, v98
	v_add_f32_e32 v96, v96, v97
	v_fmamk_f32 v96, v96, 0x3a800000, v193
	v_mul_f32_e32 v97, 0x4f800000, v96
	v_cmp_gt_f32_e32 vcc, s74, v96
	s_ashr_i32 s35, s34, 31
	s_nop 0
	v_cndmask_b32_e32 v96, v96, v97, vcc
	v_sqrt_f32_e32 v97, v96
	s_nop 0
	v_add_u32_e32 v98, -1, v97
	v_fma_f32 v99, -v98, v97, v96
	v_cmp_ge_f32_e64 s[0:1], 0, v99
	v_add_u32_e32 v99, 1, v97
	s_nop 0
	v_cndmask_b32_e64 v98, v97, v98, s[0:1]
	v_fma_f32 v97, -v99, v97, v96
	v_cmp_lt_f32_e64 s[0:1], 0, v97
	s_nop 1
	v_cndmask_b32_e64 v97, v98, v99, s[0:1]
	v_mul_f32_e32 v98, 0x37800000, v97
	v_cndmask_b32_e32 v97, v97, v98, vcc
	v_cmp_class_f32_e32 vcc, v96, v194
	s_nop 1
	v_cndmask_b32_e32 v96, v97, v96, vcc
	v_div_scale_f32 v97, s[0:1], v96, v96, 1.0
	v_rcp_f32_e32 v98, v97
	s_lshl_b64 s[0:1], s[34:35], 12
	v_lshl_add_u64 v[102:103], v[188:189], 0, s[0:1]
	v_fma_f32 v99, -v97, v98, 1.0
	v_fmac_f32_e32 v98, v99, v98
	v_div_scale_f32 v99, vcc, 1.0, v96, 1.0
	v_mul_f32_e32 v100, v99, v98
	v_fma_f32 v101, -v97, v100, v99
	v_fmac_f32_e32 v100, v101, v98
	v_fma_f32 v97, -v97, v100, v99
	v_div_fmas_f32 v97, v97, v98, v100
	v_div_fixup_f32 v100, v97, v96, 1.0
	v_lshlrev_b32_e32 v96, 16, v92
	v_and_b32_e32 v97, 0xffff0000, v92
	v_lshlrev_b32_e32 v92, 16, v93
	v_and_b32_e32 v93, 0xffff0000, v93
	v_mul_f32_e32 v92, v100, v92
	v_mul_f32_e32 v93, v100, v93
	v_mul_f32_e32 v98, v14, v92
	v_mul_f32_e32 v99, v15, v93
	v_lshlrev_b32_e32 v92, 16, v94
	v_and_b32_e32 v93, 0xffff0000, v94
	v_lshlrev_b32_e32 v94, 16, v95
	v_and_b32_e32 v95, 0xffff0000, v95
	v_mul_f32_e32 v92, v100, v92
	v_mul_f32_e32 v93, v100, v93
	v_mul_f32_e32 v94, v100, v94
	v_mul_f32_e32 v95, v100, v95
	v_mul_f32_e32 v94, v10, v94
	v_mul_f32_e32 v95, v11, v95
	v_mul_f32_e32 v92, v8, v92
	v_mul_f32_e32 v93, v9, v93
	global_store_dwordx4 v[102:103], v[92:95], off offset:16
	v_mul_f32_e32 v96, v100, v96
	v_mul_f32_e32 v97, v100, v97
	v_mul_f32_e32 v96, v12, v96
	v_mul_f32_e32 v97, v13, v97
	v_lshlrev_b32_e32 v92, 16, v76
	v_and_b32_e32 v93, 0xffff0000, v76
	v_lshlrev_b32_e32 v76, 16, v77
	v_and_b32_e32 v77, 0xffff0000, v77
	v_mul_f32_e32 v76, v100, v76
	v_mul_f32_e32 v77, v100, v77
	v_mul_f32_e32 v94, v6, v76
	v_mul_f32_e32 v95, v7, v77
	v_lshlrev_b32_e32 v76, 16, v78
	v_and_b32_e32 v77, 0xffff0000, v78
	v_lshlrev_b32_e32 v78, 16, v79
	v_and_b32_e32 v79, 0xffff0000, v79
	v_mul_f32_e32 v92, v100, v92
	v_mul_f32_e32 v93, v100, v93
	v_mul_f32_e32 v76, v100, v76
	v_mul_f32_e32 v77, v100, v77
	v_mul_f32_e32 v78, v100, v78
	v_mul_f32_e32 v79, v100, v79
	v_mul_f32_e32 v92, v4, v92
	v_mul_f32_e32 v93, v5, v93
	v_mul_f32_e32 v78, v2, v78
	v_mul_f32_e32 v79, v3, v79
	v_mul_f32_e32 v76, v0, v76
	v_mul_f32_e32 v77, v1, v77
	global_store_dwordx4 v[102:103], v[96:99], off
	global_store_dwordx4 v[102:103], v[92:95], off offset:32
	global_store_dwordx4 v[102:103], v[76:79], off offset:48
	s_andn2_b64 vcc, exec, s[30:31]
	s_cbranch_vccnz .LBB0_1205
.LBB0_1211:
	s_waitcnt vmcnt(14)
	v_add_f32_e32 v76, v88, v89
	v_add_f32_e32 v77, v90, v91
	v_add_f32_e32 v76, v76, v77
	v_add_f32_e32 v77, v84, v85
	v_add_f32_e32 v78, v86, v87
	v_add_f32_e32 v77, v77, v78
	v_add_f32_e32 v72, v72, v73
	v_add_f32_e32 v73, v74, v75
	v_add_f32_e32 v76, v76, v77
	v_add_f32_e32 v72, v72, v73
	s_waitcnt vmcnt(11)
	v_add_f32_e32 v73, v80, v81
	v_add_f32_e32 v74, v82, v83
	v_add_f32_e32 v72, v76, v72
	v_add_f32_e32 v73, v73, v74
	v_add_f32_e32 v72, v72, v73
	v_fmamk_f32 v72, v72, 0x3a800000, v193
	v_mul_f32_e32 v73, 0x4f800000, v72
	v_cmp_gt_f32_e32 vcc, s74, v72
	s_ashr_i32 s29, s28, 31
	s_nop 0
	v_cndmask_b32_e32 v72, v72, v73, vcc
	v_sqrt_f32_e32 v73, v72
	s_nop 0
	v_add_u32_e32 v74, -1, v73
	v_fma_f32 v75, -v74, v73, v72
	v_cmp_ge_f32_e64 s[0:1], 0, v75
	v_add_u32_e32 v75, 1, v73
	s_nop 0
	v_cndmask_b32_e64 v74, v73, v74, s[0:1]
	v_fma_f32 v73, -v75, v73, v72
	v_cmp_lt_f32_e64 s[0:1], 0, v73
	s_nop 1
	v_cndmask_b32_e64 v73, v74, v75, s[0:1]
	v_mul_f32_e32 v74, 0x37800000, v73
	v_cndmask_b32_e32 v73, v73, v74, vcc
	v_cmp_class_f32_e32 vcc, v72, v194
	s_nop 1
	v_cndmask_b32_e32 v72, v73, v72, vcc
	v_div_scale_f32 v73, s[0:1], v72, v72, 1.0
	v_rcp_f32_e32 v74, v73
	s_lshl_b64 s[0:1], s[28:29], 12
	v_lshl_add_u64 v[78:79], v[188:189], 0, s[0:1]
	v_fma_f32 v75, -v73, v74, 1.0
	v_fmac_f32_e32 v74, v75, v74
	v_div_scale_f32 v75, vcc, 1.0, v72, 1.0
	v_mul_f32_e32 v76, v75, v74
	v_fma_f32 v77, -v73, v76, v75
	v_fmac_f32_e32 v76, v77, v74
	v_fma_f32 v73, -v73, v76, v75
	v_div_fmas_f32 v73, v73, v74, v76
	v_div_fixup_f32 v76, v73, v72, 1.0
	v_lshlrev_b32_e32 v72, 16, v68
	v_and_b32_e32 v73, 0xffff0000, v68
	v_lshlrev_b32_e32 v68, 16, v69
	v_and_b32_e32 v69, 0xffff0000, v69
	v_mul_f32_e32 v68, v76, v68
	v_mul_f32_e32 v69, v76, v69
	v_mul_f32_e32 v74, v14, v68
	v_mul_f32_e32 v75, v15, v69
	v_lshlrev_b32_e32 v68, 16, v70
	v_and_b32_e32 v69, 0xffff0000, v70
	v_lshlrev_b32_e32 v70, 16, v71
	v_and_b32_e32 v71, 0xffff0000, v71
	v_mul_f32_e32 v68, v76, v68
	v_mul_f32_e32 v69, v76, v69
	v_mul_f32_e32 v70, v76, v70
	v_mul_f32_e32 v71, v76, v71
	v_mul_f32_e32 v70, v10, v70
	v_mul_f32_e32 v71, v11, v71
	v_mul_f32_e32 v68, v8, v68
	v_mul_f32_e32 v69, v9, v69
	global_store_dwordx4 v[78:79], v[68:71], off offset:16
	v_mul_f32_e32 v72, v76, v72
	v_mul_f32_e32 v73, v76, v73
	v_mul_f32_e32 v72, v12, v72
	v_mul_f32_e32 v73, v13, v73
	v_lshlrev_b32_e32 v68, 16, v52
	v_and_b32_e32 v69, 0xffff0000, v52
	v_lshlrev_b32_e32 v52, 16, v53
	v_and_b32_e32 v53, 0xffff0000, v53
	v_mul_f32_e32 v52, v76, v52
	v_mul_f32_e32 v53, v76, v53
	v_mul_f32_e32 v70, v6, v52
	v_mul_f32_e32 v71, v7, v53
	v_lshlrev_b32_e32 v52, 16, v54
	v_and_b32_e32 v53, 0xffff0000, v54
	v_lshlrev_b32_e32 v54, 16, v55
	v_and_b32_e32 v55, 0xffff0000, v55
	v_mul_f32_e32 v68, v76, v68
	v_mul_f32_e32 v69, v76, v69
	v_mul_f32_e32 v52, v76, v52
	v_mul_f32_e32 v53, v76, v53
	v_mul_f32_e32 v54, v76, v54
	v_mul_f32_e32 v55, v76, v55
	v_mul_f32_e32 v68, v4, v68
	v_mul_f32_e32 v69, v5, v69
	v_mul_f32_e32 v54, v2, v54
	v_mul_f32_e32 v55, v3, v55
	v_mul_f32_e32 v52, v0, v52
	v_mul_f32_e32 v53, v1, v53
	global_store_dwordx4 v[78:79], v[72:75], off
	global_store_dwordx4 v[78:79], v[68:71], off offset:32
	global_store_dwordx4 v[78:79], v[52:55], off offset:48
	s_andn2_b64 vcc, exec, s[26:27]
	s_cbranch_vccnz .LBB0_1206
.LBB0_1212:
	s_waitcnt vmcnt(10)
	v_add_f32_e32 v52, v60, v61
	v_add_f32_e32 v53, v62, v63
	v_add_f32_e32 v52, v52, v53
	v_add_f32_e32 v53, v56, v57
	v_add_f32_e32 v54, v58, v59
	v_add_f32_e32 v53, v53, v54
	v_add_f32_e32 v48, v48, v49
	v_add_f32_e32 v49, v50, v51
	v_add_f32_e32 v52, v52, v53
	v_add_f32_e32 v48, v48, v49
	s_waitcnt vmcnt(5)
	v_add_f32_e32 v49, v64, v65
	v_add_f32_e32 v50, v66, v67
	v_add_f32_e32 v48, v52, v48
	v_add_f32_e32 v49, v49, v50
	v_add_f32_e32 v48, v48, v49
	v_fmamk_f32 v48, v48, 0x3a800000, v193
	v_mul_f32_e32 v49, 0x4f800000, v48
	v_cmp_gt_f32_e32 vcc, s74, v48
	s_ashr_i32 s25, s24, 31
	s_nop 0
	v_cndmask_b32_e32 v48, v48, v49, vcc
	v_sqrt_f32_e32 v49, v48
	s_nop 0
	v_add_u32_e32 v50, -1, v49
	v_fma_f32 v51, -v50, v49, v48
	v_cmp_ge_f32_e64 s[0:1], 0, v51
	v_add_u32_e32 v51, 1, v49
	s_nop 0
	v_cndmask_b32_e64 v50, v49, v50, s[0:1]
	v_fma_f32 v49, -v51, v49, v48
	v_cmp_lt_f32_e64 s[0:1], 0, v49
	s_nop 1
	v_cndmask_b32_e64 v49, v50, v51, s[0:1]
	v_mul_f32_e32 v50, 0x37800000, v49
	v_cndmask_b32_e32 v49, v49, v50, vcc
	v_cmp_class_f32_e32 vcc, v48, v194
	s_nop 1
	v_cndmask_b32_e32 v48, v49, v48, vcc
	v_div_scale_f32 v49, s[0:1], v48, v48, 1.0
	v_rcp_f32_e32 v50, v49
	s_lshl_b64 s[0:1], s[24:25], 12
	v_lshl_add_u64 v[54:55], v[188:189], 0, s[0:1]
	v_fma_f32 v51, -v49, v50, 1.0
	v_fmac_f32_e32 v50, v51, v50
	v_div_scale_f32 v51, vcc, 1.0, v48, 1.0
	v_mul_f32_e32 v52, v51, v50
	v_fma_f32 v53, -v49, v52, v51
	v_fmac_f32_e32 v52, v53, v50
	v_fma_f32 v49, -v49, v52, v51
	v_div_fmas_f32 v49, v49, v50, v52
	v_div_fixup_f32 v52, v49, v48, 1.0
	v_lshlrev_b32_e32 v48, 16, v44
	v_and_b32_e32 v49, 0xffff0000, v44
	v_lshlrev_b32_e32 v44, 16, v45
	v_and_b32_e32 v45, 0xffff0000, v45
	v_mul_f32_e32 v44, v52, v44
	v_mul_f32_e32 v45, v52, v45
	v_mul_f32_e32 v50, v14, v44
	v_mul_f32_e32 v51, v15, v45
	v_lshlrev_b32_e32 v44, 16, v46
	v_and_b32_e32 v45, 0xffff0000, v46
	v_lshlrev_b32_e32 v46, 16, v47
	v_and_b32_e32 v47, 0xffff0000, v47
	v_mul_f32_e32 v44, v52, v44
	v_mul_f32_e32 v45, v52, v45
	v_mul_f32_e32 v46, v52, v46
	v_mul_f32_e32 v47, v52, v47
	v_mul_f32_e32 v46, v10, v46
	v_mul_f32_e32 v47, v11, v47
	v_mul_f32_e32 v44, v8, v44
	v_mul_f32_e32 v45, v9, v45
	global_store_dwordx4 v[54:55], v[44:47], off offset:16
	v_mul_f32_e32 v48, v52, v48
	v_mul_f32_e32 v49, v52, v49
	v_mul_f32_e32 v48, v12, v48
	v_mul_f32_e32 v49, v13, v49
	v_lshlrev_b32_e32 v44, 16, v28
	v_and_b32_e32 v45, 0xffff0000, v28
	v_lshlrev_b32_e32 v28, 16, v29
	v_and_b32_e32 v29, 0xffff0000, v29
	v_mul_f32_e32 v28, v52, v28
	v_mul_f32_e32 v29, v52, v29
	v_mul_f32_e32 v46, v6, v28
	v_mul_f32_e32 v47, v7, v29
	v_lshlrev_b32_e32 v28, 16, v30
	v_and_b32_e32 v29, 0xffff0000, v30
	v_lshlrev_b32_e32 v30, 16, v31
	v_and_b32_e32 v31, 0xffff0000, v31
	v_mul_f32_e32 v44, v52, v44
	v_mul_f32_e32 v45, v52, v45
	v_mul_f32_e32 v28, v52, v28
	v_mul_f32_e32 v29, v52, v29
	v_mul_f32_e32 v30, v52, v30
	v_mul_f32_e32 v31, v52, v31
	v_mul_f32_e32 v44, v4, v44
	v_mul_f32_e32 v45, v5, v45
	v_mul_f32_e32 v30, v2, v30
	v_mul_f32_e32 v31, v3, v31
	v_mul_f32_e32 v28, v0, v28
	v_mul_f32_e32 v29, v1, v29
	global_store_dwordx4 v[54:55], v[48:51], off
	global_store_dwordx4 v[54:55], v[44:47], off offset:32
	global_store_dwordx4 v[54:55], v[28:31], off offset:48
	s_andn2_b64 vcc, exec, s[22:23]
	s_cbranch_vccnz .LBB0_1199
.LBB0_1213:
	s_waitcnt vmcnt(4)
	v_add_f32_e32 v28, v40, v41
	v_add_f32_e32 v29, v42, v43
	v_add_f32_e32 v28, v28, v29
	v_add_f32_e32 v29, v36, v37
	v_add_f32_e32 v30, v38, v39
	v_add_f32_e32 v29, v29, v30
	v_add_f32_e32 v28, v28, v29
	v_add_f32_e32 v29, v32, v33
	v_add_f32_e32 v30, v34, v35
	v_add_f32_e32 v29, v29, v30
	v_add_f32_e32 v24, v24, v25
	v_add_f32_e32 v25, v26, v27
	v_add_f32_e32 v28, v28, v29
	v_add_f32_e32 v24, v24, v25
	v_add_f32_e32 v24, v28, v24
	v_fmamk_f32 v24, v24, 0x3a800000, v193
	v_mul_f32_e32 v25, 0x4f800000, v24
	v_cmp_gt_f32_e32 vcc, s74, v24
	s_ashr_i32 s19, s18, 31
	s_nop 0
	v_cndmask_b32_e32 v24, v24, v25, vcc
	v_sqrt_f32_e32 v25, v24
	s_nop 0
	v_add_u32_e32 v26, -1, v25
	v_fma_f32 v27, -v26, v25, v24
	v_cmp_ge_f32_e64 s[0:1], 0, v27
	v_add_u32_e32 v27, 1, v25
	s_nop 0
	v_cndmask_b32_e64 v26, v25, v26, s[0:1]
	v_fma_f32 v25, -v27, v25, v24
	v_cmp_lt_f32_e64 s[0:1], 0, v25
	s_nop 1
	v_cndmask_b32_e64 v25, v26, v27, s[0:1]
	v_mul_f32_e32 v26, 0x37800000, v25
	v_cndmask_b32_e32 v25, v25, v26, vcc
	v_cmp_class_f32_e32 vcc, v24, v194
	s_nop 1
	v_cndmask_b32_e32 v24, v25, v24, vcc
	v_div_scale_f32 v25, s[0:1], v24, v24, 1.0
	v_rcp_f32_e32 v26, v25
	s_lshl_b64 s[0:1], s[18:19], 12
	v_lshl_add_u64 v[30:31], v[188:189], 0, s[0:1]
	v_fma_f32 v27, -v25, v26, 1.0
	v_fmac_f32_e32 v26, v27, v26
	v_div_scale_f32 v27, vcc, 1.0, v24, 1.0
	v_mul_f32_e32 v28, v27, v26
	v_fma_f32 v29, -v25, v28, v27
	v_fmac_f32_e32 v28, v29, v26
	v_fma_f32 v25, -v25, v28, v27
	v_div_fmas_f32 v25, v25, v26, v28
	v_div_fixup_f32 v28, v25, v24, 1.0
	v_lshlrev_b32_e32 v24, 16, v20
	v_and_b32_e32 v25, 0xffff0000, v20
	v_lshlrev_b32_e32 v20, 16, v21
	v_and_b32_e32 v21, 0xffff0000, v21
	v_mul_f32_e32 v20, v28, v20
	v_mul_f32_e32 v21, v28, v21
	v_mul_f32_e32 v26, v14, v20
	v_mul_f32_e32 v27, v15, v21
	v_lshlrev_b32_e32 v20, 16, v22
	v_and_b32_e32 v21, 0xffff0000, v22
	v_lshlrev_b32_e32 v22, 16, v23
	v_and_b32_e32 v23, 0xffff0000, v23
	v_mul_f32_e32 v20, v28, v20
	v_mul_f32_e32 v21, v28, v21
	v_mul_f32_e32 v22, v28, v22
	v_mul_f32_e32 v23, v28, v23
	v_mul_f32_e32 v22, v10, v22
	v_mul_f32_e32 v23, v11, v23
	v_mul_f32_e32 v20, v8, v20
	v_mul_f32_e32 v21, v9, v21
	global_store_dwordx4 v[30:31], v[20:23], off offset:16
	v_mul_f32_e32 v24, v28, v24
	v_mul_f32_e32 v25, v28, v25
	v_mul_f32_e32 v24, v12, v24
	v_mul_f32_e32 v25, v13, v25
	v_lshlrev_b32_e32 v20, 16, v16
	v_and_b32_e32 v21, 0xffff0000, v16
	v_lshlrev_b32_e32 v16, 16, v17
	v_and_b32_e32 v17, 0xffff0000, v17
	v_mul_f32_e32 v16, v28, v16
	v_mul_f32_e32 v17, v28, v17
	v_mul_f32_e32 v22, v6, v16
	v_mul_f32_e32 v23, v7, v17
	v_lshlrev_b32_e32 v16, 16, v18
	v_and_b32_e32 v17, 0xffff0000, v18
	v_lshlrev_b32_e32 v18, 16, v19
	v_and_b32_e32 v19, 0xffff0000, v19
	v_mul_f32_e32 v20, v28, v20
	v_mul_f32_e32 v21, v28, v21
	v_mul_f32_e32 v16, v28, v16
	v_mul_f32_e32 v17, v28, v17
	v_mul_f32_e32 v18, v28, v18
	v_mul_f32_e32 v19, v28, v19
	v_mul_f32_e32 v20, v4, v20
	v_mul_f32_e32 v21, v5, v21
	v_mul_f32_e32 v18, v2, v18
	v_mul_f32_e32 v19, v3, v19
	v_mul_f32_e32 v16, v0, v16
	v_mul_f32_e32 v17, v1, v17
	global_store_dwordx4 v[30:31], v[24:27], off
	global_store_dwordx4 v[30:31], v[20:23], off offset:32
	global_store_dwordx4 v[30:31], v[16:19], off offset:48
	s_branch .LBB0_1199
